# GEMM K-loops: 2 of the 6 LDS-DMA pieces of the heavy load segment issued one segment later (4+4 instead of 6+2), its wait vmcnt 8 to 6; on top of v16
# speedup vs baseline: 1.0074x; 1.0074x over previous
; #define PG8_STAGE(bufoff, gbase, voff) do { _Pragma("unroll") for (int _i = 0; _i < 2; ++_i) \
;         __builtin_amdgcn_global_load_lds((const unsigned*)((const char*)(gbase) + (voff)[_i]), (PG8_LAS unsigned*)(lds + (bufoff) + ldsw + _i * 8192), 16, 0, 0); } while (0)
; #define PG8_LDA(dst, b, h) do { _Pragma("unroll") for (int m = 0; m < 4; ++m) _Pragma("unroll") for (int k = 0; k < 2; ++k) dst[m][k] = *(const PG8_LAS bf16x8*)(lds + PG8_SA(b, h) + aoff + m * 2048 + k * 1024); } while (0)
; #define PG8_LDB(dst, b, h) do { _Pragma("unroll") for (int n = 0; n < 2; ++n) _Pragma("unroll") for (int k = 0; k < 2; ++k) dst[n][k] = *(const PG8_LAS bf16x8*)(lds + PG8_SB(b, h) + boff + n * 2048 + k * 1024); } while (0)
; #define PG8_WAIT_V(n) asm volatile("s_waitcnt vmcnt(" #n ")" ::: "memory")
; #define PG8_WAIT_L(n) asm volatile("s_waitcnt lgkmcnt(" #n ")" ::: "memory")
; #define PG8_BAR __builtin_amdgcn_s_barrier()
; #define PG8_SCHED __builtin_amdgcn_sched_barrier(0)
; template <class Epi, class Sched, bool ALIGN_EPI = false, bool SP2 = false>
; __device__ __forceinline__ void gemm_phase(PG8_LAS unsigned char* lds, const Gemm g, const Sched& S, const Epi& E) {
;     ...
;         const char* nA = has_next ? (const char*)g.A + (size_t)nxt.pm * tstep + (size_t)nxt.ks * K * 2 : cA; const char* nB = has_next ? (const char*)g.Bt + (size_t)nxt.pn * tstep + (size_t)nxt.ks * K * 2 : cB;
;         for (int t = 0; t < nt; t += 2) {
;             const bool last = (t == nt - 2);
;             const char* a1 = cA + (size_t)(t + 1) * kstep;
;             const char* a2 = last ? nA : cA + (size_t)(t + 2) * kstep; const char* b2 = last ? nB : cB + (size_t)(t + 2) * kstep;
;             const char* a3 = a2 + kstep; const char* b3 = b2 + kstep;
;             if (last && has_next) S.a_ready(nxt);
;             if constexpr (SP2) {
;             PG8_LDB(B0, 0, 0); PG8_LDB(B1, 0, 1); PG8_SCHED; PG8_LDA(At, 0, 0); PG8_STAGE(PG8_SA(1, 1), a1 + hstep, voffA);
;             PG8_WAIT_V(8); PG8_WAIT_L(0); PG8_BAR; PG8_MMA(0, 0, At, B0); PG8_MMA(0, 1, At, B1); PG8_BAR; PG8_SCHED;
;             PG8_LDA(At, 0, 1); PG8_STAGE(PG8_SB(0, 0), b2, voffB); PG8_STAGE(PG8_SB(0, 1), b2 + hstep, voffB); PG8_STAGE(PG8_SA(0, 0), a2, voffA);
;             PG8_WAIT_V(8); PG8_WAIT_L(0); PG8_BAR; PG8_MMA(1, 0, At, B0); PG8_MMA(1, 1, At, B1); PG8_BAR; PG8_SCHED;
.LBB0_256:
	s_ashr_i32 s13, s12, 31
	s_lshl_b64 s[22:23], s[12:13], 19
	s_add_u32 s22, s28, s22
	s_addc_u32 s23, s29, s23
	s_and_b64 s[24:25], s[2:3], exec
	s_cselect_b32 s13, s23, s45
	s_cselect_b32 s36, s22, s44
	s_ashr_i32 s11, s10, 31
	s_lshl_b64 s[24:25], s[10:11], 19
	s_add_u32 s24, s30, s24
	s_addc_u32 s25, s31, s25
	s_and_b64 s[40:41], s[2:3], exec
	s_cselect_b32 s11, s25, s43
	s_cselect_b32 s37, s24, s42
	s_add_u32 s40, s42, 0x100
	s_addc_u32 s41, s43, 0
	s_add_u32 s42, s44, 0x40080
	s_addc_u32 s43, s45, 0
	s_mov_b32 s48, -2
	ds_read_b128 v[146:149], v152
	ds_read_b128 v[158:161], v152 offset:1024
	ds_read_b128 v[162:165], v152 offset:2048
	ds_read_b128 v[166:169], v152 offset:3072
	ds_read_b128 v[170:173], v153
	ds_read_b128 v[174:177], v153 offset:1024
	ds_read_b128 v[178:181], v153 offset:2048
	ds_read_b128 v[182:185], v153 offset:3072
	s_add_u32 s44, s42, 0xfffc0080
	s_addc_u32 s45, s43, -1
	s_cmp_eq_u32 s48, 12
	s_cselect_b32 s47, s13, s45
	s_cselect_b32 s46, s36, s44
	s_cselect_b32 s45, s11, s41
	s_cselect_b32 s44, s37, s40
	v_lshl_add_u64 v[218:219], s[42:43], 0, v[140:141]
	s_add_i32 m0, s61, 0xc000
	ds_read_b128 v[186:189], v154
	ds_read_b128 v[190:193], v154 offset:1024
	ds_read_b128 v[194:197], v154 offset:2048
	ds_read_b128 v[198:201], v154 offset:3072
	ds_read_b128 v[202:205], v154 offset:4096
	ds_read_b128 v[206:209], v154 offset:5120
	ds_read_b128 v[210:213], v154 offset:6144
	ds_read_b128 v[214:217], v154 offset:7168
	global_load_lds_dwordx4 v[218:219], off
	v_lshl_add_u64 v[218:219], s[42:43], 0, v[138:139]
	s_add_i32 m0, s61, 0xe000
	s_nop 0
	global_load_lds_dwordx4 v[218:219], off
	s_waitcnt vmcnt(8)
	s_waitcnt lgkmcnt(0)
	s_barrier
	s_setprio 1
	s_waitcnt lgkmcnt(0)
	v_mfma_f32_16x16x32_bf16 v[126:129], v[146:149], v[186:189], 0
	v_mfma_f32_16x16x32_bf16 v[118:121], v[162:165], v[186:189], 0
	v_mfma_f32_16x16x32_bf16 v[110:113], v[146:149], v[194:197], 0
	v_mfma_f32_16x16x32_bf16 v[102:105], v[162:165], v[194:197], 0
	v_mfma_f32_16x16x32_bf16 v[94:97], v[146:149], v[202:205], 0
	v_mfma_f32_16x16x32_bf16 v[86:89], v[162:165], v[202:205], 0
	v_mfma_f32_16x16x32_bf16 v[78:81], v[146:149], v[210:213], 0
	v_mfma_f32_16x16x32_bf16 v[70:73], v[162:165], v[210:213], 0
	v_mfma_f32_16x16x32_bf16 v[126:129], v[158:161], v[190:193], v[126:129]
	v_mfma_f32_16x16x32_bf16 v[118:121], v[166:169], v[190:193], v[118:121]
	v_mfma_f32_16x16x32_bf16 v[110:113], v[158:161], v[198:201], v[110:113]
	v_mfma_f32_16x16x32_bf16 v[102:105], v[166:169], v[198:201], v[102:105]
	v_mfma_f32_16x16x32_bf16 v[94:97], v[158:161], v[206:209], v[94:97]
	v_mfma_f32_16x16x32_bf16 v[86:89], v[166:169], v[206:209], v[86:89]
	v_mfma_f32_16x16x32_bf16 v[78:81], v[158:161], v[214:217], v[78:81]
	v_mfma_f32_16x16x32_bf16 v[70:73], v[166:169], v[214:217], v[70:73]
	s_setprio 0
	s_setprio 1
	v_mfma_f32_16x16x32_bf16 v[122:125], v[170:173], v[186:189], 0
	v_mfma_f32_16x16x32_bf16 v[114:117], v[178:181], v[186:189], 0
	v_mfma_f32_16x16x32_bf16 v[106:109], v[170:173], v[194:197], 0
	v_mfma_f32_16x16x32_bf16 v[98:101], v[178:181], v[194:197], 0
	v_mfma_f32_16x16x32_bf16 v[90:93], v[170:173], v[202:205], 0
	v_mfma_f32_16x16x32_bf16 v[82:85], v[178:181], v[202:205], 0
	v_mfma_f32_16x16x32_bf16 v[74:77], v[170:173], v[210:213], 0
	v_mfma_f32_16x16x32_bf16 v[66:69], v[178:181], v[210:213], 0
	v_mfma_f32_16x16x32_bf16 v[122:125], v[174:177], v[190:193], v[122:125]
	v_mfma_f32_16x16x32_bf16 v[114:117], v[182:185], v[190:193], v[114:117]
	v_mfma_f32_16x16x32_bf16 v[106:109], v[174:177], v[198:201], v[106:109]
	v_mfma_f32_16x16x32_bf16 v[98:101], v[182:185], v[198:201], v[98:101]
	v_mfma_f32_16x16x32_bf16 v[90:93], v[174:177], v[206:209], v[90:93]
	v_mfma_f32_16x16x32_bf16 v[82:85], v[182:185], v[206:209], v[82:85]
	v_mfma_f32_16x16x32_bf16 v[74:77], v[174:177], v[214:217], v[74:77]
	v_mfma_f32_16x16x32_bf16 v[66:69], v[182:185], v[214:217], v[66:69]
	s_setprio 0
	s_barrier
	s_mov_b32 m0, s39
	v_lshl_add_u64 v[218:219], s[44:45], 0, v[134:135]
	s_add_u32 s50, s44, 0x40000
	ds_read_b128 v[186:189], v154 offset:16384
	ds_read_b128 v[190:193], v154 offset:17408
	ds_read_b128 v[194:197], v154 offset:18432
	ds_read_b128 v[198:201], v154 offset:19456
	ds_read_b128 v[202:205], v154 offset:20480
	ds_read_b128 v[206:209], v154 offset:21504
	ds_read_b128 v[210:213], v154 offset:22528
	ds_read_b128 v[214:217], v154 offset:23552
	global_load_lds_dwordx4 v[218:219], off
	v_lshl_add_u64 v[220:221], s[44:45], 0, v[130:131]
	s_mov_b32 m0, s56
	s_addc_u32 s51, s45, 0
	global_load_lds_dwordx4 v[220:221], off
	v_lshl_add_u64 v[222:223], s[50:51], 0, v[134:135]
	s_mov_b32 m0, s57
	v_lshl_add_u64 v[224:225], s[46:47], 0, v[132:133]
	global_load_lds_dwordx4 v[222:223], off
	v_lshl_add_u64 v[222:223], s[50:51], 0, v[130:131]
	s_mov_b32 m0, s60
	s_nop 0
	global_load_lds_dwordx4 v[222:223], off
	v_lshl_add_u64 v[222:223], s[46:47], 0, v[136:137]
	s_waitcnt vmcnt(6)
	s_waitcnt lgkmcnt(0)
	s_barrier
; #define PG8_STAGE(bufoff, gbase, voff) do { _Pragma("unroll") for (int _i = 0; _i < 2; ++_i) \
;         __builtin_amdgcn_global_load_lds((const unsigned*)((const char*)(gbase) + (voff)[_i]), (PG8_LAS unsigned*)(lds + (bufoff) + ldsw + _i * 8192), 16, 0, 0); } while (0)
; #define PG8_LDA(dst, b, h) do { _Pragma("unroll") for (int m = 0; m < 4; ++m) _Pragma("unroll") for (int k = 0; k < 2; ++k) dst[m][k] = *(const PG8_LAS bf16x8*)(lds + PG8_SA(b, h) + aoff + m * 2048 + k * 1024); } while (0)
; #define PG8_LDB(dst, b, h) do { _Pragma("unroll") for (int n = 0; n < 2; ++n) _Pragma("unroll") for (int k = 0; k < 2; ++k) dst[n][k] = *(const PG8_LAS bf16x8*)(lds + PG8_SB(b, h) + boff + n * 2048 + k * 1024); } while (0)
; #define PG8_MMA(ai, bj, At, Bt) do { __builtin_amdgcn_s_setprio(1); _Pragma("unroll") for (int m = 0; m < 4; ++m) _Pragma("unroll") for (int n = 0; n < 2; ++n) _Pragma("unroll") for (int k = 0; k < 2; ++k) \
;         acc[ai][bj][m][n] = __builtin_amdgcn_mfma_f32_16x16x32_bf16(Bt[n][k], At[m][k], acc[ai][bj][m][n], 0, 0, 0); __builtin_amdgcn_s_setprio(0); } while (0)
; #define PG8_WAIT_V(n) asm volatile("s_waitcnt vmcnt(" #n ")" ::: "memory")
; #define PG8_WAIT_L(n) asm volatile("s_waitcnt lgkmcnt(" #n ")" ::: "memory")
; #define PG8_BAR __builtin_amdgcn_s_barrier()
; #define PG8_SCHED __builtin_amdgcn_sched_barrier(0)
; template <class Epi, class Sched, bool ALIGN_EPI = false, bool SP2 = false>
; __device__ __forceinline__ void gemm_phase(PG8_LAS unsigned char* lds, const Gemm g, const Sched& S, const Epi& E) {
;     ...
;             PG8_WAIT_V(8); PG8_WAIT_L(0); PG8_BAR; PG8_MMA(1, 0, At, B0); PG8_MMA(1, 1, At, B1); PG8_BAR; PG8_SCHED;
;             PG8_LDB(B0, 1, 0); PG8_LDB(B1, 1, 1); PG8_SCHED; PG8_LDA(At, 1, 0); PG8_STAGE(PG8_SA(0, 1), a2 + hstep, voffA);
;             PG8_WAIT_V(8); PG8_WAIT_L(0); PG8_BAR; PG8_MMA(0, 0, At, B0); PG8_MMA(0, 1, At, B1); PG8_BAR; PG8_SCHED;
	s_setprio 1
	s_waitcnt lgkmcnt(0)
	v_mfma_f32_16x16x32_bf16 v[62:65], v[146:149], v[186:189], 0
	v_mfma_f32_16x16x32_bf16 v[54:57], v[162:165], v[186:189], 0
	v_mfma_f32_16x16x32_bf16 v[46:49], v[146:149], v[194:197], 0
	v_mfma_f32_16x16x32_bf16 v[38:41], v[162:165], v[194:197], 0
	v_mfma_f32_16x16x32_bf16 v[30:33], v[146:149], v[202:205], 0
	v_mfma_f32_16x16x32_bf16 v[22:25], v[162:165], v[202:205], 0
	v_mfma_f32_16x16x32_bf16 v[14:17], v[146:149], v[210:213], 0
	v_mfma_f32_16x16x32_bf16 v[6:9], v[162:165], v[210:213], 0
	v_mfma_f32_16x16x32_bf16 v[62:65], v[158:161], v[190:193], v[62:65]
	v_mfma_f32_16x16x32_bf16 v[54:57], v[166:169], v[190:193], v[54:57]
	v_mfma_f32_16x16x32_bf16 v[46:49], v[158:161], v[198:201], v[46:49]
	v_mfma_f32_16x16x32_bf16 v[38:41], v[166:169], v[198:201], v[38:41]
	v_mfma_f32_16x16x32_bf16 v[30:33], v[158:161], v[206:209], v[30:33]
	v_mfma_f32_16x16x32_bf16 v[22:25], v[166:169], v[206:209], v[22:25]
	v_mfma_f32_16x16x32_bf16 v[14:17], v[158:161], v[214:217], v[14:17]
	v_mfma_f32_16x16x32_bf16 v[6:9], v[166:169], v[214:217], v[6:9]
	s_setprio 0
	s_setprio 1
	v_mfma_f32_16x16x32_bf16 v[58:61], v[170:173], v[186:189], 0
	v_mfma_f32_16x16x32_bf16 v[50:53], v[178:181], v[186:189], 0
	v_mfma_f32_16x16x32_bf16 v[42:45], v[170:173], v[194:197], 0
	v_mfma_f32_16x16x32_bf16 v[34:37], v[178:181], v[194:197], 0
	v_mfma_f32_16x16x32_bf16 v[26:29], v[170:173], v[202:205], 0
	v_mfma_f32_16x16x32_bf16 v[18:21], v[178:181], v[202:205], 0
	v_mfma_f32_16x16x32_bf16 v[10:13], v[170:173], v[210:213], 0
	v_mfma_f32_16x16x32_bf16 v[2:5], v[178:181], v[210:213], 0
	v_mfma_f32_16x16x32_bf16 v[58:61], v[174:177], v[190:193], v[58:61]
	v_mfma_f32_16x16x32_bf16 v[50:53], v[182:185], v[190:193], v[50:53]
	v_mfma_f32_16x16x32_bf16 v[42:45], v[174:177], v[198:201], v[42:45]
	v_mfma_f32_16x16x32_bf16 v[34:37], v[182:185], v[198:201], v[34:37]
	v_mfma_f32_16x16x32_bf16 v[26:29], v[174:177], v[206:209], v[26:29]
	v_mfma_f32_16x16x32_bf16 v[18:21], v[182:185], v[206:209], v[18:21]
	v_mfma_f32_16x16x32_bf16 v[10:13], v[174:177], v[214:217], v[10:13]
	v_mfma_f32_16x16x32_bf16 v[2:5], v[182:185], v[214:217], v[2:5]
	s_setprio 0
	s_barrier
	ds_read_b128 v[146:149], v155
	ds_read_b128 v[158:161], v155 offset:1024
	ds_read_b128 v[162:165], v155 offset:2048
	ds_read_b128 v[166:169], v155 offset:3072
	ds_read_b128 v[170:173], v156
	ds_read_b128 v[174:177], v156 offset:1024
	ds_read_b128 v[178:181], v156 offset:2048
	ds_read_b128 v[182:185], v156 offset:3072
	s_add_u32 s46, s46, 0x40000
	s_addc_u32 s47, s47, 0
	s_mov_b32 m0, s61
	s_nop 0
	global_load_lds_dwordx4 v[222:223], off
	s_mov_b32 m0, s62
	s_nop 0
	global_load_lds_dwordx4 v[224:225], off
	s_mov_b32 m0, s63
	v_lshl_add_u64 v[226:227], s[46:47], 0, v[136:137]
	ds_read_b128 v[186:189], v154 offset:32768
	ds_read_b128 v[190:193], v154 offset:33792
	ds_read_b128 v[194:197], v154 offset:34816
	ds_read_b128 v[198:201], v154 offset:35840
	ds_read_b128 v[202:205], v154 offset:36864
	ds_read_b128 v[206:209], v154 offset:37888
	ds_read_b128 v[210:213], v154 offset:38912
	ds_read_b128 v[214:217], v154 offset:39936
	global_load_lds_dwordx4 v[226:227], off
	v_lshl_add_u64 v[226:227], s[46:47], 0, v[132:133]
	s_mov_b32 m0, s64
	s_nop 0
	global_load_lds_dwordx4 v[226:227], off
	s_waitcnt vmcnt(8)
	s_waitcnt lgkmcnt(0)
	s_barrier
	s_setprio 1
	s_waitcnt lgkmcnt(0)
	v_mfma_f32_16x16x32_bf16 v[126:129], v[146:149], v[186:189], v[126:129]
	v_mfma_f32_16x16x32_bf16 v[118:121], v[162:165], v[186:189], v[118:121]
	v_mfma_f32_16x16x32_bf16 v[110:113], v[146:149], v[194:197], v[110:113]
	v_mfma_f32_16x16x32_bf16 v[102:105], v[162:165], v[194:197], v[102:105]
	v_mfma_f32_16x16x32_bf16 v[94:97], v[146:149], v[202:205], v[94:97]
	v_mfma_f32_16x16x32_bf16 v[86:89], v[162:165], v[202:205], v[86:89]
	v_mfma_f32_16x16x32_bf16 v[78:81], v[146:149], v[210:213], v[78:81]
	v_mfma_f32_16x16x32_bf16 v[70:73], v[162:165], v[210:213], v[70:73]
	v_mfma_f32_16x16x32_bf16 v[126:129], v[158:161], v[190:193], v[126:129]
	v_mfma_f32_16x16x32_bf16 v[118:121], v[166:169], v[190:193], v[118:121]
	v_mfma_f32_16x16x32_bf16 v[110:113], v[158:161], v[198:201], v[110:113]
	v_mfma_f32_16x16x32_bf16 v[102:105], v[166:169], v[198:201], v[102:105]
	v_mfma_f32_16x16x32_bf16 v[94:97], v[158:161], v[206:209], v[94:97]
	v_mfma_f32_16x16x32_bf16 v[86:89], v[166:169], v[206:209], v[86:89]
	v_mfma_f32_16x16x32_bf16 v[78:81], v[158:161], v[214:217], v[78:81]
	v_mfma_f32_16x16x32_bf16 v[70:73], v[166:169], v[214:217], v[70:73]
	s_setprio 0
	s_setprio 1
	v_mfma_f32_16x16x32_bf16 v[122:125], v[170:173], v[186:189], v[122:125]
	v_mfma_f32_16x16x32_bf16 v[114:117], v[178:181], v[186:189], v[114:117]
	v_mfma_f32_16x16x32_bf16 v[106:109], v[170:173], v[194:197], v[106:109]
	v_mfma_f32_16x16x32_bf16 v[98:101], v[178:181], v[194:197], v[98:101]
	v_mfma_f32_16x16x32_bf16 v[90:93], v[170:173], v[202:205], v[90:93]
	v_mfma_f32_16x16x32_bf16 v[82:85], v[178:181], v[202:205], v[82:85]
	v_mfma_f32_16x16x32_bf16 v[74:77], v[170:173], v[210:213], v[74:77]
	v_mfma_f32_16x16x32_bf16 v[66:69], v[178:181], v[210:213], v[66:69]
	v_mfma_f32_16x16x32_bf16 v[122:125], v[174:177], v[190:193], v[122:125]
	v_mfma_f32_16x16x32_bf16 v[114:117], v[182:185], v[190:193], v[114:117]
	v_mfma_f32_16x16x32_bf16 v[106:109], v[174:177], v[198:201], v[106:109]
	v_mfma_f32_16x16x32_bf16 v[98:101], v[182:185], v[198:201], v[98:101]
	v_mfma_f32_16x16x32_bf16 v[90:93], v[174:177], v[206:209], v[90:93]
	v_mfma_f32_16x16x32_bf16 v[82:85], v[182:185], v[206:209], v[82:85]
	v_mfma_f32_16x16x32_bf16 v[74:77], v[174:177], v[214:217], v[74:77]
	v_mfma_f32_16x16x32_bf16 v[66:69], v[182:185], v[214:217], v[66:69]
	s_setprio 0
	s_barrier
; #define PG8_STAGE(bufoff, gbase, voff) do { _Pragma("unroll") for (int _i = 0; _i < 2; ++_i) \
;         __builtin_amdgcn_global_load_lds((const unsigned*)((const char*)(gbase) + (voff)[_i]), (PG8_LAS unsigned*)(lds + (bufoff) + ldsw + _i * 8192), 16, 0, 0); } while (0)
; #define PG8_LDA(dst, b, h) do { _Pragma("unroll") for (int m = 0; m < 4; ++m) _Pragma("unroll") for (int k = 0; k < 2; ++k) dst[m][k] = *(const PG8_LAS bf16x8*)(lds + PG8_SA(b, h) + aoff + m * 2048 + k * 1024); } while (0)
; #define PG8_LDB(dst, b, h) do { _Pragma("unroll") for (int n = 0; n < 2; ++n) _Pragma("unroll") for (int k = 0; k < 2; ++k) dst[n][k] = *(const PG8_LAS bf16x8*)(lds + PG8_SB(b, h) + boff + n * 2048 + k * 1024); } while (0)
; #define PG8_MMA(ai, bj, At, Bt) do { __builtin_amdgcn_s_setprio(1); _Pragma("unroll") for (int m = 0; m < 4; ++m) _Pragma("unroll") for (int n = 0; n < 2; ++n) _Pragma("unroll") for (int k = 0; k < 2; ++k) \
;         acc[ai][bj][m][n] = __builtin_amdgcn_mfma_f32_16x16x32_bf16(Bt[n][k], At[m][k], acc[ai][bj][m][n], 0, 0, 0); __builtin_amdgcn_s_setprio(0); } while (0)
; #define PG8_WAIT_V(n) asm volatile("s_waitcnt vmcnt(" #n ")" ::: "memory")
; #define PG8_WAIT_L(n) asm volatile("s_waitcnt lgkmcnt(" #n ")" ::: "memory")
; #define PG8_BAR __builtin_amdgcn_s_barrier()
; #define PG8_SCHED __builtin_amdgcn_sched_barrier(0)
; template <class Epi, class Sched, bool ALIGN_EPI = false, bool SP2 = false>
; __device__ __forceinline__ void gemm_phase(PG8_LAS unsigned char* lds, const Gemm g, const Sched& S, const Epi& E) {
;     ...
;             PG8_LDB(B0, 0, 0); PG8_LDB(B1, 0, 1); PG8_SCHED; PG8_LDA(At, 0, 0); PG8_STAGE(PG8_SA(1, 1), a1 + hstep, voffA);
;             PG8_WAIT_V(8); PG8_WAIT_L(0); PG8_BAR; PG8_MMA(0, 0, At, B0); PG8_MMA(0, 1, At, B1); PG8_BAR; PG8_SCHED;
;     ...
;             PG8_LDA(At, 1, 1); PG8_STAGE(PG8_SB(1, 0), b3, voffB); PG8_STAGE(PG8_SB(1, 1), b3 + hstep, voffB); PG8_STAGE(PG8_SA(1, 0), a3, voffA);
;             PG8_WAIT_V(8); PG8_WAIT_L(0); PG8_BAR; PG8_MMA(1, 0, At, B0); PG8_MMA(1, 1, At, B1); PG8_BAR; PG8_SCHED;
	s_mov_b32 m0, s65
	v_lshl_add_u64 v[218:219], v[218:219], 0, s[6:7]
	s_add_u32 s44, s44, 0x40080
	ds_read_b128 v[186:189], v154 offset:49152
	ds_read_b128 v[190:193], v154 offset:50176
	ds_read_b128 v[194:197], v154 offset:51200
	ds_read_b128 v[198:201], v154 offset:52224
	ds_read_b128 v[202:205], v154 offset:53248
	ds_read_b128 v[206:209], v154 offset:54272
	ds_read_b128 v[210:213], v154 offset:55296
	ds_read_b128 v[214:217], v154 offset:56320
	global_load_lds_dwordx4 v[218:219], off
	v_lshl_add_u64 v[218:219], v[220:221], 0, s[6:7]
	s_mov_b32 m0, s66
	s_addc_u32 s45, s45, 0
	global_load_lds_dwordx4 v[218:219], off
	v_lshl_add_u64 v[218:219], s[44:45], 0, v[134:135]
	s_mov_b32 m0, s69
	s_nop 0
	global_load_lds_dwordx4 v[218:219], off
	v_lshl_add_u64 v[218:219], s[44:45], 0, v[130:131]
	s_mov_b32 m0, s70
	s_nop 0
	global_load_lds_dwordx4 v[218:219], off
	v_lshl_add_u64 v[218:219], v[222:223], 0, s[6:7]
	s_mov_b32 m0, s67
	s_nop 0
	global_load_lds_dwordx4 v[218:219], off
	v_lshl_add_u64 v[218:219], v[224:225], 0, s[6:7]
	s_mov_b32 m0, s68
	s_nop 0
	global_load_lds_dwordx4 v[218:219], off
	s_waitcnt vmcnt(8)
	s_waitcnt lgkmcnt(0)
	s_barrier
	s_setprio 1
	s_waitcnt lgkmcnt(0)
	v_mfma_f32_16x16x32_bf16 v[62:65], v[146:149], v[186:189], v[62:65]
	v_mfma_f32_16x16x32_bf16 v[54:57], v[162:165], v[186:189], v[54:57]
	v_mfma_f32_16x16x32_bf16 v[46:49], v[146:149], v[194:197], v[46:49]
	v_mfma_f32_16x16x32_bf16 v[38:41], v[162:165], v[194:197], v[38:41]
	v_mfma_f32_16x16x32_bf16 v[30:33], v[146:149], v[202:205], v[30:33]
	v_mfma_f32_16x16x32_bf16 v[22:25], v[162:165], v[202:205], v[22:25]
	v_mfma_f32_16x16x32_bf16 v[14:17], v[146:149], v[210:213], v[14:17]
	v_mfma_f32_16x16x32_bf16 v[6:9], v[162:165], v[210:213], v[6:9]
	v_mfma_f32_16x16x32_bf16 v[62:65], v[158:161], v[190:193], v[62:65]
	v_mfma_f32_16x16x32_bf16 v[54:57], v[166:169], v[190:193], v[54:57]
	v_mfma_f32_16x16x32_bf16 v[46:49], v[158:161], v[198:201], v[46:49]
	v_mfma_f32_16x16x32_bf16 v[38:41], v[166:169], v[198:201], v[38:41]
	v_mfma_f32_16x16x32_bf16 v[30:33], v[158:161], v[206:209], v[30:33]
	v_mfma_f32_16x16x32_bf16 v[22:25], v[166:169], v[206:209], v[22:25]
	v_mfma_f32_16x16x32_bf16 v[14:17], v[158:161], v[214:217], v[14:17]
	v_mfma_f32_16x16x32_bf16 v[6:9], v[166:169], v[214:217], v[6:9]
	s_setprio 0
	s_setprio 1
	v_mfma_f32_16x16x32_bf16 v[58:61], v[170:173], v[186:189], v[58:61]
	v_mfma_f32_16x16x32_bf16 v[50:53], v[178:181], v[186:189], v[50:53]
	v_mfma_f32_16x16x32_bf16 v[42:45], v[170:173], v[194:197], v[42:45]
	v_mfma_f32_16x16x32_bf16 v[34:37], v[178:181], v[194:197], v[34:37]
	v_mfma_f32_16x16x32_bf16 v[26:29], v[170:173], v[202:205], v[26:29]
	v_mfma_f32_16x16x32_bf16 v[18:21], v[178:181], v[202:205], v[18:21]
	v_mfma_f32_16x16x32_bf16 v[10:13], v[170:173], v[210:213], v[10:13]
	v_mfma_f32_16x16x32_bf16 v[2:5], v[178:181], v[210:213], v[2:5]
	v_mfma_f32_16x16x32_bf16 v[58:61], v[174:177], v[190:193], v[58:61]
	v_mfma_f32_16x16x32_bf16 v[50:53], v[182:185], v[190:193], v[50:53]
	v_mfma_f32_16x16x32_bf16 v[42:45], v[174:177], v[198:201], v[42:45]
	v_mfma_f32_16x16x32_bf16 v[34:37], v[182:185], v[198:201], v[34:37]
	v_mfma_f32_16x16x32_bf16 v[26:29], v[174:177], v[206:209], v[26:29]
	v_mfma_f32_16x16x32_bf16 v[18:21], v[182:185], v[206:209], v[18:21]
	v_mfma_f32_16x16x32_bf16 v[10:13], v[174:177], v[214:217], v[10:13]
	v_mfma_f32_16x16x32_bf16 v[2:5], v[182:185], v[214:217], v[2:5]
	s_setprio 0
	s_barrier
	s_add_i32 s48, s48, 2
	s_add_u32 s40, s40, 0x100
	s_addc_u32 s41, s41, 0
	s_add_u32 s42, s42, 0x100
	s_addc_u32 s43, s43, 0
	s_cmp_gt_u32 s48, 13
.LBB0_257:
	ds_read_b128 v[146:149], v152
	ds_read_b128 v[158:161], v152 offset:1024
	ds_read_b128 v[162:165], v152 offset:2048
	ds_read_b128 v[166:169], v152 offset:3072
	ds_read_b128 v[170:173], v153
	ds_read_b128 v[174:177], v153 offset:1024
	ds_read_b128 v[178:181], v153 offset:2048
	ds_read_b128 v[182:185], v153 offset:3072
	s_add_u32 s44, s42, 0xfffc0080
	s_addc_u32 s45, s43, -1
	s_cmp_eq_u32 s48, 12
	s_cselect_b32 s47, s13, s45
	s_cselect_b32 s46, s36, s44
	s_cselect_b32 s45, s11, s41
	s_cselect_b32 s44, s37, s40
	v_lshl_add_u64 v[218:219], s[42:43], 0, v[140:141]
	s_add_i32 m0, s61, 0xc000
	ds_read_b128 v[186:189], v154
	ds_read_b128 v[190:193], v154 offset:1024
	ds_read_b128 v[194:197], v154 offset:2048
	ds_read_b128 v[198:201], v154 offset:3072
	ds_read_b128 v[202:205], v154 offset:4096
	ds_read_b128 v[206:209], v154 offset:5120
	ds_read_b128 v[210:213], v154 offset:6144
	ds_read_b128 v[214:217], v154 offset:7168
	global_load_lds_dwordx4 v[218:219], off
	v_lshl_add_u64 v[218:219], s[42:43], 0, v[138:139]
	s_add_i32 m0, s61, 0xe000
	s_nop 0
	global_load_lds_dwordx4 v[218:219], off
	s_waitcnt vmcnt(8)
	s_waitcnt lgkmcnt(0)
	s_barrier
; #define PG8_STAGE(bufoff, gbase, voff) do { _Pragma("unroll") for (int _i = 0; _i < 2; ++_i) \
;         __builtin_amdgcn_global_load_lds((const unsigned*)((const char*)(gbase) + (voff)[_i]), (PG8_LAS unsigned*)(lds + (bufoff) + ldsw + _i * 8192), 16, 0, 0); } while (0)
; #define PG8_LDA(dst, b, h) do { _Pragma("unroll") for (int m = 0; m < 4; ++m) _Pragma("unroll") for (int k = 0; k < 2; ++k) dst[m][k] = *(const PG8_LAS bf16x8*)(lds + PG8_SA(b, h) + aoff + m * 2048 + k * 1024); } while (0)
; #define PG8_MMA(ai, bj, At, Bt) do { __builtin_amdgcn_s_setprio(1); _Pragma("unroll") for (int m = 0; m < 4; ++m) _Pragma("unroll") for (int n = 0; n < 2; ++n) _Pragma("unroll") for (int k = 0; k < 2; ++k) \
;         acc[ai][bj][m][n] = __builtin_amdgcn_mfma_f32_16x16x32_bf16(Bt[n][k], At[m][k], acc[ai][bj][m][n], 0, 0, 0); __builtin_amdgcn_s_setprio(0); } while (0)
; #define PG8_WAIT_V(n) asm volatile("s_waitcnt vmcnt(" #n ")" ::: "memory")
; #define PG8_WAIT_L(n) asm volatile("s_waitcnt lgkmcnt(" #n ")" ::: "memory")
; #define PG8_BAR __builtin_amdgcn_s_barrier()
; #define PG8_SCHED __builtin_amdgcn_sched_barrier(0)
; template <class Epi, class Sched, bool ALIGN_EPI = false, bool SP2 = false>
; __device__ __forceinline__ void gemm_phase(PG8_LAS unsigned char* lds, const Gemm g, const Sched& S, const Epi& E) {
;     ...
;             PG8_WAIT_V(8); PG8_WAIT_L(0); PG8_BAR; PG8_MMA(0, 0, At, B0); PG8_MMA(0, 1, At, B1); PG8_BAR; PG8_SCHED;
;             PG8_LDA(At, 0, 1); PG8_STAGE(PG8_SB(0, 0), b2, voffB); PG8_STAGE(PG8_SB(0, 1), b2 + hstep, voffB); PG8_STAGE(PG8_SA(0, 0), a2, voffA);
;             PG8_WAIT_V(8); PG8_WAIT_L(0); PG8_BAR; PG8_MMA(1, 0, At, B0); PG8_MMA(1, 1, At, B1); PG8_BAR; PG8_SCHED;
	s_setprio 1
	s_waitcnt lgkmcnt(0)
	v_mfma_f32_16x16x32_bf16 v[126:129], v[146:149], v[186:189], v[126:129]
	v_mfma_f32_16x16x32_bf16 v[118:121], v[162:165], v[186:189], v[118:121]
	v_mfma_f32_16x16x32_bf16 v[110:113], v[146:149], v[194:197], v[110:113]
	v_mfma_f32_16x16x32_bf16 v[102:105], v[162:165], v[194:197], v[102:105]
	v_mfma_f32_16x16x32_bf16 v[94:97], v[146:149], v[202:205], v[94:97]
	v_mfma_f32_16x16x32_bf16 v[86:89], v[162:165], v[202:205], v[86:89]
	v_mfma_f32_16x16x32_bf16 v[78:81], v[146:149], v[210:213], v[78:81]
	v_mfma_f32_16x16x32_bf16 v[70:73], v[162:165], v[210:213], v[70:73]
	v_mfma_f32_16x16x32_bf16 v[126:129], v[158:161], v[190:193], v[126:129]
	v_mfma_f32_16x16x32_bf16 v[118:121], v[166:169], v[190:193], v[118:121]
	v_mfma_f32_16x16x32_bf16 v[110:113], v[158:161], v[198:201], v[110:113]
	v_mfma_f32_16x16x32_bf16 v[102:105], v[166:169], v[198:201], v[102:105]
	v_mfma_f32_16x16x32_bf16 v[94:97], v[158:161], v[206:209], v[94:97]
	v_mfma_f32_16x16x32_bf16 v[86:89], v[166:169], v[206:209], v[86:89]
	v_mfma_f32_16x16x32_bf16 v[78:81], v[158:161], v[214:217], v[78:81]
	v_mfma_f32_16x16x32_bf16 v[70:73], v[166:169], v[214:217], v[70:73]
	s_setprio 0
	s_setprio 1
	v_mfma_f32_16x16x32_bf16 v[122:125], v[170:173], v[186:189], v[122:125]
	v_mfma_f32_16x16x32_bf16 v[114:117], v[178:181], v[186:189], v[114:117]
	v_mfma_f32_16x16x32_bf16 v[106:109], v[170:173], v[194:197], v[106:109]
	v_mfma_f32_16x16x32_bf16 v[98:101], v[178:181], v[194:197], v[98:101]
	v_mfma_f32_16x16x32_bf16 v[90:93], v[170:173], v[202:205], v[90:93]
	v_mfma_f32_16x16x32_bf16 v[82:85], v[178:181], v[202:205], v[82:85]
	v_mfma_f32_16x16x32_bf16 v[74:77], v[170:173], v[210:213], v[74:77]
	v_mfma_f32_16x16x32_bf16 v[66:69], v[178:181], v[210:213], v[66:69]
	v_mfma_f32_16x16x32_bf16 v[122:125], v[174:177], v[190:193], v[122:125]
	v_mfma_f32_16x16x32_bf16 v[114:117], v[182:185], v[190:193], v[114:117]
	v_mfma_f32_16x16x32_bf16 v[106:109], v[174:177], v[198:201], v[106:109]
	v_mfma_f32_16x16x32_bf16 v[98:101], v[182:185], v[198:201], v[98:101]
	v_mfma_f32_16x16x32_bf16 v[90:93], v[174:177], v[206:209], v[90:93]
	v_mfma_f32_16x16x32_bf16 v[82:85], v[182:185], v[206:209], v[82:85]
	v_mfma_f32_16x16x32_bf16 v[74:77], v[174:177], v[214:217], v[74:77]
	v_mfma_f32_16x16x32_bf16 v[66:69], v[182:185], v[214:217], v[66:69]
	s_setprio 0
	s_barrier
	s_mov_b32 m0, s39
	v_lshl_add_u64 v[218:219], s[44:45], 0, v[134:135]
	s_add_u32 s50, s44, 0x40000
	ds_read_b128 v[186:189], v154 offset:16384
	ds_read_b128 v[190:193], v154 offset:17408
	ds_read_b128 v[194:197], v154 offset:18432
	ds_read_b128 v[198:201], v154 offset:19456
	ds_read_b128 v[202:205], v154 offset:20480
	ds_read_b128 v[206:209], v154 offset:21504
	ds_read_b128 v[210:213], v154 offset:22528
	ds_read_b128 v[214:217], v154 offset:23552
	global_load_lds_dwordx4 v[218:219], off
	v_lshl_add_u64 v[220:221], s[44:45], 0, v[130:131]
	s_mov_b32 m0, s56
	s_addc_u32 s51, s45, 0
	global_load_lds_dwordx4 v[220:221], off
	v_lshl_add_u64 v[222:223], s[50:51], 0, v[134:135]
	s_mov_b32 m0, s57
	v_lshl_add_u64 v[224:225], s[46:47], 0, v[132:133]
	global_load_lds_dwordx4 v[222:223], off
	v_lshl_add_u64 v[222:223], s[50:51], 0, v[130:131]
	s_mov_b32 m0, s60
	s_nop 0
	global_load_lds_dwordx4 v[222:223], off
	v_lshl_add_u64 v[222:223], s[46:47], 0, v[136:137]
	s_waitcnt vmcnt(6)
	s_waitcnt lgkmcnt(0)
	s_barrier
	s_setprio 1
	s_waitcnt lgkmcnt(0)
	v_mfma_f32_16x16x32_bf16 v[62:65], v[146:149], v[186:189], v[62:65]
	v_mfma_f32_16x16x32_bf16 v[54:57], v[162:165], v[186:189], v[54:57]
	v_mfma_f32_16x16x32_bf16 v[46:49], v[146:149], v[194:197], v[46:49]
	v_mfma_f32_16x16x32_bf16 v[38:41], v[162:165], v[194:197], v[38:41]
	v_mfma_f32_16x16x32_bf16 v[30:33], v[146:149], v[202:205], v[30:33]
	v_mfma_f32_16x16x32_bf16 v[22:25], v[162:165], v[202:205], v[22:25]
	v_mfma_f32_16x16x32_bf16 v[14:17], v[146:149], v[210:213], v[14:17]
	v_mfma_f32_16x16x32_bf16 v[6:9], v[162:165], v[210:213], v[6:9]
	v_mfma_f32_16x16x32_bf16 v[62:65], v[158:161], v[190:193], v[62:65]
	v_mfma_f32_16x16x32_bf16 v[54:57], v[166:169], v[190:193], v[54:57]
	v_mfma_f32_16x16x32_bf16 v[46:49], v[158:161], v[198:201], v[46:49]
	v_mfma_f32_16x16x32_bf16 v[38:41], v[166:169], v[198:201], v[38:41]
	v_mfma_f32_16x16x32_bf16 v[30:33], v[158:161], v[206:209], v[30:33]
	v_mfma_f32_16x16x32_bf16 v[22:25], v[166:169], v[206:209], v[22:25]
	v_mfma_f32_16x16x32_bf16 v[14:17], v[158:161], v[214:217], v[14:17]
	v_mfma_f32_16x16x32_bf16 v[6:9], v[166:169], v[214:217], v[6:9]
	s_setprio 0
	s_setprio 1
	v_mfma_f32_16x16x32_bf16 v[58:61], v[170:173], v[186:189], v[58:61]
	v_mfma_f32_16x16x32_bf16 v[50:53], v[178:181], v[186:189], v[50:53]
	v_mfma_f32_16x16x32_bf16 v[42:45], v[170:173], v[194:197], v[42:45]
	v_mfma_f32_16x16x32_bf16 v[34:37], v[178:181], v[194:197], v[34:37]
	v_mfma_f32_16x16x32_bf16 v[26:29], v[170:173], v[202:205], v[26:29]
	v_mfma_f32_16x16x32_bf16 v[18:21], v[178:181], v[202:205], v[18:21]
	v_mfma_f32_16x16x32_bf16 v[10:13], v[170:173], v[210:213], v[10:13]
	v_mfma_f32_16x16x32_bf16 v[2:5], v[178:181], v[210:213], v[2:5]
	v_mfma_f32_16x16x32_bf16 v[58:61], v[174:177], v[190:193], v[58:61]
	v_mfma_f32_16x16x32_bf16 v[50:53], v[182:185], v[190:193], v[50:53]
	v_mfma_f32_16x16x32_bf16 v[42:45], v[174:177], v[198:201], v[42:45]
	v_mfma_f32_16x16x32_bf16 v[34:37], v[182:185], v[198:201], v[34:37]
	v_mfma_f32_16x16x32_bf16 v[26:29], v[174:177], v[206:209], v[26:29]
	v_mfma_f32_16x16x32_bf16 v[18:21], v[182:185], v[206:209], v[18:21]
	v_mfma_f32_16x16x32_bf16 v[10:13], v[174:177], v[214:217], v[10:13]
	v_mfma_f32_16x16x32_bf16 v[2:5], v[182:185], v[214:217], v[2:5]
	s_setprio 0
	s_barrier
; #define PG8_STAGE(bufoff, gbase, voff) do { _Pragma("unroll") for (int _i = 0; _i < 2; ++_i) \
;         __builtin_amdgcn_global_load_lds((const unsigned*)((const char*)(gbase) + (voff)[_i]), (PG8_LAS unsigned*)(lds + (bufoff) + ldsw + _i * 8192), 16, 0, 0); } while (0)
; #define PG8_LDA(dst, b, h) do { _Pragma("unroll") for (int m = 0; m < 4; ++m) _Pragma("unroll") for (int k = 0; k < 2; ++k) dst[m][k] = *(const PG8_LAS bf16x8*)(lds + PG8_SA(b, h) + aoff + m * 2048 + k * 1024); } while (0)
; #define PG8_LDB(dst, b, h) do { _Pragma("unroll") for (int n = 0; n < 2; ++n) _Pragma("unroll") for (int k = 0; k < 2; ++k) dst[n][k] = *(const PG8_LAS bf16x8*)(lds + PG8_SB(b, h) + boff + n * 2048 + k * 1024); } while (0)
; #define PG8_MMA(ai, bj, At, Bt) do { __builtin_amdgcn_s_setprio(1); _Pragma("unroll") for (int m = 0; m < 4; ++m) _Pragma("unroll") for (int n = 0; n < 2; ++n) _Pragma("unroll") for (int k = 0; k < 2; ++k) \
;         acc[ai][bj][m][n] = __builtin_amdgcn_mfma_f32_16x16x32_bf16(Bt[n][k], At[m][k], acc[ai][bj][m][n], 0, 0, 0); __builtin_amdgcn_s_setprio(0); } while (0)
; #define PG8_WAIT_V(n) asm volatile("s_waitcnt vmcnt(" #n ")" ::: "memory")
; #define PG8_WAIT_L(n) asm volatile("s_waitcnt lgkmcnt(" #n ")" ::: "memory")
; #define PG8_BAR __builtin_amdgcn_s_barrier()
; #define PG8_SCHED __builtin_amdgcn_sched_barrier(0)
; template <class Epi, class Sched, bool ALIGN_EPI = false, bool SP2 = false>
; __device__ __forceinline__ void gemm_phase(PG8_LAS unsigned char* lds, const Gemm g, const Sched& S, const Epi& E) {
;     ...
;             PG8_LDB(B0, 1, 0); PG8_LDB(B1, 1, 1); PG8_SCHED; PG8_LDA(At, 1, 0); PG8_STAGE(PG8_SA(0, 1), a2 + hstep, voffA);
;             PG8_WAIT_V(8); PG8_WAIT_L(0); PG8_BAR; PG8_MMA(0, 0, At, B0); PG8_MMA(0, 1, At, B1); PG8_BAR; PG8_SCHED;
	ds_read_b128 v[146:149], v155
	ds_read_b128 v[158:161], v155 offset:1024
	ds_read_b128 v[162:165], v155 offset:2048
	ds_read_b128 v[166:169], v155 offset:3072
	ds_read_b128 v[170:173], v156
	ds_read_b128 v[174:177], v156 offset:1024
	ds_read_b128 v[178:181], v156 offset:2048
	ds_read_b128 v[182:185], v156 offset:3072
	s_add_u32 s46, s46, 0x40000
	s_addc_u32 s47, s47, 0
	s_mov_b32 m0, s61
	s_nop 0
	global_load_lds_dwordx4 v[222:223], off
	s_mov_b32 m0, s62
	s_nop 0
	global_load_lds_dwordx4 v[224:225], off
	s_mov_b32 m0, s63
	v_lshl_add_u64 v[226:227], s[46:47], 0, v[136:137]
	ds_read_b128 v[186:189], v154 offset:32768
	ds_read_b128 v[190:193], v154 offset:33792
	ds_read_b128 v[194:197], v154 offset:34816
	ds_read_b128 v[198:201], v154 offset:35840
	ds_read_b128 v[202:205], v154 offset:36864
	ds_read_b128 v[206:209], v154 offset:37888
	ds_read_b128 v[210:213], v154 offset:38912
	ds_read_b128 v[214:217], v154 offset:39936
	global_load_lds_dwordx4 v[226:227], off
	v_lshl_add_u64 v[226:227], s[46:47], 0, v[132:133]
	s_mov_b32 m0, s64
	s_nop 0
	global_load_lds_dwordx4 v[226:227], off
	s_waitcnt vmcnt(8)
	s_waitcnt lgkmcnt(0)
	s_barrier
	s_setprio 1
	s_waitcnt lgkmcnt(0)
	v_mfma_f32_16x16x32_bf16 v[126:129], v[146:149], v[186:189], v[126:129]
	v_mfma_f32_16x16x32_bf16 v[118:121], v[162:165], v[186:189], v[118:121]
	v_mfma_f32_16x16x32_bf16 v[110:113], v[146:149], v[194:197], v[110:113]
	v_mfma_f32_16x16x32_bf16 v[102:105], v[162:165], v[194:197], v[102:105]
	v_mfma_f32_16x16x32_bf16 v[94:97], v[146:149], v[202:205], v[94:97]
	v_mfma_f32_16x16x32_bf16 v[86:89], v[162:165], v[202:205], v[86:89]
	v_mfma_f32_16x16x32_bf16 v[78:81], v[146:149], v[210:213], v[78:81]
	v_mfma_f32_16x16x32_bf16 v[70:73], v[162:165], v[210:213], v[70:73]
	v_mfma_f32_16x16x32_bf16 v[126:129], v[158:161], v[190:193], v[126:129]
	v_mfma_f32_16x16x32_bf16 v[118:121], v[166:169], v[190:193], v[118:121]
	v_mfma_f32_16x16x32_bf16 v[110:113], v[158:161], v[198:201], v[110:113]
	v_mfma_f32_16x16x32_bf16 v[102:105], v[166:169], v[198:201], v[102:105]
	v_mfma_f32_16x16x32_bf16 v[94:97], v[158:161], v[206:209], v[94:97]
	v_mfma_f32_16x16x32_bf16 v[86:89], v[166:169], v[206:209], v[86:89]
	v_mfma_f32_16x16x32_bf16 v[78:81], v[158:161], v[214:217], v[78:81]
	v_mfma_f32_16x16x32_bf16 v[70:73], v[166:169], v[214:217], v[70:73]
	s_setprio 0
	s_setprio 1
	v_mfma_f32_16x16x32_bf16 v[122:125], v[170:173], v[186:189], v[122:125]
	v_mfma_f32_16x16x32_bf16 v[114:117], v[178:181], v[186:189], v[114:117]
	v_mfma_f32_16x16x32_bf16 v[106:109], v[170:173], v[194:197], v[106:109]
	v_mfma_f32_16x16x32_bf16 v[98:101], v[178:181], v[194:197], v[98:101]
	v_mfma_f32_16x16x32_bf16 v[90:93], v[170:173], v[202:205], v[90:93]
	v_mfma_f32_16x16x32_bf16 v[82:85], v[178:181], v[202:205], v[82:85]
	v_mfma_f32_16x16x32_bf16 v[74:77], v[170:173], v[210:213], v[74:77]
	v_mfma_f32_16x16x32_bf16 v[66:69], v[178:181], v[210:213], v[66:69]
	v_mfma_f32_16x16x32_bf16 v[122:125], v[174:177], v[190:193], v[122:125]
	v_mfma_f32_16x16x32_bf16 v[114:117], v[182:185], v[190:193], v[114:117]
	v_mfma_f32_16x16x32_bf16 v[106:109], v[174:177], v[198:201], v[106:109]
	v_mfma_f32_16x16x32_bf16 v[98:101], v[182:185], v[198:201], v[98:101]
	v_mfma_f32_16x16x32_bf16 v[90:93], v[174:177], v[206:209], v[90:93]
	v_mfma_f32_16x16x32_bf16 v[82:85], v[182:185], v[206:209], v[82:85]
	v_mfma_f32_16x16x32_bf16 v[74:77], v[174:177], v[214:217], v[74:77]
	v_mfma_f32_16x16x32_bf16 v[66:69], v[182:185], v[214:217], v[66:69]
	s_setprio 0
	s_barrier
; #define PG8_STAGE(bufoff, gbase, voff) do { _Pragma("unroll") for (int _i = 0; _i < 2; ++_i) \
;         __builtin_amdgcn_global_load_lds((const unsigned*)((const char*)(gbase) + (voff)[_i]), (PG8_LAS unsigned*)(lds + (bufoff) + ldsw + _i * 8192), 16, 0, 0); } while (0)
; #define PG8_LDA(dst, b, h) do { _Pragma("unroll") for (int m = 0; m < 4; ++m) _Pragma("unroll") for (int k = 0; k < 2; ++k) dst[m][k] = *(const PG8_LAS bf16x8*)(lds + PG8_SA(b, h) + aoff + m * 2048 + k * 1024); } while (0)
; #define PG8_MMA(ai, bj, At, Bt) do { __builtin_amdgcn_s_setprio(1); _Pragma("unroll") for (int m = 0; m < 4; ++m) _Pragma("unroll") for (int n = 0; n < 2; ++n) _Pragma("unroll") for (int k = 0; k < 2; ++k) \
;         acc[ai][bj][m][n] = __builtin_amdgcn_mfma_f32_16x16x32_bf16(Bt[n][k], At[m][k], acc[ai][bj][m][n], 0, 0, 0); __builtin_amdgcn_s_setprio(0); } while (0)
; #define PG8_WAIT_V(n) asm volatile("s_waitcnt vmcnt(" #n ")" ::: "memory")
; #define PG8_WAIT_L(n) asm volatile("s_waitcnt lgkmcnt(" #n ")" ::: "memory")
; #define PG8_BAR __builtin_amdgcn_s_barrier()
; #define PG8_SCHED __builtin_amdgcn_sched_barrier(0)
; template <class Epi, class Sched, bool ALIGN_EPI = false, bool SP2 = false>
; __device__ __forceinline__ void gemm_phase(PG8_LAS unsigned char* lds, const Gemm g, const Sched& S, const Epi& E) {
;     ...
;             PG8_LDA(At, 1, 1); PG8_STAGE(PG8_SB(1, 0), b3, voffB); PG8_STAGE(PG8_SB(1, 1), b3 + hstep, voffB); PG8_STAGE(PG8_SA(1, 0), a3, voffA);
;             PG8_WAIT_V(8); PG8_WAIT_L(0); PG8_BAR; PG8_MMA(1, 0, At, B0); PG8_MMA(1, 1, At, B1); PG8_BAR; PG8_SCHED;
;     ...
;         if constexpr (ALIGN_EPI) { if (wr == 0) PG8_BAR; }
	s_mov_b32 m0, s65
	v_lshl_add_u64 v[218:219], v[218:219], 0, s[6:7]
	s_add_u32 s44, s44, 0x40080
	ds_read_b128 v[186:189], v154 offset:49152
	ds_read_b128 v[190:193], v154 offset:50176
	ds_read_b128 v[194:197], v154 offset:51200
	ds_read_b128 v[198:201], v154 offset:52224
	ds_read_b128 v[202:205], v154 offset:53248
	ds_read_b128 v[206:209], v154 offset:54272
	ds_read_b128 v[210:213], v154 offset:55296
	ds_read_b128 v[214:217], v154 offset:56320
	global_load_lds_dwordx4 v[218:219], off
	v_lshl_add_u64 v[218:219], v[220:221], 0, s[6:7]
	s_mov_b32 m0, s66
	s_addc_u32 s45, s45, 0
	global_load_lds_dwordx4 v[218:219], off
	v_lshl_add_u64 v[218:219], s[44:45], 0, v[134:135]
	s_mov_b32 m0, s69
	s_nop 0
	global_load_lds_dwordx4 v[218:219], off
	v_lshl_add_u64 v[218:219], s[44:45], 0, v[130:131]
	s_mov_b32 m0, s70
	s_nop 0
	global_load_lds_dwordx4 v[218:219], off
	v_lshl_add_u64 v[218:219], v[222:223], 0, s[6:7]
	s_mov_b32 m0, s67
	s_nop 0
	global_load_lds_dwordx4 v[218:219], off
	v_lshl_add_u64 v[218:219], v[224:225], 0, s[6:7]
	s_mov_b32 m0, s68
	s_nop 0
	global_load_lds_dwordx4 v[218:219], off
	s_waitcnt vmcnt(8)
	s_waitcnt lgkmcnt(0)
	s_barrier
	s_setprio 1
	s_waitcnt lgkmcnt(0)
	v_mfma_f32_16x16x32_bf16 v[62:65], v[146:149], v[186:189], v[62:65]
	v_mfma_f32_16x16x32_bf16 v[54:57], v[162:165], v[186:189], v[54:57]
	v_mfma_f32_16x16x32_bf16 v[46:49], v[146:149], v[194:197], v[46:49]
	v_mfma_f32_16x16x32_bf16 v[38:41], v[162:165], v[194:197], v[38:41]
	v_mfma_f32_16x16x32_bf16 v[30:33], v[146:149], v[202:205], v[30:33]
	v_mfma_f32_16x16x32_bf16 v[22:25], v[162:165], v[202:205], v[22:25]
	v_mfma_f32_16x16x32_bf16 v[14:17], v[146:149], v[210:213], v[14:17]
	v_mfma_f32_16x16x32_bf16 v[6:9], v[162:165], v[210:213], v[6:9]
	v_mfma_f32_16x16x32_bf16 v[62:65], v[158:161], v[190:193], v[62:65]
	v_mfma_f32_16x16x32_bf16 v[54:57], v[166:169], v[190:193], v[54:57]
	v_mfma_f32_16x16x32_bf16 v[46:49], v[158:161], v[198:201], v[46:49]
	v_mfma_f32_16x16x32_bf16 v[38:41], v[166:169], v[198:201], v[38:41]
	v_mfma_f32_16x16x32_bf16 v[30:33], v[158:161], v[206:209], v[30:33]
	v_mfma_f32_16x16x32_bf16 v[22:25], v[166:169], v[206:209], v[22:25]
	v_mfma_f32_16x16x32_bf16 v[14:17], v[158:161], v[214:217], v[14:17]
	v_mfma_f32_16x16x32_bf16 v[6:9], v[166:169], v[214:217], v[6:9]
	s_setprio 0
	s_setprio 1
	v_mfma_f32_16x16x32_bf16 v[58:61], v[170:173], v[186:189], v[58:61]
	v_mfma_f32_16x16x32_bf16 v[50:53], v[178:181], v[186:189], v[50:53]
	v_mfma_f32_16x16x32_bf16 v[42:45], v[170:173], v[194:197], v[42:45]
	v_mfma_f32_16x16x32_bf16 v[34:37], v[178:181], v[194:197], v[34:37]
	v_mfma_f32_16x16x32_bf16 v[26:29], v[170:173], v[202:205], v[26:29]
	v_mfma_f32_16x16x32_bf16 v[18:21], v[178:181], v[202:205], v[18:21]
	v_mfma_f32_16x16x32_bf16 v[10:13], v[170:173], v[210:213], v[10:13]
	v_mfma_f32_16x16x32_bf16 v[2:5], v[178:181], v[210:213], v[2:5]
	v_mfma_f32_16x16x32_bf16 v[58:61], v[174:177], v[190:193], v[58:61]
	v_mfma_f32_16x16x32_bf16 v[50:53], v[182:185], v[190:193], v[50:53]
	v_mfma_f32_16x16x32_bf16 v[42:45], v[174:177], v[198:201], v[42:45]
	v_mfma_f32_16x16x32_bf16 v[34:37], v[182:185], v[198:201], v[34:37]
	v_mfma_f32_16x16x32_bf16 v[26:29], v[174:177], v[206:209], v[26:29]
	v_mfma_f32_16x16x32_bf16 v[18:21], v[182:185], v[206:209], v[18:21]
	v_mfma_f32_16x16x32_bf16 v[10:13], v[174:177], v[214:217], v[10:13]
	v_mfma_f32_16x16x32_bf16 v[2:5], v[182:185], v[214:217], v[2:5]
	s_setprio 0
	s_barrier
	s_add_i32 s48, s48, 2
	s_add_u32 s40, s40, 0x100
	s_addc_u32 s41, s41, 0
	s_add_u32 s42, s42, 0x100
	s_addc_u32 s43, s43, 0
	s_cmp_gt_u32 s48, 13
	s_cbranch_scc0 .LBB0_257
	s_and_b64 vcc, exec, s[8:9]
	s_cbranch_vccz .LBB0_260
	s_barrier

; #define PG8_STAGE(bufoff, gbase, voff) do { _Pragma("unroll") for (int _i = 0; _i < 2; ++_i) \
;         __builtin_amdgcn_global_load_lds((const unsigned*)((const char*)(gbase) + (voff)[_i]), (PG8_LAS unsigned*)(lds + (bufoff) + ldsw + _i * 8192), 16, 0, 0); } while (0)
; #define PG8_LDA(dst, b, h) do { _Pragma("unroll") for (int m = 0; m < 4; ++m) _Pragma("unroll") for (int k = 0; k < 2; ++k) dst[m][k] = *(const PG8_LAS bf16x8*)(lds + PG8_SA(b, h) + aoff + m * 2048 + k * 1024); } while (0)
; #define PG8_LDB(dst, b, h) do { _Pragma("unroll") for (int n = 0; n < 2; ++n) _Pragma("unroll") for (int k = 0; k < 2; ++k) dst[n][k] = *(const PG8_LAS bf16x8*)(lds + PG8_SB(b, h) + boff + n * 2048 + k * 1024); } while (0)
; #define PG8_MMA(ai, bj, At, Bt) do { __builtin_amdgcn_s_setprio(1); _Pragma("unroll") for (int m = 0; m < 4; ++m) _Pragma("unroll") for (int n = 0; n < 2; ++n) _Pragma("unroll") for (int k = 0; k < 2; ++k) \
;         acc[ai][bj][m][n] = __builtin_amdgcn_mfma_f32_16x16x32_bf16(Bt[n][k], At[m][k], acc[ai][bj][m][n], 0, 0, 0); __builtin_amdgcn_s_setprio(0); } while (0)
; #define PG8_WAIT_V(n) asm volatile("s_waitcnt vmcnt(" #n ")" ::: "memory")
; #define PG8_BAR __builtin_amdgcn_s_barrier()
; template <class Epi, class Sched, bool ALIGN_EPI = false, bool SP2 = false>
; __device__ __forceinline__ void gemm_phase(PG8_LAS unsigned char* lds, const Gemm g, const Sched& S, const Epi& E) {
;     ...
;         for (int t = 0; t < nt; t += 2) {
;             const bool last = (t == nt - 2);
;             const char* a1 = cA + (size_t)(t + 1) * kstep;
;             const char* a2 = last ? nA : cA + (size_t)(t + 2) * kstep; const char* b2 = last ? nB : cB + (size_t)(t + 2) * kstep;
;             const char* a3 = a2 + kstep; const char* b3 = b2 + kstep;
;             if (last && has_next) S.a_ready(nxt);
;             if constexpr (SP2) {
;             PG8_LDB(B0, 0, 0); PG8_LDB(B1, 0, 1); PG8_SCHED; PG8_LDA(At, 0, 0); PG8_STAGE(PG8_SA(1, 1), a1 + hstep, voffA);
;             PG8_WAIT_V(8); PG8_WAIT_L(0); PG8_BAR; PG8_MMA(0, 0, At, B0); PG8_MMA(0, 1, At, B1); PG8_BAR; PG8_SCHED;
;             PG8_LDA(At, 0, 1); PG8_STAGE(PG8_SB(0, 0), b2, voffB); PG8_STAGE(PG8_SB(0, 1), b2 + hstep, voffB); PG8_STAGE(PG8_SA(0, 0), a2, voffA);
;             PG8_WAIT_V(8); PG8_WAIT_L(0); PG8_BAR; PG8_MMA(1, 0, At, B0); PG8_MMA(1, 1, At, B1); PG8_BAR; PG8_SCHED;
.LBB0_345:
	s_add_u32 vcc_lo, s72, 0x100
	s_addc_u32 vcc_hi, s73, 0
	s_mov_b32 s74, 0
	ds_read_b128 v[150:153], v147
	ds_read_b128 v[154:157], v147 offset:1024
	ds_read_b128 v[158:161], v147 offset:2048
	ds_read_b128 v[162:165], v147 offset:3072
	ds_read_b128 v[166:169], v148
	ds_read_b128 v[170:173], v148 offset:1024
	ds_read_b128 v[174:177], v148 offset:2048
	ds_read_b128 v[178:181], v148 offset:3072
	s_add_i32 s38, s74, 2
	s_add_u32 s72, s70, 0x100
	s_addc_u32 s73, s71, 0
	s_cmp_eq_u32 s50, s74
	s_cselect_b32 s74, s68, vcc_lo
	s_cselect_b32 s77, s61, s73
	s_cselect_b32 s76, s60, s72
	s_cselect_b32 s75, s69, vcc_hi
	v_lshl_add_u64 v[214:215], s[70:71], 0, v[140:141]
	s_add_i32 m0, s89, 0xc000
	ds_read_b128 v[182:185], v146
	ds_read_b128 v[186:189], v146 offset:1024
	ds_read_b128 v[190:193], v146 offset:2048
	ds_read_b128 v[194:197], v146 offset:3072
	ds_read_b128 v[198:201], v146 offset:4096
	ds_read_b128 v[202:205], v146 offset:5120
	ds_read_b128 v[206:209], v146 offset:6144
	ds_read_b128 v[210:213], v146 offset:7168
	global_load_lds_dwordx4 v[214:215], off
	v_lshl_add_u64 v[214:215], s[70:71], 0, v[138:139]
	s_add_i32 m0, s89, 0xe000
	s_nop 0
	global_load_lds_dwordx4 v[214:215], off
	s_waitcnt vmcnt(8)
	s_waitcnt lgkmcnt(0)
	s_barrier
	s_setprio 1
	s_waitcnt lgkmcnt(0)
	v_mfma_f32_16x16x32_bf16 v[126:129], v[150:153], v[182:185], 0
	v_mfma_f32_16x16x32_bf16 v[122:125], v[158:161], v[182:185], 0
	v_mfma_f32_16x16x32_bf16 v[118:121], v[150:153], v[190:193], 0
	v_mfma_f32_16x16x32_bf16 v[114:117], v[158:161], v[190:193], 0
	v_mfma_f32_16x16x32_bf16 v[102:105], v[150:153], v[198:201], 0
	v_mfma_f32_16x16x32_bf16 v[98:101], v[158:161], v[198:201], 0
	v_mfma_f32_16x16x32_bf16 v[86:89], v[150:153], v[206:209], 0
	v_mfma_f32_16x16x32_bf16 v[82:85], v[158:161], v[206:209], 0
	v_mfma_f32_16x16x32_bf16 v[126:129], v[154:157], v[186:189], v[126:129]
	v_mfma_f32_16x16x32_bf16 v[122:125], v[162:165], v[186:189], v[122:125]
	v_mfma_f32_16x16x32_bf16 v[118:121], v[154:157], v[194:197], v[118:121]
	v_mfma_f32_16x16x32_bf16 v[114:117], v[162:165], v[194:197], v[114:117]
	v_mfma_f32_16x16x32_bf16 v[102:105], v[154:157], v[202:205], v[102:105]
	v_mfma_f32_16x16x32_bf16 v[98:101], v[162:165], v[202:205], v[98:101]
	v_mfma_f32_16x16x32_bf16 v[86:89], v[154:157], v[210:213], v[86:89]
	v_mfma_f32_16x16x32_bf16 v[82:85], v[162:165], v[210:213], v[82:85]
	s_setprio 0
	s_setprio 1
	v_mfma_f32_16x16x32_bf16 v[110:113], v[166:169], v[182:185], 0
	v_mfma_f32_16x16x32_bf16 v[106:109], v[174:177], v[182:185], 0
	v_mfma_f32_16x16x32_bf16 v[94:97], v[166:169], v[190:193], 0
	v_mfma_f32_16x16x32_bf16 v[90:93], v[174:177], v[190:193], 0
	v_mfma_f32_16x16x32_bf16 v[78:81], v[166:169], v[198:201], 0
	v_mfma_f32_16x16x32_bf16 v[74:77], v[174:177], v[198:201], 0
	v_mfma_f32_16x16x32_bf16 v[70:73], v[166:169], v[206:209], 0
	v_mfma_f32_16x16x32_bf16 v[66:69], v[174:177], v[206:209], 0
	v_mfma_f32_16x16x32_bf16 v[110:113], v[170:173], v[186:189], v[110:113]
	v_mfma_f32_16x16x32_bf16 v[106:109], v[178:181], v[186:189], v[106:109]
	v_mfma_f32_16x16x32_bf16 v[94:97], v[170:173], v[194:197], v[94:97]
	v_mfma_f32_16x16x32_bf16 v[90:93], v[178:181], v[194:197], v[90:93]
	v_mfma_f32_16x16x32_bf16 v[78:81], v[170:173], v[202:205], v[78:81]
	v_mfma_f32_16x16x32_bf16 v[74:77], v[178:181], v[202:205], v[74:77]
	v_mfma_f32_16x16x32_bf16 v[70:73], v[170:173], v[210:213], v[70:73]
	v_mfma_f32_16x16x32_bf16 v[66:69], v[178:181], v[210:213], v[66:69]
	s_setprio 0
	s_barrier
	s_mov_b32 m0, s85
	v_lshl_add_u64 v[214:215], s[74:75], 0, v[130:131]
	s_add_u32 s70, s74, 0xb0000
	ds_read_b128 v[182:185], v146 offset:16384
	ds_read_b128 v[186:189], v146 offset:17408
	ds_read_b128 v[190:193], v146 offset:18432
	ds_read_b128 v[194:197], v146 offset:19456
	ds_read_b128 v[198:201], v146 offset:20480
	ds_read_b128 v[202:205], v146 offset:21504
	ds_read_b128 v[206:209], v146 offset:22528
	ds_read_b128 v[210:213], v146 offset:23552
	global_load_lds_dwordx4 v[214:215], off
	v_lshl_add_u64 v[216:217], s[74:75], 0, v[136:137]
	s_mov_b32 m0, s86
	s_addc_u32 s71, s75, 0
	global_load_lds_dwordx4 v[216:217], off
	v_lshl_add_u64 v[218:219], s[70:71], 0, v[130:131]
	s_mov_b32 m0, s87
	v_lshl_add_u64 v[220:221], s[76:77], 0, v[134:135]
	global_load_lds_dwordx4 v[218:219], off
	v_lshl_add_u64 v[218:219], s[70:71], 0, v[136:137]
	s_mov_b32 m0, s88
	s_nop 0
	global_load_lds_dwordx4 v[218:219], off
	v_lshl_add_u64 v[218:219], s[76:77], 0, v[132:133]
	s_waitcnt vmcnt(6)
	s_waitcnt lgkmcnt(0)
	s_barrier
	s_setprio 1
	s_waitcnt lgkmcnt(0)
	v_mfma_f32_16x16x32_bf16 v[62:65], v[150:153], v[182:185], 0
	v_mfma_f32_16x16x32_bf16 v[58:61], v[158:161], v[182:185], 0
	v_mfma_f32_16x16x32_bf16 v[54:57], v[150:153], v[190:193], 0
	v_mfma_f32_16x16x32_bf16 v[50:53], v[158:161], v[190:193], 0
	v_mfma_f32_16x16x32_bf16 v[38:41], v[150:153], v[198:201], 0
	v_mfma_f32_16x16x32_bf16 v[34:37], v[158:161], v[198:201], 0
	v_mfma_f32_16x16x32_bf16 v[22:25], v[150:153], v[206:209], 0
	v_mfma_f32_16x16x32_bf16 v[18:21], v[158:161], v[206:209], 0
	v_mfma_f32_16x16x32_bf16 v[62:65], v[154:157], v[186:189], v[62:65]
	v_mfma_f32_16x16x32_bf16 v[58:61], v[162:165], v[186:189], v[58:61]
	v_mfma_f32_16x16x32_bf16 v[54:57], v[154:157], v[194:197], v[54:57]
	v_mfma_f32_16x16x32_bf16 v[50:53], v[162:165], v[194:197], v[50:53]
	v_mfma_f32_16x16x32_bf16 v[38:41], v[154:157], v[202:205], v[38:41]
	v_mfma_f32_16x16x32_bf16 v[34:37], v[162:165], v[202:205], v[34:37]
	v_mfma_f32_16x16x32_bf16 v[22:25], v[154:157], v[210:213], v[22:25]
	v_mfma_f32_16x16x32_bf16 v[18:21], v[162:165], v[210:213], v[18:21]
	s_setprio 0
	s_setprio 1
	v_mfma_f32_16x16x32_bf16 v[46:49], v[166:169], v[182:185], 0
	v_mfma_f32_16x16x32_bf16 v[42:45], v[174:177], v[182:185], 0
	v_mfma_f32_16x16x32_bf16 v[30:33], v[166:169], v[190:193], 0
	v_mfma_f32_16x16x32_bf16 v[26:29], v[174:177], v[190:193], 0
	v_mfma_f32_16x16x32_bf16 v[14:17], v[166:169], v[198:201], 0
	v_mfma_f32_16x16x32_bf16 v[10:13], v[174:177], v[198:201], 0
	v_mfma_f32_16x16x32_bf16 v[6:9], v[166:169], v[206:209], 0
	v_mfma_f32_16x16x32_bf16 v[2:5], v[174:177], v[206:209], 0
	v_mfma_f32_16x16x32_bf16 v[46:49], v[170:173], v[186:189], v[46:49]
	v_mfma_f32_16x16x32_bf16 v[42:45], v[178:181], v[186:189], v[42:45]
	v_mfma_f32_16x16x32_bf16 v[30:33], v[170:173], v[194:197], v[30:33]
	v_mfma_f32_16x16x32_bf16 v[26:29], v[178:181], v[194:197], v[26:29]
	v_mfma_f32_16x16x32_bf16 v[14:17], v[170:173], v[202:205], v[14:17]
	v_mfma_f32_16x16x32_bf16 v[10:13], v[178:181], v[202:205], v[10:13]
	v_mfma_f32_16x16x32_bf16 v[6:9], v[170:173], v[210:213], v[6:9]
	v_mfma_f32_16x16x32_bf16 v[2:5], v[178:181], v[210:213], v[2:5]
	s_setprio 0
	s_barrier
; #define PG8_STAGE(bufoff, gbase, voff) do { _Pragma("unroll") for (int _i = 0; _i < 2; ++_i) \
;         __builtin_amdgcn_global_load_lds((const unsigned*)((const char*)(gbase) + (voff)[_i]), (PG8_LAS unsigned*)(lds + (bufoff) + ldsw + _i * 8192), 16, 0, 0); } while (0)
; #define PG8_LDA(dst, b, h) do { _Pragma("unroll") for (int m = 0; m < 4; ++m) _Pragma("unroll") for (int k = 0; k < 2; ++k) dst[m][k] = *(const PG8_LAS bf16x8*)(lds + PG8_SA(b, h) + aoff + m * 2048 + k * 1024); } while (0)
; #define PG8_LDB(dst, b, h) do { _Pragma("unroll") for (int n = 0; n < 2; ++n) _Pragma("unroll") for (int k = 0; k < 2; ++k) dst[n][k] = *(const PG8_LAS bf16x8*)(lds + PG8_SB(b, h) + boff + n * 2048 + k * 1024); } while (0)
; #define PG8_MMA(ai, bj, At, Bt) do { __builtin_amdgcn_s_setprio(1); _Pragma("unroll") for (int m = 0; m < 4; ++m) _Pragma("unroll") for (int n = 0; n < 2; ++n) _Pragma("unroll") for (int k = 0; k < 2; ++k) \
;         acc[ai][bj][m][n] = __builtin_amdgcn_mfma_f32_16x16x32_bf16(Bt[n][k], At[m][k], acc[ai][bj][m][n], 0, 0, 0); __builtin_amdgcn_s_setprio(0); } while (0)
; #define PG8_WAIT_V(n) asm volatile("s_waitcnt vmcnt(" #n ")" ::: "memory")
; #define PG8_WAIT_L(n) asm volatile("s_waitcnt lgkmcnt(" #n ")" ::: "memory")
; #define PG8_BAR __builtin_amdgcn_s_barrier()
; #define PG8_SCHED __builtin_amdgcn_sched_barrier(0)
; template <class Epi, class Sched, bool ALIGN_EPI = false, bool SP2 = false>
; __device__ __forceinline__ void gemm_phase(PG8_LAS unsigned char* lds, const Gemm g, const Sched& S, const Epi& E) {
;     ...
;             PG8_LDB(B0, 1, 0); PG8_LDB(B1, 1, 1); PG8_SCHED; PG8_LDA(At, 1, 0); PG8_STAGE(PG8_SA(0, 1), a2 + hstep, voffA);
;             PG8_WAIT_V(8); PG8_WAIT_L(0); PG8_BAR; PG8_MMA(0, 0, At, B0); PG8_MMA(0, 1, At, B1); PG8_BAR; PG8_SCHED;
;             PG8_LDA(At, 1, 1); PG8_STAGE(PG8_SB(1, 0), b3, voffB); PG8_STAGE(PG8_SB(1, 1), b3 + hstep, voffB); PG8_STAGE(PG8_SA(1, 0), a3, voffA);
;             PG8_WAIT_V(8); PG8_WAIT_L(0); PG8_BAR; PG8_MMA(1, 0, At, B0); PG8_MMA(1, 1, At, B1); PG8_BAR; PG8_SCHED;
	v_add_u32_e32 v178, s78, v144
	ds_read_b128 v[150:153], v149
	ds_read_b128 v[154:157], v149 offset:1024
	ds_read_b128 v[158:161], v149 offset:2048
	ds_read_b128 v[162:165], v149 offset:3072
	ds_read_b128 v[166:169], v178
	ds_read_b128 v[170:173], v178 offset:1024
	ds_read_b128 v[174:177], v178 offset:2048
	ds_read_b128 v[178:181], v178 offset:3072
	s_add_u32 s70, s76, 0xb0000
	s_addc_u32 s71, s77, 0
	s_mov_b32 m0, s89
	s_nop 0
	global_load_lds_dwordx4 v[218:219], off
	s_mov_b32 m0, s90
	s_nop 0
	global_load_lds_dwordx4 v[220:221], off
	s_mov_b32 m0, s91
	v_lshl_add_u64 v[222:223], s[70:71], 0, v[132:133]
	ds_read_b128 v[182:185], v146 offset:32768
	ds_read_b128 v[186:189], v146 offset:33792
	ds_read_b128 v[190:193], v146 offset:34816
	ds_read_b128 v[194:197], v146 offset:35840
	ds_read_b128 v[198:201], v146 offset:36864
	ds_read_b128 v[202:205], v146 offset:37888
	ds_read_b128 v[206:209], v146 offset:38912
	ds_read_b128 v[210:213], v146 offset:39936
	global_load_lds_dwordx4 v[222:223], off
	v_lshl_add_u64 v[222:223], s[70:71], 0, v[134:135]
	s_mov_b32 m0, s92
	s_nop 0
	global_load_lds_dwordx4 v[222:223], off
	s_waitcnt vmcnt(8)
	s_waitcnt lgkmcnt(0)
	s_barrier
	s_setprio 1
	s_waitcnt lgkmcnt(0)
	v_mfma_f32_16x16x32_bf16 v[126:129], v[150:153], v[182:185], v[126:129]
	v_mfma_f32_16x16x32_bf16 v[122:125], v[158:161], v[182:185], v[122:125]
	v_mfma_f32_16x16x32_bf16 v[118:121], v[150:153], v[190:193], v[118:121]
	v_mfma_f32_16x16x32_bf16 v[114:117], v[158:161], v[190:193], v[114:117]
	v_mfma_f32_16x16x32_bf16 v[102:105], v[150:153], v[198:201], v[102:105]
	v_mfma_f32_16x16x32_bf16 v[98:101], v[158:161], v[198:201], v[98:101]
	v_mfma_f32_16x16x32_bf16 v[86:89], v[150:153], v[206:209], v[86:89]
	v_mfma_f32_16x16x32_bf16 v[82:85], v[158:161], v[206:209], v[82:85]
	v_mfma_f32_16x16x32_bf16 v[126:129], v[154:157], v[186:189], v[126:129]
	v_mfma_f32_16x16x32_bf16 v[122:125], v[162:165], v[186:189], v[122:125]
	v_mfma_f32_16x16x32_bf16 v[118:121], v[154:157], v[194:197], v[118:121]
	v_mfma_f32_16x16x32_bf16 v[114:117], v[162:165], v[194:197], v[114:117]
	v_mfma_f32_16x16x32_bf16 v[102:105], v[154:157], v[202:205], v[102:105]
	v_mfma_f32_16x16x32_bf16 v[98:101], v[162:165], v[202:205], v[98:101]
	v_mfma_f32_16x16x32_bf16 v[86:89], v[154:157], v[210:213], v[86:89]
	v_mfma_f32_16x16x32_bf16 v[82:85], v[162:165], v[210:213], v[82:85]
	s_setprio 0
	s_setprio 1
	v_mfma_f32_16x16x32_bf16 v[110:113], v[166:169], v[182:185], v[110:113]
	v_mfma_f32_16x16x32_bf16 v[106:109], v[174:177], v[182:185], v[106:109]
	v_mfma_f32_16x16x32_bf16 v[94:97], v[166:169], v[190:193], v[94:97]
	v_mfma_f32_16x16x32_bf16 v[90:93], v[174:177], v[190:193], v[90:93]
	v_mfma_f32_16x16x32_bf16 v[78:81], v[166:169], v[198:201], v[78:81]
	v_mfma_f32_16x16x32_bf16 v[74:77], v[174:177], v[198:201], v[74:77]
	v_mfma_f32_16x16x32_bf16 v[70:73], v[166:169], v[206:209], v[70:73]
	v_mfma_f32_16x16x32_bf16 v[66:69], v[174:177], v[206:209], v[66:69]
	v_mfma_f32_16x16x32_bf16 v[110:113], v[170:173], v[186:189], v[110:113]
	v_mfma_f32_16x16x32_bf16 v[106:109], v[178:181], v[186:189], v[106:109]
	v_mfma_f32_16x16x32_bf16 v[94:97], v[170:173], v[194:197], v[94:97]
	v_mfma_f32_16x16x32_bf16 v[90:93], v[178:181], v[194:197], v[90:93]
	v_mfma_f32_16x16x32_bf16 v[78:81], v[170:173], v[202:205], v[78:81]
	v_mfma_f32_16x16x32_bf16 v[74:77], v[178:181], v[202:205], v[74:77]
	v_mfma_f32_16x16x32_bf16 v[70:73], v[170:173], v[210:213], v[70:73]
	v_mfma_f32_16x16x32_bf16 v[66:69], v[178:181], v[210:213], v[66:69]
	s_setprio 0
	s_barrier
	s_mov_b32 m0, s33
	v_lshl_add_u64 v[214:215], v[214:215], 0, s[24:25]
	s_add_u32 s70, s74, 0xb0080
	ds_read_b128 v[182:185], v146 offset:49152
	ds_read_b128 v[186:189], v146 offset:50176
	ds_read_b128 v[190:193], v146 offset:51200
	ds_read_b128 v[194:197], v146 offset:52224
	ds_read_b128 v[198:201], v146 offset:53248
	ds_read_b128 v[202:205], v146 offset:54272
	ds_read_b128 v[206:209], v146 offset:55296
	ds_read_b128 v[210:213], v146 offset:56320
	global_load_lds_dwordx4 v[214:215], off
	v_lshl_add_u64 v[214:215], v[216:217], 0, s[24:25]
	s_mov_b32 m0, s36
	s_addc_u32 s71, s75, 0
	global_load_lds_dwordx4 v[214:215], off
	v_lshl_add_u64 v[214:215], s[70:71], 0, v[130:131]
	s_mov_b32 m0, s48
	s_nop 0
	global_load_lds_dwordx4 v[214:215], off
	v_lshl_add_u64 v[214:215], s[70:71], 0, v[136:137]
	s_mov_b32 m0, s49
	s_nop 0
	global_load_lds_dwordx4 v[214:215], off
	v_lshl_add_u64 v[214:215], v[218:219], 0, s[24:25]
	s_mov_b32 m0, s37
	s_nop 0
	global_load_lds_dwordx4 v[214:215], off
	v_lshl_add_u64 v[214:215], v[220:221], 0, s[24:25]
	s_mov_b32 m0, s40
	s_nop 0
	global_load_lds_dwordx4 v[214:215], off
	s_waitcnt vmcnt(8)
	s_waitcnt lgkmcnt(0)
	s_barrier
; #define PG8_STAGE(bufoff, gbase, voff) do { _Pragma("unroll") for (int _i = 0; _i < 2; ++_i) \
;         __builtin_amdgcn_global_load_lds((const unsigned*)((const char*)(gbase) + (voff)[_i]), (PG8_LAS unsigned*)(lds + (bufoff) + ldsw + _i * 8192), 16, 0, 0); } while (0)
; #define PG8_LDA(dst, b, h) do { _Pragma("unroll") for (int m = 0; m < 4; ++m) _Pragma("unroll") for (int k = 0; k < 2; ++k) dst[m][k] = *(const PG8_LAS bf16x8*)(lds + PG8_SA(b, h) + aoff + m * 2048 + k * 1024); } while (0)
; #define PG8_LDB(dst, b, h) do { _Pragma("unroll") for (int n = 0; n < 2; ++n) _Pragma("unroll") for (int k = 0; k < 2; ++k) dst[n][k] = *(const PG8_LAS bf16x8*)(lds + PG8_SB(b, h) + boff + n * 2048 + k * 1024); } while (0)
; #define PG8_MMA(ai, bj, At, Bt) do { __builtin_amdgcn_s_setprio(1); _Pragma("unroll") for (int m = 0; m < 4; ++m) _Pragma("unroll") for (int n = 0; n < 2; ++n) _Pragma("unroll") for (int k = 0; k < 2; ++k) \
;         acc[ai][bj][m][n] = __builtin_amdgcn_mfma_f32_16x16x32_bf16(Bt[n][k], At[m][k], acc[ai][bj][m][n], 0, 0, 0); __builtin_amdgcn_s_setprio(0); } while (0)
; #define PG8_WAIT_V(n) asm volatile("s_waitcnt vmcnt(" #n ")" ::: "memory")
; template <class Epi, class Sched, bool ALIGN_EPI = false, bool SP2 = false>
; __device__ __forceinline__ void gemm_phase(PG8_LAS unsigned char* lds, const Gemm g, const Sched& S, const Epi& E) {
;     ...
;             PG8_LDB(B0, 0, 0); PG8_LDB(B1, 0, 1); PG8_SCHED; PG8_LDA(At, 0, 0); PG8_STAGE(PG8_SA(1, 1), a1 + hstep, voffA);
;             PG8_WAIT_V(8); PG8_WAIT_L(0); PG8_BAR; PG8_MMA(0, 0, At, B0); PG8_MMA(0, 1, At, B1); PG8_BAR; PG8_SCHED;
;             PG8_LDA(At, 0, 1); PG8_STAGE(PG8_SB(0, 0), b2, voffB); PG8_STAGE(PG8_SB(0, 1), b2 + hstep, voffB); PG8_STAGE(PG8_SA(0, 0), a2, voffA);
;             PG8_WAIT_V(8); PG8_WAIT_L(0); PG8_BAR; PG8_MMA(1, 0, At, B0); PG8_MMA(1, 1, At, B1); PG8_BAR; PG8_SCHED;
;             PG8_LDB(B0, 1, 0); PG8_LDB(B1, 1, 1); PG8_SCHED; PG8_LDA(At, 1, 0); PG8_STAGE(PG8_SA(0, 1), a2 + hstep, voffA);
;             PG8_WAIT_V(8); PG8_WAIT_L(0); PG8_BAR; PG8_MMA(0, 0, At, B0); PG8_MMA(0, 1, At, B1); PG8_BAR; PG8_SCHED;
;             PG8_LDA(At, 1, 1); PG8_STAGE(PG8_SB(1, 0), b3, voffB); PG8_STAGE(PG8_SB(1, 1), b3 + hstep, voffB); PG8_STAGE(PG8_SA(1, 0), a3, voffA);
;             PG8_WAIT_V(8); PG8_WAIT_L(0); PG8_BAR; PG8_MMA(1, 0, At, B0); PG8_MMA(1, 1, At, B1); PG8_BAR; PG8_SCHED;
	s_setprio 1
	s_waitcnt lgkmcnt(0)
	v_mfma_f32_16x16x32_bf16 v[62:65], v[150:153], v[182:185], v[62:65]
	v_mfma_f32_16x16x32_bf16 v[58:61], v[158:161], v[182:185], v[58:61]
	v_mfma_f32_16x16x32_bf16 v[54:57], v[150:153], v[190:193], v[54:57]
	v_mfma_f32_16x16x32_bf16 v[50:53], v[158:161], v[190:193], v[50:53]
	v_mfma_f32_16x16x32_bf16 v[38:41], v[150:153], v[198:201], v[38:41]
	v_mfma_f32_16x16x32_bf16 v[34:37], v[158:161], v[198:201], v[34:37]
	v_mfma_f32_16x16x32_bf16 v[22:25], v[150:153], v[206:209], v[22:25]
	v_mfma_f32_16x16x32_bf16 v[18:21], v[158:161], v[206:209], v[18:21]
	v_mfma_f32_16x16x32_bf16 v[62:65], v[154:157], v[186:189], v[62:65]
	v_mfma_f32_16x16x32_bf16 v[58:61], v[162:165], v[186:189], v[58:61]
	v_mfma_f32_16x16x32_bf16 v[54:57], v[154:157], v[194:197], v[54:57]
	v_mfma_f32_16x16x32_bf16 v[50:53], v[162:165], v[194:197], v[50:53]
	v_mfma_f32_16x16x32_bf16 v[38:41], v[154:157], v[202:205], v[38:41]
	v_mfma_f32_16x16x32_bf16 v[34:37], v[162:165], v[202:205], v[34:37]
	v_mfma_f32_16x16x32_bf16 v[22:25], v[154:157], v[210:213], v[22:25]
	v_mfma_f32_16x16x32_bf16 v[18:21], v[162:165], v[210:213], v[18:21]
	s_setprio 0
	s_setprio 1
	v_mfma_f32_16x16x32_bf16 v[46:49], v[166:169], v[182:185], v[46:49]
	v_mfma_f32_16x16x32_bf16 v[42:45], v[174:177], v[182:185], v[42:45]
	v_mfma_f32_16x16x32_bf16 v[30:33], v[166:169], v[190:193], v[30:33]
	v_mfma_f32_16x16x32_bf16 v[26:29], v[174:177], v[190:193], v[26:29]
	v_mfma_f32_16x16x32_bf16 v[14:17], v[166:169], v[198:201], v[14:17]
	v_mfma_f32_16x16x32_bf16 v[10:13], v[174:177], v[198:201], v[10:13]
	v_mfma_f32_16x16x32_bf16 v[6:9], v[166:169], v[206:209], v[6:9]
	v_mfma_f32_16x16x32_bf16 v[2:5], v[174:177], v[206:209], v[2:5]
	v_mfma_f32_16x16x32_bf16 v[46:49], v[170:173], v[186:189], v[46:49]
	v_mfma_f32_16x16x32_bf16 v[42:45], v[178:181], v[186:189], v[42:45]
	v_mfma_f32_16x16x32_bf16 v[30:33], v[170:173], v[194:197], v[30:33]
	v_mfma_f32_16x16x32_bf16 v[26:29], v[178:181], v[194:197], v[26:29]
	v_mfma_f32_16x16x32_bf16 v[14:17], v[170:173], v[202:205], v[14:17]
	v_mfma_f32_16x16x32_bf16 v[10:13], v[178:181], v[202:205], v[10:13]
	v_mfma_f32_16x16x32_bf16 v[6:9], v[170:173], v[210:213], v[6:9]
	v_mfma_f32_16x16x32_bf16 v[2:5], v[178:181], v[210:213], v[2:5]
	s_setprio 0
	s_barrier
	s_add_u32 vcc_lo, vcc_lo, 0x100
	s_addc_u32 vcc_hi, vcc_hi, 0
	s_cmp_ge_u32 s38, s93
	s_mov_b64 s[70:71], s[72:73]
	s_mov_b32 s74, s38
.LBB0_346:
	ds_read_b128 v[150:153], v147
	ds_read_b128 v[154:157], v147 offset:1024
	ds_read_b128 v[158:161], v147 offset:2048
	ds_read_b128 v[162:165], v147 offset:3072
	ds_read_b128 v[166:169], v148
	ds_read_b128 v[170:173], v148 offset:1024
	ds_read_b128 v[174:177], v148 offset:2048
	ds_read_b128 v[178:181], v148 offset:3072
	s_add_i32 s38, s74, 2
	s_add_u32 s72, s70, 0x100
	s_addc_u32 s73, s71, 0
	s_cmp_eq_u32 s50, s74
	s_cselect_b32 s74, s68, vcc_lo
	s_cselect_b32 s77, s61, s73
	s_cselect_b32 s76, s60, s72
	s_cselect_b32 s75, s69, vcc_hi
	v_lshl_add_u64 v[214:215], s[70:71], 0, v[140:141]
	s_add_i32 m0, s89, 0xc000
	ds_read_b128 v[182:185], v146
	ds_read_b128 v[186:189], v146 offset:1024
	ds_read_b128 v[190:193], v146 offset:2048
	ds_read_b128 v[194:197], v146 offset:3072
	ds_read_b128 v[198:201], v146 offset:4096
	ds_read_b128 v[202:205], v146 offset:5120
	ds_read_b128 v[206:209], v146 offset:6144
	ds_read_b128 v[210:213], v146 offset:7168
	global_load_lds_dwordx4 v[214:215], off
	v_lshl_add_u64 v[214:215], s[70:71], 0, v[138:139]
	s_add_i32 m0, s89, 0xe000
	s_nop 0
	global_load_lds_dwordx4 v[214:215], off
	s_waitcnt vmcnt(8)
	s_waitcnt lgkmcnt(0)
	s_barrier
	s_setprio 1
	s_waitcnt lgkmcnt(0)
	v_mfma_f32_16x16x32_bf16 v[126:129], v[150:153], v[182:185], v[126:129]
	v_mfma_f32_16x16x32_bf16 v[122:125], v[158:161], v[182:185], v[122:125]
	v_mfma_f32_16x16x32_bf16 v[118:121], v[150:153], v[190:193], v[118:121]
	v_mfma_f32_16x16x32_bf16 v[114:117], v[158:161], v[190:193], v[114:117]
	v_mfma_f32_16x16x32_bf16 v[102:105], v[150:153], v[198:201], v[102:105]
	v_mfma_f32_16x16x32_bf16 v[98:101], v[158:161], v[198:201], v[98:101]
	v_mfma_f32_16x16x32_bf16 v[86:89], v[150:153], v[206:209], v[86:89]
	v_mfma_f32_16x16x32_bf16 v[82:85], v[158:161], v[206:209], v[82:85]
	v_mfma_f32_16x16x32_bf16 v[126:129], v[154:157], v[186:189], v[126:129]
	v_mfma_f32_16x16x32_bf16 v[122:125], v[162:165], v[186:189], v[122:125]
	v_mfma_f32_16x16x32_bf16 v[118:121], v[154:157], v[194:197], v[118:121]
	v_mfma_f32_16x16x32_bf16 v[114:117], v[162:165], v[194:197], v[114:117]
	v_mfma_f32_16x16x32_bf16 v[102:105], v[154:157], v[202:205], v[102:105]
	v_mfma_f32_16x16x32_bf16 v[98:101], v[162:165], v[202:205], v[98:101]
	v_mfma_f32_16x16x32_bf16 v[86:89], v[154:157], v[210:213], v[86:89]
	v_mfma_f32_16x16x32_bf16 v[82:85], v[162:165], v[210:213], v[82:85]
	s_setprio 0
	s_setprio 1
	v_mfma_f32_16x16x32_bf16 v[110:113], v[166:169], v[182:185], v[110:113]
	v_mfma_f32_16x16x32_bf16 v[106:109], v[174:177], v[182:185], v[106:109]
	v_mfma_f32_16x16x32_bf16 v[94:97], v[166:169], v[190:193], v[94:97]
	v_mfma_f32_16x16x32_bf16 v[90:93], v[174:177], v[190:193], v[90:93]
	v_mfma_f32_16x16x32_bf16 v[78:81], v[166:169], v[198:201], v[78:81]
	v_mfma_f32_16x16x32_bf16 v[74:77], v[174:177], v[198:201], v[74:77]
	v_mfma_f32_16x16x32_bf16 v[70:73], v[166:169], v[206:209], v[70:73]
	v_mfma_f32_16x16x32_bf16 v[66:69], v[174:177], v[206:209], v[66:69]
	v_mfma_f32_16x16x32_bf16 v[110:113], v[170:173], v[186:189], v[110:113]
	v_mfma_f32_16x16x32_bf16 v[106:109], v[178:181], v[186:189], v[106:109]
	v_mfma_f32_16x16x32_bf16 v[94:97], v[170:173], v[194:197], v[94:97]
	v_mfma_f32_16x16x32_bf16 v[90:93], v[178:181], v[194:197], v[90:93]
	v_mfma_f32_16x16x32_bf16 v[78:81], v[170:173], v[202:205], v[78:81]
	v_mfma_f32_16x16x32_bf16 v[74:77], v[178:181], v[202:205], v[74:77]
	v_mfma_f32_16x16x32_bf16 v[70:73], v[170:173], v[210:213], v[70:73]
	v_mfma_f32_16x16x32_bf16 v[66:69], v[178:181], v[210:213], v[66:69]
	s_setprio 0
	s_barrier
; #define PG8_STAGE(bufoff, gbase, voff) do { _Pragma("unroll") for (int _i = 0; _i < 2; ++_i) \
;         __builtin_amdgcn_global_load_lds((const unsigned*)((const char*)(gbase) + (voff)[_i]), (PG8_LAS unsigned*)(lds + (bufoff) + ldsw + _i * 8192), 16, 0, 0); } while (0)
; #define PG8_LDA(dst, b, h) do { _Pragma("unroll") for (int m = 0; m < 4; ++m) _Pragma("unroll") for (int k = 0; k < 2; ++k) dst[m][k] = *(const PG8_LAS bf16x8*)(lds + PG8_SA(b, h) + aoff + m * 2048 + k * 1024); } while (0)
; #define PG8_LDB(dst, b, h) do { _Pragma("unroll") for (int n = 0; n < 2; ++n) _Pragma("unroll") for (int k = 0; k < 2; ++k) dst[n][k] = *(const PG8_LAS bf16x8*)(lds + PG8_SB(b, h) + boff + n * 2048 + k * 1024); } while (0)
; #define PG8_MMA(ai, bj, At, Bt) do { __builtin_amdgcn_s_setprio(1); _Pragma("unroll") for (int m = 0; m < 4; ++m) _Pragma("unroll") for (int n = 0; n < 2; ++n) _Pragma("unroll") for (int k = 0; k < 2; ++k) \
;         acc[ai][bj][m][n] = __builtin_amdgcn_mfma_f32_16x16x32_bf16(Bt[n][k], At[m][k], acc[ai][bj][m][n], 0, 0, 0); __builtin_amdgcn_s_setprio(0); } while (0)
; #define PG8_WAIT_V(n) asm volatile("s_waitcnt vmcnt(" #n ")" ::: "memory")
; #define PG8_WAIT_L(n) asm volatile("s_waitcnt lgkmcnt(" #n ")" ::: "memory")
; #define PG8_BAR __builtin_amdgcn_s_barrier()
; #define PG8_SCHED __builtin_amdgcn_sched_barrier(0)
; template <class Epi, class Sched, bool ALIGN_EPI = false, bool SP2 = false>
; __device__ __forceinline__ void gemm_phase(PG8_LAS unsigned char* lds, const Gemm g, const Sched& S, const Epi& E) {
;     ...
;             PG8_LDA(At, 0, 1); PG8_STAGE(PG8_SB(0, 0), b2, voffB); PG8_STAGE(PG8_SB(0, 1), b2 + hstep, voffB); PG8_STAGE(PG8_SA(0, 0), a2, voffA);
;             PG8_WAIT_V(8); PG8_WAIT_L(0); PG8_BAR; PG8_MMA(1, 0, At, B0); PG8_MMA(1, 1, At, B1); PG8_BAR; PG8_SCHED;
;             PG8_LDB(B0, 1, 0); PG8_LDB(B1, 1, 1); PG8_SCHED; PG8_LDA(At, 1, 0); PG8_STAGE(PG8_SA(0, 1), a2 + hstep, voffA);
;             PG8_WAIT_V(8); PG8_WAIT_L(0); PG8_BAR; PG8_MMA(0, 0, At, B0); PG8_MMA(0, 1, At, B1); PG8_BAR; PG8_SCHED;
	s_mov_b32 m0, s85
	v_lshl_add_u64 v[214:215], s[74:75], 0, v[130:131]
	s_add_u32 s70, s74, 0xb0000
	ds_read_b128 v[182:185], v146 offset:16384
	ds_read_b128 v[186:189], v146 offset:17408
	ds_read_b128 v[190:193], v146 offset:18432
	ds_read_b128 v[194:197], v146 offset:19456
	ds_read_b128 v[198:201], v146 offset:20480
	ds_read_b128 v[202:205], v146 offset:21504
	ds_read_b128 v[206:209], v146 offset:22528
	ds_read_b128 v[210:213], v146 offset:23552
	global_load_lds_dwordx4 v[214:215], off
	v_lshl_add_u64 v[216:217], s[74:75], 0, v[136:137]
	s_mov_b32 m0, s86
	s_addc_u32 s71, s75, 0
	global_load_lds_dwordx4 v[216:217], off
	v_lshl_add_u64 v[218:219], s[70:71], 0, v[130:131]
	s_mov_b32 m0, s87
	v_lshl_add_u64 v[220:221], s[76:77], 0, v[134:135]
	global_load_lds_dwordx4 v[218:219], off
	v_lshl_add_u64 v[218:219], s[70:71], 0, v[136:137]
	s_mov_b32 m0, s88
	s_nop 0
	global_load_lds_dwordx4 v[218:219], off
	v_lshl_add_u64 v[218:219], s[76:77], 0, v[132:133]
	s_waitcnt vmcnt(6)
	s_waitcnt lgkmcnt(0)
	s_barrier
	s_setprio 1
	s_waitcnt lgkmcnt(0)
	v_mfma_f32_16x16x32_bf16 v[62:65], v[150:153], v[182:185], v[62:65]
	v_mfma_f32_16x16x32_bf16 v[58:61], v[158:161], v[182:185], v[58:61]
	v_mfma_f32_16x16x32_bf16 v[54:57], v[150:153], v[190:193], v[54:57]
	v_mfma_f32_16x16x32_bf16 v[50:53], v[158:161], v[190:193], v[50:53]
	v_mfma_f32_16x16x32_bf16 v[38:41], v[150:153], v[198:201], v[38:41]
	v_mfma_f32_16x16x32_bf16 v[34:37], v[158:161], v[198:201], v[34:37]
	v_mfma_f32_16x16x32_bf16 v[22:25], v[150:153], v[206:209], v[22:25]
	v_mfma_f32_16x16x32_bf16 v[18:21], v[158:161], v[206:209], v[18:21]
	v_mfma_f32_16x16x32_bf16 v[62:65], v[154:157], v[186:189], v[62:65]
	v_mfma_f32_16x16x32_bf16 v[58:61], v[162:165], v[186:189], v[58:61]
	v_mfma_f32_16x16x32_bf16 v[54:57], v[154:157], v[194:197], v[54:57]
	v_mfma_f32_16x16x32_bf16 v[50:53], v[162:165], v[194:197], v[50:53]
	v_mfma_f32_16x16x32_bf16 v[38:41], v[154:157], v[202:205], v[38:41]
	v_mfma_f32_16x16x32_bf16 v[34:37], v[162:165], v[202:205], v[34:37]
	v_mfma_f32_16x16x32_bf16 v[22:25], v[154:157], v[210:213], v[22:25]
	v_mfma_f32_16x16x32_bf16 v[18:21], v[162:165], v[210:213], v[18:21]
	s_setprio 0
	s_setprio 1
	v_mfma_f32_16x16x32_bf16 v[46:49], v[166:169], v[182:185], v[46:49]
	v_mfma_f32_16x16x32_bf16 v[42:45], v[174:177], v[182:185], v[42:45]
	v_mfma_f32_16x16x32_bf16 v[30:33], v[166:169], v[190:193], v[30:33]
	v_mfma_f32_16x16x32_bf16 v[26:29], v[174:177], v[190:193], v[26:29]
	v_mfma_f32_16x16x32_bf16 v[14:17], v[166:169], v[198:201], v[14:17]
	v_mfma_f32_16x16x32_bf16 v[10:13], v[174:177], v[198:201], v[10:13]
	v_mfma_f32_16x16x32_bf16 v[6:9], v[166:169], v[206:209], v[6:9]
	v_mfma_f32_16x16x32_bf16 v[2:5], v[174:177], v[206:209], v[2:5]
	v_mfma_f32_16x16x32_bf16 v[46:49], v[170:173], v[186:189], v[46:49]
	v_mfma_f32_16x16x32_bf16 v[42:45], v[178:181], v[186:189], v[42:45]
	v_mfma_f32_16x16x32_bf16 v[30:33], v[170:173], v[194:197], v[30:33]
	v_mfma_f32_16x16x32_bf16 v[26:29], v[178:181], v[194:197], v[26:29]
	v_mfma_f32_16x16x32_bf16 v[14:17], v[170:173], v[202:205], v[14:17]
	v_mfma_f32_16x16x32_bf16 v[10:13], v[178:181], v[202:205], v[10:13]
	v_mfma_f32_16x16x32_bf16 v[6:9], v[170:173], v[210:213], v[6:9]
	v_mfma_f32_16x16x32_bf16 v[2:5], v[178:181], v[210:213], v[2:5]
	s_setprio 0
	s_barrier
	v_add_u32_e32 v178, s78, v144
	ds_read_b128 v[150:153], v149
	ds_read_b128 v[154:157], v149 offset:1024
	ds_read_b128 v[158:161], v149 offset:2048
	ds_read_b128 v[162:165], v149 offset:3072
	ds_read_b128 v[166:169], v178
	ds_read_b128 v[170:173], v178 offset:1024
	ds_read_b128 v[174:177], v178 offset:2048
	ds_read_b128 v[178:181], v178 offset:3072
	s_add_u32 s70, s76, 0xb0000
	s_addc_u32 s71, s77, 0
	s_mov_b32 m0, s89
	s_nop 0
	global_load_lds_dwordx4 v[218:219], off
	s_mov_b32 m0, s90
	s_nop 0
	global_load_lds_dwordx4 v[220:221], off
	s_mov_b32 m0, s91
	v_lshl_add_u64 v[222:223], s[70:71], 0, v[132:133]
	ds_read_b128 v[182:185], v146 offset:32768
	ds_read_b128 v[186:189], v146 offset:33792
	ds_read_b128 v[190:193], v146 offset:34816
	ds_read_b128 v[194:197], v146 offset:35840
	ds_read_b128 v[198:201], v146 offset:36864
	ds_read_b128 v[202:205], v146 offset:37888
	ds_read_b128 v[206:209], v146 offset:38912
	ds_read_b128 v[210:213], v146 offset:39936
	global_load_lds_dwordx4 v[222:223], off
	v_lshl_add_u64 v[222:223], s[70:71], 0, v[134:135]
	s_mov_b32 m0, s92
	s_nop 0
	global_load_lds_dwordx4 v[222:223], off
	s_waitcnt vmcnt(8)
	s_waitcnt lgkmcnt(0)
	s_barrier
; #define PG8_STAGE(bufoff, gbase, voff) do { _Pragma("unroll") for (int _i = 0; _i < 2; ++_i) \
;         __builtin_amdgcn_global_load_lds((const unsigned*)((const char*)(gbase) + (voff)[_i]), (PG8_LAS unsigned*)(lds + (bufoff) + ldsw + _i * 8192), 16, 0, 0); } while (0)
; #define PG8_LDA(dst, b, h) do { _Pragma("unroll") for (int m = 0; m < 4; ++m) _Pragma("unroll") for (int k = 0; k < 2; ++k) dst[m][k] = *(const PG8_LAS bf16x8*)(lds + PG8_SA(b, h) + aoff + m * 2048 + k * 1024); } while (0)
; #define PG8_MMA(ai, bj, At, Bt) do { __builtin_amdgcn_s_setprio(1); _Pragma("unroll") for (int m = 0; m < 4; ++m) _Pragma("unroll") for (int n = 0; n < 2; ++n) _Pragma("unroll") for (int k = 0; k < 2; ++k) \
;         acc[ai][bj][m][n] = __builtin_amdgcn_mfma_f32_16x16x32_bf16(Bt[n][k], At[m][k], acc[ai][bj][m][n], 0, 0, 0); __builtin_amdgcn_s_setprio(0); } while (0)
; #define PG8_WAIT_V(n) asm volatile("s_waitcnt vmcnt(" #n ")" ::: "memory")
; #define PG8_WAIT_L(n) asm volatile("s_waitcnt lgkmcnt(" #n ")" ::: "memory")
; #define PG8_BAR __builtin_amdgcn_s_barrier()
; #define PG8_SCHED __builtin_amdgcn_sched_barrier(0)
; template <class Epi, class Sched, bool ALIGN_EPI = false, bool SP2 = false>
; __device__ __forceinline__ void gemm_phase(PG8_LAS unsigned char* lds, const Gemm g, const Sched& S, const Epi& E) {
;     ...
;             PG8_WAIT_V(8); PG8_WAIT_L(0); PG8_BAR; PG8_MMA(0, 0, At, B0); PG8_MMA(0, 1, At, B1); PG8_BAR; PG8_SCHED;
;             PG8_LDA(At, 1, 1); PG8_STAGE(PG8_SB(1, 0), b3, voffB); PG8_STAGE(PG8_SB(1, 1), b3 + hstep, voffB); PG8_STAGE(PG8_SA(1, 0), a3, voffA);
;             PG8_WAIT_V(8); PG8_WAIT_L(0); PG8_BAR; PG8_MMA(1, 0, At, B0); PG8_MMA(1, 1, At, B1); PG8_BAR; PG8_SCHED;
;     ...
;         if constexpr (ALIGN_EPI) { if (wr == 0) PG8_BAR; }
	s_setprio 1
	s_waitcnt lgkmcnt(0)
	v_mfma_f32_16x16x32_bf16 v[126:129], v[150:153], v[182:185], v[126:129]
	v_mfma_f32_16x16x32_bf16 v[122:125], v[158:161], v[182:185], v[122:125]
	v_mfma_f32_16x16x32_bf16 v[118:121], v[150:153], v[190:193], v[118:121]
	v_mfma_f32_16x16x32_bf16 v[114:117], v[158:161], v[190:193], v[114:117]
	v_mfma_f32_16x16x32_bf16 v[102:105], v[150:153], v[198:201], v[102:105]
	v_mfma_f32_16x16x32_bf16 v[98:101], v[158:161], v[198:201], v[98:101]
	v_mfma_f32_16x16x32_bf16 v[86:89], v[150:153], v[206:209], v[86:89]
	v_mfma_f32_16x16x32_bf16 v[82:85], v[158:161], v[206:209], v[82:85]
	v_mfma_f32_16x16x32_bf16 v[126:129], v[154:157], v[186:189], v[126:129]
	v_mfma_f32_16x16x32_bf16 v[122:125], v[162:165], v[186:189], v[122:125]
	v_mfma_f32_16x16x32_bf16 v[118:121], v[154:157], v[194:197], v[118:121]
	v_mfma_f32_16x16x32_bf16 v[114:117], v[162:165], v[194:197], v[114:117]
	v_mfma_f32_16x16x32_bf16 v[102:105], v[154:157], v[202:205], v[102:105]
	v_mfma_f32_16x16x32_bf16 v[98:101], v[162:165], v[202:205], v[98:101]
	v_mfma_f32_16x16x32_bf16 v[86:89], v[154:157], v[210:213], v[86:89]
	v_mfma_f32_16x16x32_bf16 v[82:85], v[162:165], v[210:213], v[82:85]
	s_setprio 0
	s_setprio 1
	v_mfma_f32_16x16x32_bf16 v[110:113], v[166:169], v[182:185], v[110:113]
	v_mfma_f32_16x16x32_bf16 v[106:109], v[174:177], v[182:185], v[106:109]
	v_mfma_f32_16x16x32_bf16 v[94:97], v[166:169], v[190:193], v[94:97]
	v_mfma_f32_16x16x32_bf16 v[90:93], v[174:177], v[190:193], v[90:93]
	v_mfma_f32_16x16x32_bf16 v[78:81], v[166:169], v[198:201], v[78:81]
	v_mfma_f32_16x16x32_bf16 v[74:77], v[174:177], v[198:201], v[74:77]
	v_mfma_f32_16x16x32_bf16 v[70:73], v[166:169], v[206:209], v[70:73]
	v_mfma_f32_16x16x32_bf16 v[66:69], v[174:177], v[206:209], v[66:69]
	v_mfma_f32_16x16x32_bf16 v[110:113], v[170:173], v[186:189], v[110:113]
	v_mfma_f32_16x16x32_bf16 v[106:109], v[178:181], v[186:189], v[106:109]
	v_mfma_f32_16x16x32_bf16 v[94:97], v[170:173], v[194:197], v[94:97]
	v_mfma_f32_16x16x32_bf16 v[90:93], v[178:181], v[194:197], v[90:93]
	v_mfma_f32_16x16x32_bf16 v[78:81], v[170:173], v[202:205], v[78:81]
	v_mfma_f32_16x16x32_bf16 v[74:77], v[178:181], v[202:205], v[74:77]
	v_mfma_f32_16x16x32_bf16 v[70:73], v[170:173], v[210:213], v[70:73]
	v_mfma_f32_16x16x32_bf16 v[66:69], v[178:181], v[210:213], v[66:69]
	s_setprio 0
	s_barrier
	s_mov_b32 m0, s33
	v_lshl_add_u64 v[214:215], v[214:215], 0, s[24:25]
	s_add_u32 s70, s74, 0xb0080
	ds_read_b128 v[182:185], v146 offset:49152
	ds_read_b128 v[186:189], v146 offset:50176
	ds_read_b128 v[190:193], v146 offset:51200
	ds_read_b128 v[194:197], v146 offset:52224
	ds_read_b128 v[198:201], v146 offset:53248
	ds_read_b128 v[202:205], v146 offset:54272
	ds_read_b128 v[206:209], v146 offset:55296
	ds_read_b128 v[210:213], v146 offset:56320
	global_load_lds_dwordx4 v[214:215], off
	v_lshl_add_u64 v[214:215], v[216:217], 0, s[24:25]
	s_mov_b32 m0, s36
	s_addc_u32 s71, s75, 0
	global_load_lds_dwordx4 v[214:215], off
	v_lshl_add_u64 v[214:215], s[70:71], 0, v[130:131]
	s_mov_b32 m0, s48
	s_nop 0
	global_load_lds_dwordx4 v[214:215], off
	v_lshl_add_u64 v[214:215], s[70:71], 0, v[136:137]
	s_mov_b32 m0, s49
	s_nop 0
	global_load_lds_dwordx4 v[214:215], off
	v_lshl_add_u64 v[214:215], v[218:219], 0, s[24:25]
	s_mov_b32 m0, s37
	s_nop 0
	global_load_lds_dwordx4 v[214:215], off
	v_lshl_add_u64 v[214:215], v[220:221], 0, s[24:25]
	s_mov_b32 m0, s40
	s_nop 0
	global_load_lds_dwordx4 v[214:215], off
	s_waitcnt vmcnt(8)
	s_waitcnt lgkmcnt(0)
	s_barrier
	s_setprio 1
	s_waitcnt lgkmcnt(0)
	v_mfma_f32_16x16x32_bf16 v[62:65], v[150:153], v[182:185], v[62:65]
	v_mfma_f32_16x16x32_bf16 v[58:61], v[158:161], v[182:185], v[58:61]
	v_mfma_f32_16x16x32_bf16 v[54:57], v[150:153], v[190:193], v[54:57]
	v_mfma_f32_16x16x32_bf16 v[50:53], v[158:161], v[190:193], v[50:53]
	v_mfma_f32_16x16x32_bf16 v[38:41], v[150:153], v[198:201], v[38:41]
	v_mfma_f32_16x16x32_bf16 v[34:37], v[158:161], v[198:201], v[34:37]
	v_mfma_f32_16x16x32_bf16 v[22:25], v[150:153], v[206:209], v[22:25]
	v_mfma_f32_16x16x32_bf16 v[18:21], v[158:161], v[206:209], v[18:21]
	v_mfma_f32_16x16x32_bf16 v[62:65], v[154:157], v[186:189], v[62:65]
	v_mfma_f32_16x16x32_bf16 v[58:61], v[162:165], v[186:189], v[58:61]
	v_mfma_f32_16x16x32_bf16 v[54:57], v[154:157], v[194:197], v[54:57]
	v_mfma_f32_16x16x32_bf16 v[50:53], v[162:165], v[194:197], v[50:53]
	v_mfma_f32_16x16x32_bf16 v[38:41], v[154:157], v[202:205], v[38:41]
	v_mfma_f32_16x16x32_bf16 v[34:37], v[162:165], v[202:205], v[34:37]
	v_mfma_f32_16x16x32_bf16 v[22:25], v[154:157], v[210:213], v[22:25]
	v_mfma_f32_16x16x32_bf16 v[18:21], v[162:165], v[210:213], v[18:21]
	s_setprio 0
	s_setprio 1
	v_mfma_f32_16x16x32_bf16 v[46:49], v[166:169], v[182:185], v[46:49]
	v_mfma_f32_16x16x32_bf16 v[42:45], v[174:177], v[182:185], v[42:45]
	v_mfma_f32_16x16x32_bf16 v[30:33], v[166:169], v[190:193], v[30:33]
	v_mfma_f32_16x16x32_bf16 v[26:29], v[174:177], v[190:193], v[26:29]
	v_mfma_f32_16x16x32_bf16 v[14:17], v[166:169], v[198:201], v[14:17]
	v_mfma_f32_16x16x32_bf16 v[10:13], v[174:177], v[198:201], v[10:13]
	v_mfma_f32_16x16x32_bf16 v[6:9], v[166:169], v[206:209], v[6:9]
	v_mfma_f32_16x16x32_bf16 v[2:5], v[174:177], v[206:209], v[2:5]
	v_mfma_f32_16x16x32_bf16 v[46:49], v[170:173], v[186:189], v[46:49]
	v_mfma_f32_16x16x32_bf16 v[42:45], v[178:181], v[186:189], v[42:45]
	v_mfma_f32_16x16x32_bf16 v[30:33], v[170:173], v[194:197], v[30:33]
	v_mfma_f32_16x16x32_bf16 v[26:29], v[178:181], v[194:197], v[26:29]
	v_mfma_f32_16x16x32_bf16 v[14:17], v[170:173], v[202:205], v[14:17]
	v_mfma_f32_16x16x32_bf16 v[10:13], v[178:181], v[202:205], v[10:13]
	v_mfma_f32_16x16x32_bf16 v[6:9], v[170:173], v[210:213], v[6:9]
	v_mfma_f32_16x16x32_bf16 v[2:5], v[178:181], v[210:213], v[2:5]
	s_setprio 0
	s_barrier
	s_add_u32 vcc_lo, vcc_lo, 0x100
	s_addc_u32 vcc_hi, vcc_hi, 0
	s_cmp_ge_u32 s38, s93
	s_mov_b64 s[70:71], s[72:73]
	s_mov_b32 s74, s38
	s_cbranch_scc0 .LBB0_346
	s_and_b64 vcc, exec, s[56:57]
	s_cbranch_vccz .LBB0_349
	s_barrier

; #define PG8_STAGE(bufoff, gbase, voff) do { _Pragma("unroll") for (int _i = 0; _i < 2; ++_i) \
;         __builtin_amdgcn_global_load_lds((const unsigned*)((const char*)(gbase) + (voff)[_i]), (PG8_LAS unsigned*)(lds + (bufoff) + ldsw + _i * 8192), 16, 0, 0); } while (0)
; #define PG8_LDA(dst, b, h) do { _Pragma("unroll") for (int m = 0; m < 4; ++m) _Pragma("unroll") for (int k = 0; k < 2; ++k) dst[m][k] = *(const PG8_LAS bf16x8*)(lds + PG8_SA(b, h) + aoff + m * 2048 + k * 1024); } while (0)
; #define PG8_LDB(dst, b, h) do { _Pragma("unroll") for (int n = 0; n < 2; ++n) _Pragma("unroll") for (int k = 0; k < 2; ++k) dst[n][k] = *(const PG8_LAS bf16x8*)(lds + PG8_SB(b, h) + boff + n * 2048 + k * 1024); } while (0)
; #define PG8_WAIT_V(n) asm volatile("s_waitcnt vmcnt(" #n ")" ::: "memory")
; #define PG8_WAIT_L(n) asm volatile("s_waitcnt lgkmcnt(" #n ")" ::: "memory")
; #define PG8_BAR __builtin_amdgcn_s_barrier()
; #define PG8_SCHED __builtin_amdgcn_sched_barrier(0)
; template <class Epi, class Sched, bool ALIGN_EPI = false, bool SP2 = false>
; __device__ __forceinline__ void gemm_phase(PG8_LAS unsigned char* lds, const Gemm g, const Sched& S, const Epi& E) {
;     ...
;         const char* nA = has_next ? (const char*)g.A + (size_t)nxt.pm * tstep + (size_t)nxt.ks * K * 2 : cA; const char* nB = has_next ? (const char*)g.Bt + (size_t)nxt.pn * tstep + (size_t)nxt.ks * K * 2 : cB;
;         for (int t = 0; t < nt; t += 2) {
;             const bool last = (t == nt - 2);
;             const char* a1 = cA + (size_t)(t + 1) * kstep;
;             const char* a2 = last ? nA : cA + (size_t)(t + 2) * kstep; const char* b2 = last ? nB : cB + (size_t)(t + 2) * kstep;
;             const char* a3 = a2 + kstep; const char* b3 = b2 + kstep;
;             if (last && has_next) S.a_ready(nxt);
;             if constexpr (SP2) {
;             PG8_LDB(B0, 0, 0); PG8_LDB(B1, 0, 1); PG8_SCHED; PG8_LDA(At, 0, 0); PG8_STAGE(PG8_SA(1, 1), a1 + hstep, voffA);
;             PG8_WAIT_V(8); PG8_WAIT_L(0); PG8_BAR; PG8_MMA(0, 0, At, B0); PG8_MMA(0, 1, At, B1); PG8_BAR; PG8_SCHED;
;             PG8_LDA(At, 0, 1); PG8_STAGE(PG8_SB(0, 0), b2, voffB); PG8_STAGE(PG8_SB(0, 1), b2 + hstep, voffB); PG8_STAGE(PG8_SA(0, 0), a2, voffA);
;             PG8_WAIT_V(8); PG8_WAIT_L(0); PG8_BAR; PG8_MMA(1, 0, At, B0); PG8_MMA(1, 1, At, B1); PG8_BAR; PG8_SCHED;
.LBB0_516:
	s_ashr_i32 s39, s38, 31
	s_lshl_b64 s[40:41], s[38:39], 19
	s_add_u32 s40, s28, s40
	s_addc_u32 s41, s29, s41
	s_and_b64 s[42:43], s[2:3], exec
	s_cselect_b32 s33, s41, s53
	s_cselect_b32 s39, s40, s52
	s_ashr_i32 s37, s36, 31
	s_lshl_b64 s[42:43], s[36:37], 19
	s_add_u32 s42, s30, s42
	s_addc_u32 s43, s31, s43
	s_and_b64 s[48:49], s[2:3], exec
	s_cselect_b32 s37, s43, s47
	s_cselect_b32 s45, s42, s46
	s_add_u32 s48, s46, 0x100
	s_addc_u32 s49, s47, 0
	s_add_u32 s46, s52, 0x40080
	s_addc_u32 s47, s53, 0
	s_mov_b32 s50, -2
	ds_read_b128 v[148:151], v161
	ds_read_b128 v[152:155], v161 offset:1024
	ds_read_b128 v[166:169], v161 offset:2048
	ds_read_b128 v[170:173], v161 offset:3072
	ds_read_b128 v[174:177], v162
	ds_read_b128 v[178:181], v162 offset:1024
	ds_read_b128 v[182:185], v162 offset:2048
	ds_read_b128 v[186:189], v162 offset:3072
	s_add_u32 s51, s46, 0xfffc0080
	s_addc_u32 s52, s47, -1
	s_cmp_eq_u32 s50, 12
	s_cselect_b32 s57, s33, s52
	s_cselect_b32 s56, s39, s51
	s_cselect_b32 s53, s37, s49
	s_cselect_b32 s52, s45, s48
	v_lshl_add_u64 v[156:157], s[46:47], 0, v[142:143]
	s_add_i32 m0, s66, 0xc000
	ds_read_b128 v[190:193], v163
	ds_read_b128 v[194:197], v163 offset:1024
	ds_read_b128 v[198:201], v163 offset:2048
	ds_read_b128 v[202:205], v163 offset:3072
	ds_read_b128 v[206:209], v163 offset:4096
	ds_read_b128 v[210:213], v163 offset:5120
	ds_read_b128 v[214:217], v163 offset:6144
	ds_read_b128 v[218:221], v163 offset:7168
	global_load_lds_dwordx4 v[156:157], off
	v_lshl_add_u64 v[156:157], s[46:47], 0, v[140:141]
	s_add_i32 m0, s66, 0xe000
	s_nop 0
	global_load_lds_dwordx4 v[156:157], off
	s_waitcnt vmcnt(8)
	s_waitcnt lgkmcnt(0)
	s_barrier
	s_setprio 1
	s_waitcnt lgkmcnt(0)
	v_mfma_f32_16x16x32_bf16 v[126:129], v[148:151], v[190:193], 0
	v_mfma_f32_16x16x32_bf16 v[122:125], v[166:169], v[190:193], 0
	v_mfma_f32_16x16x32_bf16 v[118:121], v[148:151], v[198:201], 0
	v_mfma_f32_16x16x32_bf16 v[114:117], v[166:169], v[198:201], 0
	v_mfma_f32_16x16x32_bf16 v[102:105], v[148:151], v[206:209], 0
	v_mfma_f32_16x16x32_bf16 v[98:101], v[166:169], v[206:209], 0
	v_mfma_f32_16x16x32_bf16 v[86:89], v[148:151], v[214:217], 0
	v_mfma_f32_16x16x32_bf16 v[82:85], v[166:169], v[214:217], 0
	v_mfma_f32_16x16x32_bf16 v[126:129], v[152:155], v[194:197], v[126:129]
	v_mfma_f32_16x16x32_bf16 v[122:125], v[170:173], v[194:197], v[122:125]
	v_mfma_f32_16x16x32_bf16 v[118:121], v[152:155], v[202:205], v[118:121]
	v_mfma_f32_16x16x32_bf16 v[114:117], v[170:173], v[202:205], v[114:117]
	v_mfma_f32_16x16x32_bf16 v[102:105], v[152:155], v[210:213], v[102:105]
	v_mfma_f32_16x16x32_bf16 v[98:101], v[170:173], v[210:213], v[98:101]
	v_mfma_f32_16x16x32_bf16 v[86:89], v[152:155], v[218:221], v[86:89]
	v_mfma_f32_16x16x32_bf16 v[82:85], v[170:173], v[218:221], v[82:85]
	s_setprio 0
	s_setprio 1
	v_mfma_f32_16x16x32_bf16 v[110:113], v[174:177], v[190:193], 0
	v_mfma_f32_16x16x32_bf16 v[106:109], v[182:185], v[190:193], 0
	v_mfma_f32_16x16x32_bf16 v[94:97], v[174:177], v[198:201], 0
	v_mfma_f32_16x16x32_bf16 v[90:93], v[182:185], v[198:201], 0
	v_mfma_f32_16x16x32_bf16 v[78:81], v[174:177], v[206:209], 0
	v_mfma_f32_16x16x32_bf16 v[74:77], v[182:185], v[206:209], 0
	v_mfma_f32_16x16x32_bf16 v[70:73], v[174:177], v[214:217], 0
	v_mfma_f32_16x16x32_bf16 v[66:69], v[182:185], v[214:217], 0
	v_mfma_f32_16x16x32_bf16 v[110:113], v[178:181], v[194:197], v[110:113]
	v_mfma_f32_16x16x32_bf16 v[106:109], v[186:189], v[194:197], v[106:109]
	v_mfma_f32_16x16x32_bf16 v[94:97], v[178:181], v[202:205], v[94:97]
	v_mfma_f32_16x16x32_bf16 v[90:93], v[186:189], v[202:205], v[90:93]
	v_mfma_f32_16x16x32_bf16 v[78:81], v[178:181], v[210:213], v[78:81]
	v_mfma_f32_16x16x32_bf16 v[74:77], v[186:189], v[210:213], v[74:77]
	v_mfma_f32_16x16x32_bf16 v[70:73], v[178:181], v[218:221], v[70:73]
	v_mfma_f32_16x16x32_bf16 v[66:69], v[186:189], v[218:221], v[66:69]
	s_setprio 0
	s_barrier
	s_mov_b32 m0, s62
	v_lshl_add_u64 v[156:157], s[52:53], 0, v[134:135]
	s_add_u32 s54, s52, 0x40000
	ds_read_b128 v[190:193], v163 offset:16384
	ds_read_b128 v[194:197], v163 offset:17408
	ds_read_b128 v[198:201], v163 offset:18432
	ds_read_b128 v[202:205], v163 offset:19456
	ds_read_b128 v[206:209], v163 offset:20480
	ds_read_b128 v[210:213], v163 offset:21504
	ds_read_b128 v[214:217], v163 offset:22528
	ds_read_b128 v[218:221], v163 offset:23552
	global_load_lds_dwordx4 v[156:157], off
	v_lshl_add_u64 v[222:223], s[52:53], 0, v[130:131]
	s_mov_b32 m0, s63
	s_addc_u32 s55, s53, 0
	global_load_lds_dwordx4 v[222:223], off
	v_lshl_add_u64 v[224:225], s[54:55], 0, v[134:135]
	s_mov_b32 m0, s64
	v_lshl_add_u64 v[226:227], s[56:57], 0, v[132:133]
	global_load_lds_dwordx4 v[224:225], off
	v_lshl_add_u64 v[224:225], s[54:55], 0, v[130:131]
	s_mov_b32 m0, s65
	s_nop 0
	global_load_lds_dwordx4 v[224:225], off
	v_lshl_add_u64 v[224:225], s[56:57], 0, v[136:137]
	s_waitcnt vmcnt(6)
	s_waitcnt lgkmcnt(0)
	s_barrier
; #define PG8_STAGE(bufoff, gbase, voff) do { _Pragma("unroll") for (int _i = 0; _i < 2; ++_i) \
;         __builtin_amdgcn_global_load_lds((const unsigned*)((const char*)(gbase) + (voff)[_i]), (PG8_LAS unsigned*)(lds + (bufoff) + ldsw + _i * 8192), 16, 0, 0); } while (0)
; #define PG8_LDA(dst, b, h) do { _Pragma("unroll") for (int m = 0; m < 4; ++m) _Pragma("unroll") for (int k = 0; k < 2; ++k) dst[m][k] = *(const PG8_LAS bf16x8*)(lds + PG8_SA(b, h) + aoff + m * 2048 + k * 1024); } while (0)
; #define PG8_LDB(dst, b, h) do { _Pragma("unroll") for (int n = 0; n < 2; ++n) _Pragma("unroll") for (int k = 0; k < 2; ++k) dst[n][k] = *(const PG8_LAS bf16x8*)(lds + PG8_SB(b, h) + boff + n * 2048 + k * 1024); } while (0)
; #define PG8_MMA(ai, bj, At, Bt) do { __builtin_amdgcn_s_setprio(1); _Pragma("unroll") for (int m = 0; m < 4; ++m) _Pragma("unroll") for (int n = 0; n < 2; ++n) _Pragma("unroll") for (int k = 0; k < 2; ++k) \
;         acc[ai][bj][m][n] = __builtin_amdgcn_mfma_f32_16x16x32_bf16(Bt[n][k], At[m][k], acc[ai][bj][m][n], 0, 0, 0); __builtin_amdgcn_s_setprio(0); } while (0)
; #define PG8_WAIT_V(n) asm volatile("s_waitcnt vmcnt(" #n ")" ::: "memory")
; #define PG8_WAIT_L(n) asm volatile("s_waitcnt lgkmcnt(" #n ")" ::: "memory")
; #define PG8_BAR __builtin_amdgcn_s_barrier()
; #define PG8_SCHED __builtin_amdgcn_sched_barrier(0)
; template <class Epi, class Sched, bool ALIGN_EPI = false, bool SP2 = false>
; __device__ __forceinline__ void gemm_phase(PG8_LAS unsigned char* lds, const Gemm g, const Sched& S, const Epi& E) {
;     ...
;             PG8_WAIT_V(8); PG8_WAIT_L(0); PG8_BAR; PG8_MMA(1, 0, At, B0); PG8_MMA(1, 1, At, B1); PG8_BAR; PG8_SCHED;
;             PG8_LDB(B0, 1, 0); PG8_LDB(B1, 1, 1); PG8_SCHED; PG8_LDA(At, 1, 0); PG8_STAGE(PG8_SA(0, 1), a2 + hstep, voffA);
;             PG8_WAIT_V(8); PG8_WAIT_L(0); PG8_BAR; PG8_MMA(0, 0, At, B0); PG8_MMA(0, 1, At, B1); PG8_BAR; PG8_SCHED;
	s_setprio 1
	s_waitcnt lgkmcnt(0)
	v_mfma_f32_16x16x32_bf16 v[62:65], v[148:151], v[190:193], 0
	v_mfma_f32_16x16x32_bf16 v[58:61], v[166:169], v[190:193], 0
	v_mfma_f32_16x16x32_bf16 v[54:57], v[148:151], v[198:201], 0
	v_mfma_f32_16x16x32_bf16 v[50:53], v[166:169], v[198:201], 0
	v_mfma_f32_16x16x32_bf16 v[38:41], v[148:151], v[206:209], 0
	v_mfma_f32_16x16x32_bf16 v[34:37], v[166:169], v[206:209], 0
	v_mfma_f32_16x16x32_bf16 v[22:25], v[148:151], v[214:217], 0
	v_mfma_f32_16x16x32_bf16 v[18:21], v[166:169], v[214:217], 0
	v_mfma_f32_16x16x32_bf16 v[62:65], v[152:155], v[194:197], v[62:65]
	v_mfma_f32_16x16x32_bf16 v[58:61], v[170:173], v[194:197], v[58:61]
	v_mfma_f32_16x16x32_bf16 v[54:57], v[152:155], v[202:205], v[54:57]
	v_mfma_f32_16x16x32_bf16 v[50:53], v[170:173], v[202:205], v[50:53]
	v_mfma_f32_16x16x32_bf16 v[38:41], v[152:155], v[210:213], v[38:41]
	v_mfma_f32_16x16x32_bf16 v[34:37], v[170:173], v[210:213], v[34:37]
	v_mfma_f32_16x16x32_bf16 v[22:25], v[152:155], v[218:221], v[22:25]
	v_mfma_f32_16x16x32_bf16 v[18:21], v[170:173], v[218:221], v[18:21]
	s_setprio 0
	s_setprio 1
	v_mfma_f32_16x16x32_bf16 v[46:49], v[174:177], v[190:193], 0
	v_mfma_f32_16x16x32_bf16 v[42:45], v[182:185], v[190:193], 0
	v_mfma_f32_16x16x32_bf16 v[30:33], v[174:177], v[198:201], 0
	v_mfma_f32_16x16x32_bf16 v[26:29], v[182:185], v[198:201], 0
	v_mfma_f32_16x16x32_bf16 v[14:17], v[174:177], v[206:209], 0
	v_mfma_f32_16x16x32_bf16 v[10:13], v[182:185], v[206:209], 0
	v_mfma_f32_16x16x32_bf16 v[6:9], v[174:177], v[214:217], 0
	v_mfma_f32_16x16x32_bf16 v[2:5], v[182:185], v[214:217], 0
	v_mfma_f32_16x16x32_bf16 v[46:49], v[178:181], v[194:197], v[46:49]
	v_mfma_f32_16x16x32_bf16 v[42:45], v[186:189], v[194:197], v[42:45]
	v_mfma_f32_16x16x32_bf16 v[30:33], v[178:181], v[202:205], v[30:33]
	v_mfma_f32_16x16x32_bf16 v[26:29], v[186:189], v[202:205], v[26:29]
	v_mfma_f32_16x16x32_bf16 v[14:17], v[178:181], v[210:213], v[14:17]
	v_mfma_f32_16x16x32_bf16 v[10:13], v[186:189], v[210:213], v[10:13]
	v_mfma_f32_16x16x32_bf16 v[6:9], v[178:181], v[218:221], v[6:9]
	v_mfma_f32_16x16x32_bf16 v[2:5], v[186:189], v[218:221], v[2:5]
	s_setprio 0
	s_barrier
	ds_read_b128 v[148:151], v164
	ds_read_b128 v[152:155], v164 offset:1024
	ds_read_b128 v[166:169], v164 offset:2048
	ds_read_b128 v[170:173], v164 offset:3072
	ds_read_b128 v[174:177], v165
	ds_read_b128 v[178:181], v165 offset:1024
	ds_read_b128 v[182:185], v165 offset:2048
	ds_read_b128 v[186:189], v165 offset:3072
	s_add_u32 s54, s56, 0x40000
	s_addc_u32 s55, s57, 0
	s_mov_b32 m0, s66
	s_nop 0
	global_load_lds_dwordx4 v[224:225], off
	s_mov_b32 m0, s67
	s_nop 0
	global_load_lds_dwordx4 v[226:227], off
	s_mov_b32 m0, s68
	v_lshl_add_u64 v[228:229], s[54:55], 0, v[136:137]
	ds_read_b128 v[190:193], v163 offset:32768
	ds_read_b128 v[194:197], v163 offset:33792
	ds_read_b128 v[198:201], v163 offset:34816
	ds_read_b128 v[202:205], v163 offset:35840
	ds_read_b128 v[206:209], v163 offset:36864
	ds_read_b128 v[210:213], v163 offset:37888
	ds_read_b128 v[214:217], v163 offset:38912
	ds_read_b128 v[218:221], v163 offset:39936
	global_load_lds_dwordx4 v[228:229], off
	v_lshl_add_u64 v[228:229], s[54:55], 0, v[132:133]
	s_mov_b32 m0, s69
	s_nop 0
	global_load_lds_dwordx4 v[228:229], off
	s_waitcnt vmcnt(8)
	s_waitcnt lgkmcnt(0)
	s_barrier
	s_setprio 1
	s_waitcnt lgkmcnt(0)
	v_mfma_f32_16x16x32_bf16 v[126:129], v[148:151], v[190:193], v[126:129]
	v_mfma_f32_16x16x32_bf16 v[122:125], v[166:169], v[190:193], v[122:125]
	v_mfma_f32_16x16x32_bf16 v[118:121], v[148:151], v[198:201], v[118:121]
	v_mfma_f32_16x16x32_bf16 v[114:117], v[166:169], v[198:201], v[114:117]
	v_mfma_f32_16x16x32_bf16 v[102:105], v[148:151], v[206:209], v[102:105]
	v_mfma_f32_16x16x32_bf16 v[98:101], v[166:169], v[206:209], v[98:101]
	v_mfma_f32_16x16x32_bf16 v[86:89], v[148:151], v[214:217], v[86:89]
	v_mfma_f32_16x16x32_bf16 v[82:85], v[166:169], v[214:217], v[82:85]
	v_mfma_f32_16x16x32_bf16 v[126:129], v[152:155], v[194:197], v[126:129]
	v_mfma_f32_16x16x32_bf16 v[122:125], v[170:173], v[194:197], v[122:125]
	v_mfma_f32_16x16x32_bf16 v[118:121], v[152:155], v[202:205], v[118:121]
	v_mfma_f32_16x16x32_bf16 v[114:117], v[170:173], v[202:205], v[114:117]
	v_mfma_f32_16x16x32_bf16 v[102:105], v[152:155], v[210:213], v[102:105]
	v_mfma_f32_16x16x32_bf16 v[98:101], v[170:173], v[210:213], v[98:101]
	v_mfma_f32_16x16x32_bf16 v[86:89], v[152:155], v[218:221], v[86:89]
	v_mfma_f32_16x16x32_bf16 v[82:85], v[170:173], v[218:221], v[82:85]
	s_setprio 0
	s_setprio 1
	v_mfma_f32_16x16x32_bf16 v[110:113], v[174:177], v[190:193], v[110:113]
	v_mfma_f32_16x16x32_bf16 v[106:109], v[182:185], v[190:193], v[106:109]
	v_mfma_f32_16x16x32_bf16 v[94:97], v[174:177], v[198:201], v[94:97]
	v_mfma_f32_16x16x32_bf16 v[90:93], v[182:185], v[198:201], v[90:93]
	v_mfma_f32_16x16x32_bf16 v[78:81], v[174:177], v[206:209], v[78:81]
	v_mfma_f32_16x16x32_bf16 v[74:77], v[182:185], v[206:209], v[74:77]
	v_mfma_f32_16x16x32_bf16 v[70:73], v[174:177], v[214:217], v[70:73]
	v_mfma_f32_16x16x32_bf16 v[66:69], v[182:185], v[214:217], v[66:69]
	v_mfma_f32_16x16x32_bf16 v[110:113], v[178:181], v[194:197], v[110:113]
	v_mfma_f32_16x16x32_bf16 v[106:109], v[186:189], v[194:197], v[106:109]
	v_mfma_f32_16x16x32_bf16 v[94:97], v[178:181], v[202:205], v[94:97]
	v_mfma_f32_16x16x32_bf16 v[90:93], v[186:189], v[202:205], v[90:93]
	v_mfma_f32_16x16x32_bf16 v[78:81], v[178:181], v[210:213], v[78:81]
	v_mfma_f32_16x16x32_bf16 v[74:77], v[186:189], v[210:213], v[74:77]
	v_mfma_f32_16x16x32_bf16 v[70:73], v[178:181], v[218:221], v[70:73]
	v_mfma_f32_16x16x32_bf16 v[66:69], v[186:189], v[218:221], v[66:69]
	s_setprio 0
	s_barrier
; #define PG8_STAGE(bufoff, gbase, voff) do { _Pragma("unroll") for (int _i = 0; _i < 2; ++_i) \
;         __builtin_amdgcn_global_load_lds((const unsigned*)((const char*)(gbase) + (voff)[_i]), (PG8_LAS unsigned*)(lds + (bufoff) + ldsw + _i * 8192), 16, 0, 0); } while (0)
; #define PG8_LDA(dst, b, h) do { _Pragma("unroll") for (int m = 0; m < 4; ++m) _Pragma("unroll") for (int k = 0; k < 2; ++k) dst[m][k] = *(const PG8_LAS bf16x8*)(lds + PG8_SA(b, h) + aoff + m * 2048 + k * 1024); } while (0)
; #define PG8_LDB(dst, b, h) do { _Pragma("unroll") for (int n = 0; n < 2; ++n) _Pragma("unroll") for (int k = 0; k < 2; ++k) dst[n][k] = *(const PG8_LAS bf16x8*)(lds + PG8_SB(b, h) + boff + n * 2048 + k * 1024); } while (0)
; #define PG8_MMA(ai, bj, At, Bt) do { __builtin_amdgcn_s_setprio(1); _Pragma("unroll") for (int m = 0; m < 4; ++m) _Pragma("unroll") for (int n = 0; n < 2; ++n) _Pragma("unroll") for (int k = 0; k < 2; ++k) \
;         acc[ai][bj][m][n] = __builtin_amdgcn_mfma_f32_16x16x32_bf16(Bt[n][k], At[m][k], acc[ai][bj][m][n], 0, 0, 0); __builtin_amdgcn_s_setprio(0); } while (0)
; #define PG8_WAIT_V(n) asm volatile("s_waitcnt vmcnt(" #n ")" ::: "memory")
; #define PG8_WAIT_L(n) asm volatile("s_waitcnt lgkmcnt(" #n ")" ::: "memory")
; #define PG8_BAR __builtin_amdgcn_s_barrier()
; #define PG8_SCHED __builtin_amdgcn_sched_barrier(0)
; template <class Epi, class Sched, bool ALIGN_EPI = false, bool SP2 = false>
; __device__ __forceinline__ void gemm_phase(PG8_LAS unsigned char* lds, const Gemm g, const Sched& S, const Epi& E) {
;     ...
;             PG8_LDB(B0, 0, 0); PG8_LDB(B1, 0, 1); PG8_SCHED; PG8_LDA(At, 0, 0); PG8_STAGE(PG8_SA(1, 1), a1 + hstep, voffA);
;             PG8_WAIT_V(8); PG8_WAIT_L(0); PG8_BAR; PG8_MMA(0, 0, At, B0); PG8_MMA(0, 1, At, B1); PG8_BAR; PG8_SCHED;
;     ...
;             PG8_LDA(At, 1, 1); PG8_STAGE(PG8_SB(1, 0), b3, voffB); PG8_STAGE(PG8_SB(1, 1), b3 + hstep, voffB); PG8_STAGE(PG8_SA(1, 0), a3, voffA);
;             PG8_WAIT_V(8); PG8_WAIT_L(0); PG8_BAR; PG8_MMA(1, 0, At, B0); PG8_MMA(1, 1, At, B1); PG8_BAR; PG8_SCHED;
	s_mov_b32 m0, s70
	v_lshl_add_u64 v[156:157], v[156:157], 0, s[8:9]
	s_add_u32 s52, s52, 0x40080
	ds_read_b128 v[190:193], v163 offset:49152
	ds_read_b128 v[194:197], v163 offset:50176
	ds_read_b128 v[198:201], v163 offset:51200
	ds_read_b128 v[202:205], v163 offset:52224
	ds_read_b128 v[206:209], v163 offset:53248
	ds_read_b128 v[210:213], v163 offset:54272
	ds_read_b128 v[214:217], v163 offset:55296
	ds_read_b128 v[218:221], v163 offset:56320
	global_load_lds_dwordx4 v[156:157], off
	v_lshl_add_u64 v[156:157], v[222:223], 0, s[8:9]
	s_mov_b32 m0, s71
	s_addc_u32 s53, s53, 0
	global_load_lds_dwordx4 v[156:157], off
	v_lshl_add_u64 v[156:157], s[52:53], 0, v[134:135]
	s_mov_b32 m0, s74
	s_nop 0
	global_load_lds_dwordx4 v[156:157], off
	v_lshl_add_u64 v[156:157], s[52:53], 0, v[130:131]
	s_mov_b32 m0, s75
	s_nop 0
	global_load_lds_dwordx4 v[156:157], off
	v_lshl_add_u64 v[156:157], v[224:225], 0, s[8:9]
	s_mov_b32 m0, s72
	s_nop 0
	global_load_lds_dwordx4 v[156:157], off
	v_lshl_add_u64 v[156:157], v[226:227], 0, s[8:9]
	s_mov_b32 m0, s73
	s_nop 0
	global_load_lds_dwordx4 v[156:157], off
	s_waitcnt vmcnt(8)
	s_waitcnt lgkmcnt(0)
	s_barrier
	s_setprio 1
	s_waitcnt lgkmcnt(0)
	v_mfma_f32_16x16x32_bf16 v[62:65], v[148:151], v[190:193], v[62:65]
	v_mfma_f32_16x16x32_bf16 v[58:61], v[166:169], v[190:193], v[58:61]
	v_mfma_f32_16x16x32_bf16 v[54:57], v[148:151], v[198:201], v[54:57]
	v_mfma_f32_16x16x32_bf16 v[50:53], v[166:169], v[198:201], v[50:53]
	v_mfma_f32_16x16x32_bf16 v[38:41], v[148:151], v[206:209], v[38:41]
	v_mfma_f32_16x16x32_bf16 v[34:37], v[166:169], v[206:209], v[34:37]
	v_mfma_f32_16x16x32_bf16 v[22:25], v[148:151], v[214:217], v[22:25]
	v_mfma_f32_16x16x32_bf16 v[18:21], v[166:169], v[214:217], v[18:21]
	v_mfma_f32_16x16x32_bf16 v[62:65], v[152:155], v[194:197], v[62:65]
	v_mfma_f32_16x16x32_bf16 v[58:61], v[170:173], v[194:197], v[58:61]
	v_mfma_f32_16x16x32_bf16 v[54:57], v[152:155], v[202:205], v[54:57]
	v_mfma_f32_16x16x32_bf16 v[50:53], v[170:173], v[202:205], v[50:53]
	v_mfma_f32_16x16x32_bf16 v[38:41], v[152:155], v[210:213], v[38:41]
	v_mfma_f32_16x16x32_bf16 v[34:37], v[170:173], v[210:213], v[34:37]
	v_mfma_f32_16x16x32_bf16 v[22:25], v[152:155], v[218:221], v[22:25]
	v_mfma_f32_16x16x32_bf16 v[18:21], v[170:173], v[218:221], v[18:21]
	s_setprio 0
	s_setprio 1
	v_mfma_f32_16x16x32_bf16 v[46:49], v[174:177], v[190:193], v[46:49]
	v_mfma_f32_16x16x32_bf16 v[42:45], v[182:185], v[190:193], v[42:45]
	v_mfma_f32_16x16x32_bf16 v[30:33], v[174:177], v[198:201], v[30:33]
	v_mfma_f32_16x16x32_bf16 v[26:29], v[182:185], v[198:201], v[26:29]
	v_mfma_f32_16x16x32_bf16 v[14:17], v[174:177], v[206:209], v[14:17]
	v_mfma_f32_16x16x32_bf16 v[10:13], v[182:185], v[206:209], v[10:13]
	v_mfma_f32_16x16x32_bf16 v[6:9], v[174:177], v[214:217], v[6:9]
	v_mfma_f32_16x16x32_bf16 v[2:5], v[182:185], v[214:217], v[2:5]
	v_mfma_f32_16x16x32_bf16 v[46:49], v[178:181], v[194:197], v[46:49]
	v_mfma_f32_16x16x32_bf16 v[42:45], v[186:189], v[194:197], v[42:45]
	v_mfma_f32_16x16x32_bf16 v[30:33], v[178:181], v[202:205], v[30:33]
	v_mfma_f32_16x16x32_bf16 v[26:29], v[186:189], v[202:205], v[26:29]
	v_mfma_f32_16x16x32_bf16 v[14:17], v[178:181], v[210:213], v[14:17]
	v_mfma_f32_16x16x32_bf16 v[10:13], v[186:189], v[210:213], v[10:13]
	v_mfma_f32_16x16x32_bf16 v[6:9], v[178:181], v[218:221], v[6:9]
	v_mfma_f32_16x16x32_bf16 v[2:5], v[186:189], v[218:221], v[2:5]
	s_setprio 0
	s_barrier
	s_add_i32 s50, s50, 2
	s_add_u32 s48, s48, 0x100
	s_addc_u32 s49, s49, 0
	s_add_u32 s46, s46, 0x100
	s_addc_u32 s47, s47, 0
	s_cmp_gt_u32 s50, 13
.LBB0_517:
	ds_read_b128 v[148:151], v161
	ds_read_b128 v[152:155], v161 offset:1024
	ds_read_b128 v[166:169], v161 offset:2048
	ds_read_b128 v[170:173], v161 offset:3072
	ds_read_b128 v[174:177], v162
	ds_read_b128 v[178:181], v162 offset:1024
	ds_read_b128 v[182:185], v162 offset:2048
	ds_read_b128 v[186:189], v162 offset:3072
	s_add_u32 s51, s46, 0xfffc0080
	s_addc_u32 s52, s47, -1
	s_cmp_eq_u32 s50, 12
	s_cselect_b32 s57, s33, s52
	s_cselect_b32 s56, s39, s51
	s_cselect_b32 s53, s37, s49
	s_cselect_b32 s52, s45, s48
	v_lshl_add_u64 v[156:157], s[46:47], 0, v[142:143]
	s_add_i32 m0, s66, 0xc000
	ds_read_b128 v[190:193], v163
	ds_read_b128 v[194:197], v163 offset:1024
	ds_read_b128 v[198:201], v163 offset:2048
	ds_read_b128 v[202:205], v163 offset:3072
	ds_read_b128 v[206:209], v163 offset:4096
	ds_read_b128 v[210:213], v163 offset:5120
	ds_read_b128 v[214:217], v163 offset:6144
	ds_read_b128 v[218:221], v163 offset:7168
	global_load_lds_dwordx4 v[156:157], off
	v_lshl_add_u64 v[156:157], s[46:47], 0, v[140:141]
	s_add_i32 m0, s66, 0xe000
	s_nop 0
	global_load_lds_dwordx4 v[156:157], off
	s_waitcnt vmcnt(8)
	s_waitcnt lgkmcnt(0)
	s_barrier
; #define PG8_STAGE(bufoff, gbase, voff) do { _Pragma("unroll") for (int _i = 0; _i < 2; ++_i) \
;         __builtin_amdgcn_global_load_lds((const unsigned*)((const char*)(gbase) + (voff)[_i]), (PG8_LAS unsigned*)(lds + (bufoff) + ldsw + _i * 8192), 16, 0, 0); } while (0)
; #define PG8_LDA(dst, b, h) do { _Pragma("unroll") for (int m = 0; m < 4; ++m) _Pragma("unroll") for (int k = 0; k < 2; ++k) dst[m][k] = *(const PG8_LAS bf16x8*)(lds + PG8_SA(b, h) + aoff + m * 2048 + k * 1024); } while (0)
; #define PG8_MMA(ai, bj, At, Bt) do { __builtin_amdgcn_s_setprio(1); _Pragma("unroll") for (int m = 0; m < 4; ++m) _Pragma("unroll") for (int n = 0; n < 2; ++n) _Pragma("unroll") for (int k = 0; k < 2; ++k) \
;         acc[ai][bj][m][n] = __builtin_amdgcn_mfma_f32_16x16x32_bf16(Bt[n][k], At[m][k], acc[ai][bj][m][n], 0, 0, 0); __builtin_amdgcn_s_setprio(0); } while (0)
; #define PG8_WAIT_V(n) asm volatile("s_waitcnt vmcnt(" #n ")" ::: "memory")
; #define PG8_WAIT_L(n) asm volatile("s_waitcnt lgkmcnt(" #n ")" ::: "memory")
; #define PG8_BAR __builtin_amdgcn_s_barrier()
; #define PG8_SCHED __builtin_amdgcn_sched_barrier(0)
; template <class Epi, class Sched, bool ALIGN_EPI = false, bool SP2 = false>
; __device__ __forceinline__ void gemm_phase(PG8_LAS unsigned char* lds, const Gemm g, const Sched& S, const Epi& E) {
;     ...
;             PG8_WAIT_V(8); PG8_WAIT_L(0); PG8_BAR; PG8_MMA(0, 0, At, B0); PG8_MMA(0, 1, At, B1); PG8_BAR; PG8_SCHED;
;             PG8_LDA(At, 0, 1); PG8_STAGE(PG8_SB(0, 0), b2, voffB); PG8_STAGE(PG8_SB(0, 1), b2 + hstep, voffB); PG8_STAGE(PG8_SA(0, 0), a2, voffA);
;             PG8_WAIT_V(8); PG8_WAIT_L(0); PG8_BAR; PG8_MMA(1, 0, At, B0); PG8_MMA(1, 1, At, B1); PG8_BAR; PG8_SCHED;
	s_setprio 1
	s_waitcnt lgkmcnt(0)
	v_mfma_f32_16x16x32_bf16 v[126:129], v[148:151], v[190:193], v[126:129]
	v_mfma_f32_16x16x32_bf16 v[122:125], v[166:169], v[190:193], v[122:125]
	v_mfma_f32_16x16x32_bf16 v[118:121], v[148:151], v[198:201], v[118:121]
	v_mfma_f32_16x16x32_bf16 v[114:117], v[166:169], v[198:201], v[114:117]
	v_mfma_f32_16x16x32_bf16 v[102:105], v[148:151], v[206:209], v[102:105]
	v_mfma_f32_16x16x32_bf16 v[98:101], v[166:169], v[206:209], v[98:101]
	v_mfma_f32_16x16x32_bf16 v[86:89], v[148:151], v[214:217], v[86:89]
	v_mfma_f32_16x16x32_bf16 v[82:85], v[166:169], v[214:217], v[82:85]
	v_mfma_f32_16x16x32_bf16 v[126:129], v[152:155], v[194:197], v[126:129]
	v_mfma_f32_16x16x32_bf16 v[122:125], v[170:173], v[194:197], v[122:125]
	v_mfma_f32_16x16x32_bf16 v[118:121], v[152:155], v[202:205], v[118:121]
	v_mfma_f32_16x16x32_bf16 v[114:117], v[170:173], v[202:205], v[114:117]
	v_mfma_f32_16x16x32_bf16 v[102:105], v[152:155], v[210:213], v[102:105]
	v_mfma_f32_16x16x32_bf16 v[98:101], v[170:173], v[210:213], v[98:101]
	v_mfma_f32_16x16x32_bf16 v[86:89], v[152:155], v[218:221], v[86:89]
	v_mfma_f32_16x16x32_bf16 v[82:85], v[170:173], v[218:221], v[82:85]
	s_setprio 0
	s_setprio 1
	v_mfma_f32_16x16x32_bf16 v[110:113], v[174:177], v[190:193], v[110:113]
	v_mfma_f32_16x16x32_bf16 v[106:109], v[182:185], v[190:193], v[106:109]
	v_mfma_f32_16x16x32_bf16 v[94:97], v[174:177], v[198:201], v[94:97]
	v_mfma_f32_16x16x32_bf16 v[90:93], v[182:185], v[198:201], v[90:93]
	v_mfma_f32_16x16x32_bf16 v[78:81], v[174:177], v[206:209], v[78:81]
	v_mfma_f32_16x16x32_bf16 v[74:77], v[182:185], v[206:209], v[74:77]
	v_mfma_f32_16x16x32_bf16 v[70:73], v[174:177], v[214:217], v[70:73]
	v_mfma_f32_16x16x32_bf16 v[66:69], v[182:185], v[214:217], v[66:69]
	v_mfma_f32_16x16x32_bf16 v[110:113], v[178:181], v[194:197], v[110:113]
	v_mfma_f32_16x16x32_bf16 v[106:109], v[186:189], v[194:197], v[106:109]
	v_mfma_f32_16x16x32_bf16 v[94:97], v[178:181], v[202:205], v[94:97]
	v_mfma_f32_16x16x32_bf16 v[90:93], v[186:189], v[202:205], v[90:93]
	v_mfma_f32_16x16x32_bf16 v[78:81], v[178:181], v[210:213], v[78:81]
	v_mfma_f32_16x16x32_bf16 v[74:77], v[186:189], v[210:213], v[74:77]
	v_mfma_f32_16x16x32_bf16 v[70:73], v[178:181], v[218:221], v[70:73]
	v_mfma_f32_16x16x32_bf16 v[66:69], v[186:189], v[218:221], v[66:69]
	s_setprio 0
	s_barrier
	s_mov_b32 m0, s62
	v_lshl_add_u64 v[156:157], s[52:53], 0, v[134:135]
	s_add_u32 s54, s52, 0x40000
	ds_read_b128 v[190:193], v163 offset:16384
	ds_read_b128 v[194:197], v163 offset:17408
	ds_read_b128 v[198:201], v163 offset:18432
	ds_read_b128 v[202:205], v163 offset:19456
	ds_read_b128 v[206:209], v163 offset:20480
	ds_read_b128 v[210:213], v163 offset:21504
	ds_read_b128 v[214:217], v163 offset:22528
	ds_read_b128 v[218:221], v163 offset:23552
	global_load_lds_dwordx4 v[156:157], off
	v_lshl_add_u64 v[222:223], s[52:53], 0, v[130:131]
	s_mov_b32 m0, s63
	s_addc_u32 s55, s53, 0
	global_load_lds_dwordx4 v[222:223], off
	v_lshl_add_u64 v[224:225], s[54:55], 0, v[134:135]
	s_mov_b32 m0, s64
	v_lshl_add_u64 v[226:227], s[56:57], 0, v[132:133]
	global_load_lds_dwordx4 v[224:225], off
	v_lshl_add_u64 v[224:225], s[54:55], 0, v[130:131]
	s_mov_b32 m0, s65
	s_nop 0
	global_load_lds_dwordx4 v[224:225], off
	v_lshl_add_u64 v[224:225], s[56:57], 0, v[136:137]
	s_waitcnt vmcnt(6)
	s_waitcnt lgkmcnt(0)
	s_barrier
	s_setprio 1
	s_waitcnt lgkmcnt(0)
	v_mfma_f32_16x16x32_bf16 v[62:65], v[148:151], v[190:193], v[62:65]
	v_mfma_f32_16x16x32_bf16 v[58:61], v[166:169], v[190:193], v[58:61]
	v_mfma_f32_16x16x32_bf16 v[54:57], v[148:151], v[198:201], v[54:57]
	v_mfma_f32_16x16x32_bf16 v[50:53], v[166:169], v[198:201], v[50:53]
	v_mfma_f32_16x16x32_bf16 v[38:41], v[148:151], v[206:209], v[38:41]
	v_mfma_f32_16x16x32_bf16 v[34:37], v[166:169], v[206:209], v[34:37]
	v_mfma_f32_16x16x32_bf16 v[22:25], v[148:151], v[214:217], v[22:25]
	v_mfma_f32_16x16x32_bf16 v[18:21], v[166:169], v[214:217], v[18:21]
	v_mfma_f32_16x16x32_bf16 v[62:65], v[152:155], v[194:197], v[62:65]
	v_mfma_f32_16x16x32_bf16 v[58:61], v[170:173], v[194:197], v[58:61]
	v_mfma_f32_16x16x32_bf16 v[54:57], v[152:155], v[202:205], v[54:57]
	v_mfma_f32_16x16x32_bf16 v[50:53], v[170:173], v[202:205], v[50:53]
	v_mfma_f32_16x16x32_bf16 v[38:41], v[152:155], v[210:213], v[38:41]
	v_mfma_f32_16x16x32_bf16 v[34:37], v[170:173], v[210:213], v[34:37]
	v_mfma_f32_16x16x32_bf16 v[22:25], v[152:155], v[218:221], v[22:25]
	v_mfma_f32_16x16x32_bf16 v[18:21], v[170:173], v[218:221], v[18:21]
	s_setprio 0
	s_setprio 1
	v_mfma_f32_16x16x32_bf16 v[46:49], v[174:177], v[190:193], v[46:49]
	v_mfma_f32_16x16x32_bf16 v[42:45], v[182:185], v[190:193], v[42:45]
	v_mfma_f32_16x16x32_bf16 v[30:33], v[174:177], v[198:201], v[30:33]
	v_mfma_f32_16x16x32_bf16 v[26:29], v[182:185], v[198:201], v[26:29]
	v_mfma_f32_16x16x32_bf16 v[14:17], v[174:177], v[206:209], v[14:17]
	v_mfma_f32_16x16x32_bf16 v[10:13], v[182:185], v[206:209], v[10:13]
	v_mfma_f32_16x16x32_bf16 v[6:9], v[174:177], v[214:217], v[6:9]
	v_mfma_f32_16x16x32_bf16 v[2:5], v[182:185], v[214:217], v[2:5]
	v_mfma_f32_16x16x32_bf16 v[46:49], v[178:181], v[194:197], v[46:49]
	v_mfma_f32_16x16x32_bf16 v[42:45], v[186:189], v[194:197], v[42:45]
	v_mfma_f32_16x16x32_bf16 v[30:33], v[178:181], v[202:205], v[30:33]
	v_mfma_f32_16x16x32_bf16 v[26:29], v[186:189], v[202:205], v[26:29]
	v_mfma_f32_16x16x32_bf16 v[14:17], v[178:181], v[210:213], v[14:17]
	v_mfma_f32_16x16x32_bf16 v[10:13], v[186:189], v[210:213], v[10:13]
	v_mfma_f32_16x16x32_bf16 v[6:9], v[178:181], v[218:221], v[6:9]
	v_mfma_f32_16x16x32_bf16 v[2:5], v[186:189], v[218:221], v[2:5]
	s_setprio 0
	s_barrier
; #define PG8_STAGE(bufoff, gbase, voff) do { _Pragma("unroll") for (int _i = 0; _i < 2; ++_i) \
;         __builtin_amdgcn_global_load_lds((const unsigned*)((const char*)(gbase) + (voff)[_i]), (PG8_LAS unsigned*)(lds + (bufoff) + ldsw + _i * 8192), 16, 0, 0); } while (0)
; #define PG8_LDA(dst, b, h) do { _Pragma("unroll") for (int m = 0; m < 4; ++m) _Pragma("unroll") for (int k = 0; k < 2; ++k) dst[m][k] = *(const PG8_LAS bf16x8*)(lds + PG8_SA(b, h) + aoff + m * 2048 + k * 1024); } while (0)
; #define PG8_LDB(dst, b, h) do { _Pragma("unroll") for (int n = 0; n < 2; ++n) _Pragma("unroll") for (int k = 0; k < 2; ++k) dst[n][k] = *(const PG8_LAS bf16x8*)(lds + PG8_SB(b, h) + boff + n * 2048 + k * 1024); } while (0)
; #define PG8_MMA(ai, bj, At, Bt) do { __builtin_amdgcn_s_setprio(1); _Pragma("unroll") for (int m = 0; m < 4; ++m) _Pragma("unroll") for (int n = 0; n < 2; ++n) _Pragma("unroll") for (int k = 0; k < 2; ++k) \
;         acc[ai][bj][m][n] = __builtin_amdgcn_mfma_f32_16x16x32_bf16(Bt[n][k], At[m][k], acc[ai][bj][m][n], 0, 0, 0); __builtin_amdgcn_s_setprio(0); } while (0)
; #define PG8_WAIT_V(n) asm volatile("s_waitcnt vmcnt(" #n ")" ::: "memory")
; #define PG8_WAIT_L(n) asm volatile("s_waitcnt lgkmcnt(" #n ")" ::: "memory")
; #define PG8_BAR __builtin_amdgcn_s_barrier()
; #define PG8_SCHED __builtin_amdgcn_sched_barrier(0)
; template <class Epi, class Sched, bool ALIGN_EPI = false, bool SP2 = false>
; __device__ __forceinline__ void gemm_phase(PG8_LAS unsigned char* lds, const Gemm g, const Sched& S, const Epi& E) {
;     ...
;             PG8_LDB(B0, 1, 0); PG8_LDB(B1, 1, 1); PG8_SCHED; PG8_LDA(At, 1, 0); PG8_STAGE(PG8_SA(0, 1), a2 + hstep, voffA);
;             PG8_WAIT_V(8); PG8_WAIT_L(0); PG8_BAR; PG8_MMA(0, 0, At, B0); PG8_MMA(0, 1, At, B1); PG8_BAR; PG8_SCHED;
	ds_read_b128 v[148:151], v164
	ds_read_b128 v[152:155], v164 offset:1024
	ds_read_b128 v[166:169], v164 offset:2048
	ds_read_b128 v[170:173], v164 offset:3072
	ds_read_b128 v[174:177], v165
	ds_read_b128 v[178:181], v165 offset:1024
	ds_read_b128 v[182:185], v165 offset:2048
	ds_read_b128 v[186:189], v165 offset:3072
	s_add_u32 s54, s56, 0x40000
	s_addc_u32 s55, s57, 0
	s_mov_b32 m0, s66
	s_nop 0
	global_load_lds_dwordx4 v[224:225], off
	s_mov_b32 m0, s67
	s_nop 0
	global_load_lds_dwordx4 v[226:227], off
	s_mov_b32 m0, s68
	v_lshl_add_u64 v[228:229], s[54:55], 0, v[136:137]
	ds_read_b128 v[190:193], v163 offset:32768
	ds_read_b128 v[194:197], v163 offset:33792
	ds_read_b128 v[198:201], v163 offset:34816
	ds_read_b128 v[202:205], v163 offset:35840
	ds_read_b128 v[206:209], v163 offset:36864
	ds_read_b128 v[210:213], v163 offset:37888
	ds_read_b128 v[214:217], v163 offset:38912
	ds_read_b128 v[218:221], v163 offset:39936
	global_load_lds_dwordx4 v[228:229], off
	v_lshl_add_u64 v[228:229], s[54:55], 0, v[132:133]
	s_mov_b32 m0, s69
	s_nop 0
	global_load_lds_dwordx4 v[228:229], off
	s_waitcnt vmcnt(8)
	s_waitcnt lgkmcnt(0)
	s_barrier
	s_setprio 1
	s_waitcnt lgkmcnt(0)
	v_mfma_f32_16x16x32_bf16 v[126:129], v[148:151], v[190:193], v[126:129]
	v_mfma_f32_16x16x32_bf16 v[122:125], v[166:169], v[190:193], v[122:125]
	v_mfma_f32_16x16x32_bf16 v[118:121], v[148:151], v[198:201], v[118:121]
	v_mfma_f32_16x16x32_bf16 v[114:117], v[166:169], v[198:201], v[114:117]
	v_mfma_f32_16x16x32_bf16 v[102:105], v[148:151], v[206:209], v[102:105]
	v_mfma_f32_16x16x32_bf16 v[98:101], v[166:169], v[206:209], v[98:101]
	v_mfma_f32_16x16x32_bf16 v[86:89], v[148:151], v[214:217], v[86:89]
	v_mfma_f32_16x16x32_bf16 v[82:85], v[166:169], v[214:217], v[82:85]
	v_mfma_f32_16x16x32_bf16 v[126:129], v[152:155], v[194:197], v[126:129]
	v_mfma_f32_16x16x32_bf16 v[122:125], v[170:173], v[194:197], v[122:125]
	v_mfma_f32_16x16x32_bf16 v[118:121], v[152:155], v[202:205], v[118:121]
	v_mfma_f32_16x16x32_bf16 v[114:117], v[170:173], v[202:205], v[114:117]
	v_mfma_f32_16x16x32_bf16 v[102:105], v[152:155], v[210:213], v[102:105]
	v_mfma_f32_16x16x32_bf16 v[98:101], v[170:173], v[210:213], v[98:101]
	v_mfma_f32_16x16x32_bf16 v[86:89], v[152:155], v[218:221], v[86:89]
	v_mfma_f32_16x16x32_bf16 v[82:85], v[170:173], v[218:221], v[82:85]
	s_setprio 0
	s_setprio 1
	v_mfma_f32_16x16x32_bf16 v[110:113], v[174:177], v[190:193], v[110:113]
	v_mfma_f32_16x16x32_bf16 v[106:109], v[182:185], v[190:193], v[106:109]
	v_mfma_f32_16x16x32_bf16 v[94:97], v[174:177], v[198:201], v[94:97]
	v_mfma_f32_16x16x32_bf16 v[90:93], v[182:185], v[198:201], v[90:93]
	v_mfma_f32_16x16x32_bf16 v[78:81], v[174:177], v[206:209], v[78:81]
	v_mfma_f32_16x16x32_bf16 v[74:77], v[182:185], v[206:209], v[74:77]
	v_mfma_f32_16x16x32_bf16 v[70:73], v[174:177], v[214:217], v[70:73]
	v_mfma_f32_16x16x32_bf16 v[66:69], v[182:185], v[214:217], v[66:69]
	v_mfma_f32_16x16x32_bf16 v[110:113], v[178:181], v[194:197], v[110:113]
	v_mfma_f32_16x16x32_bf16 v[106:109], v[186:189], v[194:197], v[106:109]
	v_mfma_f32_16x16x32_bf16 v[94:97], v[178:181], v[202:205], v[94:97]
	v_mfma_f32_16x16x32_bf16 v[90:93], v[186:189], v[202:205], v[90:93]
	v_mfma_f32_16x16x32_bf16 v[78:81], v[178:181], v[210:213], v[78:81]
	v_mfma_f32_16x16x32_bf16 v[74:77], v[186:189], v[210:213], v[74:77]
	v_mfma_f32_16x16x32_bf16 v[70:73], v[178:181], v[218:221], v[70:73]
	v_mfma_f32_16x16x32_bf16 v[66:69], v[186:189], v[218:221], v[66:69]
	s_setprio 0
	s_barrier
; #define PG8_STAGE(bufoff, gbase, voff) do { _Pragma("unroll") for (int _i = 0; _i < 2; ++_i) \
;         __builtin_amdgcn_global_load_lds((const unsigned*)((const char*)(gbase) + (voff)[_i]), (PG8_LAS unsigned*)(lds + (bufoff) + ldsw + _i * 8192), 16, 0, 0); } while (0)
; #define PG8_LDA(dst, b, h) do { _Pragma("unroll") for (int m = 0; m < 4; ++m) _Pragma("unroll") for (int k = 0; k < 2; ++k) dst[m][k] = *(const PG8_LAS bf16x8*)(lds + PG8_SA(b, h) + aoff + m * 2048 + k * 1024); } while (0)
; #define PG8_MMA(ai, bj, At, Bt) do { __builtin_amdgcn_s_setprio(1); _Pragma("unroll") for (int m = 0; m < 4; ++m) _Pragma("unroll") for (int n = 0; n < 2; ++n) _Pragma("unroll") for (int k = 0; k < 2; ++k) \
;         acc[ai][bj][m][n] = __builtin_amdgcn_mfma_f32_16x16x32_bf16(Bt[n][k], At[m][k], acc[ai][bj][m][n], 0, 0, 0); __builtin_amdgcn_s_setprio(0); } while (0)
; #define PG8_WAIT_V(n) asm volatile("s_waitcnt vmcnt(" #n ")" ::: "memory")
; #define PG8_WAIT_L(n) asm volatile("s_waitcnt lgkmcnt(" #n ")" ::: "memory")
; #define PG8_BAR __builtin_amdgcn_s_barrier()
; #define PG8_SCHED __builtin_amdgcn_sched_barrier(0)
; template <class Epi, class Sched, bool ALIGN_EPI = false, bool SP2 = false>
; __device__ __forceinline__ void gemm_phase(PG8_LAS unsigned char* lds, const Gemm g, const Sched& S, const Epi& E) {
;     ...
;             PG8_LDA(At, 1, 1); PG8_STAGE(PG8_SB(1, 0), b3, voffB); PG8_STAGE(PG8_SB(1, 1), b3 + hstep, voffB); PG8_STAGE(PG8_SA(1, 0), a3, voffA);
;             PG8_WAIT_V(8); PG8_WAIT_L(0); PG8_BAR; PG8_MMA(1, 0, At, B0); PG8_MMA(1, 1, At, B1); PG8_BAR; PG8_SCHED;
;     ...
;         if constexpr (ALIGN_EPI) { if (wr == 0) PG8_BAR; }
	s_mov_b32 m0, s70
	v_lshl_add_u64 v[156:157], v[156:157], 0, s[8:9]
	s_add_u32 s52, s52, 0x40080
	ds_read_b128 v[190:193], v163 offset:49152
	ds_read_b128 v[194:197], v163 offset:50176
	ds_read_b128 v[198:201], v163 offset:51200
	ds_read_b128 v[202:205], v163 offset:52224
	ds_read_b128 v[206:209], v163 offset:53248
	ds_read_b128 v[210:213], v163 offset:54272
	ds_read_b128 v[214:217], v163 offset:55296
	ds_read_b128 v[218:221], v163 offset:56320
	global_load_lds_dwordx4 v[156:157], off
	v_lshl_add_u64 v[156:157], v[222:223], 0, s[8:9]
	s_mov_b32 m0, s71
	s_addc_u32 s53, s53, 0
	global_load_lds_dwordx4 v[156:157], off
	v_lshl_add_u64 v[156:157], s[52:53], 0, v[134:135]
	s_mov_b32 m0, s74
	s_nop 0
	global_load_lds_dwordx4 v[156:157], off
	v_lshl_add_u64 v[156:157], s[52:53], 0, v[130:131]
	s_mov_b32 m0, s75
	s_nop 0
	global_load_lds_dwordx4 v[156:157], off
	v_lshl_add_u64 v[156:157], v[224:225], 0, s[8:9]
	s_mov_b32 m0, s72
	s_nop 0
	global_load_lds_dwordx4 v[156:157], off
	v_lshl_add_u64 v[156:157], v[226:227], 0, s[8:9]
	s_mov_b32 m0, s73
	s_nop 0
	global_load_lds_dwordx4 v[156:157], off
	s_waitcnt vmcnt(8)
	s_waitcnt lgkmcnt(0)
	s_barrier
	s_setprio 1
	s_waitcnt lgkmcnt(0)
	v_mfma_f32_16x16x32_bf16 v[62:65], v[148:151], v[190:193], v[62:65]
	v_mfma_f32_16x16x32_bf16 v[58:61], v[166:169], v[190:193], v[58:61]
	v_mfma_f32_16x16x32_bf16 v[54:57], v[148:151], v[198:201], v[54:57]
	v_mfma_f32_16x16x32_bf16 v[50:53], v[166:169], v[198:201], v[50:53]
	v_mfma_f32_16x16x32_bf16 v[38:41], v[148:151], v[206:209], v[38:41]
	v_mfma_f32_16x16x32_bf16 v[34:37], v[166:169], v[206:209], v[34:37]
	v_mfma_f32_16x16x32_bf16 v[22:25], v[148:151], v[214:217], v[22:25]
	v_mfma_f32_16x16x32_bf16 v[18:21], v[166:169], v[214:217], v[18:21]
	v_mfma_f32_16x16x32_bf16 v[62:65], v[152:155], v[194:197], v[62:65]
	v_mfma_f32_16x16x32_bf16 v[58:61], v[170:173], v[194:197], v[58:61]
	v_mfma_f32_16x16x32_bf16 v[54:57], v[152:155], v[202:205], v[54:57]
	v_mfma_f32_16x16x32_bf16 v[50:53], v[170:173], v[202:205], v[50:53]
	v_mfma_f32_16x16x32_bf16 v[38:41], v[152:155], v[210:213], v[38:41]
	v_mfma_f32_16x16x32_bf16 v[34:37], v[170:173], v[210:213], v[34:37]
	v_mfma_f32_16x16x32_bf16 v[22:25], v[152:155], v[218:221], v[22:25]
	v_mfma_f32_16x16x32_bf16 v[18:21], v[170:173], v[218:221], v[18:21]
	s_setprio 0
	s_setprio 1
	v_mfma_f32_16x16x32_bf16 v[46:49], v[174:177], v[190:193], v[46:49]
	v_mfma_f32_16x16x32_bf16 v[42:45], v[182:185], v[190:193], v[42:45]
	v_mfma_f32_16x16x32_bf16 v[30:33], v[174:177], v[198:201], v[30:33]
	v_mfma_f32_16x16x32_bf16 v[26:29], v[182:185], v[198:201], v[26:29]
	v_mfma_f32_16x16x32_bf16 v[14:17], v[174:177], v[206:209], v[14:17]
	v_mfma_f32_16x16x32_bf16 v[10:13], v[182:185], v[206:209], v[10:13]
	v_mfma_f32_16x16x32_bf16 v[6:9], v[174:177], v[214:217], v[6:9]
	v_mfma_f32_16x16x32_bf16 v[2:5], v[182:185], v[214:217], v[2:5]
	v_mfma_f32_16x16x32_bf16 v[46:49], v[178:181], v[194:197], v[46:49]
	v_mfma_f32_16x16x32_bf16 v[42:45], v[186:189], v[194:197], v[42:45]
	v_mfma_f32_16x16x32_bf16 v[30:33], v[178:181], v[202:205], v[30:33]
	v_mfma_f32_16x16x32_bf16 v[26:29], v[186:189], v[202:205], v[26:29]
	v_mfma_f32_16x16x32_bf16 v[14:17], v[178:181], v[210:213], v[14:17]
	v_mfma_f32_16x16x32_bf16 v[10:13], v[186:189], v[210:213], v[10:13]
	v_mfma_f32_16x16x32_bf16 v[6:9], v[178:181], v[218:221], v[6:9]
	v_mfma_f32_16x16x32_bf16 v[2:5], v[186:189], v[218:221], v[2:5]
	s_setprio 0
	s_barrier
	s_add_i32 s50, s50, 2
	s_add_u32 s48, s48, 0x100
	s_addc_u32 s49, s49, 0
	s_add_u32 s46, s46, 0x100
	s_addc_u32 s47, s47, 0
	s_cmp_gt_u32 s50, 13
	s_cbranch_scc0 .LBB0_517
	s_and_b64 vcc, exec, s[10:11]
	s_cbranch_vccz .LBB0_520
	s_barrier

; #define PG8_STAGE(bufoff, gbase, voff) do { _Pragma("unroll") for (int _i = 0; _i < 2; ++_i) \
;         __builtin_amdgcn_global_load_lds((const unsigned*)((const char*)(gbase) + (voff)[_i]), (PG8_LAS unsigned*)(lds + (bufoff) + ldsw + _i * 8192), 16, 0, 0); } while (0)
; #define PG8_LDA(dst, b, h) do { _Pragma("unroll") for (int m = 0; m < 4; ++m) _Pragma("unroll") for (int k = 0; k < 2; ++k) dst[m][k] = *(const PG8_LAS bf16x8*)(lds + PG8_SA(b, h) + aoff + m * 2048 + k * 1024); } while (0)
; #define PG8_LDB(dst, b, h) do { _Pragma("unroll") for (int n = 0; n < 2; ++n) _Pragma("unroll") for (int k = 0; k < 2; ++k) dst[n][k] = *(const PG8_LAS bf16x8*)(lds + PG8_SB(b, h) + boff + n * 2048 + k * 1024); } while (0)
; #define PG8_WAIT_V(n) asm volatile("s_waitcnt vmcnt(" #n ")" ::: "memory")
; #define PG8_WAIT_L(n) asm volatile("s_waitcnt lgkmcnt(" #n ")" ::: "memory")
; #define PG8_BAR __builtin_amdgcn_s_barrier()
; #define PG8_SCHED __builtin_amdgcn_sched_barrier(0)
; template <class Epi, class Sched, bool ALIGN_EPI = false, bool SP2 = false>
; __device__ __forceinline__ void gemm_phase(PG8_LAS unsigned char* lds, const Gemm g, const Sched& S, const Epi& E) {
;     ...
;         const char* nA = has_next ? (const char*)g.A + (size_t)nxt.pm * tstep + (size_t)nxt.ks * K * 2 : cA; const char* nB = has_next ? (const char*)g.Bt + (size_t)nxt.pn * tstep + (size_t)nxt.ks * K * 2 : cB;
;         for (int t = 0; t < nt; t += 2) {
;             const bool last = (t == nt - 2);
;             const char* a1 = cA + (size_t)(t + 1) * kstep;
;             const char* a2 = last ? nA : cA + (size_t)(t + 2) * kstep; const char* b2 = last ? nB : cB + (size_t)(t + 2) * kstep;
;             const char* a3 = a2 + kstep; const char* b3 = b2 + kstep;
;             if (last && has_next) S.a_ready(nxt);
;             if constexpr (SP2) {
;             PG8_LDB(B0, 0, 0); PG8_LDB(B1, 0, 1); PG8_SCHED; PG8_LDA(At, 0, 0); PG8_STAGE(PG8_SA(1, 1), a1 + hstep, voffA);
;             PG8_WAIT_V(8); PG8_WAIT_L(0); PG8_BAR; PG8_MMA(0, 0, At, B0); PG8_MMA(0, 1, At, B1); PG8_BAR; PG8_SCHED;
;             PG8_LDA(At, 0, 1); PG8_STAGE(PG8_SB(0, 0), b2, voffB); PG8_STAGE(PG8_SB(0, 1), b2 + hstep, voffB); PG8_STAGE(PG8_SA(0, 0), a2, voffA);
;             PG8_WAIT_V(8); PG8_WAIT_L(0); PG8_BAR; PG8_MMA(1, 0, At, B0); PG8_MMA(1, 1, At, B1); PG8_BAR; PG8_SCHED;
.LBB0_858:
	s_add_u32 s43, s56, 0x100
	s_addc_u32 s45, s57, 0
	s_add_u32 s56, s60, 0x40080
	s_addc_u32 s57, s61, 0
	s_mov_b32 s59, 0
	ds_read_b128 v[150:153], v146
	ds_read_b128 v[154:157], v146 offset:1024
	ds_read_b128 v[158:161], v146 offset:2048
	ds_read_b128 v[162:165], v146 offset:3072
	ds_read_b128 v[166:169], v147
	ds_read_b128 v[170:173], v147 offset:1024
	ds_read_b128 v[174:177], v147 offset:2048
	ds_read_b128 v[178:181], v147 offset:3072
	s_add_i32 s88, s59, 2
	s_add_u32 s60, s56, 0xfffc0080
	s_addc_u32 s61, s57, -1
	s_cmp_eq_u32 s84, s59
	s_cselect_b32 s69, s47, s61
	s_cselect_b32 s68, s46, s60
	s_cselect_b32 s61, s53, s45
	s_cselect_b32 s60, s52, s43
	v_lshl_add_u64 v[214:215], s[56:57], 0, v[140:141]
	s_add_i32 m0, s77, 0xc000
	ds_read_b128 v[182:185], v145
	ds_read_b128 v[186:189], v145 offset:1024
	ds_read_b128 v[190:193], v145 offset:2048
	ds_read_b128 v[194:197], v145 offset:3072
	ds_read_b128 v[198:201], v145 offset:4096
	ds_read_b128 v[202:205], v145 offset:5120
	ds_read_b128 v[206:209], v145 offset:6144
	ds_read_b128 v[210:213], v145 offset:7168
	global_load_lds_dwordx4 v[214:215], off
	v_lshl_add_u64 v[214:215], s[56:57], 0, v[138:139]
	s_add_i32 m0, s77, 0xe000
	s_nop 0
	global_load_lds_dwordx4 v[214:215], off
	s_waitcnt vmcnt(8)
	s_waitcnt lgkmcnt(0)
	s_barrier
	s_setprio 1
	s_waitcnt lgkmcnt(0)
	v_mfma_f32_16x16x32_bf16 v[126:129], v[150:153], v[182:185], 0
	v_mfma_f32_16x16x32_bf16 v[122:125], v[158:161], v[182:185], 0
	v_mfma_f32_16x16x32_bf16 v[118:121], v[150:153], v[190:193], 0
	v_mfma_f32_16x16x32_bf16 v[114:117], v[158:161], v[190:193], 0
	v_mfma_f32_16x16x32_bf16 v[102:105], v[150:153], v[198:201], 0
	v_mfma_f32_16x16x32_bf16 v[98:101], v[158:161], v[198:201], 0
	v_mfma_f32_16x16x32_bf16 v[86:89], v[150:153], v[206:209], 0
	v_mfma_f32_16x16x32_bf16 v[82:85], v[158:161], v[206:209], 0
	v_mfma_f32_16x16x32_bf16 v[126:129], v[154:157], v[186:189], v[126:129]
	v_mfma_f32_16x16x32_bf16 v[122:125], v[162:165], v[186:189], v[122:125]
	v_mfma_f32_16x16x32_bf16 v[118:121], v[154:157], v[194:197], v[118:121]
	v_mfma_f32_16x16x32_bf16 v[114:117], v[162:165], v[194:197], v[114:117]
	v_mfma_f32_16x16x32_bf16 v[102:105], v[154:157], v[202:205], v[102:105]
	v_mfma_f32_16x16x32_bf16 v[98:101], v[162:165], v[202:205], v[98:101]
	v_mfma_f32_16x16x32_bf16 v[86:89], v[154:157], v[210:213], v[86:89]
	v_mfma_f32_16x16x32_bf16 v[82:85], v[162:165], v[210:213], v[82:85]
	s_setprio 0
	s_setprio 1
	v_mfma_f32_16x16x32_bf16 v[110:113], v[166:169], v[182:185], 0
	v_mfma_f32_16x16x32_bf16 v[106:109], v[174:177], v[182:185], 0
	v_mfma_f32_16x16x32_bf16 v[94:97], v[166:169], v[190:193], 0
	v_mfma_f32_16x16x32_bf16 v[90:93], v[174:177], v[190:193], 0
	v_mfma_f32_16x16x32_bf16 v[78:81], v[166:169], v[198:201], 0
	v_mfma_f32_16x16x32_bf16 v[74:77], v[174:177], v[198:201], 0
	v_mfma_f32_16x16x32_bf16 v[70:73], v[166:169], v[206:209], 0
	v_mfma_f32_16x16x32_bf16 v[66:69], v[174:177], v[206:209], 0
	v_mfma_f32_16x16x32_bf16 v[110:113], v[170:173], v[186:189], v[110:113]
	v_mfma_f32_16x16x32_bf16 v[106:109], v[178:181], v[186:189], v[106:109]
	v_mfma_f32_16x16x32_bf16 v[94:97], v[170:173], v[194:197], v[94:97]
	v_mfma_f32_16x16x32_bf16 v[90:93], v[178:181], v[194:197], v[90:93]
	v_mfma_f32_16x16x32_bf16 v[78:81], v[170:173], v[202:205], v[78:81]
	v_mfma_f32_16x16x32_bf16 v[74:77], v[178:181], v[202:205], v[74:77]
	v_mfma_f32_16x16x32_bf16 v[70:73], v[170:173], v[210:213], v[70:73]
	v_mfma_f32_16x16x32_bf16 v[66:69], v[178:181], v[210:213], v[66:69]
	s_setprio 0
	s_barrier
	s_mov_b32 m0, s37
	v_lshl_add_u64 v[214:215], s[60:61], 0, v[130:131]
	s_add_u32 s90, s60, 0x40000
	ds_read_b128 v[182:185], v145 offset:16384
	ds_read_b128 v[186:189], v145 offset:17408
	ds_read_b128 v[190:193], v145 offset:18432
	ds_read_b128 v[194:197], v145 offset:19456
	ds_read_b128 v[198:201], v145 offset:20480
	ds_read_b128 v[202:205], v145 offset:21504
	ds_read_b128 v[206:209], v145 offset:22528
	ds_read_b128 v[210:213], v145 offset:23552
	global_load_lds_dwordx4 v[214:215], off
	v_lshl_add_u64 v[216:217], s[60:61], 0, v[136:137]
	s_mov_b32 m0, s39
	s_addc_u32 s91, s61, 0
	global_load_lds_dwordx4 v[216:217], off
	v_lshl_add_u64 v[218:219], s[90:91], 0, v[130:131]
	s_mov_b32 m0, s75
	v_lshl_add_u64 v[220:221], s[68:69], 0, v[134:135]
	global_load_lds_dwordx4 v[218:219], off
	v_lshl_add_u64 v[218:219], s[90:91], 0, v[136:137]
	s_mov_b32 m0, s76
	s_nop 0
	global_load_lds_dwordx4 v[218:219], off
	v_lshl_add_u64 v[218:219], s[68:69], 0, v[132:133]
	s_waitcnt vmcnt(6)
	s_waitcnt lgkmcnt(0)
	s_barrier
	s_setprio 1
	s_waitcnt lgkmcnt(0)
	v_mfma_f32_16x16x32_bf16 v[62:65], v[150:153], v[182:185], 0
	v_mfma_f32_16x16x32_bf16 v[58:61], v[158:161], v[182:185], 0
	v_mfma_f32_16x16x32_bf16 v[54:57], v[150:153], v[190:193], 0
	v_mfma_f32_16x16x32_bf16 v[50:53], v[158:161], v[190:193], 0
	v_mfma_f32_16x16x32_bf16 v[38:41], v[150:153], v[198:201], 0
	v_mfma_f32_16x16x32_bf16 v[34:37], v[158:161], v[198:201], 0
	v_mfma_f32_16x16x32_bf16 v[22:25], v[150:153], v[206:209], 0
	v_mfma_f32_16x16x32_bf16 v[18:21], v[158:161], v[206:209], 0
	v_mfma_f32_16x16x32_bf16 v[62:65], v[154:157], v[186:189], v[62:65]
	v_mfma_f32_16x16x32_bf16 v[58:61], v[162:165], v[186:189], v[58:61]
	v_mfma_f32_16x16x32_bf16 v[54:57], v[154:157], v[194:197], v[54:57]
	v_mfma_f32_16x16x32_bf16 v[50:53], v[162:165], v[194:197], v[50:53]
	v_mfma_f32_16x16x32_bf16 v[38:41], v[154:157], v[202:205], v[38:41]
	v_mfma_f32_16x16x32_bf16 v[34:37], v[162:165], v[202:205], v[34:37]
	v_mfma_f32_16x16x32_bf16 v[22:25], v[154:157], v[210:213], v[22:25]
	v_mfma_f32_16x16x32_bf16 v[18:21], v[162:165], v[210:213], v[18:21]
	s_setprio 0
	s_setprio 1
	v_mfma_f32_16x16x32_bf16 v[46:49], v[166:169], v[182:185], 0
	v_mfma_f32_16x16x32_bf16 v[42:45], v[174:177], v[182:185], 0
	v_mfma_f32_16x16x32_bf16 v[30:33], v[166:169], v[190:193], 0
	v_mfma_f32_16x16x32_bf16 v[26:29], v[174:177], v[190:193], 0
	v_mfma_f32_16x16x32_bf16 v[14:17], v[166:169], v[198:201], 0
	v_mfma_f32_16x16x32_bf16 v[10:13], v[174:177], v[198:201], 0
	v_mfma_f32_16x16x32_bf16 v[6:9], v[166:169], v[206:209], 0
	v_mfma_f32_16x16x32_bf16 v[2:5], v[174:177], v[206:209], 0
	v_mfma_f32_16x16x32_bf16 v[46:49], v[170:173], v[186:189], v[46:49]
	v_mfma_f32_16x16x32_bf16 v[42:45], v[178:181], v[186:189], v[42:45]
	v_mfma_f32_16x16x32_bf16 v[30:33], v[170:173], v[194:197], v[30:33]
	v_mfma_f32_16x16x32_bf16 v[26:29], v[178:181], v[194:197], v[26:29]
	v_mfma_f32_16x16x32_bf16 v[14:17], v[170:173], v[202:205], v[14:17]
	v_mfma_f32_16x16x32_bf16 v[10:13], v[178:181], v[202:205], v[10:13]
	v_mfma_f32_16x16x32_bf16 v[6:9], v[170:173], v[210:213], v[6:9]
	v_mfma_f32_16x16x32_bf16 v[2:5], v[178:181], v[210:213], v[2:5]
	s_setprio 0
	s_barrier
; #define PG8_STAGE(bufoff, gbase, voff) do { _Pragma("unroll") for (int _i = 0; _i < 2; ++_i) \
;         __builtin_amdgcn_global_load_lds((const unsigned*)((const char*)(gbase) + (voff)[_i]), (PG8_LAS unsigned*)(lds + (bufoff) + ldsw + _i * 8192), 16, 0, 0); } while (0)
; #define PG8_LDA(dst, b, h) do { _Pragma("unroll") for (int m = 0; m < 4; ++m) _Pragma("unroll") for (int k = 0; k < 2; ++k) dst[m][k] = *(const PG8_LAS bf16x8*)(lds + PG8_SA(b, h) + aoff + m * 2048 + k * 1024); } while (0)
; #define PG8_LDB(dst, b, h) do { _Pragma("unroll") for (int n = 0; n < 2; ++n) _Pragma("unroll") for (int k = 0; k < 2; ++k) dst[n][k] = *(const PG8_LAS bf16x8*)(lds + PG8_SB(b, h) + boff + n * 2048 + k * 1024); } while (0)
; #define PG8_MMA(ai, bj, At, Bt) do { __builtin_amdgcn_s_setprio(1); _Pragma("unroll") for (int m = 0; m < 4; ++m) _Pragma("unroll") for (int n = 0; n < 2; ++n) _Pragma("unroll") for (int k = 0; k < 2; ++k) \
;         acc[ai][bj][m][n] = __builtin_amdgcn_mfma_f32_16x16x32_bf16(Bt[n][k], At[m][k], acc[ai][bj][m][n], 0, 0, 0); __builtin_amdgcn_s_setprio(0); } while (0)
; #define PG8_WAIT_V(n) asm volatile("s_waitcnt vmcnt(" #n ")" ::: "memory")
; #define PG8_WAIT_L(n) asm volatile("s_waitcnt lgkmcnt(" #n ")" ::: "memory")
; #define PG8_BAR __builtin_amdgcn_s_barrier()
; #define PG8_SCHED __builtin_amdgcn_sched_barrier(0)
; template <class Epi, class Sched, bool ALIGN_EPI = false, bool SP2 = false>
; __device__ __forceinline__ void gemm_phase(PG8_LAS unsigned char* lds, const Gemm g, const Sched& S, const Epi& E) {
;     ...
;             PG8_LDB(B0, 1, 0); PG8_LDB(B1, 1, 1); PG8_SCHED; PG8_LDA(At, 1, 0); PG8_STAGE(PG8_SA(0, 1), a2 + hstep, voffA);
;             PG8_WAIT_V(8); PG8_WAIT_L(0); PG8_BAR; PG8_MMA(0, 0, At, B0); PG8_MMA(0, 1, At, B1); PG8_BAR; PG8_SCHED;
;             PG8_LDA(At, 1, 1); PG8_STAGE(PG8_SB(1, 0), b3, voffB); PG8_STAGE(PG8_SB(1, 1), b3 + hstep, voffB); PG8_STAGE(PG8_SA(1, 0), a3, voffA);
;             PG8_WAIT_V(8); PG8_WAIT_L(0); PG8_BAR; PG8_MMA(1, 0, At, B0); PG8_MMA(1, 1, At, B1); PG8_BAR; PG8_SCHED;
	ds_read_b128 v[150:153], v148
	ds_read_b128 v[154:157], v148 offset:1024
	ds_read_b128 v[158:161], v148 offset:2048
	ds_read_b128 v[162:165], v148 offset:3072
	ds_read_b128 v[166:169], v149
	ds_read_b128 v[170:173], v149 offset:1024
	ds_read_b128 v[174:177], v149 offset:2048
	ds_read_b128 v[178:181], v149 offset:3072
	s_add_u32 s68, s68, 0x40000
	s_addc_u32 s69, s69, 0
	s_mov_b32 m0, s77
	s_nop 0
	global_load_lds_dwordx4 v[218:219], off
	s_mov_b32 m0, s78
	s_nop 0
	global_load_lds_dwordx4 v[220:221], off
	s_mov_b32 m0, s79
	v_lshl_add_u64 v[222:223], s[68:69], 0, v[132:133]
	ds_read_b128 v[182:185], v145 offset:32768
	ds_read_b128 v[186:189], v145 offset:33792
	ds_read_b128 v[190:193], v145 offset:34816
	ds_read_b128 v[194:197], v145 offset:35840
	ds_read_b128 v[198:201], v145 offset:36864
	ds_read_b128 v[202:205], v145 offset:37888
	ds_read_b128 v[206:209], v145 offset:38912
	ds_read_b128 v[210:213], v145 offset:39936
	global_load_lds_dwordx4 v[222:223], off
	v_lshl_add_u64 v[222:223], s[68:69], 0, v[134:135]
	s_mov_b32 m0, s80
	s_nop 0
	global_load_lds_dwordx4 v[222:223], off
	s_waitcnt vmcnt(8)
	s_waitcnt lgkmcnt(0)
	s_barrier
	s_setprio 1
	s_waitcnt lgkmcnt(0)
	v_mfma_f32_16x16x32_bf16 v[126:129], v[150:153], v[182:185], v[126:129]
	v_mfma_f32_16x16x32_bf16 v[122:125], v[158:161], v[182:185], v[122:125]
	v_mfma_f32_16x16x32_bf16 v[118:121], v[150:153], v[190:193], v[118:121]
	v_mfma_f32_16x16x32_bf16 v[114:117], v[158:161], v[190:193], v[114:117]
	v_mfma_f32_16x16x32_bf16 v[102:105], v[150:153], v[198:201], v[102:105]
	v_mfma_f32_16x16x32_bf16 v[98:101], v[158:161], v[198:201], v[98:101]
	v_mfma_f32_16x16x32_bf16 v[86:89], v[150:153], v[206:209], v[86:89]
	v_mfma_f32_16x16x32_bf16 v[82:85], v[158:161], v[206:209], v[82:85]
	v_mfma_f32_16x16x32_bf16 v[126:129], v[154:157], v[186:189], v[126:129]
	v_mfma_f32_16x16x32_bf16 v[122:125], v[162:165], v[186:189], v[122:125]
	v_mfma_f32_16x16x32_bf16 v[118:121], v[154:157], v[194:197], v[118:121]
	v_mfma_f32_16x16x32_bf16 v[114:117], v[162:165], v[194:197], v[114:117]
	v_mfma_f32_16x16x32_bf16 v[102:105], v[154:157], v[202:205], v[102:105]
	v_mfma_f32_16x16x32_bf16 v[98:101], v[162:165], v[202:205], v[98:101]
	v_mfma_f32_16x16x32_bf16 v[86:89], v[154:157], v[210:213], v[86:89]
	v_mfma_f32_16x16x32_bf16 v[82:85], v[162:165], v[210:213], v[82:85]
	s_setprio 0
	s_setprio 1
	v_mfma_f32_16x16x32_bf16 v[110:113], v[166:169], v[182:185], v[110:113]
	v_mfma_f32_16x16x32_bf16 v[106:109], v[174:177], v[182:185], v[106:109]
	v_mfma_f32_16x16x32_bf16 v[94:97], v[166:169], v[190:193], v[94:97]
	v_mfma_f32_16x16x32_bf16 v[90:93], v[174:177], v[190:193], v[90:93]
	v_mfma_f32_16x16x32_bf16 v[78:81], v[166:169], v[198:201], v[78:81]
	v_mfma_f32_16x16x32_bf16 v[74:77], v[174:177], v[198:201], v[74:77]
	v_mfma_f32_16x16x32_bf16 v[70:73], v[166:169], v[206:209], v[70:73]
	v_mfma_f32_16x16x32_bf16 v[66:69], v[174:177], v[206:209], v[66:69]
	v_mfma_f32_16x16x32_bf16 v[110:113], v[170:173], v[186:189], v[110:113]
	v_mfma_f32_16x16x32_bf16 v[106:109], v[178:181], v[186:189], v[106:109]
	v_mfma_f32_16x16x32_bf16 v[94:97], v[170:173], v[194:197], v[94:97]
	v_mfma_f32_16x16x32_bf16 v[90:93], v[178:181], v[194:197], v[90:93]
	v_mfma_f32_16x16x32_bf16 v[78:81], v[170:173], v[202:205], v[78:81]
	v_mfma_f32_16x16x32_bf16 v[74:77], v[178:181], v[202:205], v[74:77]
	v_mfma_f32_16x16x32_bf16 v[70:73], v[170:173], v[210:213], v[70:73]
	v_mfma_f32_16x16x32_bf16 v[66:69], v[178:181], v[210:213], v[66:69]
	s_setprio 0
	s_barrier
	s_mov_b32 m0, s48
	v_lshl_add_u64 v[214:215], v[214:215], 0, s[16:17]
	s_add_u32 s60, s60, 0x40080
	ds_read_b128 v[182:185], v145 offset:49152
	ds_read_b128 v[186:189], v145 offset:50176
	ds_read_b128 v[190:193], v145 offset:51200
	ds_read_b128 v[194:197], v145 offset:52224
	ds_read_b128 v[198:201], v145 offset:53248
	ds_read_b128 v[202:205], v145 offset:54272
	ds_read_b128 v[206:209], v145 offset:55296
	ds_read_b128 v[210:213], v145 offset:56320
	global_load_lds_dwordx4 v[214:215], off
	v_lshl_add_u64 v[214:215], v[216:217], 0, s[16:17]
	s_mov_b32 m0, s49
	s_addc_u32 s61, s61, 0
	global_load_lds_dwordx4 v[214:215], off
	v_lshl_add_u64 v[214:215], s[60:61], 0, v[130:131]
	s_mov_b32 m0, s82
	s_nop 0
	global_load_lds_dwordx4 v[214:215], off
	v_lshl_add_u64 v[214:215], s[60:61], 0, v[136:137]
	s_mov_b32 m0, s83
	s_nop 0
	global_load_lds_dwordx4 v[214:215], off
	v_lshl_add_u64 v[214:215], v[218:219], 0, s[16:17]
	s_mov_b32 m0, s50
	s_nop 0
	global_load_lds_dwordx4 v[214:215], off
	v_lshl_add_u64 v[214:215], v[220:221], 0, s[16:17]
	s_mov_b32 m0, s51
	s_nop 0
	global_load_lds_dwordx4 v[214:215], off
	s_waitcnt vmcnt(8)
	s_waitcnt lgkmcnt(0)
	s_barrier
; #define PG8_STAGE(bufoff, gbase, voff) do { _Pragma("unroll") for (int _i = 0; _i < 2; ++_i) \
;         __builtin_amdgcn_global_load_lds((const unsigned*)((const char*)(gbase) + (voff)[_i]), (PG8_LAS unsigned*)(lds + (bufoff) + ldsw + _i * 8192), 16, 0, 0); } while (0)
; #define PG8_LDA(dst, b, h) do { _Pragma("unroll") for (int m = 0; m < 4; ++m) _Pragma("unroll") for (int k = 0; k < 2; ++k) dst[m][k] = *(const PG8_LAS bf16x8*)(lds + PG8_SA(b, h) + aoff + m * 2048 + k * 1024); } while (0)
; #define PG8_LDB(dst, b, h) do { _Pragma("unroll") for (int n = 0; n < 2; ++n) _Pragma("unroll") for (int k = 0; k < 2; ++k) dst[n][k] = *(const PG8_LAS bf16x8*)(lds + PG8_SB(b, h) + boff + n * 2048 + k * 1024); } while (0)
; #define PG8_MMA(ai, bj, At, Bt) do { __builtin_amdgcn_s_setprio(1); _Pragma("unroll") for (int m = 0; m < 4; ++m) _Pragma("unroll") for (int n = 0; n < 2; ++n) _Pragma("unroll") for (int k = 0; k < 2; ++k) \
;         acc[ai][bj][m][n] = __builtin_amdgcn_mfma_f32_16x16x32_bf16(Bt[n][k], At[m][k], acc[ai][bj][m][n], 0, 0, 0); __builtin_amdgcn_s_setprio(0); } while (0)
; #define PG8_WAIT_V(n) asm volatile("s_waitcnt vmcnt(" #n ")" ::: "memory")
; template <class Epi, class Sched, bool ALIGN_EPI = false, bool SP2 = false>
; __device__ __forceinline__ void gemm_phase(PG8_LAS unsigned char* lds, const Gemm g, const Sched& S, const Epi& E) {
;     ...
;             PG8_LDB(B0, 0, 0); PG8_LDB(B1, 0, 1); PG8_SCHED; PG8_LDA(At, 0, 0); PG8_STAGE(PG8_SA(1, 1), a1 + hstep, voffA);
;             PG8_WAIT_V(8); PG8_WAIT_L(0); PG8_BAR; PG8_MMA(0, 0, At, B0); PG8_MMA(0, 1, At, B1); PG8_BAR; PG8_SCHED;
;             PG8_LDA(At, 0, 1); PG8_STAGE(PG8_SB(0, 0), b2, voffB); PG8_STAGE(PG8_SB(0, 1), b2 + hstep, voffB); PG8_STAGE(PG8_SA(0, 0), a2, voffA);
;             PG8_WAIT_V(8); PG8_WAIT_L(0); PG8_BAR; PG8_MMA(1, 0, At, B0); PG8_MMA(1, 1, At, B1); PG8_BAR; PG8_SCHED;
;             PG8_LDB(B0, 1, 0); PG8_LDB(B1, 1, 1); PG8_SCHED; PG8_LDA(At, 1, 0); PG8_STAGE(PG8_SA(0, 1), a2 + hstep, voffA);
;             PG8_WAIT_V(8); PG8_WAIT_L(0); PG8_BAR; PG8_MMA(0, 0, At, B0); PG8_MMA(0, 1, At, B1); PG8_BAR; PG8_SCHED;
;             PG8_LDA(At, 1, 1); PG8_STAGE(PG8_SB(1, 0), b3, voffB); PG8_STAGE(PG8_SB(1, 1), b3 + hstep, voffB); PG8_STAGE(PG8_SA(1, 0), a3, voffA);
;             PG8_WAIT_V(8); PG8_WAIT_L(0); PG8_BAR; PG8_MMA(1, 0, At, B0); PG8_MMA(1, 1, At, B1); PG8_BAR; PG8_SCHED;
	s_setprio 1
	s_waitcnt lgkmcnt(0)
	v_mfma_f32_16x16x32_bf16 v[62:65], v[150:153], v[182:185], v[62:65]
	v_mfma_f32_16x16x32_bf16 v[58:61], v[158:161], v[182:185], v[58:61]
	v_mfma_f32_16x16x32_bf16 v[54:57], v[150:153], v[190:193], v[54:57]
	v_mfma_f32_16x16x32_bf16 v[50:53], v[158:161], v[190:193], v[50:53]
	v_mfma_f32_16x16x32_bf16 v[38:41], v[150:153], v[198:201], v[38:41]
	v_mfma_f32_16x16x32_bf16 v[34:37], v[158:161], v[198:201], v[34:37]
	v_mfma_f32_16x16x32_bf16 v[22:25], v[150:153], v[206:209], v[22:25]
	v_mfma_f32_16x16x32_bf16 v[18:21], v[158:161], v[206:209], v[18:21]
	v_mfma_f32_16x16x32_bf16 v[62:65], v[154:157], v[186:189], v[62:65]
	v_mfma_f32_16x16x32_bf16 v[58:61], v[162:165], v[186:189], v[58:61]
	v_mfma_f32_16x16x32_bf16 v[54:57], v[154:157], v[194:197], v[54:57]
	v_mfma_f32_16x16x32_bf16 v[50:53], v[162:165], v[194:197], v[50:53]
	v_mfma_f32_16x16x32_bf16 v[38:41], v[154:157], v[202:205], v[38:41]
	v_mfma_f32_16x16x32_bf16 v[34:37], v[162:165], v[202:205], v[34:37]
	v_mfma_f32_16x16x32_bf16 v[22:25], v[154:157], v[210:213], v[22:25]
	v_mfma_f32_16x16x32_bf16 v[18:21], v[162:165], v[210:213], v[18:21]
	s_setprio 0
	s_setprio 1
	v_mfma_f32_16x16x32_bf16 v[46:49], v[166:169], v[182:185], v[46:49]
	v_mfma_f32_16x16x32_bf16 v[42:45], v[174:177], v[182:185], v[42:45]
	v_mfma_f32_16x16x32_bf16 v[30:33], v[166:169], v[190:193], v[30:33]
	v_mfma_f32_16x16x32_bf16 v[26:29], v[174:177], v[190:193], v[26:29]
	v_mfma_f32_16x16x32_bf16 v[14:17], v[166:169], v[198:201], v[14:17]
	v_mfma_f32_16x16x32_bf16 v[10:13], v[174:177], v[198:201], v[10:13]
	v_mfma_f32_16x16x32_bf16 v[6:9], v[166:169], v[206:209], v[6:9]
	v_mfma_f32_16x16x32_bf16 v[2:5], v[174:177], v[206:209], v[2:5]
	v_mfma_f32_16x16x32_bf16 v[46:49], v[170:173], v[186:189], v[46:49]
	v_mfma_f32_16x16x32_bf16 v[42:45], v[178:181], v[186:189], v[42:45]
	v_mfma_f32_16x16x32_bf16 v[30:33], v[170:173], v[194:197], v[30:33]
	v_mfma_f32_16x16x32_bf16 v[26:29], v[178:181], v[194:197], v[26:29]
	v_mfma_f32_16x16x32_bf16 v[14:17], v[170:173], v[202:205], v[14:17]
	v_mfma_f32_16x16x32_bf16 v[10:13], v[178:181], v[202:205], v[10:13]
	v_mfma_f32_16x16x32_bf16 v[6:9], v[170:173], v[210:213], v[6:9]
	v_mfma_f32_16x16x32_bf16 v[2:5], v[178:181], v[210:213], v[2:5]
	s_setprio 0
	s_barrier
	s_add_u32 s43, s43, 0x100
	s_addc_u32 s45, s45, 0
	s_add_u32 s56, s56, 0x100
	s_addc_u32 s57, s57, 0
	s_cmp_ge_u32 s88, s81
	s_mov_b32 s59, s88
.LBB0_859:
	ds_read_b128 v[150:153], v146
	ds_read_b128 v[154:157], v146 offset:1024
	ds_read_b128 v[158:161], v146 offset:2048
	ds_read_b128 v[162:165], v146 offset:3072
	ds_read_b128 v[166:169], v147
	ds_read_b128 v[170:173], v147 offset:1024
	ds_read_b128 v[174:177], v147 offset:2048
	ds_read_b128 v[178:181], v147 offset:3072
	s_add_i32 s88, s59, 2
	s_add_u32 s60, s56, 0xfffc0080
	s_addc_u32 s61, s57, -1
	s_cmp_eq_u32 s84, s59
	s_cselect_b32 s69, s47, s61
	s_cselect_b32 s68, s46, s60
	s_cselect_b32 s61, s53, s45
	s_cselect_b32 s60, s52, s43
	v_lshl_add_u64 v[214:215], s[56:57], 0, v[140:141]
	s_add_i32 m0, s77, 0xc000
	ds_read_b128 v[182:185], v145
	ds_read_b128 v[186:189], v145 offset:1024
	ds_read_b128 v[190:193], v145 offset:2048
	ds_read_b128 v[194:197], v145 offset:3072
	ds_read_b128 v[198:201], v145 offset:4096
	ds_read_b128 v[202:205], v145 offset:5120
	ds_read_b128 v[206:209], v145 offset:6144
	ds_read_b128 v[210:213], v145 offset:7168
	global_load_lds_dwordx4 v[214:215], off
	v_lshl_add_u64 v[214:215], s[56:57], 0, v[138:139]
	s_add_i32 m0, s77, 0xe000
	s_nop 0
	global_load_lds_dwordx4 v[214:215], off
	s_waitcnt vmcnt(8)
	s_waitcnt lgkmcnt(0)
	s_barrier
	s_setprio 1
	s_waitcnt lgkmcnt(0)
	v_mfma_f32_16x16x32_bf16 v[126:129], v[150:153], v[182:185], v[126:129]
	v_mfma_f32_16x16x32_bf16 v[122:125], v[158:161], v[182:185], v[122:125]
	v_mfma_f32_16x16x32_bf16 v[118:121], v[150:153], v[190:193], v[118:121]
	v_mfma_f32_16x16x32_bf16 v[114:117], v[158:161], v[190:193], v[114:117]
	v_mfma_f32_16x16x32_bf16 v[102:105], v[150:153], v[198:201], v[102:105]
	v_mfma_f32_16x16x32_bf16 v[98:101], v[158:161], v[198:201], v[98:101]
	v_mfma_f32_16x16x32_bf16 v[86:89], v[150:153], v[206:209], v[86:89]
	v_mfma_f32_16x16x32_bf16 v[82:85], v[158:161], v[206:209], v[82:85]
	v_mfma_f32_16x16x32_bf16 v[126:129], v[154:157], v[186:189], v[126:129]
	v_mfma_f32_16x16x32_bf16 v[122:125], v[162:165], v[186:189], v[122:125]
	v_mfma_f32_16x16x32_bf16 v[118:121], v[154:157], v[194:197], v[118:121]
	v_mfma_f32_16x16x32_bf16 v[114:117], v[162:165], v[194:197], v[114:117]
	v_mfma_f32_16x16x32_bf16 v[102:105], v[154:157], v[202:205], v[102:105]
	v_mfma_f32_16x16x32_bf16 v[98:101], v[162:165], v[202:205], v[98:101]
	v_mfma_f32_16x16x32_bf16 v[86:89], v[154:157], v[210:213], v[86:89]
	v_mfma_f32_16x16x32_bf16 v[82:85], v[162:165], v[210:213], v[82:85]
	s_setprio 0
	s_setprio 1
	v_mfma_f32_16x16x32_bf16 v[110:113], v[166:169], v[182:185], v[110:113]
	v_mfma_f32_16x16x32_bf16 v[106:109], v[174:177], v[182:185], v[106:109]
	v_mfma_f32_16x16x32_bf16 v[94:97], v[166:169], v[190:193], v[94:97]
	v_mfma_f32_16x16x32_bf16 v[90:93], v[174:177], v[190:193], v[90:93]
	v_mfma_f32_16x16x32_bf16 v[78:81], v[166:169], v[198:201], v[78:81]
	v_mfma_f32_16x16x32_bf16 v[74:77], v[174:177], v[198:201], v[74:77]
	v_mfma_f32_16x16x32_bf16 v[70:73], v[166:169], v[206:209], v[70:73]
	v_mfma_f32_16x16x32_bf16 v[66:69], v[174:177], v[206:209], v[66:69]
	v_mfma_f32_16x16x32_bf16 v[110:113], v[170:173], v[186:189], v[110:113]
	v_mfma_f32_16x16x32_bf16 v[106:109], v[178:181], v[186:189], v[106:109]
	v_mfma_f32_16x16x32_bf16 v[94:97], v[170:173], v[194:197], v[94:97]
	v_mfma_f32_16x16x32_bf16 v[90:93], v[178:181], v[194:197], v[90:93]
	v_mfma_f32_16x16x32_bf16 v[78:81], v[170:173], v[202:205], v[78:81]
	v_mfma_f32_16x16x32_bf16 v[74:77], v[178:181], v[202:205], v[74:77]
	v_mfma_f32_16x16x32_bf16 v[70:73], v[170:173], v[210:213], v[70:73]
	v_mfma_f32_16x16x32_bf16 v[66:69], v[178:181], v[210:213], v[66:69]
	s_setprio 0
	s_barrier
; #define PG8_STAGE(bufoff, gbase, voff) do { _Pragma("unroll") for (int _i = 0; _i < 2; ++_i) \
;         __builtin_amdgcn_global_load_lds((const unsigned*)((const char*)(gbase) + (voff)[_i]), (PG8_LAS unsigned*)(lds + (bufoff) + ldsw + _i * 8192), 16, 0, 0); } while (0)
; #define PG8_LDA(dst, b, h) do { _Pragma("unroll") for (int m = 0; m < 4; ++m) _Pragma("unroll") for (int k = 0; k < 2; ++k) dst[m][k] = *(const PG8_LAS bf16x8*)(lds + PG8_SA(b, h) + aoff + m * 2048 + k * 1024); } while (0)
; #define PG8_LDB(dst, b, h) do { _Pragma("unroll") for (int n = 0; n < 2; ++n) _Pragma("unroll") for (int k = 0; k < 2; ++k) dst[n][k] = *(const PG8_LAS bf16x8*)(lds + PG8_SB(b, h) + boff + n * 2048 + k * 1024); } while (0)
; #define PG8_MMA(ai, bj, At, Bt) do { __builtin_amdgcn_s_setprio(1); _Pragma("unroll") for (int m = 0; m < 4; ++m) _Pragma("unroll") for (int n = 0; n < 2; ++n) _Pragma("unroll") for (int k = 0; k < 2; ++k) \
;         acc[ai][bj][m][n] = __builtin_amdgcn_mfma_f32_16x16x32_bf16(Bt[n][k], At[m][k], acc[ai][bj][m][n], 0, 0, 0); __builtin_amdgcn_s_setprio(0); } while (0)
; #define PG8_WAIT_V(n) asm volatile("s_waitcnt vmcnt(" #n ")" ::: "memory")
; #define PG8_WAIT_L(n) asm volatile("s_waitcnt lgkmcnt(" #n ")" ::: "memory")
; #define PG8_BAR __builtin_amdgcn_s_barrier()
; #define PG8_SCHED __builtin_amdgcn_sched_barrier(0)
; template <class Epi, class Sched, bool ALIGN_EPI = false, bool SP2 = false>
; __device__ __forceinline__ void gemm_phase(PG8_LAS unsigned char* lds, const Gemm g, const Sched& S, const Epi& E) {
;     ...
;             PG8_LDA(At, 0, 1); PG8_STAGE(PG8_SB(0, 0), b2, voffB); PG8_STAGE(PG8_SB(0, 1), b2 + hstep, voffB); PG8_STAGE(PG8_SA(0, 0), a2, voffA);
;             PG8_WAIT_V(8); PG8_WAIT_L(0); PG8_BAR; PG8_MMA(1, 0, At, B0); PG8_MMA(1, 1, At, B1); PG8_BAR; PG8_SCHED;
;             PG8_LDB(B0, 1, 0); PG8_LDB(B1, 1, 1); PG8_SCHED; PG8_LDA(At, 1, 0); PG8_STAGE(PG8_SA(0, 1), a2 + hstep, voffA);
;             PG8_WAIT_V(8); PG8_WAIT_L(0); PG8_BAR; PG8_MMA(0, 0, At, B0); PG8_MMA(0, 1, At, B1); PG8_BAR; PG8_SCHED;
	s_mov_b32 m0, s37
	v_lshl_add_u64 v[214:215], s[60:61], 0, v[130:131]
	s_add_u32 s90, s60, 0x40000
	ds_read_b128 v[182:185], v145 offset:16384
	ds_read_b128 v[186:189], v145 offset:17408
	ds_read_b128 v[190:193], v145 offset:18432
	ds_read_b128 v[194:197], v145 offset:19456
	ds_read_b128 v[198:201], v145 offset:20480
	ds_read_b128 v[202:205], v145 offset:21504
	ds_read_b128 v[206:209], v145 offset:22528
	ds_read_b128 v[210:213], v145 offset:23552
	global_load_lds_dwordx4 v[214:215], off
	v_lshl_add_u64 v[216:217], s[60:61], 0, v[136:137]
	s_mov_b32 m0, s39
	s_addc_u32 s91, s61, 0
	global_load_lds_dwordx4 v[216:217], off
	v_lshl_add_u64 v[218:219], s[90:91], 0, v[130:131]
	s_mov_b32 m0, s75
	v_lshl_add_u64 v[220:221], s[68:69], 0, v[134:135]
	global_load_lds_dwordx4 v[218:219], off
	v_lshl_add_u64 v[218:219], s[90:91], 0, v[136:137]
	s_mov_b32 m0, s76
	s_nop 0
	global_load_lds_dwordx4 v[218:219], off
	v_lshl_add_u64 v[218:219], s[68:69], 0, v[132:133]
	s_waitcnt vmcnt(6)
	s_waitcnt lgkmcnt(0)
	s_barrier
	s_setprio 1
	s_waitcnt lgkmcnt(0)
	v_mfma_f32_16x16x32_bf16 v[62:65], v[150:153], v[182:185], v[62:65]
	v_mfma_f32_16x16x32_bf16 v[58:61], v[158:161], v[182:185], v[58:61]
	v_mfma_f32_16x16x32_bf16 v[54:57], v[150:153], v[190:193], v[54:57]
	v_mfma_f32_16x16x32_bf16 v[50:53], v[158:161], v[190:193], v[50:53]
	v_mfma_f32_16x16x32_bf16 v[38:41], v[150:153], v[198:201], v[38:41]
	v_mfma_f32_16x16x32_bf16 v[34:37], v[158:161], v[198:201], v[34:37]
	v_mfma_f32_16x16x32_bf16 v[22:25], v[150:153], v[206:209], v[22:25]
	v_mfma_f32_16x16x32_bf16 v[18:21], v[158:161], v[206:209], v[18:21]
	v_mfma_f32_16x16x32_bf16 v[62:65], v[154:157], v[186:189], v[62:65]
	v_mfma_f32_16x16x32_bf16 v[58:61], v[162:165], v[186:189], v[58:61]
	v_mfma_f32_16x16x32_bf16 v[54:57], v[154:157], v[194:197], v[54:57]
	v_mfma_f32_16x16x32_bf16 v[50:53], v[162:165], v[194:197], v[50:53]
	v_mfma_f32_16x16x32_bf16 v[38:41], v[154:157], v[202:205], v[38:41]
	v_mfma_f32_16x16x32_bf16 v[34:37], v[162:165], v[202:205], v[34:37]
	v_mfma_f32_16x16x32_bf16 v[22:25], v[154:157], v[210:213], v[22:25]
	v_mfma_f32_16x16x32_bf16 v[18:21], v[162:165], v[210:213], v[18:21]
	s_setprio 0
	s_setprio 1
	v_mfma_f32_16x16x32_bf16 v[46:49], v[166:169], v[182:185], v[46:49]
	v_mfma_f32_16x16x32_bf16 v[42:45], v[174:177], v[182:185], v[42:45]
	v_mfma_f32_16x16x32_bf16 v[30:33], v[166:169], v[190:193], v[30:33]
	v_mfma_f32_16x16x32_bf16 v[26:29], v[174:177], v[190:193], v[26:29]
	v_mfma_f32_16x16x32_bf16 v[14:17], v[166:169], v[198:201], v[14:17]
	v_mfma_f32_16x16x32_bf16 v[10:13], v[174:177], v[198:201], v[10:13]
	v_mfma_f32_16x16x32_bf16 v[6:9], v[166:169], v[206:209], v[6:9]
	v_mfma_f32_16x16x32_bf16 v[2:5], v[174:177], v[206:209], v[2:5]
	v_mfma_f32_16x16x32_bf16 v[46:49], v[170:173], v[186:189], v[46:49]
	v_mfma_f32_16x16x32_bf16 v[42:45], v[178:181], v[186:189], v[42:45]
	v_mfma_f32_16x16x32_bf16 v[30:33], v[170:173], v[194:197], v[30:33]
	v_mfma_f32_16x16x32_bf16 v[26:29], v[178:181], v[194:197], v[26:29]
	v_mfma_f32_16x16x32_bf16 v[14:17], v[170:173], v[202:205], v[14:17]
	v_mfma_f32_16x16x32_bf16 v[10:13], v[178:181], v[202:205], v[10:13]
	v_mfma_f32_16x16x32_bf16 v[6:9], v[170:173], v[210:213], v[6:9]
	v_mfma_f32_16x16x32_bf16 v[2:5], v[178:181], v[210:213], v[2:5]
	s_setprio 0
	s_barrier
	ds_read_b128 v[150:153], v148
	ds_read_b128 v[154:157], v148 offset:1024
	ds_read_b128 v[158:161], v148 offset:2048
	ds_read_b128 v[162:165], v148 offset:3072
	ds_read_b128 v[166:169], v149
	ds_read_b128 v[170:173], v149 offset:1024
	ds_read_b128 v[174:177], v149 offset:2048
	ds_read_b128 v[178:181], v149 offset:3072
	s_add_u32 s68, s68, 0x40000
	s_addc_u32 s69, s69, 0
	s_mov_b32 m0, s77
	s_nop 0
	global_load_lds_dwordx4 v[218:219], off
	s_mov_b32 m0, s78
	s_nop 0
	global_load_lds_dwordx4 v[220:221], off
	s_mov_b32 m0, s79
	v_lshl_add_u64 v[222:223], s[68:69], 0, v[132:133]
	ds_read_b128 v[182:185], v145 offset:32768
	ds_read_b128 v[186:189], v145 offset:33792
	ds_read_b128 v[190:193], v145 offset:34816
	ds_read_b128 v[194:197], v145 offset:35840
	ds_read_b128 v[198:201], v145 offset:36864
	ds_read_b128 v[202:205], v145 offset:37888
	ds_read_b128 v[206:209], v145 offset:38912
	ds_read_b128 v[210:213], v145 offset:39936
	global_load_lds_dwordx4 v[222:223], off
	v_lshl_add_u64 v[222:223], s[68:69], 0, v[134:135]
	s_mov_b32 m0, s80
	s_nop 0
	global_load_lds_dwordx4 v[222:223], off
	s_waitcnt vmcnt(8)
	s_waitcnt lgkmcnt(0)
	s_barrier
; #define PG8_STAGE(bufoff, gbase, voff) do { _Pragma("unroll") for (int _i = 0; _i < 2; ++_i) \
;         __builtin_amdgcn_global_load_lds((const unsigned*)((const char*)(gbase) + (voff)[_i]), (PG8_LAS unsigned*)(lds + (bufoff) + ldsw + _i * 8192), 16, 0, 0); } while (0)
; #define PG8_LDA(dst, b, h) do { _Pragma("unroll") for (int m = 0; m < 4; ++m) _Pragma("unroll") for (int k = 0; k < 2; ++k) dst[m][k] = *(const PG8_LAS bf16x8*)(lds + PG8_SA(b, h) + aoff + m * 2048 + k * 1024); } while (0)
; #define PG8_MMA(ai, bj, At, Bt) do { __builtin_amdgcn_s_setprio(1); _Pragma("unroll") for (int m = 0; m < 4; ++m) _Pragma("unroll") for (int n = 0; n < 2; ++n) _Pragma("unroll") for (int k = 0; k < 2; ++k) \
;         acc[ai][bj][m][n] = __builtin_amdgcn_mfma_f32_16x16x32_bf16(Bt[n][k], At[m][k], acc[ai][bj][m][n], 0, 0, 0); __builtin_amdgcn_s_setprio(0); } while (0)
; #define PG8_WAIT_V(n) asm volatile("s_waitcnt vmcnt(" #n ")" ::: "memory")
; #define PG8_WAIT_L(n) asm volatile("s_waitcnt lgkmcnt(" #n ")" ::: "memory")
; #define PG8_BAR __builtin_amdgcn_s_barrier()
; #define PG8_SCHED __builtin_amdgcn_sched_barrier(0)
; template <class Epi, class Sched, bool ALIGN_EPI = false, bool SP2 = false>
; __device__ __forceinline__ void gemm_phase(PG8_LAS unsigned char* lds, const Gemm g, const Sched& S, const Epi& E) {
;     ...
;             PG8_WAIT_V(8); PG8_WAIT_L(0); PG8_BAR; PG8_MMA(0, 0, At, B0); PG8_MMA(0, 1, At, B1); PG8_BAR; PG8_SCHED;
;             PG8_LDA(At, 1, 1); PG8_STAGE(PG8_SB(1, 0), b3, voffB); PG8_STAGE(PG8_SB(1, 1), b3 + hstep, voffB); PG8_STAGE(PG8_SA(1, 0), a3, voffA);
;             PG8_WAIT_V(8); PG8_WAIT_L(0); PG8_BAR; PG8_MMA(1, 0, At, B0); PG8_MMA(1, 1, At, B1); PG8_BAR; PG8_SCHED;
;     ...
;         if constexpr (ALIGN_EPI) { if (wr == 0) PG8_BAR; }
	s_setprio 1
	s_waitcnt lgkmcnt(0)
	v_mfma_f32_16x16x32_bf16 v[126:129], v[150:153], v[182:185], v[126:129]
	v_mfma_f32_16x16x32_bf16 v[122:125], v[158:161], v[182:185], v[122:125]
	v_mfma_f32_16x16x32_bf16 v[118:121], v[150:153], v[190:193], v[118:121]
	v_mfma_f32_16x16x32_bf16 v[114:117], v[158:161], v[190:193], v[114:117]
	v_mfma_f32_16x16x32_bf16 v[102:105], v[150:153], v[198:201], v[102:105]
	v_mfma_f32_16x16x32_bf16 v[98:101], v[158:161], v[198:201], v[98:101]
	v_mfma_f32_16x16x32_bf16 v[86:89], v[150:153], v[206:209], v[86:89]
	v_mfma_f32_16x16x32_bf16 v[82:85], v[158:161], v[206:209], v[82:85]
	v_mfma_f32_16x16x32_bf16 v[126:129], v[154:157], v[186:189], v[126:129]
	v_mfma_f32_16x16x32_bf16 v[122:125], v[162:165], v[186:189], v[122:125]
	v_mfma_f32_16x16x32_bf16 v[118:121], v[154:157], v[194:197], v[118:121]
	v_mfma_f32_16x16x32_bf16 v[114:117], v[162:165], v[194:197], v[114:117]
	v_mfma_f32_16x16x32_bf16 v[102:105], v[154:157], v[202:205], v[102:105]
	v_mfma_f32_16x16x32_bf16 v[98:101], v[162:165], v[202:205], v[98:101]
	v_mfma_f32_16x16x32_bf16 v[86:89], v[154:157], v[210:213], v[86:89]
	v_mfma_f32_16x16x32_bf16 v[82:85], v[162:165], v[210:213], v[82:85]
	s_setprio 0
	s_setprio 1
	v_mfma_f32_16x16x32_bf16 v[110:113], v[166:169], v[182:185], v[110:113]
	v_mfma_f32_16x16x32_bf16 v[106:109], v[174:177], v[182:185], v[106:109]
	v_mfma_f32_16x16x32_bf16 v[94:97], v[166:169], v[190:193], v[94:97]
	v_mfma_f32_16x16x32_bf16 v[90:93], v[174:177], v[190:193], v[90:93]
	v_mfma_f32_16x16x32_bf16 v[78:81], v[166:169], v[198:201], v[78:81]
	v_mfma_f32_16x16x32_bf16 v[74:77], v[174:177], v[198:201], v[74:77]
	v_mfma_f32_16x16x32_bf16 v[70:73], v[166:169], v[206:209], v[70:73]
	v_mfma_f32_16x16x32_bf16 v[66:69], v[174:177], v[206:209], v[66:69]
	v_mfma_f32_16x16x32_bf16 v[110:113], v[170:173], v[186:189], v[110:113]
	v_mfma_f32_16x16x32_bf16 v[106:109], v[178:181], v[186:189], v[106:109]
	v_mfma_f32_16x16x32_bf16 v[94:97], v[170:173], v[194:197], v[94:97]
	v_mfma_f32_16x16x32_bf16 v[90:93], v[178:181], v[194:197], v[90:93]
	v_mfma_f32_16x16x32_bf16 v[78:81], v[170:173], v[202:205], v[78:81]
	v_mfma_f32_16x16x32_bf16 v[74:77], v[178:181], v[202:205], v[74:77]
	v_mfma_f32_16x16x32_bf16 v[70:73], v[170:173], v[210:213], v[70:73]
	v_mfma_f32_16x16x32_bf16 v[66:69], v[178:181], v[210:213], v[66:69]
	s_setprio 0
	s_barrier
	s_mov_b32 m0, s48
	v_lshl_add_u64 v[214:215], v[214:215], 0, s[16:17]
	s_add_u32 s60, s60, 0x40080
	ds_read_b128 v[182:185], v145 offset:49152
	ds_read_b128 v[186:189], v145 offset:50176
	ds_read_b128 v[190:193], v145 offset:51200
	ds_read_b128 v[194:197], v145 offset:52224
	ds_read_b128 v[198:201], v145 offset:53248
	ds_read_b128 v[202:205], v145 offset:54272
	ds_read_b128 v[206:209], v145 offset:55296
	ds_read_b128 v[210:213], v145 offset:56320
	global_load_lds_dwordx4 v[214:215], off
	v_lshl_add_u64 v[214:215], v[216:217], 0, s[16:17]
	s_mov_b32 m0, s49
	s_addc_u32 s61, s61, 0
	global_load_lds_dwordx4 v[214:215], off
	v_lshl_add_u64 v[214:215], s[60:61], 0, v[130:131]
	s_mov_b32 m0, s82
	s_nop 0
	global_load_lds_dwordx4 v[214:215], off
	v_lshl_add_u64 v[214:215], s[60:61], 0, v[136:137]
	s_mov_b32 m0, s83
	s_nop 0
	global_load_lds_dwordx4 v[214:215], off
	v_lshl_add_u64 v[214:215], v[218:219], 0, s[16:17]
	s_mov_b32 m0, s50
	s_nop 0
	global_load_lds_dwordx4 v[214:215], off
	v_lshl_add_u64 v[214:215], v[220:221], 0, s[16:17]
	s_mov_b32 m0, s51
	s_nop 0
	global_load_lds_dwordx4 v[214:215], off
	s_waitcnt vmcnt(8)
	s_waitcnt lgkmcnt(0)
	s_barrier
	s_setprio 1
	s_waitcnt lgkmcnt(0)
	v_mfma_f32_16x16x32_bf16 v[62:65], v[150:153], v[182:185], v[62:65]
	v_mfma_f32_16x16x32_bf16 v[58:61], v[158:161], v[182:185], v[58:61]
	v_mfma_f32_16x16x32_bf16 v[54:57], v[150:153], v[190:193], v[54:57]
	v_mfma_f32_16x16x32_bf16 v[50:53], v[158:161], v[190:193], v[50:53]
	v_mfma_f32_16x16x32_bf16 v[38:41], v[150:153], v[198:201], v[38:41]
	v_mfma_f32_16x16x32_bf16 v[34:37], v[158:161], v[198:201], v[34:37]
	v_mfma_f32_16x16x32_bf16 v[22:25], v[150:153], v[206:209], v[22:25]
	v_mfma_f32_16x16x32_bf16 v[18:21], v[158:161], v[206:209], v[18:21]
	v_mfma_f32_16x16x32_bf16 v[62:65], v[154:157], v[186:189], v[62:65]
	v_mfma_f32_16x16x32_bf16 v[58:61], v[162:165], v[186:189], v[58:61]
	v_mfma_f32_16x16x32_bf16 v[54:57], v[154:157], v[194:197], v[54:57]
	v_mfma_f32_16x16x32_bf16 v[50:53], v[162:165], v[194:197], v[50:53]
	v_mfma_f32_16x16x32_bf16 v[38:41], v[154:157], v[202:205], v[38:41]
	v_mfma_f32_16x16x32_bf16 v[34:37], v[162:165], v[202:205], v[34:37]
	v_mfma_f32_16x16x32_bf16 v[22:25], v[154:157], v[210:213], v[22:25]
	v_mfma_f32_16x16x32_bf16 v[18:21], v[162:165], v[210:213], v[18:21]
	s_setprio 0
	s_setprio 1
	v_mfma_f32_16x16x32_bf16 v[46:49], v[166:169], v[182:185], v[46:49]
	v_mfma_f32_16x16x32_bf16 v[42:45], v[174:177], v[182:185], v[42:45]
	v_mfma_f32_16x16x32_bf16 v[30:33], v[166:169], v[190:193], v[30:33]
	v_mfma_f32_16x16x32_bf16 v[26:29], v[174:177], v[190:193], v[26:29]
	v_mfma_f32_16x16x32_bf16 v[14:17], v[166:169], v[198:201], v[14:17]
	v_mfma_f32_16x16x32_bf16 v[10:13], v[174:177], v[198:201], v[10:13]
	v_mfma_f32_16x16x32_bf16 v[6:9], v[166:169], v[206:209], v[6:9]
	v_mfma_f32_16x16x32_bf16 v[2:5], v[174:177], v[206:209], v[2:5]
	v_mfma_f32_16x16x32_bf16 v[46:49], v[170:173], v[186:189], v[46:49]
	v_mfma_f32_16x16x32_bf16 v[42:45], v[178:181], v[186:189], v[42:45]
	v_mfma_f32_16x16x32_bf16 v[30:33], v[170:173], v[194:197], v[30:33]
	v_mfma_f32_16x16x32_bf16 v[26:29], v[178:181], v[194:197], v[26:29]
	v_mfma_f32_16x16x32_bf16 v[14:17], v[170:173], v[202:205], v[14:17]
	v_mfma_f32_16x16x32_bf16 v[10:13], v[178:181], v[202:205], v[10:13]
	v_mfma_f32_16x16x32_bf16 v[6:9], v[170:173], v[210:213], v[6:9]
	v_mfma_f32_16x16x32_bf16 v[2:5], v[178:181], v[210:213], v[2:5]
	s_setprio 0
	s_barrier
	s_add_u32 s43, s43, 0x100
	s_addc_u32 s45, s45, 0
	s_add_u32 s56, s56, 0x100
	s_addc_u32 s57, s57, 0
	s_cmp_ge_u32 s88, s81
	s_mov_b32 s59, s88
	s_cbranch_scc0 .LBB0_859
	s_and_b64 vcc, exec, s[40:41]
	s_cbranch_vccz .LBB0_862
	s_barrier

; #define PG8_STAGE(bufoff, gbase, voff) do { _Pragma("unroll") for (int _i = 0; _i < 2; ++_i) \
;         __builtin_amdgcn_global_load_lds((const unsigned*)((const char*)(gbase) + (voff)[_i]), (PG8_LAS unsigned*)(lds + (bufoff) + ldsw + _i * 8192), 16, 0, 0); } while (0)
; #define PG8_LDA(dst, b, h) do { _Pragma("unroll") for (int m = 0; m < 4; ++m) _Pragma("unroll") for (int k = 0; k < 2; ++k) dst[m][k] = *(const PG8_LAS bf16x8*)(lds + PG8_SA(b, h) + aoff + m * 2048 + k * 1024); } while (0)
; #define PG8_LDB(dst, b, h) do { _Pragma("unroll") for (int n = 0; n < 2; ++n) _Pragma("unroll") for (int k = 0; k < 2; ++k) dst[n][k] = *(const PG8_LAS bf16x8*)(lds + PG8_SB(b, h) + boff + n * 2048 + k * 1024); } while (0)
; #define PG8_WAIT_V(n) asm volatile("s_waitcnt vmcnt(" #n ")" ::: "memory")
; #define PG8_WAIT_L(n) asm volatile("s_waitcnt lgkmcnt(" #n ")" ::: "memory")
; #define PG8_BAR __builtin_amdgcn_s_barrier()
; #define PG8_SCHED __builtin_amdgcn_sched_barrier(0)
; template <class Epi, class Sched, bool ALIGN_EPI = false, bool SP2 = false>
; __device__ __forceinline__ void gemm_phase(PG8_LAS unsigned char* lds, const Gemm g, const Sched& S, const Epi& E) {
;     ...
;         const char* nA = has_next ? (const char*)g.A + (size_t)nxt.pm * tstep + (size_t)nxt.ks * K * 2 : cA; const char* nB = has_next ? (const char*)g.Bt + (size_t)nxt.pn * tstep + (size_t)nxt.ks * K * 2 : cB;
;         for (int t = 0; t < nt; t += 2) {
;             const bool last = (t == nt - 2);
;             const char* a1 = cA + (size_t)(t + 1) * kstep;
;             const char* a2 = last ? nA : cA + (size_t)(t + 2) * kstep; const char* b2 = last ? nB : cB + (size_t)(t + 2) * kstep;
;             const char* a3 = a2 + kstep; const char* b3 = b2 + kstep;
;             if (last && has_next) S.a_ready(nxt);
;             if constexpr (SP2) {
;             PG8_LDB(B0, 0, 0); PG8_LDB(B1, 0, 1); PG8_SCHED; PG8_LDA(At, 0, 0); PG8_STAGE(PG8_SA(1, 1), a1 + hstep, voffA);
;             PG8_WAIT_V(8); PG8_WAIT_L(0); PG8_BAR; PG8_MMA(0, 0, At, B0); PG8_MMA(0, 1, At, B1); PG8_BAR; PG8_SCHED;
;             PG8_LDA(At, 0, 1); PG8_STAGE(PG8_SB(0, 0), b2, voffB); PG8_STAGE(PG8_SB(0, 1), b2 + hstep, voffB); PG8_STAGE(PG8_SA(0, 0), a2, voffA);
;             PG8_WAIT_V(8); PG8_WAIT_L(0); PG8_BAR; PG8_MMA(1, 0, At, B0); PG8_MMA(1, 1, At, B1); PG8_BAR; PG8_SCHED;
.LBB0_1037:
	s_ashr_i32 s13, s12, 31
	s_lshl_b64 s[14:15], s[12:13], 19
	s_add_u32 s14, s28, s14
	s_addc_u32 s15, s29, s15
	s_and_b64 s[16:17], s[2:3], exec
	s_cselect_b32 s13, s15, s23
	s_cselect_b32 s48, s14, s22
	s_ashr_i32 s11, s10, 31
	s_lshl_b64 s[16:17], s[10:11], 19
	s_add_u32 s16, s30, s16
	s_addc_u32 s17, s31, s17
	s_and_b64 s[24:25], s[2:3], exec
	s_cselect_b32 s11, s17, s21
	s_cselect_b32 s49, s16, s20
	s_add_u32 s50, s20, 0x100
	s_addc_u32 s51, s21, 0
	s_add_u32 s20, s22, 0x40080
	s_addc_u32 s21, s23, 0
	s_mov_b32 s54, -2
	ds_read_b128 v[146:149], v152
	ds_read_b128 v[158:161], v152 offset:1024
	ds_read_b128 v[162:165], v152 offset:2048
	ds_read_b128 v[166:169], v152 offset:3072
	ds_read_b128 v[170:173], v153
	ds_read_b128 v[174:177], v153 offset:1024
	ds_read_b128 v[178:181], v153 offset:2048
	ds_read_b128 v[182:185], v153 offset:3072
	s_add_u32 s22, s20, 0xfffc0080
	s_addc_u32 s23, s21, -1
	s_cmp_eq_u32 s54, 12
	s_cselect_b32 s25, s13, s23
	s_cselect_b32 s24, s48, s22
	s_cselect_b32 s23, s11, s51
	s_cselect_b32 s22, s49, s50
	v_lshl_add_u64 v[218:219], s[20:21], 0, v[140:141]
	s_add_i32 m0, s41, 0xc000
	ds_read_b128 v[186:189], v154
	ds_read_b128 v[190:193], v154 offset:1024
	ds_read_b128 v[194:197], v154 offset:2048
	ds_read_b128 v[198:201], v154 offset:3072
	ds_read_b128 v[202:205], v154 offset:4096
	ds_read_b128 v[206:209], v154 offset:5120
	ds_read_b128 v[210:213], v154 offset:6144
	ds_read_b128 v[214:217], v154 offset:7168
	global_load_lds_dwordx4 v[218:219], off
	v_lshl_add_u64 v[218:219], s[20:21], 0, v[138:139]
	s_add_i32 m0, s41, 0xe000
	s_nop 0
	global_load_lds_dwordx4 v[218:219], off
	s_waitcnt vmcnt(8)
	s_waitcnt lgkmcnt(0)
	s_barrier
	s_setprio 1
	s_waitcnt lgkmcnt(0)
	v_mfma_f32_16x16x32_bf16 v[126:129], v[146:149], v[186:189], 0
	v_mfma_f32_16x16x32_bf16 v[118:121], v[162:165], v[186:189], 0
	v_mfma_f32_16x16x32_bf16 v[110:113], v[146:149], v[194:197], 0
	v_mfma_f32_16x16x32_bf16 v[102:105], v[162:165], v[194:197], 0
	v_mfma_f32_16x16x32_bf16 v[94:97], v[146:149], v[202:205], 0
	v_mfma_f32_16x16x32_bf16 v[86:89], v[162:165], v[202:205], 0
	v_mfma_f32_16x16x32_bf16 v[78:81], v[146:149], v[210:213], 0
	v_mfma_f32_16x16x32_bf16 v[70:73], v[162:165], v[210:213], 0
	v_mfma_f32_16x16x32_bf16 v[126:129], v[158:161], v[190:193], v[126:129]
	v_mfma_f32_16x16x32_bf16 v[118:121], v[166:169], v[190:193], v[118:121]
	v_mfma_f32_16x16x32_bf16 v[110:113], v[158:161], v[198:201], v[110:113]
	v_mfma_f32_16x16x32_bf16 v[102:105], v[166:169], v[198:201], v[102:105]
	v_mfma_f32_16x16x32_bf16 v[94:97], v[158:161], v[206:209], v[94:97]
	v_mfma_f32_16x16x32_bf16 v[86:89], v[166:169], v[206:209], v[86:89]
	v_mfma_f32_16x16x32_bf16 v[78:81], v[158:161], v[214:217], v[78:81]
	v_mfma_f32_16x16x32_bf16 v[70:73], v[166:169], v[214:217], v[70:73]
	s_setprio 0
	s_setprio 1
	v_mfma_f32_16x16x32_bf16 v[122:125], v[170:173], v[186:189], 0
	v_mfma_f32_16x16x32_bf16 v[114:117], v[178:181], v[186:189], 0
	v_mfma_f32_16x16x32_bf16 v[106:109], v[170:173], v[194:197], 0
	v_mfma_f32_16x16x32_bf16 v[98:101], v[178:181], v[194:197], 0
	v_mfma_f32_16x16x32_bf16 v[90:93], v[170:173], v[202:205], 0
	v_mfma_f32_16x16x32_bf16 v[82:85], v[178:181], v[202:205], 0
	v_mfma_f32_16x16x32_bf16 v[74:77], v[170:173], v[210:213], 0
	v_mfma_f32_16x16x32_bf16 v[66:69], v[178:181], v[210:213], 0
	v_mfma_f32_16x16x32_bf16 v[122:125], v[174:177], v[190:193], v[122:125]
	v_mfma_f32_16x16x32_bf16 v[114:117], v[182:185], v[190:193], v[114:117]
	v_mfma_f32_16x16x32_bf16 v[106:109], v[174:177], v[198:201], v[106:109]
	v_mfma_f32_16x16x32_bf16 v[98:101], v[182:185], v[198:201], v[98:101]
	v_mfma_f32_16x16x32_bf16 v[90:93], v[174:177], v[206:209], v[90:93]
	v_mfma_f32_16x16x32_bf16 v[82:85], v[182:185], v[206:209], v[82:85]
	v_mfma_f32_16x16x32_bf16 v[74:77], v[174:177], v[214:217], v[74:77]
	v_mfma_f32_16x16x32_bf16 v[66:69], v[182:185], v[214:217], v[66:69]
	s_setprio 0
	s_barrier
	s_mov_b32 m0, s19
	v_lshl_add_u64 v[218:219], s[22:23], 0, v[134:135]
	s_add_u32 s58, s22, 0x40000
	ds_read_b128 v[186:189], v154 offset:16384
	ds_read_b128 v[190:193], v154 offset:17408
	ds_read_b128 v[194:197], v154 offset:18432
	ds_read_b128 v[198:201], v154 offset:19456
	ds_read_b128 v[202:205], v154 offset:20480
	ds_read_b128 v[206:209], v154 offset:21504
	ds_read_b128 v[210:213], v154 offset:22528
	ds_read_b128 v[214:217], v154 offset:23552
	global_load_lds_dwordx4 v[218:219], off
	v_lshl_add_u64 v[220:221], s[22:23], 0, v[130:131]
	s_mov_b32 m0, s38
	s_addc_u32 s59, s23, 0
	global_load_lds_dwordx4 v[220:221], off
	v_lshl_add_u64 v[222:223], s[58:59], 0, v[134:135]
	s_mov_b32 m0, s39
	v_lshl_add_u64 v[224:225], s[24:25], 0, v[132:133]
	global_load_lds_dwordx4 v[222:223], off
	v_lshl_add_u64 v[222:223], s[58:59], 0, v[130:131]
	s_mov_b32 m0, s40
	s_nop 0
	global_load_lds_dwordx4 v[222:223], off
	v_lshl_add_u64 v[222:223], s[24:25], 0, v[136:137]
	s_waitcnt vmcnt(6)
	s_waitcnt lgkmcnt(0)
	s_barrier
; #define PG8_STAGE(bufoff, gbase, voff) do { _Pragma("unroll") for (int _i = 0; _i < 2; ++_i) \
;         __builtin_amdgcn_global_load_lds((const unsigned*)((const char*)(gbase) + (voff)[_i]), (PG8_LAS unsigned*)(lds + (bufoff) + ldsw + _i * 8192), 16, 0, 0); } while (0)
; #define PG8_LDA(dst, b, h) do { _Pragma("unroll") for (int m = 0; m < 4; ++m) _Pragma("unroll") for (int k = 0; k < 2; ++k) dst[m][k] = *(const PG8_LAS bf16x8*)(lds + PG8_SA(b, h) + aoff + m * 2048 + k * 1024); } while (0)
; #define PG8_LDB(dst, b, h) do { _Pragma("unroll") for (int n = 0; n < 2; ++n) _Pragma("unroll") for (int k = 0; k < 2; ++k) dst[n][k] = *(const PG8_LAS bf16x8*)(lds + PG8_SB(b, h) + boff + n * 2048 + k * 1024); } while (0)
; #define PG8_MMA(ai, bj, At, Bt) do { __builtin_amdgcn_s_setprio(1); _Pragma("unroll") for (int m = 0; m < 4; ++m) _Pragma("unroll") for (int n = 0; n < 2; ++n) _Pragma("unroll") for (int k = 0; k < 2; ++k) \
;         acc[ai][bj][m][n] = __builtin_amdgcn_mfma_f32_16x16x32_bf16(Bt[n][k], At[m][k], acc[ai][bj][m][n], 0, 0, 0); __builtin_amdgcn_s_setprio(0); } while (0)
; #define PG8_WAIT_V(n) asm volatile("s_waitcnt vmcnt(" #n ")" ::: "memory")
; #define PG8_WAIT_L(n) asm volatile("s_waitcnt lgkmcnt(" #n ")" ::: "memory")
; #define PG8_BAR __builtin_amdgcn_s_barrier()
; #define PG8_SCHED __builtin_amdgcn_sched_barrier(0)
; template <class Epi, class Sched, bool ALIGN_EPI = false, bool SP2 = false>
; __device__ __forceinline__ void gemm_phase(PG8_LAS unsigned char* lds, const Gemm g, const Sched& S, const Epi& E) {
;     ...
;             PG8_WAIT_V(8); PG8_WAIT_L(0); PG8_BAR; PG8_MMA(1, 0, At, B0); PG8_MMA(1, 1, At, B1); PG8_BAR; PG8_SCHED;
;             PG8_LDB(B0, 1, 0); PG8_LDB(B1, 1, 1); PG8_SCHED; PG8_LDA(At, 1, 0); PG8_STAGE(PG8_SA(0, 1), a2 + hstep, voffA);
;             PG8_WAIT_V(8); PG8_WAIT_L(0); PG8_BAR; PG8_MMA(0, 0, At, B0); PG8_MMA(0, 1, At, B1); PG8_BAR; PG8_SCHED;
	s_setprio 1
	s_waitcnt lgkmcnt(0)
	v_mfma_f32_16x16x32_bf16 v[62:65], v[146:149], v[186:189], 0
	v_mfma_f32_16x16x32_bf16 v[54:57], v[162:165], v[186:189], 0
	v_mfma_f32_16x16x32_bf16 v[46:49], v[146:149], v[194:197], 0
	v_mfma_f32_16x16x32_bf16 v[38:41], v[162:165], v[194:197], 0
	v_mfma_f32_16x16x32_bf16 v[30:33], v[146:149], v[202:205], 0
	v_mfma_f32_16x16x32_bf16 v[22:25], v[162:165], v[202:205], 0
	v_mfma_f32_16x16x32_bf16 v[14:17], v[146:149], v[210:213], 0
	v_mfma_f32_16x16x32_bf16 v[6:9], v[162:165], v[210:213], 0
	v_mfma_f32_16x16x32_bf16 v[62:65], v[158:161], v[190:193], v[62:65]
	v_mfma_f32_16x16x32_bf16 v[54:57], v[166:169], v[190:193], v[54:57]
	v_mfma_f32_16x16x32_bf16 v[46:49], v[158:161], v[198:201], v[46:49]
	v_mfma_f32_16x16x32_bf16 v[38:41], v[166:169], v[198:201], v[38:41]
	v_mfma_f32_16x16x32_bf16 v[30:33], v[158:161], v[206:209], v[30:33]
	v_mfma_f32_16x16x32_bf16 v[22:25], v[166:169], v[206:209], v[22:25]
	v_mfma_f32_16x16x32_bf16 v[14:17], v[158:161], v[214:217], v[14:17]
	v_mfma_f32_16x16x32_bf16 v[6:9], v[166:169], v[214:217], v[6:9]
	s_setprio 0
	s_setprio 1
	v_mfma_f32_16x16x32_bf16 v[58:61], v[170:173], v[186:189], 0
	v_mfma_f32_16x16x32_bf16 v[50:53], v[178:181], v[186:189], 0
	v_mfma_f32_16x16x32_bf16 v[42:45], v[170:173], v[194:197], 0
	v_mfma_f32_16x16x32_bf16 v[34:37], v[178:181], v[194:197], 0
	v_mfma_f32_16x16x32_bf16 v[26:29], v[170:173], v[202:205], 0
	v_mfma_f32_16x16x32_bf16 v[18:21], v[178:181], v[202:205], 0
	v_mfma_f32_16x16x32_bf16 v[10:13], v[170:173], v[210:213], 0
	v_mfma_f32_16x16x32_bf16 v[2:5], v[178:181], v[210:213], 0
	v_mfma_f32_16x16x32_bf16 v[58:61], v[174:177], v[190:193], v[58:61]
	v_mfma_f32_16x16x32_bf16 v[50:53], v[182:185], v[190:193], v[50:53]
	v_mfma_f32_16x16x32_bf16 v[42:45], v[174:177], v[198:201], v[42:45]
	v_mfma_f32_16x16x32_bf16 v[34:37], v[182:185], v[198:201], v[34:37]
	v_mfma_f32_16x16x32_bf16 v[26:29], v[174:177], v[206:209], v[26:29]
	v_mfma_f32_16x16x32_bf16 v[18:21], v[182:185], v[206:209], v[18:21]
	v_mfma_f32_16x16x32_bf16 v[10:13], v[174:177], v[214:217], v[10:13]
	v_mfma_f32_16x16x32_bf16 v[2:5], v[182:185], v[214:217], v[2:5]
	s_setprio 0
	s_barrier
	ds_read_b128 v[146:149], v155
	ds_read_b128 v[158:161], v155 offset:1024
	ds_read_b128 v[162:165], v155 offset:2048
	ds_read_b128 v[166:169], v155 offset:3072
	ds_read_b128 v[170:173], v156
	ds_read_b128 v[174:177], v156 offset:1024
	ds_read_b128 v[178:181], v156 offset:2048
	ds_read_b128 v[182:185], v156 offset:3072
	s_add_u32 s24, s24, 0x40000
	s_addc_u32 s25, s25, 0
	s_mov_b32 m0, s41
	s_nop 0
	global_load_lds_dwordx4 v[222:223], off
	s_mov_b32 m0, s42
	s_nop 0
	global_load_lds_dwordx4 v[224:225], off
	s_mov_b32 m0, s43
	v_lshl_add_u64 v[226:227], s[24:25], 0, v[136:137]
	ds_read_b128 v[186:189], v154 offset:32768
	ds_read_b128 v[190:193], v154 offset:33792
	ds_read_b128 v[194:197], v154 offset:34816
	ds_read_b128 v[198:201], v154 offset:35840
	ds_read_b128 v[202:205], v154 offset:36864
	ds_read_b128 v[206:209], v154 offset:37888
	ds_read_b128 v[210:213], v154 offset:38912
	ds_read_b128 v[214:217], v154 offset:39936
	global_load_lds_dwordx4 v[226:227], off
	v_lshl_add_u64 v[226:227], s[24:25], 0, v[132:133]
	s_mov_b32 m0, s44
	s_nop 0
	global_load_lds_dwordx4 v[226:227], off
	s_waitcnt vmcnt(8)
	s_waitcnt lgkmcnt(0)
	s_barrier
	s_setprio 1
	s_waitcnt lgkmcnt(0)
	v_mfma_f32_16x16x32_bf16 v[126:129], v[146:149], v[186:189], v[126:129]
	v_mfma_f32_16x16x32_bf16 v[118:121], v[162:165], v[186:189], v[118:121]
	v_mfma_f32_16x16x32_bf16 v[110:113], v[146:149], v[194:197], v[110:113]
	v_mfma_f32_16x16x32_bf16 v[102:105], v[162:165], v[194:197], v[102:105]
	v_mfma_f32_16x16x32_bf16 v[94:97], v[146:149], v[202:205], v[94:97]
	v_mfma_f32_16x16x32_bf16 v[86:89], v[162:165], v[202:205], v[86:89]
	v_mfma_f32_16x16x32_bf16 v[78:81], v[146:149], v[210:213], v[78:81]
	v_mfma_f32_16x16x32_bf16 v[70:73], v[162:165], v[210:213], v[70:73]
	v_mfma_f32_16x16x32_bf16 v[126:129], v[158:161], v[190:193], v[126:129]
	v_mfma_f32_16x16x32_bf16 v[118:121], v[166:169], v[190:193], v[118:121]
	v_mfma_f32_16x16x32_bf16 v[110:113], v[158:161], v[198:201], v[110:113]
	v_mfma_f32_16x16x32_bf16 v[102:105], v[166:169], v[198:201], v[102:105]
	v_mfma_f32_16x16x32_bf16 v[94:97], v[158:161], v[206:209], v[94:97]
	v_mfma_f32_16x16x32_bf16 v[86:89], v[166:169], v[206:209], v[86:89]
	v_mfma_f32_16x16x32_bf16 v[78:81], v[158:161], v[214:217], v[78:81]
	v_mfma_f32_16x16x32_bf16 v[70:73], v[166:169], v[214:217], v[70:73]
	s_setprio 0
	s_setprio 1
	v_mfma_f32_16x16x32_bf16 v[122:125], v[170:173], v[186:189], v[122:125]
	v_mfma_f32_16x16x32_bf16 v[114:117], v[178:181], v[186:189], v[114:117]
	v_mfma_f32_16x16x32_bf16 v[106:109], v[170:173], v[194:197], v[106:109]
	v_mfma_f32_16x16x32_bf16 v[98:101], v[178:181], v[194:197], v[98:101]
	v_mfma_f32_16x16x32_bf16 v[90:93], v[170:173], v[202:205], v[90:93]
	v_mfma_f32_16x16x32_bf16 v[82:85], v[178:181], v[202:205], v[82:85]
	v_mfma_f32_16x16x32_bf16 v[74:77], v[170:173], v[210:213], v[74:77]
	v_mfma_f32_16x16x32_bf16 v[66:69], v[178:181], v[210:213], v[66:69]
	v_mfma_f32_16x16x32_bf16 v[122:125], v[174:177], v[190:193], v[122:125]
	v_mfma_f32_16x16x32_bf16 v[114:117], v[182:185], v[190:193], v[114:117]
	v_mfma_f32_16x16x32_bf16 v[106:109], v[174:177], v[198:201], v[106:109]
	v_mfma_f32_16x16x32_bf16 v[98:101], v[182:185], v[198:201], v[98:101]
	v_mfma_f32_16x16x32_bf16 v[90:93], v[174:177], v[206:209], v[90:93]
	v_mfma_f32_16x16x32_bf16 v[82:85], v[182:185], v[206:209], v[82:85]
	v_mfma_f32_16x16x32_bf16 v[74:77], v[174:177], v[214:217], v[74:77]
	v_mfma_f32_16x16x32_bf16 v[66:69], v[182:185], v[214:217], v[66:69]
	s_setprio 0
	s_barrier
; #define PG8_STAGE(bufoff, gbase, voff) do { _Pragma("unroll") for (int _i = 0; _i < 2; ++_i) \
;         __builtin_amdgcn_global_load_lds((const unsigned*)((const char*)(gbase) + (voff)[_i]), (PG8_LAS unsigned*)(lds + (bufoff) + ldsw + _i * 8192), 16, 0, 0); } while (0)
; #define PG8_LDA(dst, b, h) do { _Pragma("unroll") for (int m = 0; m < 4; ++m) _Pragma("unroll") for (int k = 0; k < 2; ++k) dst[m][k] = *(const PG8_LAS bf16x8*)(lds + PG8_SA(b, h) + aoff + m * 2048 + k * 1024); } while (0)
; #define PG8_LDB(dst, b, h) do { _Pragma("unroll") for (int n = 0; n < 2; ++n) _Pragma("unroll") for (int k = 0; k < 2; ++k) dst[n][k] = *(const PG8_LAS bf16x8*)(lds + PG8_SB(b, h) + boff + n * 2048 + k * 1024); } while (0)
; #define PG8_MMA(ai, bj, At, Bt) do { __builtin_amdgcn_s_setprio(1); _Pragma("unroll") for (int m = 0; m < 4; ++m) _Pragma("unroll") for (int n = 0; n < 2; ++n) _Pragma("unroll") for (int k = 0; k < 2; ++k) \
;         acc[ai][bj][m][n] = __builtin_amdgcn_mfma_f32_16x16x32_bf16(Bt[n][k], At[m][k], acc[ai][bj][m][n], 0, 0, 0); __builtin_amdgcn_s_setprio(0); } while (0)
; #define PG8_WAIT_V(n) asm volatile("s_waitcnt vmcnt(" #n ")" ::: "memory")
; #define PG8_BAR __builtin_amdgcn_s_barrier()
; template <class Epi, class Sched, bool ALIGN_EPI = false, bool SP2 = false>
; __device__ __forceinline__ void gemm_phase(PG8_LAS unsigned char* lds, const Gemm g, const Sched& S, const Epi& E) {
;     ...
;         for (int t = 0; t < nt; t += 2) {
;             const bool last = (t == nt - 2);
;             const char* a1 = cA + (size_t)(t + 1) * kstep;
;             const char* a2 = last ? nA : cA + (size_t)(t + 2) * kstep; const char* b2 = last ? nB : cB + (size_t)(t + 2) * kstep;
;             const char* a3 = a2 + kstep; const char* b3 = b2 + kstep;
;             if (last && has_next) S.a_ready(nxt);
;             if constexpr (SP2) {
;             PG8_LDB(B0, 0, 0); PG8_LDB(B1, 0, 1); PG8_SCHED; PG8_LDA(At, 0, 0); PG8_STAGE(PG8_SA(1, 1), a1 + hstep, voffA);
;             PG8_WAIT_V(8); PG8_WAIT_L(0); PG8_BAR; PG8_MMA(0, 0, At, B0); PG8_MMA(0, 1, At, B1); PG8_BAR; PG8_SCHED;
;     ...
;             PG8_LDA(At, 1, 1); PG8_STAGE(PG8_SB(1, 0), b3, voffB); PG8_STAGE(PG8_SB(1, 1), b3 + hstep, voffB); PG8_STAGE(PG8_SA(1, 0), a3, voffA);
;             PG8_WAIT_V(8); PG8_WAIT_L(0); PG8_BAR; PG8_MMA(1, 0, At, B0); PG8_MMA(1, 1, At, B1); PG8_BAR; PG8_SCHED;
	s_mov_b32 m0, s45
	v_lshl_add_u64 v[218:219], v[218:219], 0, s[6:7]
	s_add_u32 s22, s22, 0x40080
	ds_read_b128 v[186:189], v154 offset:49152
	ds_read_b128 v[190:193], v154 offset:50176
	ds_read_b128 v[194:197], v154 offset:51200
	ds_read_b128 v[198:201], v154 offset:52224
	ds_read_b128 v[202:205], v154 offset:53248
	ds_read_b128 v[206:209], v154 offset:54272
	ds_read_b128 v[210:213], v154 offset:55296
	ds_read_b128 v[214:217], v154 offset:56320
	global_load_lds_dwordx4 v[218:219], off
	v_lshl_add_u64 v[218:219], v[220:221], 0, s[6:7]
	s_mov_b32 m0, s46
	s_addc_u32 s23, s23, 0
	global_load_lds_dwordx4 v[218:219], off
	v_lshl_add_u64 v[218:219], s[22:23], 0, v[134:135]
	s_mov_b32 m0, s53
	s_nop 0
	global_load_lds_dwordx4 v[218:219], off
	v_lshl_add_u64 v[218:219], s[22:23], 0, v[130:131]
	s_mov_b32 m0, s56
	s_nop 0
	global_load_lds_dwordx4 v[218:219], off
	v_lshl_add_u64 v[218:219], v[222:223], 0, s[6:7]
	s_mov_b32 m0, s47
	s_nop 0
	global_load_lds_dwordx4 v[218:219], off
	v_lshl_add_u64 v[218:219], v[224:225], 0, s[6:7]
	s_mov_b32 m0, s52
	s_nop 0
	global_load_lds_dwordx4 v[218:219], off
	s_waitcnt vmcnt(8)
	s_waitcnt lgkmcnt(0)
	s_barrier
	s_setprio 1
	s_waitcnt lgkmcnt(0)
	v_mfma_f32_16x16x32_bf16 v[62:65], v[146:149], v[186:189], v[62:65]
	v_mfma_f32_16x16x32_bf16 v[54:57], v[162:165], v[186:189], v[54:57]
	v_mfma_f32_16x16x32_bf16 v[46:49], v[146:149], v[194:197], v[46:49]
	v_mfma_f32_16x16x32_bf16 v[38:41], v[162:165], v[194:197], v[38:41]
	v_mfma_f32_16x16x32_bf16 v[30:33], v[146:149], v[202:205], v[30:33]
	v_mfma_f32_16x16x32_bf16 v[22:25], v[162:165], v[202:205], v[22:25]
	v_mfma_f32_16x16x32_bf16 v[14:17], v[146:149], v[210:213], v[14:17]
	v_mfma_f32_16x16x32_bf16 v[6:9], v[162:165], v[210:213], v[6:9]
	v_mfma_f32_16x16x32_bf16 v[62:65], v[158:161], v[190:193], v[62:65]
	v_mfma_f32_16x16x32_bf16 v[54:57], v[166:169], v[190:193], v[54:57]
	v_mfma_f32_16x16x32_bf16 v[46:49], v[158:161], v[198:201], v[46:49]
	v_mfma_f32_16x16x32_bf16 v[38:41], v[166:169], v[198:201], v[38:41]
	v_mfma_f32_16x16x32_bf16 v[30:33], v[158:161], v[206:209], v[30:33]
	v_mfma_f32_16x16x32_bf16 v[22:25], v[166:169], v[206:209], v[22:25]
	v_mfma_f32_16x16x32_bf16 v[14:17], v[158:161], v[214:217], v[14:17]
	v_mfma_f32_16x16x32_bf16 v[6:9], v[166:169], v[214:217], v[6:9]
	s_setprio 0
	s_setprio 1
	v_mfma_f32_16x16x32_bf16 v[58:61], v[170:173], v[186:189], v[58:61]
	v_mfma_f32_16x16x32_bf16 v[50:53], v[178:181], v[186:189], v[50:53]
	v_mfma_f32_16x16x32_bf16 v[42:45], v[170:173], v[194:197], v[42:45]
	v_mfma_f32_16x16x32_bf16 v[34:37], v[178:181], v[194:197], v[34:37]
	v_mfma_f32_16x16x32_bf16 v[26:29], v[170:173], v[202:205], v[26:29]
	v_mfma_f32_16x16x32_bf16 v[18:21], v[178:181], v[202:205], v[18:21]
	v_mfma_f32_16x16x32_bf16 v[10:13], v[170:173], v[210:213], v[10:13]
	v_mfma_f32_16x16x32_bf16 v[2:5], v[178:181], v[210:213], v[2:5]
	v_mfma_f32_16x16x32_bf16 v[58:61], v[174:177], v[190:193], v[58:61]
	v_mfma_f32_16x16x32_bf16 v[50:53], v[182:185], v[190:193], v[50:53]
	v_mfma_f32_16x16x32_bf16 v[42:45], v[174:177], v[198:201], v[42:45]
	v_mfma_f32_16x16x32_bf16 v[34:37], v[182:185], v[198:201], v[34:37]
	v_mfma_f32_16x16x32_bf16 v[26:29], v[174:177], v[206:209], v[26:29]
	v_mfma_f32_16x16x32_bf16 v[18:21], v[182:185], v[206:209], v[18:21]
	v_mfma_f32_16x16x32_bf16 v[10:13], v[174:177], v[214:217], v[10:13]
	v_mfma_f32_16x16x32_bf16 v[2:5], v[182:185], v[214:217], v[2:5]
	s_setprio 0
	s_barrier
	s_add_i32 s54, s54, 2
	s_add_u32 s50, s50, 0x100
	s_addc_u32 s51, s51, 0
	s_add_u32 s20, s20, 0x100
	s_addc_u32 s21, s21, 0
	s_cmp_gt_u32 s54, 13
.LBB0_1038:
	ds_read_b128 v[146:149], v152
	ds_read_b128 v[158:161], v152 offset:1024
	ds_read_b128 v[162:165], v152 offset:2048
	ds_read_b128 v[166:169], v152 offset:3072
	ds_read_b128 v[170:173], v153
	ds_read_b128 v[174:177], v153 offset:1024
	ds_read_b128 v[178:181], v153 offset:2048
	ds_read_b128 v[182:185], v153 offset:3072
	s_add_u32 s22, s20, 0xfffc0080
	s_addc_u32 s23, s21, -1
	s_cmp_eq_u32 s54, 12
	s_cselect_b32 s25, s13, s23
	s_cselect_b32 s24, s48, s22
	s_cselect_b32 s23, s11, s51
	s_cselect_b32 s22, s49, s50
	v_lshl_add_u64 v[218:219], s[20:21], 0, v[140:141]
	s_add_i32 m0, s41, 0xc000
	ds_read_b128 v[186:189], v154
	ds_read_b128 v[190:193], v154 offset:1024
	ds_read_b128 v[194:197], v154 offset:2048
	ds_read_b128 v[198:201], v154 offset:3072
	ds_read_b128 v[202:205], v154 offset:4096
	ds_read_b128 v[206:209], v154 offset:5120
	ds_read_b128 v[210:213], v154 offset:6144
	ds_read_b128 v[214:217], v154 offset:7168
	global_load_lds_dwordx4 v[218:219], off
	v_lshl_add_u64 v[218:219], s[20:21], 0, v[138:139]
	s_add_i32 m0, s41, 0xe000
	s_nop 0
	global_load_lds_dwordx4 v[218:219], off
	s_waitcnt vmcnt(8)
	s_waitcnt lgkmcnt(0)
	s_barrier
; #define PG8_STAGE(bufoff, gbase, voff) do { _Pragma("unroll") for (int _i = 0; _i < 2; ++_i) \
;         __builtin_amdgcn_global_load_lds((const unsigned*)((const char*)(gbase) + (voff)[_i]), (PG8_LAS unsigned*)(lds + (bufoff) + ldsw + _i * 8192), 16, 0, 0); } while (0)
; #define PG8_LDA(dst, b, h) do { _Pragma("unroll") for (int m = 0; m < 4; ++m) _Pragma("unroll") for (int k = 0; k < 2; ++k) dst[m][k] = *(const PG8_LAS bf16x8*)(lds + PG8_SA(b, h) + aoff + m * 2048 + k * 1024); } while (0)
; #define PG8_MMA(ai, bj, At, Bt) do { __builtin_amdgcn_s_setprio(1); _Pragma("unroll") for (int m = 0; m < 4; ++m) _Pragma("unroll") for (int n = 0; n < 2; ++n) _Pragma("unroll") for (int k = 0; k < 2; ++k) \
;         acc[ai][bj][m][n] = __builtin_amdgcn_mfma_f32_16x16x32_bf16(Bt[n][k], At[m][k], acc[ai][bj][m][n], 0, 0, 0); __builtin_amdgcn_s_setprio(0); } while (0)
; #define PG8_WAIT_V(n) asm volatile("s_waitcnt vmcnt(" #n ")" ::: "memory")
; #define PG8_WAIT_L(n) asm volatile("s_waitcnt lgkmcnt(" #n ")" ::: "memory")
; #define PG8_BAR __builtin_amdgcn_s_barrier()
; #define PG8_SCHED __builtin_amdgcn_sched_barrier(0)
; template <class Epi, class Sched, bool ALIGN_EPI = false, bool SP2 = false>
; __device__ __forceinline__ void gemm_phase(PG8_LAS unsigned char* lds, const Gemm g, const Sched& S, const Epi& E) {
;     ...
;             PG8_WAIT_V(8); PG8_WAIT_L(0); PG8_BAR; PG8_MMA(0, 0, At, B0); PG8_MMA(0, 1, At, B1); PG8_BAR; PG8_SCHED;
;             PG8_LDA(At, 0, 1); PG8_STAGE(PG8_SB(0, 0), b2, voffB); PG8_STAGE(PG8_SB(0, 1), b2 + hstep, voffB); PG8_STAGE(PG8_SA(0, 0), a2, voffA);
;             PG8_WAIT_V(8); PG8_WAIT_L(0); PG8_BAR; PG8_MMA(1, 0, At, B0); PG8_MMA(1, 1, At, B1); PG8_BAR; PG8_SCHED;
	s_setprio 1
	s_waitcnt lgkmcnt(0)
	v_mfma_f32_16x16x32_bf16 v[126:129], v[146:149], v[186:189], v[126:129]
	v_mfma_f32_16x16x32_bf16 v[118:121], v[162:165], v[186:189], v[118:121]
	v_mfma_f32_16x16x32_bf16 v[110:113], v[146:149], v[194:197], v[110:113]
	v_mfma_f32_16x16x32_bf16 v[102:105], v[162:165], v[194:197], v[102:105]
	v_mfma_f32_16x16x32_bf16 v[94:97], v[146:149], v[202:205], v[94:97]
	v_mfma_f32_16x16x32_bf16 v[86:89], v[162:165], v[202:205], v[86:89]
	v_mfma_f32_16x16x32_bf16 v[78:81], v[146:149], v[210:213], v[78:81]
	v_mfma_f32_16x16x32_bf16 v[70:73], v[162:165], v[210:213], v[70:73]
	v_mfma_f32_16x16x32_bf16 v[126:129], v[158:161], v[190:193], v[126:129]
	v_mfma_f32_16x16x32_bf16 v[118:121], v[166:169], v[190:193], v[118:121]
	v_mfma_f32_16x16x32_bf16 v[110:113], v[158:161], v[198:201], v[110:113]
	v_mfma_f32_16x16x32_bf16 v[102:105], v[166:169], v[198:201], v[102:105]
	v_mfma_f32_16x16x32_bf16 v[94:97], v[158:161], v[206:209], v[94:97]
	v_mfma_f32_16x16x32_bf16 v[86:89], v[166:169], v[206:209], v[86:89]
	v_mfma_f32_16x16x32_bf16 v[78:81], v[158:161], v[214:217], v[78:81]
	v_mfma_f32_16x16x32_bf16 v[70:73], v[166:169], v[214:217], v[70:73]
	s_setprio 0
	s_setprio 1
	v_mfma_f32_16x16x32_bf16 v[122:125], v[170:173], v[186:189], v[122:125]
	v_mfma_f32_16x16x32_bf16 v[114:117], v[178:181], v[186:189], v[114:117]
	v_mfma_f32_16x16x32_bf16 v[106:109], v[170:173], v[194:197], v[106:109]
	v_mfma_f32_16x16x32_bf16 v[98:101], v[178:181], v[194:197], v[98:101]
	v_mfma_f32_16x16x32_bf16 v[90:93], v[170:173], v[202:205], v[90:93]
	v_mfma_f32_16x16x32_bf16 v[82:85], v[178:181], v[202:205], v[82:85]
	v_mfma_f32_16x16x32_bf16 v[74:77], v[170:173], v[210:213], v[74:77]
	v_mfma_f32_16x16x32_bf16 v[66:69], v[178:181], v[210:213], v[66:69]
	v_mfma_f32_16x16x32_bf16 v[122:125], v[174:177], v[190:193], v[122:125]
	v_mfma_f32_16x16x32_bf16 v[114:117], v[182:185], v[190:193], v[114:117]
	v_mfma_f32_16x16x32_bf16 v[106:109], v[174:177], v[198:201], v[106:109]
	v_mfma_f32_16x16x32_bf16 v[98:101], v[182:185], v[198:201], v[98:101]
	v_mfma_f32_16x16x32_bf16 v[90:93], v[174:177], v[206:209], v[90:93]
	v_mfma_f32_16x16x32_bf16 v[82:85], v[182:185], v[206:209], v[82:85]
	v_mfma_f32_16x16x32_bf16 v[74:77], v[174:177], v[214:217], v[74:77]
	v_mfma_f32_16x16x32_bf16 v[66:69], v[182:185], v[214:217], v[66:69]
	s_setprio 0
	s_barrier
	s_mov_b32 m0, s19
	v_lshl_add_u64 v[218:219], s[22:23], 0, v[134:135]
	s_add_u32 s58, s22, 0x40000
	ds_read_b128 v[186:189], v154 offset:16384
	ds_read_b128 v[190:193], v154 offset:17408
	ds_read_b128 v[194:197], v154 offset:18432
	ds_read_b128 v[198:201], v154 offset:19456
	ds_read_b128 v[202:205], v154 offset:20480
	ds_read_b128 v[206:209], v154 offset:21504
	ds_read_b128 v[210:213], v154 offset:22528
	ds_read_b128 v[214:217], v154 offset:23552
	global_load_lds_dwordx4 v[218:219], off
	v_lshl_add_u64 v[220:221], s[22:23], 0, v[130:131]
	s_mov_b32 m0, s38
	s_addc_u32 s59, s23, 0
	global_load_lds_dwordx4 v[220:221], off
	v_lshl_add_u64 v[222:223], s[58:59], 0, v[134:135]
	s_mov_b32 m0, s39
	v_lshl_add_u64 v[224:225], s[24:25], 0, v[132:133]
	global_load_lds_dwordx4 v[222:223], off
	v_lshl_add_u64 v[222:223], s[58:59], 0, v[130:131]
	s_mov_b32 m0, s40
	s_nop 0
	global_load_lds_dwordx4 v[222:223], off
	v_lshl_add_u64 v[222:223], s[24:25], 0, v[136:137]
	s_waitcnt vmcnt(6)
	s_waitcnt lgkmcnt(0)
	s_barrier
	s_setprio 1
	s_waitcnt lgkmcnt(0)
	v_mfma_f32_16x16x32_bf16 v[62:65], v[146:149], v[186:189], v[62:65]
	v_mfma_f32_16x16x32_bf16 v[54:57], v[162:165], v[186:189], v[54:57]
	v_mfma_f32_16x16x32_bf16 v[46:49], v[146:149], v[194:197], v[46:49]
	v_mfma_f32_16x16x32_bf16 v[38:41], v[162:165], v[194:197], v[38:41]
	v_mfma_f32_16x16x32_bf16 v[30:33], v[146:149], v[202:205], v[30:33]
	v_mfma_f32_16x16x32_bf16 v[22:25], v[162:165], v[202:205], v[22:25]
	v_mfma_f32_16x16x32_bf16 v[14:17], v[146:149], v[210:213], v[14:17]
	v_mfma_f32_16x16x32_bf16 v[6:9], v[162:165], v[210:213], v[6:9]
	v_mfma_f32_16x16x32_bf16 v[62:65], v[158:161], v[190:193], v[62:65]
	v_mfma_f32_16x16x32_bf16 v[54:57], v[166:169], v[190:193], v[54:57]
	v_mfma_f32_16x16x32_bf16 v[46:49], v[158:161], v[198:201], v[46:49]
	v_mfma_f32_16x16x32_bf16 v[38:41], v[166:169], v[198:201], v[38:41]
	v_mfma_f32_16x16x32_bf16 v[30:33], v[158:161], v[206:209], v[30:33]
	v_mfma_f32_16x16x32_bf16 v[22:25], v[166:169], v[206:209], v[22:25]
	v_mfma_f32_16x16x32_bf16 v[14:17], v[158:161], v[214:217], v[14:17]
	v_mfma_f32_16x16x32_bf16 v[6:9], v[166:169], v[214:217], v[6:9]
	s_setprio 0
	s_setprio 1
	v_mfma_f32_16x16x32_bf16 v[58:61], v[170:173], v[186:189], v[58:61]
	v_mfma_f32_16x16x32_bf16 v[50:53], v[178:181], v[186:189], v[50:53]
	v_mfma_f32_16x16x32_bf16 v[42:45], v[170:173], v[194:197], v[42:45]
	v_mfma_f32_16x16x32_bf16 v[34:37], v[178:181], v[194:197], v[34:37]
	v_mfma_f32_16x16x32_bf16 v[26:29], v[170:173], v[202:205], v[26:29]
	v_mfma_f32_16x16x32_bf16 v[18:21], v[178:181], v[202:205], v[18:21]
	v_mfma_f32_16x16x32_bf16 v[10:13], v[170:173], v[210:213], v[10:13]
	v_mfma_f32_16x16x32_bf16 v[2:5], v[178:181], v[210:213], v[2:5]
	v_mfma_f32_16x16x32_bf16 v[58:61], v[174:177], v[190:193], v[58:61]
	v_mfma_f32_16x16x32_bf16 v[50:53], v[182:185], v[190:193], v[50:53]
	v_mfma_f32_16x16x32_bf16 v[42:45], v[174:177], v[198:201], v[42:45]
	v_mfma_f32_16x16x32_bf16 v[34:37], v[182:185], v[198:201], v[34:37]
	v_mfma_f32_16x16x32_bf16 v[26:29], v[174:177], v[206:209], v[26:29]
	v_mfma_f32_16x16x32_bf16 v[18:21], v[182:185], v[206:209], v[18:21]
	v_mfma_f32_16x16x32_bf16 v[10:13], v[174:177], v[214:217], v[10:13]
	v_mfma_f32_16x16x32_bf16 v[2:5], v[182:185], v[214:217], v[2:5]
	s_setprio 0
	s_barrier
; #define PG8_STAGE(bufoff, gbase, voff) do { _Pragma("unroll") for (int _i = 0; _i < 2; ++_i) \
;         __builtin_amdgcn_global_load_lds((const unsigned*)((const char*)(gbase) + (voff)[_i]), (PG8_LAS unsigned*)(lds + (bufoff) + ldsw + _i * 8192), 16, 0, 0); } while (0)
; #define PG8_LDA(dst, b, h) do { _Pragma("unroll") for (int m = 0; m < 4; ++m) _Pragma("unroll") for (int k = 0; k < 2; ++k) dst[m][k] = *(const PG8_LAS bf16x8*)(lds + PG8_SA(b, h) + aoff + m * 2048 + k * 1024); } while (0)
; #define PG8_LDB(dst, b, h) do { _Pragma("unroll") for (int n = 0; n < 2; ++n) _Pragma("unroll") for (int k = 0; k < 2; ++k) dst[n][k] = *(const PG8_LAS bf16x8*)(lds + PG8_SB(b, h) + boff + n * 2048 + k * 1024); } while (0)
; #define PG8_MMA(ai, bj, At, Bt) do { __builtin_amdgcn_s_setprio(1); _Pragma("unroll") for (int m = 0; m < 4; ++m) _Pragma("unroll") for (int n = 0; n < 2; ++n) _Pragma("unroll") for (int k = 0; k < 2; ++k) \
;         acc[ai][bj][m][n] = __builtin_amdgcn_mfma_f32_16x16x32_bf16(Bt[n][k], At[m][k], acc[ai][bj][m][n], 0, 0, 0); __builtin_amdgcn_s_setprio(0); } while (0)
; #define PG8_WAIT_V(n) asm volatile("s_waitcnt vmcnt(" #n ")" ::: "memory")
; #define PG8_WAIT_L(n) asm volatile("s_waitcnt lgkmcnt(" #n ")" ::: "memory")
; #define PG8_BAR __builtin_amdgcn_s_barrier()
; #define PG8_SCHED __builtin_amdgcn_sched_barrier(0)
; template <class Epi, class Sched, bool ALIGN_EPI = false, bool SP2 = false>
; __device__ __forceinline__ void gemm_phase(PG8_LAS unsigned char* lds, const Gemm g, const Sched& S, const Epi& E) {
;     ...
;             PG8_LDB(B0, 1, 0); PG8_LDB(B1, 1, 1); PG8_SCHED; PG8_LDA(At, 1, 0); PG8_STAGE(PG8_SA(0, 1), a2 + hstep, voffA);
;             PG8_WAIT_V(8); PG8_WAIT_L(0); PG8_BAR; PG8_MMA(0, 0, At, B0); PG8_MMA(0, 1, At, B1); PG8_BAR; PG8_SCHED;
	ds_read_b128 v[146:149], v155
	ds_read_b128 v[158:161], v155 offset:1024
	ds_read_b128 v[162:165], v155 offset:2048
	ds_read_b128 v[166:169], v155 offset:3072
	ds_read_b128 v[170:173], v156
	ds_read_b128 v[174:177], v156 offset:1024
	ds_read_b128 v[178:181], v156 offset:2048
	ds_read_b128 v[182:185], v156 offset:3072
	s_add_u32 s24, s24, 0x40000
	s_addc_u32 s25, s25, 0
	s_mov_b32 m0, s41
	s_nop 0
	global_load_lds_dwordx4 v[222:223], off
	s_mov_b32 m0, s42
	s_nop 0
	global_load_lds_dwordx4 v[224:225], off
	s_mov_b32 m0, s43
	v_lshl_add_u64 v[226:227], s[24:25], 0, v[136:137]
	ds_read_b128 v[186:189], v154 offset:32768
	ds_read_b128 v[190:193], v154 offset:33792
	ds_read_b128 v[194:197], v154 offset:34816
	ds_read_b128 v[198:201], v154 offset:35840
	ds_read_b128 v[202:205], v154 offset:36864
	ds_read_b128 v[206:209], v154 offset:37888
	ds_read_b128 v[210:213], v154 offset:38912
	ds_read_b128 v[214:217], v154 offset:39936
	global_load_lds_dwordx4 v[226:227], off
	v_lshl_add_u64 v[226:227], s[24:25], 0, v[132:133]
	s_mov_b32 m0, s44
	s_nop 0
	global_load_lds_dwordx4 v[226:227], off
	s_waitcnt vmcnt(8)
	s_waitcnt lgkmcnt(0)
	s_barrier
	s_setprio 1
	s_waitcnt lgkmcnt(0)
	v_mfma_f32_16x16x32_bf16 v[126:129], v[146:149], v[186:189], v[126:129]
	v_mfma_f32_16x16x32_bf16 v[118:121], v[162:165], v[186:189], v[118:121]
	v_mfma_f32_16x16x32_bf16 v[110:113], v[146:149], v[194:197], v[110:113]
	v_mfma_f32_16x16x32_bf16 v[102:105], v[162:165], v[194:197], v[102:105]
	v_mfma_f32_16x16x32_bf16 v[94:97], v[146:149], v[202:205], v[94:97]
	v_mfma_f32_16x16x32_bf16 v[86:89], v[162:165], v[202:205], v[86:89]
	v_mfma_f32_16x16x32_bf16 v[78:81], v[146:149], v[210:213], v[78:81]
	v_mfma_f32_16x16x32_bf16 v[70:73], v[162:165], v[210:213], v[70:73]
	v_mfma_f32_16x16x32_bf16 v[126:129], v[158:161], v[190:193], v[126:129]
	v_mfma_f32_16x16x32_bf16 v[118:121], v[166:169], v[190:193], v[118:121]
	v_mfma_f32_16x16x32_bf16 v[110:113], v[158:161], v[198:201], v[110:113]
	v_mfma_f32_16x16x32_bf16 v[102:105], v[166:169], v[198:201], v[102:105]
	v_mfma_f32_16x16x32_bf16 v[94:97], v[158:161], v[206:209], v[94:97]
	v_mfma_f32_16x16x32_bf16 v[86:89], v[166:169], v[206:209], v[86:89]
	v_mfma_f32_16x16x32_bf16 v[78:81], v[158:161], v[214:217], v[78:81]
	v_mfma_f32_16x16x32_bf16 v[70:73], v[166:169], v[214:217], v[70:73]
	s_setprio 0
	s_setprio 1
	v_mfma_f32_16x16x32_bf16 v[122:125], v[170:173], v[186:189], v[122:125]
	v_mfma_f32_16x16x32_bf16 v[114:117], v[178:181], v[186:189], v[114:117]
	v_mfma_f32_16x16x32_bf16 v[106:109], v[170:173], v[194:197], v[106:109]
	v_mfma_f32_16x16x32_bf16 v[98:101], v[178:181], v[194:197], v[98:101]
	v_mfma_f32_16x16x32_bf16 v[90:93], v[170:173], v[202:205], v[90:93]
	v_mfma_f32_16x16x32_bf16 v[82:85], v[178:181], v[202:205], v[82:85]
	v_mfma_f32_16x16x32_bf16 v[74:77], v[170:173], v[210:213], v[74:77]
	v_mfma_f32_16x16x32_bf16 v[66:69], v[178:181], v[210:213], v[66:69]
	v_mfma_f32_16x16x32_bf16 v[122:125], v[174:177], v[190:193], v[122:125]
	v_mfma_f32_16x16x32_bf16 v[114:117], v[182:185], v[190:193], v[114:117]
	v_mfma_f32_16x16x32_bf16 v[106:109], v[174:177], v[198:201], v[106:109]
	v_mfma_f32_16x16x32_bf16 v[98:101], v[182:185], v[198:201], v[98:101]
	v_mfma_f32_16x16x32_bf16 v[90:93], v[174:177], v[206:209], v[90:93]
	v_mfma_f32_16x16x32_bf16 v[82:85], v[182:185], v[206:209], v[82:85]
	v_mfma_f32_16x16x32_bf16 v[74:77], v[174:177], v[214:217], v[74:77]
	v_mfma_f32_16x16x32_bf16 v[66:69], v[182:185], v[214:217], v[66:69]
	s_setprio 0
	s_barrier
; #define PG8_STAGE(bufoff, gbase, voff) do { _Pragma("unroll") for (int _i = 0; _i < 2; ++_i) \
;         __builtin_amdgcn_global_load_lds((const unsigned*)((const char*)(gbase) + (voff)[_i]), (PG8_LAS unsigned*)(lds + (bufoff) + ldsw + _i * 8192), 16, 0, 0); } while (0)
; #define PG8_LDA(dst, b, h) do { _Pragma("unroll") for (int m = 0; m < 4; ++m) _Pragma("unroll") for (int k = 0; k < 2; ++k) dst[m][k] = *(const PG8_LAS bf16x8*)(lds + PG8_SA(b, h) + aoff + m * 2048 + k * 1024); } while (0)
; #define PG8_MMA(ai, bj, At, Bt) do { __builtin_amdgcn_s_setprio(1); _Pragma("unroll") for (int m = 0; m < 4; ++m) _Pragma("unroll") for (int n = 0; n < 2; ++n) _Pragma("unroll") for (int k = 0; k < 2; ++k) \
;         acc[ai][bj][m][n] = __builtin_amdgcn_mfma_f32_16x16x32_bf16(Bt[n][k], At[m][k], acc[ai][bj][m][n], 0, 0, 0); __builtin_amdgcn_s_setprio(0); } while (0)
; #define PG8_WAIT_V(n) asm volatile("s_waitcnt vmcnt(" #n ")" ::: "memory")
; #define PG8_WAIT_L(n) asm volatile("s_waitcnt lgkmcnt(" #n ")" ::: "memory")
; #define PG8_BAR __builtin_amdgcn_s_barrier()
; #define PG8_SCHED __builtin_amdgcn_sched_barrier(0)
; template <class Epi, class Sched, bool ALIGN_EPI = false, bool SP2 = false>
; __device__ __forceinline__ void gemm_phase(PG8_LAS unsigned char* lds, const Gemm g, const Sched& S, const Epi& E) {
;     ...
;             PG8_LDA(At, 1, 1); PG8_STAGE(PG8_SB(1, 0), b3, voffB); PG8_STAGE(PG8_SB(1, 1), b3 + hstep, voffB); PG8_STAGE(PG8_SA(1, 0), a3, voffA);
;             PG8_WAIT_V(8); PG8_WAIT_L(0); PG8_BAR; PG8_MMA(1, 0, At, B0); PG8_MMA(1, 1, At, B1); PG8_BAR; PG8_SCHED;
	s_mov_b32 m0, s45
	v_lshl_add_u64 v[218:219], v[218:219], 0, s[6:7]
	s_add_u32 s22, s22, 0x40080
	ds_read_b128 v[186:189], v154 offset:49152
	ds_read_b128 v[190:193], v154 offset:50176
	ds_read_b128 v[194:197], v154 offset:51200
	ds_read_b128 v[198:201], v154 offset:52224
	ds_read_b128 v[202:205], v154 offset:53248
	ds_read_b128 v[206:209], v154 offset:54272
	ds_read_b128 v[210:213], v154 offset:55296
	ds_read_b128 v[214:217], v154 offset:56320
	global_load_lds_dwordx4 v[218:219], off
	v_lshl_add_u64 v[218:219], v[220:221], 0, s[6:7]
	s_mov_b32 m0, s46
	s_addc_u32 s23, s23, 0
	global_load_lds_dwordx4 v[218:219], off
	v_lshl_add_u64 v[218:219], s[22:23], 0, v[134:135]
	s_mov_b32 m0, s53
	s_nop 0
	global_load_lds_dwordx4 v[218:219], off
	v_lshl_add_u64 v[218:219], s[22:23], 0, v[130:131]
	s_mov_b32 m0, s56
	s_nop 0
	global_load_lds_dwordx4 v[218:219], off
	v_lshl_add_u64 v[218:219], v[222:223], 0, s[6:7]
	s_mov_b32 m0, s47
	s_nop 0
	global_load_lds_dwordx4 v[218:219], off
	v_lshl_add_u64 v[218:219], v[224:225], 0, s[6:7]
	s_mov_b32 m0, s52
	s_nop 0
	global_load_lds_dwordx4 v[218:219], off
	s_waitcnt vmcnt(8)
	s_waitcnt lgkmcnt(0)
	s_barrier
	s_setprio 1
	s_waitcnt lgkmcnt(0)
	v_mfma_f32_16x16x32_bf16 v[62:65], v[146:149], v[186:189], v[62:65]
	v_mfma_f32_16x16x32_bf16 v[54:57], v[162:165], v[186:189], v[54:57]
	v_mfma_f32_16x16x32_bf16 v[46:49], v[146:149], v[194:197], v[46:49]
	v_mfma_f32_16x16x32_bf16 v[38:41], v[162:165], v[194:197], v[38:41]
	v_mfma_f32_16x16x32_bf16 v[30:33], v[146:149], v[202:205], v[30:33]
	v_mfma_f32_16x16x32_bf16 v[22:25], v[162:165], v[202:205], v[22:25]
	v_mfma_f32_16x16x32_bf16 v[14:17], v[146:149], v[210:213], v[14:17]
	v_mfma_f32_16x16x32_bf16 v[6:9], v[162:165], v[210:213], v[6:9]
	v_mfma_f32_16x16x32_bf16 v[62:65], v[158:161], v[190:193], v[62:65]
	v_mfma_f32_16x16x32_bf16 v[54:57], v[166:169], v[190:193], v[54:57]
	v_mfma_f32_16x16x32_bf16 v[46:49], v[158:161], v[198:201], v[46:49]
	v_mfma_f32_16x16x32_bf16 v[38:41], v[166:169], v[198:201], v[38:41]
	v_mfma_f32_16x16x32_bf16 v[30:33], v[158:161], v[206:209], v[30:33]
	v_mfma_f32_16x16x32_bf16 v[22:25], v[166:169], v[206:209], v[22:25]
	v_mfma_f32_16x16x32_bf16 v[14:17], v[158:161], v[214:217], v[14:17]
	v_mfma_f32_16x16x32_bf16 v[6:9], v[166:169], v[214:217], v[6:9]
	s_setprio 0
	s_setprio 1
	v_mfma_f32_16x16x32_bf16 v[58:61], v[170:173], v[186:189], v[58:61]
	v_mfma_f32_16x16x32_bf16 v[50:53], v[178:181], v[186:189], v[50:53]
	v_mfma_f32_16x16x32_bf16 v[42:45], v[170:173], v[194:197], v[42:45]
	v_mfma_f32_16x16x32_bf16 v[34:37], v[178:181], v[194:197], v[34:37]
	v_mfma_f32_16x16x32_bf16 v[26:29], v[170:173], v[202:205], v[26:29]
	v_mfma_f32_16x16x32_bf16 v[18:21], v[178:181], v[202:205], v[18:21]
	v_mfma_f32_16x16x32_bf16 v[10:13], v[170:173], v[210:213], v[10:13]
	v_mfma_f32_16x16x32_bf16 v[2:5], v[178:181], v[210:213], v[2:5]
	v_mfma_f32_16x16x32_bf16 v[58:61], v[174:177], v[190:193], v[58:61]
	v_mfma_f32_16x16x32_bf16 v[50:53], v[182:185], v[190:193], v[50:53]
	v_mfma_f32_16x16x32_bf16 v[42:45], v[174:177], v[198:201], v[42:45]
	v_mfma_f32_16x16x32_bf16 v[34:37], v[182:185], v[198:201], v[34:37]
	v_mfma_f32_16x16x32_bf16 v[26:29], v[174:177], v[206:209], v[26:29]
	v_mfma_f32_16x16x32_bf16 v[18:21], v[182:185], v[206:209], v[18:21]
	v_mfma_f32_16x16x32_bf16 v[10:13], v[174:177], v[214:217], v[10:13]
	v_mfma_f32_16x16x32_bf16 v[2:5], v[182:185], v[214:217], v[2:5]
	s_setprio 0
	s_barrier
	s_add_i32 s54, s54, 2
	s_add_u32 s50, s50, 0x100
	s_addc_u32 s51, s51, 0
	s_add_u32 s20, s20, 0x100
	s_addc_u32 s21, s21, 0
	s_cmp_gt_u32 s54, 13
	s_cbranch_scc0 .LBB0_1038
	s_and_b64 vcc, exec, s[8:9]
	s_cbranch_vccz .LBB0_1041
	s_barrier

; #define PG8_STAGE(bufoff, gbase, voff) do { _Pragma("unroll") for (int _i = 0; _i < 2; ++_i) \
;         __builtin_amdgcn_global_load_lds((const unsigned*)((const char*)(gbase) + (voff)[_i]), (PG8_LAS unsigned*)(lds + (bufoff) + ldsw + _i * 8192), 16, 0, 0); } while (0)
; #define PG8_LDA(dst, b, h) do { _Pragma("unroll") for (int m = 0; m < 4; ++m) _Pragma("unroll") for (int k = 0; k < 2; ++k) dst[m][k] = *(const PG8_LAS bf16x8*)(lds + PG8_SA(b, h) + aoff + m * 2048 + k * 1024); } while (0)
; #define PG8_LDB(dst, b, h) do { _Pragma("unroll") for (int n = 0; n < 2; ++n) _Pragma("unroll") for (int k = 0; k < 2; ++k) dst[n][k] = *(const PG8_LAS bf16x8*)(lds + PG8_SB(b, h) + boff + n * 2048 + k * 1024); } while (0)
; #define PG8_WAIT_V(n) asm volatile("s_waitcnt vmcnt(" #n ")" ::: "memory")
; #define PG8_WAIT_L(n) asm volatile("s_waitcnt lgkmcnt(" #n ")" ::: "memory")
; #define PG8_BAR __builtin_amdgcn_s_barrier()
; template <class Epi, class Sched, bool ALIGN_EPI = false, bool SP2 = false>
; __device__ __forceinline__ void gemm_phase(PG8_LAS unsigned char* lds, const Gemm g, const Sched& S, const Epi& E) {
;     ...
;     for (;;) {
;         const bool has_next = S.next(ui + 1, nxt);
;         const char* nA = has_next ? (const char*)g.A + (size_t)nxt.pm * tstep + (size_t)nxt.ks * K * 2 : cA; const char* nB = has_next ? (const char*)g.Bt + (size_t)nxt.pn * tstep + (size_t)nxt.ks * K * 2 : cB;
;         for (int t = 0; t < nt; t += 2) {
;             const bool last = (t == nt - 2);
;             const char* a1 = cA + (size_t)(t + 1) * kstep;
;             const char* a2 = last ? nA : cA + (size_t)(t + 2) * kstep; const char* b2 = last ? nB : cB + (size_t)(t + 2) * kstep;
;             const char* a3 = a2 + kstep; const char* b3 = b2 + kstep;
;             if (last && has_next) S.a_ready(nxt);
;             if constexpr (SP2) {
;             PG8_LDB(B0, 0, 0); PG8_LDB(B1, 0, 1); PG8_SCHED; PG8_LDA(At, 0, 0); PG8_STAGE(PG8_SA(1, 1), a1 + hstep, voffA);
;             PG8_WAIT_V(8); PG8_WAIT_L(0); PG8_BAR; PG8_MMA(0, 0, At, B0); PG8_MMA(0, 1, At, B1); PG8_BAR; PG8_SCHED;
;             PG8_LDA(At, 0, 1); PG8_STAGE(PG8_SB(0, 0), b2, voffB); PG8_STAGE(PG8_SB(0, 1), b2 + hstep, voffB); PG8_STAGE(PG8_SA(0, 0), a2, voffA);
;             PG8_WAIT_V(8); PG8_WAIT_L(0); PG8_BAR; PG8_MMA(1, 0, At, B0); PG8_MMA(1, 1, At, B1); PG8_BAR; PG8_SCHED;
.LBB0_1125:
	s_add_u32 s91, s46, 0x100
	s_addc_u32 s92, s47, 0
	s_mov_b32 s52, 0
	ds_read_b128 v[150:153], v147
	ds_read_b128 v[154:157], v147 offset:1024
	ds_read_b128 v[158:161], v147 offset:2048
	ds_read_b128 v[162:165], v147 offset:3072
	ds_read_b128 v[166:169], v148
	ds_read_b128 v[170:173], v148 offset:1024
	ds_read_b128 v[174:177], v148 offset:2048
	ds_read_b128 v[178:181], v148 offset:3072
	s_add_i32 s93, s52, 2
	s_add_u32 s46, s44, 0x100
	s_addc_u32 s47, s45, 0
	s_cmp_eq_u32 s86, s52
	s_cselect_b32 s52, s42, s91
	s_cselect_b32 s57, s41, s47
	s_cselect_b32 s56, s40, s46
	s_cselect_b32 s53, s43, s92
	v_lshl_add_u64 v[214:215], s[44:45], 0, v[140:141]
	s_add_i32 m0, s77, 0xc000
	ds_read_b128 v[182:185], v146
	ds_read_b128 v[186:189], v146 offset:1024
	ds_read_b128 v[190:193], v146 offset:2048
	ds_read_b128 v[194:197], v146 offset:3072
	ds_read_b128 v[198:201], v146 offset:4096
	ds_read_b128 v[202:205], v146 offset:5120
	ds_read_b128 v[206:209], v146 offset:6144
	ds_read_b128 v[210:213], v146 offset:7168
	global_load_lds_dwordx4 v[214:215], off
	v_lshl_add_u64 v[214:215], s[44:45], 0, v[138:139]
	s_add_i32 m0, s77, 0xe000
	s_nop 0
	global_load_lds_dwordx4 v[214:215], off
	s_waitcnt vmcnt(8)
	s_waitcnt lgkmcnt(0)
	s_barrier
	s_setprio 1
	s_waitcnt lgkmcnt(0)
	v_mfma_f32_16x16x32_bf16 v[126:129], v[150:153], v[182:185], 0
	v_mfma_f32_16x16x32_bf16 v[122:125], v[158:161], v[182:185], 0
	v_mfma_f32_16x16x32_bf16 v[118:121], v[150:153], v[190:193], 0
	v_mfma_f32_16x16x32_bf16 v[114:117], v[158:161], v[190:193], 0
	v_mfma_f32_16x16x32_bf16 v[102:105], v[150:153], v[198:201], 0
	v_mfma_f32_16x16x32_bf16 v[98:101], v[158:161], v[198:201], 0
	v_mfma_f32_16x16x32_bf16 v[86:89], v[150:153], v[206:209], 0
	v_mfma_f32_16x16x32_bf16 v[82:85], v[158:161], v[206:209], 0
	v_mfma_f32_16x16x32_bf16 v[126:129], v[154:157], v[186:189], v[126:129]
	v_mfma_f32_16x16x32_bf16 v[122:125], v[162:165], v[186:189], v[122:125]
	v_mfma_f32_16x16x32_bf16 v[118:121], v[154:157], v[194:197], v[118:121]
	v_mfma_f32_16x16x32_bf16 v[114:117], v[162:165], v[194:197], v[114:117]
	v_mfma_f32_16x16x32_bf16 v[102:105], v[154:157], v[202:205], v[102:105]
	v_mfma_f32_16x16x32_bf16 v[98:101], v[162:165], v[202:205], v[98:101]
	v_mfma_f32_16x16x32_bf16 v[86:89], v[154:157], v[210:213], v[86:89]
	v_mfma_f32_16x16x32_bf16 v[82:85], v[162:165], v[210:213], v[82:85]
	s_setprio 0
	s_setprio 1
	v_mfma_f32_16x16x32_bf16 v[110:113], v[166:169], v[182:185], 0
	v_mfma_f32_16x16x32_bf16 v[106:109], v[174:177], v[182:185], 0
	v_mfma_f32_16x16x32_bf16 v[94:97], v[166:169], v[190:193], 0
	v_mfma_f32_16x16x32_bf16 v[90:93], v[174:177], v[190:193], 0
	v_mfma_f32_16x16x32_bf16 v[78:81], v[166:169], v[198:201], 0
	v_mfma_f32_16x16x32_bf16 v[74:77], v[174:177], v[198:201], 0
	v_mfma_f32_16x16x32_bf16 v[70:73], v[166:169], v[206:209], 0
	v_mfma_f32_16x16x32_bf16 v[66:69], v[174:177], v[206:209], 0
	v_mfma_f32_16x16x32_bf16 v[110:113], v[170:173], v[186:189], v[110:113]
	v_mfma_f32_16x16x32_bf16 v[106:109], v[178:181], v[186:189], v[106:109]
	v_mfma_f32_16x16x32_bf16 v[94:97], v[170:173], v[194:197], v[94:97]
	v_mfma_f32_16x16x32_bf16 v[90:93], v[178:181], v[194:197], v[90:93]
	v_mfma_f32_16x16x32_bf16 v[78:81], v[170:173], v[202:205], v[78:81]
	v_mfma_f32_16x16x32_bf16 v[74:77], v[178:181], v[202:205], v[74:77]
	v_mfma_f32_16x16x32_bf16 v[70:73], v[170:173], v[210:213], v[70:73]
	v_mfma_f32_16x16x32_bf16 v[66:69], v[178:181], v[210:213], v[66:69]
	s_setprio 0
	s_barrier
	s_mov_b32 m0, s73
	v_lshl_add_u64 v[214:215], s[52:53], 0, v[130:131]
	s_add_u32 s44, s52, 0xb0000
	ds_read_b128 v[182:185], v146 offset:16384
	ds_read_b128 v[186:189], v146 offset:17408
	ds_read_b128 v[190:193], v146 offset:18432
	ds_read_b128 v[194:197], v146 offset:19456
	ds_read_b128 v[198:201], v146 offset:20480
	ds_read_b128 v[202:205], v146 offset:21504
	ds_read_b128 v[206:209], v146 offset:22528
	ds_read_b128 v[210:213], v146 offset:23552
	global_load_lds_dwordx4 v[214:215], off
	v_lshl_add_u64 v[216:217], s[52:53], 0, v[136:137]
	s_mov_b32 m0, s74
	s_addc_u32 s45, s53, 0
	global_load_lds_dwordx4 v[216:217], off
	v_lshl_add_u64 v[218:219], s[44:45], 0, v[130:131]
	s_mov_b32 m0, s75
	v_lshl_add_u64 v[220:221], s[56:57], 0, v[134:135]
	global_load_lds_dwordx4 v[218:219], off
	v_lshl_add_u64 v[218:219], s[44:45], 0, v[136:137]
	s_mov_b32 m0, s76
	s_nop 0
	global_load_lds_dwordx4 v[218:219], off
	v_lshl_add_u64 v[218:219], s[56:57], 0, v[132:133]
	s_waitcnt vmcnt(6)
	s_waitcnt lgkmcnt(0)
	s_barrier
	s_setprio 1
	s_waitcnt lgkmcnt(0)
	v_mfma_f32_16x16x32_bf16 v[62:65], v[150:153], v[182:185], 0
	v_mfma_f32_16x16x32_bf16 v[58:61], v[158:161], v[182:185], 0
	v_mfma_f32_16x16x32_bf16 v[54:57], v[150:153], v[190:193], 0
	v_mfma_f32_16x16x32_bf16 v[50:53], v[158:161], v[190:193], 0
	v_mfma_f32_16x16x32_bf16 v[38:41], v[150:153], v[198:201], 0
	v_mfma_f32_16x16x32_bf16 v[34:37], v[158:161], v[198:201], 0
	v_mfma_f32_16x16x32_bf16 v[22:25], v[150:153], v[206:209], 0
	v_mfma_f32_16x16x32_bf16 v[18:21], v[158:161], v[206:209], 0
	v_mfma_f32_16x16x32_bf16 v[62:65], v[154:157], v[186:189], v[62:65]
	v_mfma_f32_16x16x32_bf16 v[58:61], v[162:165], v[186:189], v[58:61]
	v_mfma_f32_16x16x32_bf16 v[54:57], v[154:157], v[194:197], v[54:57]
	v_mfma_f32_16x16x32_bf16 v[50:53], v[162:165], v[194:197], v[50:53]
	v_mfma_f32_16x16x32_bf16 v[38:41], v[154:157], v[202:205], v[38:41]
	v_mfma_f32_16x16x32_bf16 v[34:37], v[162:165], v[202:205], v[34:37]
	v_mfma_f32_16x16x32_bf16 v[22:25], v[154:157], v[210:213], v[22:25]
	v_mfma_f32_16x16x32_bf16 v[18:21], v[162:165], v[210:213], v[18:21]
	s_setprio 0
	s_setprio 1
	v_mfma_f32_16x16x32_bf16 v[46:49], v[166:169], v[182:185], 0
	v_mfma_f32_16x16x32_bf16 v[42:45], v[174:177], v[182:185], 0
	v_mfma_f32_16x16x32_bf16 v[30:33], v[166:169], v[190:193], 0
	v_mfma_f32_16x16x32_bf16 v[26:29], v[174:177], v[190:193], 0
	v_mfma_f32_16x16x32_bf16 v[14:17], v[166:169], v[198:201], 0
	v_mfma_f32_16x16x32_bf16 v[10:13], v[174:177], v[198:201], 0
	v_mfma_f32_16x16x32_bf16 v[6:9], v[166:169], v[206:209], 0
	v_mfma_f32_16x16x32_bf16 v[2:5], v[174:177], v[206:209], 0
	v_mfma_f32_16x16x32_bf16 v[46:49], v[170:173], v[186:189], v[46:49]
	v_mfma_f32_16x16x32_bf16 v[42:45], v[178:181], v[186:189], v[42:45]
	v_mfma_f32_16x16x32_bf16 v[30:33], v[170:173], v[194:197], v[30:33]
	v_mfma_f32_16x16x32_bf16 v[26:29], v[178:181], v[194:197], v[26:29]
	v_mfma_f32_16x16x32_bf16 v[14:17], v[170:173], v[202:205], v[14:17]
	v_mfma_f32_16x16x32_bf16 v[10:13], v[178:181], v[202:205], v[10:13]
	v_mfma_f32_16x16x32_bf16 v[6:9], v[170:173], v[210:213], v[6:9]
	v_mfma_f32_16x16x32_bf16 v[2:5], v[178:181], v[210:213], v[2:5]
	s_setprio 0
	s_barrier
; #define PG8_STAGE(bufoff, gbase, voff) do { _Pragma("unroll") for (int _i = 0; _i < 2; ++_i) \
;         __builtin_amdgcn_global_load_lds((const unsigned*)((const char*)(gbase) + (voff)[_i]), (PG8_LAS unsigned*)(lds + (bufoff) + ldsw + _i * 8192), 16, 0, 0); } while (0)
; #define PG8_LDA(dst, b, h) do { _Pragma("unroll") for (int m = 0; m < 4; ++m) _Pragma("unroll") for (int k = 0; k < 2; ++k) dst[m][k] = *(const PG8_LAS bf16x8*)(lds + PG8_SA(b, h) + aoff + m * 2048 + k * 1024); } while (0)
; #define PG8_LDB(dst, b, h) do { _Pragma("unroll") for (int n = 0; n < 2; ++n) _Pragma("unroll") for (int k = 0; k < 2; ++k) dst[n][k] = *(const PG8_LAS bf16x8*)(lds + PG8_SB(b, h) + boff + n * 2048 + k * 1024); } while (0)
; #define PG8_MMA(ai, bj, At, Bt) do { __builtin_amdgcn_s_setprio(1); _Pragma("unroll") for (int m = 0; m < 4; ++m) _Pragma("unroll") for (int n = 0; n < 2; ++n) _Pragma("unroll") for (int k = 0; k < 2; ++k) \
;         acc[ai][bj][m][n] = __builtin_amdgcn_mfma_f32_16x16x32_bf16(Bt[n][k], At[m][k], acc[ai][bj][m][n], 0, 0, 0); __builtin_amdgcn_s_setprio(0); } while (0)
; #define PG8_WAIT_V(n) asm volatile("s_waitcnt vmcnt(" #n ")" ::: "memory")
; #define PG8_WAIT_L(n) asm volatile("s_waitcnt lgkmcnt(" #n ")" ::: "memory")
; #define PG8_BAR __builtin_amdgcn_s_barrier()
; #define PG8_SCHED __builtin_amdgcn_sched_barrier(0)
; template <class Epi, class Sched, bool ALIGN_EPI = false, bool SP2 = false>
; __device__ __forceinline__ void gemm_phase(PG8_LAS unsigned char* lds, const Gemm g, const Sched& S, const Epi& E) {
;     ...
;             PG8_LDB(B0, 1, 0); PG8_LDB(B1, 1, 1); PG8_SCHED; PG8_LDA(At, 1, 0); PG8_STAGE(PG8_SA(0, 1), a2 + hstep, voffA);
;             PG8_WAIT_V(8); PG8_WAIT_L(0); PG8_BAR; PG8_MMA(0, 0, At, B0); PG8_MMA(0, 1, At, B1); PG8_BAR; PG8_SCHED;
;             PG8_LDA(At, 1, 1); PG8_STAGE(PG8_SB(1, 0), b3, voffB); PG8_STAGE(PG8_SB(1, 1), b3 + hstep, voffB); PG8_STAGE(PG8_SA(1, 0), a3, voffA);
;             PG8_WAIT_V(8); PG8_WAIT_L(0); PG8_BAR; PG8_MMA(1, 0, At, B0); PG8_MMA(1, 1, At, B1); PG8_BAR; PG8_SCHED;
	v_add_u32_e32 v178, s66, v144
	ds_read_b128 v[150:153], v149
	ds_read_b128 v[154:157], v149 offset:1024
	ds_read_b128 v[158:161], v149 offset:2048
	ds_read_b128 v[162:165], v149 offset:3072
	ds_read_b128 v[166:169], v178
	ds_read_b128 v[170:173], v178 offset:1024
	ds_read_b128 v[174:177], v178 offset:2048
	ds_read_b128 v[178:181], v178 offset:3072
	s_add_u32 s44, s56, 0xb0000
	s_addc_u32 s45, s57, 0
	s_mov_b32 m0, s77
	s_nop 0
	global_load_lds_dwordx4 v[218:219], off
	s_mov_b32 m0, s78
	s_nop 0
	global_load_lds_dwordx4 v[220:221], off
	s_mov_b32 m0, s79
	v_lshl_add_u64 v[222:223], s[44:45], 0, v[132:133]
	ds_read_b128 v[182:185], v146 offset:32768
	ds_read_b128 v[186:189], v146 offset:33792
	ds_read_b128 v[190:193], v146 offset:34816
	ds_read_b128 v[194:197], v146 offset:35840
	ds_read_b128 v[198:201], v146 offset:36864
	ds_read_b128 v[202:205], v146 offset:37888
	ds_read_b128 v[206:209], v146 offset:38912
	ds_read_b128 v[210:213], v146 offset:39936
	global_load_lds_dwordx4 v[222:223], off
	v_lshl_add_u64 v[222:223], s[44:45], 0, v[134:135]
	s_mov_b32 m0, s80
	s_nop 0
	global_load_lds_dwordx4 v[222:223], off
	s_waitcnt vmcnt(8)
	s_waitcnt lgkmcnt(0)
	s_barrier
	s_setprio 1
	s_waitcnt lgkmcnt(0)
	v_mfma_f32_16x16x32_bf16 v[126:129], v[150:153], v[182:185], v[126:129]
	v_mfma_f32_16x16x32_bf16 v[122:125], v[158:161], v[182:185], v[122:125]
	v_mfma_f32_16x16x32_bf16 v[118:121], v[150:153], v[190:193], v[118:121]
	v_mfma_f32_16x16x32_bf16 v[114:117], v[158:161], v[190:193], v[114:117]
	v_mfma_f32_16x16x32_bf16 v[102:105], v[150:153], v[198:201], v[102:105]
	v_mfma_f32_16x16x32_bf16 v[98:101], v[158:161], v[198:201], v[98:101]
	v_mfma_f32_16x16x32_bf16 v[86:89], v[150:153], v[206:209], v[86:89]
	v_mfma_f32_16x16x32_bf16 v[82:85], v[158:161], v[206:209], v[82:85]
	v_mfma_f32_16x16x32_bf16 v[126:129], v[154:157], v[186:189], v[126:129]
	v_mfma_f32_16x16x32_bf16 v[122:125], v[162:165], v[186:189], v[122:125]
	v_mfma_f32_16x16x32_bf16 v[118:121], v[154:157], v[194:197], v[118:121]
	v_mfma_f32_16x16x32_bf16 v[114:117], v[162:165], v[194:197], v[114:117]
	v_mfma_f32_16x16x32_bf16 v[102:105], v[154:157], v[202:205], v[102:105]
	v_mfma_f32_16x16x32_bf16 v[98:101], v[162:165], v[202:205], v[98:101]
	v_mfma_f32_16x16x32_bf16 v[86:89], v[154:157], v[210:213], v[86:89]
	v_mfma_f32_16x16x32_bf16 v[82:85], v[162:165], v[210:213], v[82:85]
	s_setprio 0
	s_setprio 1
	v_mfma_f32_16x16x32_bf16 v[110:113], v[166:169], v[182:185], v[110:113]
	v_mfma_f32_16x16x32_bf16 v[106:109], v[174:177], v[182:185], v[106:109]
	v_mfma_f32_16x16x32_bf16 v[94:97], v[166:169], v[190:193], v[94:97]
	v_mfma_f32_16x16x32_bf16 v[90:93], v[174:177], v[190:193], v[90:93]
	v_mfma_f32_16x16x32_bf16 v[78:81], v[166:169], v[198:201], v[78:81]
	v_mfma_f32_16x16x32_bf16 v[74:77], v[174:177], v[198:201], v[74:77]
	v_mfma_f32_16x16x32_bf16 v[70:73], v[166:169], v[206:209], v[70:73]
	v_mfma_f32_16x16x32_bf16 v[66:69], v[174:177], v[206:209], v[66:69]
	v_mfma_f32_16x16x32_bf16 v[110:113], v[170:173], v[186:189], v[110:113]
	v_mfma_f32_16x16x32_bf16 v[106:109], v[178:181], v[186:189], v[106:109]
	v_mfma_f32_16x16x32_bf16 v[94:97], v[170:173], v[194:197], v[94:97]
	v_mfma_f32_16x16x32_bf16 v[90:93], v[178:181], v[194:197], v[90:93]
	v_mfma_f32_16x16x32_bf16 v[78:81], v[170:173], v[202:205], v[78:81]
	v_mfma_f32_16x16x32_bf16 v[74:77], v[178:181], v[202:205], v[74:77]
	v_mfma_f32_16x16x32_bf16 v[70:73], v[170:173], v[210:213], v[70:73]
	v_mfma_f32_16x16x32_bf16 v[66:69], v[178:181], v[210:213], v[66:69]
	s_setprio 0
	s_barrier
	s_mov_b32 m0, s48
	v_lshl_add_u64 v[214:215], v[214:215], 0, s[16:17]
	s_add_u32 s44, s52, 0xb0080
	ds_read_b128 v[182:185], v146 offset:49152
	ds_read_b128 v[186:189], v146 offset:50176
	ds_read_b128 v[190:193], v146 offset:51200
	ds_read_b128 v[194:197], v146 offset:52224
	ds_read_b128 v[198:201], v146 offset:53248
	ds_read_b128 v[202:205], v146 offset:54272
	ds_read_b128 v[206:209], v146 offset:55296
	ds_read_b128 v[210:213], v146 offset:56320
	global_load_lds_dwordx4 v[214:215], off
	v_lshl_add_u64 v[214:215], v[216:217], 0, s[16:17]
	s_mov_b32 m0, s49
	s_addc_u32 s45, s53, 0
	global_load_lds_dwordx4 v[214:215], off
	v_lshl_add_u64 v[214:215], s[44:45], 0, v[130:131]
	s_mov_b32 m0, s83
	s_nop 0
	global_load_lds_dwordx4 v[214:215], off
	v_lshl_add_u64 v[214:215], s[44:45], 0, v[136:137]
	s_mov_b32 m0, s84
	s_nop 0
	global_load_lds_dwordx4 v[214:215], off
	v_lshl_add_u64 v[214:215], v[218:219], 0, s[16:17]
	s_mov_b32 m0, s50
	s_nop 0
	global_load_lds_dwordx4 v[214:215], off
	v_lshl_add_u64 v[214:215], v[220:221], 0, s[16:17]
	s_mov_b32 m0, s51
	s_nop 0
	global_load_lds_dwordx4 v[214:215], off
	s_waitcnt vmcnt(8)
	s_waitcnt lgkmcnt(0)
	s_barrier
; #define PG8_STAGE(bufoff, gbase, voff) do { _Pragma("unroll") for (int _i = 0; _i < 2; ++_i) \
;         __builtin_amdgcn_global_load_lds((const unsigned*)((const char*)(gbase) + (voff)[_i]), (PG8_LAS unsigned*)(lds + (bufoff) + ldsw + _i * 8192), 16, 0, 0); } while (0)
; #define PG8_LDA(dst, b, h) do { _Pragma("unroll") for (int m = 0; m < 4; ++m) _Pragma("unroll") for (int k = 0; k < 2; ++k) dst[m][k] = *(const PG8_LAS bf16x8*)(lds + PG8_SA(b, h) + aoff + m * 2048 + k * 1024); } while (0)
; #define PG8_LDB(dst, b, h) do { _Pragma("unroll") for (int n = 0; n < 2; ++n) _Pragma("unroll") for (int k = 0; k < 2; ++k) dst[n][k] = *(const PG8_LAS bf16x8*)(lds + PG8_SB(b, h) + boff + n * 2048 + k * 1024); } while (0)
; #define PG8_MMA(ai, bj, At, Bt) do { __builtin_amdgcn_s_setprio(1); _Pragma("unroll") for (int m = 0; m < 4; ++m) _Pragma("unroll") for (int n = 0; n < 2; ++n) _Pragma("unroll") for (int k = 0; k < 2; ++k) \
;         acc[ai][bj][m][n] = __builtin_amdgcn_mfma_f32_16x16x32_bf16(Bt[n][k], At[m][k], acc[ai][bj][m][n], 0, 0, 0); __builtin_amdgcn_s_setprio(0); } while (0)
; #define PG8_WAIT_V(n) asm volatile("s_waitcnt vmcnt(" #n ")" ::: "memory")
; #define PG8_WAIT_L(n) asm volatile("s_waitcnt lgkmcnt(" #n ")" ::: "memory")
; #define PG8_BAR __builtin_amdgcn_s_barrier()
; #define PG8_SCHED __builtin_amdgcn_sched_barrier(0)
; template <class Epi, class Sched, bool ALIGN_EPI = false, bool SP2 = false>
; __device__ __forceinline__ void gemm_phase(PG8_LAS unsigned char* lds, const Gemm g, const Sched& S, const Epi& E) {
;     ...
;         for (int t = 0; t < nt; t += 2) {
;             const bool last = (t == nt - 2);
;             const char* a1 = cA + (size_t)(t + 1) * kstep;
;             const char* a2 = last ? nA : cA + (size_t)(t + 2) * kstep; const char* b2 = last ? nB : cB + (size_t)(t + 2) * kstep;
;             const char* a3 = a2 + kstep; const char* b3 = b2 + kstep;
;             if (last && has_next) S.a_ready(nxt);
;             if constexpr (SP2) {
;             PG8_LDB(B0, 0, 0); PG8_LDB(B1, 0, 1); PG8_SCHED; PG8_LDA(At, 0, 0); PG8_STAGE(PG8_SA(1, 1), a1 + hstep, voffA);
;             PG8_WAIT_V(8); PG8_WAIT_L(0); PG8_BAR; PG8_MMA(0, 0, At, B0); PG8_MMA(0, 1, At, B1); PG8_BAR; PG8_SCHED;
;     ...
;             PG8_WAIT_V(8); PG8_WAIT_L(0); PG8_BAR; PG8_MMA(1, 0, At, B0); PG8_MMA(1, 1, At, B1); PG8_BAR; PG8_SCHED;
	s_setprio 1
	s_waitcnt lgkmcnt(0)
	v_mfma_f32_16x16x32_bf16 v[62:65], v[150:153], v[182:185], v[62:65]
	v_mfma_f32_16x16x32_bf16 v[58:61], v[158:161], v[182:185], v[58:61]
	v_mfma_f32_16x16x32_bf16 v[54:57], v[150:153], v[190:193], v[54:57]
	v_mfma_f32_16x16x32_bf16 v[50:53], v[158:161], v[190:193], v[50:53]
	v_mfma_f32_16x16x32_bf16 v[38:41], v[150:153], v[198:201], v[38:41]
	v_mfma_f32_16x16x32_bf16 v[34:37], v[158:161], v[198:201], v[34:37]
	v_mfma_f32_16x16x32_bf16 v[22:25], v[150:153], v[206:209], v[22:25]
	v_mfma_f32_16x16x32_bf16 v[18:21], v[158:161], v[206:209], v[18:21]
	v_mfma_f32_16x16x32_bf16 v[62:65], v[154:157], v[186:189], v[62:65]
	v_mfma_f32_16x16x32_bf16 v[58:61], v[162:165], v[186:189], v[58:61]
	v_mfma_f32_16x16x32_bf16 v[54:57], v[154:157], v[194:197], v[54:57]
	v_mfma_f32_16x16x32_bf16 v[50:53], v[162:165], v[194:197], v[50:53]
	v_mfma_f32_16x16x32_bf16 v[38:41], v[154:157], v[202:205], v[38:41]
	v_mfma_f32_16x16x32_bf16 v[34:37], v[162:165], v[202:205], v[34:37]
	v_mfma_f32_16x16x32_bf16 v[22:25], v[154:157], v[210:213], v[22:25]
	v_mfma_f32_16x16x32_bf16 v[18:21], v[162:165], v[210:213], v[18:21]
	s_setprio 0
	s_setprio 1
	v_mfma_f32_16x16x32_bf16 v[46:49], v[166:169], v[182:185], v[46:49]
	v_mfma_f32_16x16x32_bf16 v[42:45], v[174:177], v[182:185], v[42:45]
	v_mfma_f32_16x16x32_bf16 v[30:33], v[166:169], v[190:193], v[30:33]
	v_mfma_f32_16x16x32_bf16 v[26:29], v[174:177], v[190:193], v[26:29]
	v_mfma_f32_16x16x32_bf16 v[14:17], v[166:169], v[198:201], v[14:17]
	v_mfma_f32_16x16x32_bf16 v[10:13], v[174:177], v[198:201], v[10:13]
	v_mfma_f32_16x16x32_bf16 v[6:9], v[166:169], v[206:209], v[6:9]
	v_mfma_f32_16x16x32_bf16 v[2:5], v[174:177], v[206:209], v[2:5]
	v_mfma_f32_16x16x32_bf16 v[46:49], v[170:173], v[186:189], v[46:49]
	v_mfma_f32_16x16x32_bf16 v[42:45], v[178:181], v[186:189], v[42:45]
	v_mfma_f32_16x16x32_bf16 v[30:33], v[170:173], v[194:197], v[30:33]
	v_mfma_f32_16x16x32_bf16 v[26:29], v[178:181], v[194:197], v[26:29]
	v_mfma_f32_16x16x32_bf16 v[14:17], v[170:173], v[202:205], v[14:17]
	v_mfma_f32_16x16x32_bf16 v[10:13], v[178:181], v[202:205], v[10:13]
	v_mfma_f32_16x16x32_bf16 v[6:9], v[170:173], v[210:213], v[6:9]
	v_mfma_f32_16x16x32_bf16 v[2:5], v[178:181], v[210:213], v[2:5]
	s_setprio 0
	s_barrier
	s_add_u32 s91, s91, 0x100
	s_addc_u32 s92, s92, 0
	s_cmp_ge_u32 s93, s81
	s_mov_b64 s[44:45], s[46:47]
	s_mov_b32 s52, s93
.LBB0_1126:
	ds_read_b128 v[150:153], v147
	ds_read_b128 v[154:157], v147 offset:1024
	ds_read_b128 v[158:161], v147 offset:2048
	ds_read_b128 v[162:165], v147 offset:3072
	ds_read_b128 v[166:169], v148
	ds_read_b128 v[170:173], v148 offset:1024
	ds_read_b128 v[174:177], v148 offset:2048
	ds_read_b128 v[178:181], v148 offset:3072
	s_add_i32 s93, s52, 2
	s_add_u32 s46, s44, 0x100
	s_addc_u32 s47, s45, 0
	s_cmp_eq_u32 s86, s52
	s_cselect_b32 s52, s42, s91
	s_cselect_b32 s57, s41, s47
	s_cselect_b32 s56, s40, s46
	s_cselect_b32 s53, s43, s92
	v_lshl_add_u64 v[214:215], s[44:45], 0, v[140:141]
	s_add_i32 m0, s77, 0xc000
	ds_read_b128 v[182:185], v146
	ds_read_b128 v[186:189], v146 offset:1024
	ds_read_b128 v[190:193], v146 offset:2048
	ds_read_b128 v[194:197], v146 offset:3072
	ds_read_b128 v[198:201], v146 offset:4096
	ds_read_b128 v[202:205], v146 offset:5120
	ds_read_b128 v[206:209], v146 offset:6144
	ds_read_b128 v[210:213], v146 offset:7168
	global_load_lds_dwordx4 v[214:215], off
	v_lshl_add_u64 v[214:215], s[44:45], 0, v[138:139]
	s_add_i32 m0, s77, 0xe000
	s_nop 0
	global_load_lds_dwordx4 v[214:215], off
	s_waitcnt vmcnt(8)
	s_waitcnt lgkmcnt(0)
	s_barrier
	s_setprio 1
	s_waitcnt lgkmcnt(0)
	v_mfma_f32_16x16x32_bf16 v[126:129], v[150:153], v[182:185], v[126:129]
	v_mfma_f32_16x16x32_bf16 v[122:125], v[158:161], v[182:185], v[122:125]
	v_mfma_f32_16x16x32_bf16 v[118:121], v[150:153], v[190:193], v[118:121]
	v_mfma_f32_16x16x32_bf16 v[114:117], v[158:161], v[190:193], v[114:117]
	v_mfma_f32_16x16x32_bf16 v[102:105], v[150:153], v[198:201], v[102:105]
	v_mfma_f32_16x16x32_bf16 v[98:101], v[158:161], v[198:201], v[98:101]
	v_mfma_f32_16x16x32_bf16 v[86:89], v[150:153], v[206:209], v[86:89]
	v_mfma_f32_16x16x32_bf16 v[82:85], v[158:161], v[206:209], v[82:85]
	v_mfma_f32_16x16x32_bf16 v[126:129], v[154:157], v[186:189], v[126:129]
	v_mfma_f32_16x16x32_bf16 v[122:125], v[162:165], v[186:189], v[122:125]
	v_mfma_f32_16x16x32_bf16 v[118:121], v[154:157], v[194:197], v[118:121]
	v_mfma_f32_16x16x32_bf16 v[114:117], v[162:165], v[194:197], v[114:117]
	v_mfma_f32_16x16x32_bf16 v[102:105], v[154:157], v[202:205], v[102:105]
	v_mfma_f32_16x16x32_bf16 v[98:101], v[162:165], v[202:205], v[98:101]
	v_mfma_f32_16x16x32_bf16 v[86:89], v[154:157], v[210:213], v[86:89]
	v_mfma_f32_16x16x32_bf16 v[82:85], v[162:165], v[210:213], v[82:85]
	s_setprio 0
	s_setprio 1
	v_mfma_f32_16x16x32_bf16 v[110:113], v[166:169], v[182:185], v[110:113]
	v_mfma_f32_16x16x32_bf16 v[106:109], v[174:177], v[182:185], v[106:109]
	v_mfma_f32_16x16x32_bf16 v[94:97], v[166:169], v[190:193], v[94:97]
	v_mfma_f32_16x16x32_bf16 v[90:93], v[174:177], v[190:193], v[90:93]
	v_mfma_f32_16x16x32_bf16 v[78:81], v[166:169], v[198:201], v[78:81]
	v_mfma_f32_16x16x32_bf16 v[74:77], v[174:177], v[198:201], v[74:77]
	v_mfma_f32_16x16x32_bf16 v[70:73], v[166:169], v[206:209], v[70:73]
	v_mfma_f32_16x16x32_bf16 v[66:69], v[174:177], v[206:209], v[66:69]
	v_mfma_f32_16x16x32_bf16 v[110:113], v[170:173], v[186:189], v[110:113]
	v_mfma_f32_16x16x32_bf16 v[106:109], v[178:181], v[186:189], v[106:109]
	v_mfma_f32_16x16x32_bf16 v[94:97], v[170:173], v[194:197], v[94:97]
	v_mfma_f32_16x16x32_bf16 v[90:93], v[178:181], v[194:197], v[90:93]
	v_mfma_f32_16x16x32_bf16 v[78:81], v[170:173], v[202:205], v[78:81]
	v_mfma_f32_16x16x32_bf16 v[74:77], v[178:181], v[202:205], v[74:77]
	v_mfma_f32_16x16x32_bf16 v[70:73], v[170:173], v[210:213], v[70:73]
	v_mfma_f32_16x16x32_bf16 v[66:69], v[178:181], v[210:213], v[66:69]
	s_setprio 0
	s_barrier
; #define PG8_STAGE(bufoff, gbase, voff) do { _Pragma("unroll") for (int _i = 0; _i < 2; ++_i) \
;         __builtin_amdgcn_global_load_lds((const unsigned*)((const char*)(gbase) + (voff)[_i]), (PG8_LAS unsigned*)(lds + (bufoff) + ldsw + _i * 8192), 16, 0, 0); } while (0)
; #define PG8_LDA(dst, b, h) do { _Pragma("unroll") for (int m = 0; m < 4; ++m) _Pragma("unroll") for (int k = 0; k < 2; ++k) dst[m][k] = *(const PG8_LAS bf16x8*)(lds + PG8_SA(b, h) + aoff + m * 2048 + k * 1024); } while (0)
; #define PG8_LDB(dst, b, h) do { _Pragma("unroll") for (int n = 0; n < 2; ++n) _Pragma("unroll") for (int k = 0; k < 2; ++k) dst[n][k] = *(const PG8_LAS bf16x8*)(lds + PG8_SB(b, h) + boff + n * 2048 + k * 1024); } while (0)
; #define PG8_MMA(ai, bj, At, Bt) do { __builtin_amdgcn_s_setprio(1); _Pragma("unroll") for (int m = 0; m < 4; ++m) _Pragma("unroll") for (int n = 0; n < 2; ++n) _Pragma("unroll") for (int k = 0; k < 2; ++k) \
;         acc[ai][bj][m][n] = __builtin_amdgcn_mfma_f32_16x16x32_bf16(Bt[n][k], At[m][k], acc[ai][bj][m][n], 0, 0, 0); __builtin_amdgcn_s_setprio(0); } while (0)
; #define PG8_WAIT_V(n) asm volatile("s_waitcnt vmcnt(" #n ")" ::: "memory")
; #define PG8_WAIT_L(n) asm volatile("s_waitcnt lgkmcnt(" #n ")" ::: "memory")
; #define PG8_BAR __builtin_amdgcn_s_barrier()
; #define PG8_SCHED __builtin_amdgcn_sched_barrier(0)
; template <class Epi, class Sched, bool ALIGN_EPI = false, bool SP2 = false>
; __device__ __forceinline__ void gemm_phase(PG8_LAS unsigned char* lds, const Gemm g, const Sched& S, const Epi& E) {
;     ...
;             PG8_LDA(At, 0, 1); PG8_STAGE(PG8_SB(0, 0), b2, voffB); PG8_STAGE(PG8_SB(0, 1), b2 + hstep, voffB); PG8_STAGE(PG8_SA(0, 0), a2, voffA);
;             PG8_WAIT_V(8); PG8_WAIT_L(0); PG8_BAR; PG8_MMA(1, 0, At, B0); PG8_MMA(1, 1, At, B1); PG8_BAR; PG8_SCHED;
;             PG8_LDB(B0, 1, 0); PG8_LDB(B1, 1, 1); PG8_SCHED; PG8_LDA(At, 1, 0); PG8_STAGE(PG8_SA(0, 1), a2 + hstep, voffA);
;             PG8_WAIT_V(8); PG8_WAIT_L(0); PG8_BAR; PG8_MMA(0, 0, At, B0); PG8_MMA(0, 1, At, B1); PG8_BAR; PG8_SCHED;
	s_mov_b32 m0, s73
	v_lshl_add_u64 v[214:215], s[52:53], 0, v[130:131]
	s_add_u32 s44, s52, 0xb0000
	ds_read_b128 v[182:185], v146 offset:16384
	ds_read_b128 v[186:189], v146 offset:17408
	ds_read_b128 v[190:193], v146 offset:18432
	ds_read_b128 v[194:197], v146 offset:19456
	ds_read_b128 v[198:201], v146 offset:20480
	ds_read_b128 v[202:205], v146 offset:21504
	ds_read_b128 v[206:209], v146 offset:22528
	ds_read_b128 v[210:213], v146 offset:23552
	global_load_lds_dwordx4 v[214:215], off
	v_lshl_add_u64 v[216:217], s[52:53], 0, v[136:137]
	s_mov_b32 m0, s74
	s_addc_u32 s45, s53, 0
	global_load_lds_dwordx4 v[216:217], off
	v_lshl_add_u64 v[218:219], s[44:45], 0, v[130:131]
	s_mov_b32 m0, s75
	v_lshl_add_u64 v[220:221], s[56:57], 0, v[134:135]
	global_load_lds_dwordx4 v[218:219], off
	v_lshl_add_u64 v[218:219], s[44:45], 0, v[136:137]
	s_mov_b32 m0, s76
	s_nop 0
	global_load_lds_dwordx4 v[218:219], off
	v_lshl_add_u64 v[218:219], s[56:57], 0, v[132:133]
	s_waitcnt vmcnt(6)
	s_waitcnt lgkmcnt(0)
	s_barrier
	s_setprio 1
	s_waitcnt lgkmcnt(0)
	v_mfma_f32_16x16x32_bf16 v[62:65], v[150:153], v[182:185], v[62:65]
	v_mfma_f32_16x16x32_bf16 v[58:61], v[158:161], v[182:185], v[58:61]
	v_mfma_f32_16x16x32_bf16 v[54:57], v[150:153], v[190:193], v[54:57]
	v_mfma_f32_16x16x32_bf16 v[50:53], v[158:161], v[190:193], v[50:53]
	v_mfma_f32_16x16x32_bf16 v[38:41], v[150:153], v[198:201], v[38:41]
	v_mfma_f32_16x16x32_bf16 v[34:37], v[158:161], v[198:201], v[34:37]
	v_mfma_f32_16x16x32_bf16 v[22:25], v[150:153], v[206:209], v[22:25]
	v_mfma_f32_16x16x32_bf16 v[18:21], v[158:161], v[206:209], v[18:21]
	v_mfma_f32_16x16x32_bf16 v[62:65], v[154:157], v[186:189], v[62:65]
	v_mfma_f32_16x16x32_bf16 v[58:61], v[162:165], v[186:189], v[58:61]
	v_mfma_f32_16x16x32_bf16 v[54:57], v[154:157], v[194:197], v[54:57]
	v_mfma_f32_16x16x32_bf16 v[50:53], v[162:165], v[194:197], v[50:53]
	v_mfma_f32_16x16x32_bf16 v[38:41], v[154:157], v[202:205], v[38:41]
	v_mfma_f32_16x16x32_bf16 v[34:37], v[162:165], v[202:205], v[34:37]
	v_mfma_f32_16x16x32_bf16 v[22:25], v[154:157], v[210:213], v[22:25]
	v_mfma_f32_16x16x32_bf16 v[18:21], v[162:165], v[210:213], v[18:21]
	s_setprio 0
	s_setprio 1
	v_mfma_f32_16x16x32_bf16 v[46:49], v[166:169], v[182:185], v[46:49]
	v_mfma_f32_16x16x32_bf16 v[42:45], v[174:177], v[182:185], v[42:45]
	v_mfma_f32_16x16x32_bf16 v[30:33], v[166:169], v[190:193], v[30:33]
	v_mfma_f32_16x16x32_bf16 v[26:29], v[174:177], v[190:193], v[26:29]
	v_mfma_f32_16x16x32_bf16 v[14:17], v[166:169], v[198:201], v[14:17]
	v_mfma_f32_16x16x32_bf16 v[10:13], v[174:177], v[198:201], v[10:13]
	v_mfma_f32_16x16x32_bf16 v[6:9], v[166:169], v[206:209], v[6:9]
	v_mfma_f32_16x16x32_bf16 v[2:5], v[174:177], v[206:209], v[2:5]
	v_mfma_f32_16x16x32_bf16 v[46:49], v[170:173], v[186:189], v[46:49]
	v_mfma_f32_16x16x32_bf16 v[42:45], v[178:181], v[186:189], v[42:45]
	v_mfma_f32_16x16x32_bf16 v[30:33], v[170:173], v[194:197], v[30:33]
	v_mfma_f32_16x16x32_bf16 v[26:29], v[178:181], v[194:197], v[26:29]
	v_mfma_f32_16x16x32_bf16 v[14:17], v[170:173], v[202:205], v[14:17]
	v_mfma_f32_16x16x32_bf16 v[10:13], v[178:181], v[202:205], v[10:13]
	v_mfma_f32_16x16x32_bf16 v[6:9], v[170:173], v[210:213], v[6:9]
	v_mfma_f32_16x16x32_bf16 v[2:5], v[178:181], v[210:213], v[2:5]
	s_setprio 0
	s_barrier
	v_add_u32_e32 v178, s66, v144
	ds_read_b128 v[150:153], v149
	ds_read_b128 v[154:157], v149 offset:1024
	ds_read_b128 v[158:161], v149 offset:2048
	ds_read_b128 v[162:165], v149 offset:3072
	ds_read_b128 v[166:169], v178
	ds_read_b128 v[170:173], v178 offset:1024
	ds_read_b128 v[174:177], v178 offset:2048
	ds_read_b128 v[178:181], v178 offset:3072
	s_add_u32 s44, s56, 0xb0000
	s_addc_u32 s45, s57, 0
	s_mov_b32 m0, s77
	s_nop 0
	global_load_lds_dwordx4 v[218:219], off
	s_mov_b32 m0, s78
	s_nop 0
	global_load_lds_dwordx4 v[220:221], off
	s_mov_b32 m0, s79
	v_lshl_add_u64 v[222:223], s[44:45], 0, v[132:133]
	ds_read_b128 v[182:185], v146 offset:32768
	ds_read_b128 v[186:189], v146 offset:33792
	ds_read_b128 v[190:193], v146 offset:34816
	ds_read_b128 v[194:197], v146 offset:35840
	ds_read_b128 v[198:201], v146 offset:36864
	ds_read_b128 v[202:205], v146 offset:37888
	ds_read_b128 v[206:209], v146 offset:38912
	ds_read_b128 v[210:213], v146 offset:39936
	global_load_lds_dwordx4 v[222:223], off
	v_lshl_add_u64 v[222:223], s[44:45], 0, v[134:135]
	s_mov_b32 m0, s80
	s_nop 0
	global_load_lds_dwordx4 v[222:223], off
	s_waitcnt vmcnt(8)
	s_waitcnt lgkmcnt(0)
	s_barrier
; #define PG8_STAGE(bufoff, gbase, voff) do { _Pragma("unroll") for (int _i = 0; _i < 2; ++_i) \
;         __builtin_amdgcn_global_load_lds((const unsigned*)((const char*)(gbase) + (voff)[_i]), (PG8_LAS unsigned*)(lds + (bufoff) + ldsw + _i * 8192), 16, 0, 0); } while (0)
; #define PG8_LDA(dst, b, h) do { _Pragma("unroll") for (int m = 0; m < 4; ++m) _Pragma("unroll") for (int k = 0; k < 2; ++k) dst[m][k] = *(const PG8_LAS bf16x8*)(lds + PG8_SA(b, h) + aoff + m * 2048 + k * 1024); } while (0)
; #define PG8_MMA(ai, bj, At, Bt) do { __builtin_amdgcn_s_setprio(1); _Pragma("unroll") for (int m = 0; m < 4; ++m) _Pragma("unroll") for (int n = 0; n < 2; ++n) _Pragma("unroll") for (int k = 0; k < 2; ++k) \
;         acc[ai][bj][m][n] = __builtin_amdgcn_mfma_f32_16x16x32_bf16(Bt[n][k], At[m][k], acc[ai][bj][m][n], 0, 0, 0); __builtin_amdgcn_s_setprio(0); } while (0)
; #define PG8_WAIT_V(n) asm volatile("s_waitcnt vmcnt(" #n ")" ::: "memory")
; #define PG8_WAIT_L(n) asm volatile("s_waitcnt lgkmcnt(" #n ")" ::: "memory")
; #define PG8_BAR __builtin_amdgcn_s_barrier()
; #define PG8_SCHED __builtin_amdgcn_sched_barrier(0)
; template <class Epi, class Sched, bool ALIGN_EPI = false, bool SP2 = false>
; __device__ __forceinline__ void gemm_phase(PG8_LAS unsigned char* lds, const Gemm g, const Sched& S, const Epi& E) {
;     ...
;             PG8_WAIT_V(8); PG8_WAIT_L(0); PG8_BAR; PG8_MMA(0, 0, At, B0); PG8_MMA(0, 1, At, B1); PG8_BAR; PG8_SCHED;
;             PG8_LDA(At, 1, 1); PG8_STAGE(PG8_SB(1, 0), b3, voffB); PG8_STAGE(PG8_SB(1, 1), b3 + hstep, voffB); PG8_STAGE(PG8_SA(1, 0), a3, voffA);
;             PG8_WAIT_V(8); PG8_WAIT_L(0); PG8_BAR; PG8_MMA(1, 0, At, B0); PG8_MMA(1, 1, At, B1); PG8_BAR; PG8_SCHED;
	s_setprio 1
	s_waitcnt lgkmcnt(0)
	v_mfma_f32_16x16x32_bf16 v[126:129], v[150:153], v[182:185], v[126:129]
	v_mfma_f32_16x16x32_bf16 v[122:125], v[158:161], v[182:185], v[122:125]
	v_mfma_f32_16x16x32_bf16 v[118:121], v[150:153], v[190:193], v[118:121]
	v_mfma_f32_16x16x32_bf16 v[114:117], v[158:161], v[190:193], v[114:117]
	v_mfma_f32_16x16x32_bf16 v[102:105], v[150:153], v[198:201], v[102:105]
	v_mfma_f32_16x16x32_bf16 v[98:101], v[158:161], v[198:201], v[98:101]
	v_mfma_f32_16x16x32_bf16 v[86:89], v[150:153], v[206:209], v[86:89]
	v_mfma_f32_16x16x32_bf16 v[82:85], v[158:161], v[206:209], v[82:85]
	v_mfma_f32_16x16x32_bf16 v[126:129], v[154:157], v[186:189], v[126:129]
	v_mfma_f32_16x16x32_bf16 v[122:125], v[162:165], v[186:189], v[122:125]
	v_mfma_f32_16x16x32_bf16 v[118:121], v[154:157], v[194:197], v[118:121]
	v_mfma_f32_16x16x32_bf16 v[114:117], v[162:165], v[194:197], v[114:117]
	v_mfma_f32_16x16x32_bf16 v[102:105], v[154:157], v[202:205], v[102:105]
	v_mfma_f32_16x16x32_bf16 v[98:101], v[162:165], v[202:205], v[98:101]
	v_mfma_f32_16x16x32_bf16 v[86:89], v[154:157], v[210:213], v[86:89]
	v_mfma_f32_16x16x32_bf16 v[82:85], v[162:165], v[210:213], v[82:85]
	s_setprio 0
	s_setprio 1
	v_mfma_f32_16x16x32_bf16 v[110:113], v[166:169], v[182:185], v[110:113]
	v_mfma_f32_16x16x32_bf16 v[106:109], v[174:177], v[182:185], v[106:109]
	v_mfma_f32_16x16x32_bf16 v[94:97], v[166:169], v[190:193], v[94:97]
	v_mfma_f32_16x16x32_bf16 v[90:93], v[174:177], v[190:193], v[90:93]
	v_mfma_f32_16x16x32_bf16 v[78:81], v[166:169], v[198:201], v[78:81]
	v_mfma_f32_16x16x32_bf16 v[74:77], v[174:177], v[198:201], v[74:77]
	v_mfma_f32_16x16x32_bf16 v[70:73], v[166:169], v[206:209], v[70:73]
	v_mfma_f32_16x16x32_bf16 v[66:69], v[174:177], v[206:209], v[66:69]
	v_mfma_f32_16x16x32_bf16 v[110:113], v[170:173], v[186:189], v[110:113]
	v_mfma_f32_16x16x32_bf16 v[106:109], v[178:181], v[186:189], v[106:109]
	v_mfma_f32_16x16x32_bf16 v[94:97], v[170:173], v[194:197], v[94:97]
	v_mfma_f32_16x16x32_bf16 v[90:93], v[178:181], v[194:197], v[90:93]
	v_mfma_f32_16x16x32_bf16 v[78:81], v[170:173], v[202:205], v[78:81]
	v_mfma_f32_16x16x32_bf16 v[74:77], v[178:181], v[202:205], v[74:77]
	v_mfma_f32_16x16x32_bf16 v[70:73], v[170:173], v[210:213], v[70:73]
	v_mfma_f32_16x16x32_bf16 v[66:69], v[178:181], v[210:213], v[66:69]
	s_setprio 0
	s_barrier
	s_mov_b32 m0, s48
	v_lshl_add_u64 v[214:215], v[214:215], 0, s[16:17]
	s_add_u32 s44, s52, 0xb0080
	ds_read_b128 v[182:185], v146 offset:49152
	ds_read_b128 v[186:189], v146 offset:50176
	ds_read_b128 v[190:193], v146 offset:51200
	ds_read_b128 v[194:197], v146 offset:52224
	ds_read_b128 v[198:201], v146 offset:53248
	ds_read_b128 v[202:205], v146 offset:54272
	ds_read_b128 v[206:209], v146 offset:55296
	ds_read_b128 v[210:213], v146 offset:56320
	global_load_lds_dwordx4 v[214:215], off
	v_lshl_add_u64 v[214:215], v[216:217], 0, s[16:17]
	s_mov_b32 m0, s49
	s_addc_u32 s45, s53, 0
	global_load_lds_dwordx4 v[214:215], off
	v_lshl_add_u64 v[214:215], s[44:45], 0, v[130:131]
	s_mov_b32 m0, s83
	s_nop 0
	global_load_lds_dwordx4 v[214:215], off
	v_lshl_add_u64 v[214:215], s[44:45], 0, v[136:137]
	s_mov_b32 m0, s84
	s_nop 0
	global_load_lds_dwordx4 v[214:215], off
	v_lshl_add_u64 v[214:215], v[218:219], 0, s[16:17]
	s_mov_b32 m0, s50
	s_nop 0
	global_load_lds_dwordx4 v[214:215], off
	v_lshl_add_u64 v[214:215], v[220:221], 0, s[16:17]
	s_mov_b32 m0, s51
	s_nop 0
	global_load_lds_dwordx4 v[214:215], off
	s_waitcnt vmcnt(8)
	s_waitcnt lgkmcnt(0)
	s_barrier
	s_setprio 1
	s_waitcnt lgkmcnt(0)
	v_mfma_f32_16x16x32_bf16 v[62:65], v[150:153], v[182:185], v[62:65]
	v_mfma_f32_16x16x32_bf16 v[58:61], v[158:161], v[182:185], v[58:61]
	v_mfma_f32_16x16x32_bf16 v[54:57], v[150:153], v[190:193], v[54:57]
	v_mfma_f32_16x16x32_bf16 v[50:53], v[158:161], v[190:193], v[50:53]
	v_mfma_f32_16x16x32_bf16 v[38:41], v[150:153], v[198:201], v[38:41]
	v_mfma_f32_16x16x32_bf16 v[34:37], v[158:161], v[198:201], v[34:37]
	v_mfma_f32_16x16x32_bf16 v[22:25], v[150:153], v[206:209], v[22:25]
	v_mfma_f32_16x16x32_bf16 v[18:21], v[158:161], v[206:209], v[18:21]
	v_mfma_f32_16x16x32_bf16 v[62:65], v[154:157], v[186:189], v[62:65]
	v_mfma_f32_16x16x32_bf16 v[58:61], v[162:165], v[186:189], v[58:61]
	v_mfma_f32_16x16x32_bf16 v[54:57], v[154:157], v[194:197], v[54:57]
	v_mfma_f32_16x16x32_bf16 v[50:53], v[162:165], v[194:197], v[50:53]
	v_mfma_f32_16x16x32_bf16 v[38:41], v[154:157], v[202:205], v[38:41]
	v_mfma_f32_16x16x32_bf16 v[34:37], v[162:165], v[202:205], v[34:37]
	v_mfma_f32_16x16x32_bf16 v[22:25], v[154:157], v[210:213], v[22:25]
	v_mfma_f32_16x16x32_bf16 v[18:21], v[162:165], v[210:213], v[18:21]
	s_setprio 0
	s_setprio 1
	v_mfma_f32_16x16x32_bf16 v[46:49], v[166:169], v[182:185], v[46:49]
	v_mfma_f32_16x16x32_bf16 v[42:45], v[174:177], v[182:185], v[42:45]
	v_mfma_f32_16x16x32_bf16 v[30:33], v[166:169], v[190:193], v[30:33]
	v_mfma_f32_16x16x32_bf16 v[26:29], v[174:177], v[190:193], v[26:29]
	v_mfma_f32_16x16x32_bf16 v[14:17], v[166:169], v[198:201], v[14:17]
	v_mfma_f32_16x16x32_bf16 v[10:13], v[174:177], v[198:201], v[10:13]
	v_mfma_f32_16x16x32_bf16 v[6:9], v[166:169], v[206:209], v[6:9]
	v_mfma_f32_16x16x32_bf16 v[2:5], v[174:177], v[206:209], v[2:5]
	v_mfma_f32_16x16x32_bf16 v[46:49], v[170:173], v[186:189], v[46:49]
	v_mfma_f32_16x16x32_bf16 v[42:45], v[178:181], v[186:189], v[42:45]
	v_mfma_f32_16x16x32_bf16 v[30:33], v[170:173], v[194:197], v[30:33]
	v_mfma_f32_16x16x32_bf16 v[26:29], v[178:181], v[194:197], v[26:29]
	v_mfma_f32_16x16x32_bf16 v[14:17], v[170:173], v[202:205], v[14:17]
	v_mfma_f32_16x16x32_bf16 v[10:13], v[178:181], v[202:205], v[10:13]
	v_mfma_f32_16x16x32_bf16 v[6:9], v[170:173], v[210:213], v[6:9]
	v_mfma_f32_16x16x32_bf16 v[2:5], v[178:181], v[210:213], v[2:5]
	s_setprio 0
	s_barrier
	s_add_u32 s91, s91, 0x100
	s_addc_u32 s92, s92, 0
	s_cmp_ge_u32 s93, s81
	s_mov_b64 s[44:45], s[46:47]
	s_mov_b32 s52, s93
	s_cbranch_scc0 .LBB0_1126
	s_and_b64 vcc, exec, s[38:39]
	s_cbranch_vccz .LBB0_1129
	s_barrier

; #define PG8_STAGE(bufoff, gbase, voff) do { _Pragma("unroll") for (int _i = 0; _i < 2; ++_i) \
;         __builtin_amdgcn_global_load_lds((const unsigned*)((const char*)(gbase) + (voff)[_i]), (PG8_LAS unsigned*)(lds + (bufoff) + ldsw + _i * 8192), 16, 0, 0); } while (0)
; #define PG8_LDA(dst, b, h) do { _Pragma("unroll") for (int m = 0; m < 4; ++m) _Pragma("unroll") for (int k = 0; k < 2; ++k) dst[m][k] = *(const PG8_LAS bf16x8*)(lds + PG8_SA(b, h) + aoff + m * 2048 + k * 1024); } while (0)
; #define PG8_LDB(dst, b, h) do { _Pragma("unroll") for (int n = 0; n < 2; ++n) _Pragma("unroll") for (int k = 0; k < 2; ++k) dst[n][k] = *(const PG8_LAS bf16x8*)(lds + PG8_SB(b, h) + boff + n * 2048 + k * 1024); } while (0)
; #define PG8_WAIT_V(n) asm volatile("s_waitcnt vmcnt(" #n ")" ::: "memory")
; #define PG8_WAIT_L(n) asm volatile("s_waitcnt lgkmcnt(" #n ")" ::: "memory")
; #define PG8_BAR __builtin_amdgcn_s_barrier()
; template <class Epi, class Sched, bool ALIGN_EPI = false, bool SP2 = false>
; __device__ __forceinline__ void gemm_phase(PG8_LAS unsigned char* lds, const Gemm g, const Sched& S, const Epi& E) {
;     ...
;     for (;;) {
;         const bool has_next = S.next(ui + 1, nxt);
;         const char* nA = has_next ? (const char*)g.A + (size_t)nxt.pm * tstep + (size_t)nxt.ks * K * 2 : cA; const char* nB = has_next ? (const char*)g.Bt + (size_t)nxt.pn * tstep + (size_t)nxt.ks * K * 2 : cB;
;         for (int t = 0; t < nt; t += 2) {
;             const bool last = (t == nt - 2);
;             const char* a1 = cA + (size_t)(t + 1) * kstep;
;             const char* a2 = last ? nA : cA + (size_t)(t + 2) * kstep; const char* b2 = last ? nB : cB + (size_t)(t + 2) * kstep;
;             const char* a3 = a2 + kstep; const char* b3 = b2 + kstep;
;             if (last && has_next) S.a_ready(nxt);
;             if constexpr (SP2) {
;             PG8_LDB(B0, 0, 0); PG8_LDB(B1, 0, 1); PG8_SCHED; PG8_LDA(At, 0, 0); PG8_STAGE(PG8_SA(1, 1), a1 + hstep, voffA);
;             PG8_WAIT_V(8); PG8_WAIT_L(0); PG8_BAR; PG8_MMA(0, 0, At, B0); PG8_MMA(0, 1, At, B1); PG8_BAR; PG8_SCHED;
;             PG8_LDA(At, 0, 1); PG8_STAGE(PG8_SB(0, 0), b2, voffB); PG8_STAGE(PG8_SB(0, 1), b2 + hstep, voffB); PG8_STAGE(PG8_SA(0, 0), a2, voffA);
;             PG8_WAIT_V(8); PG8_WAIT_L(0); PG8_BAR; PG8_MMA(1, 0, At, B0); PG8_MMA(1, 1, At, B1); PG8_BAR; PG8_SCHED;
.LBB0_1582:
	s_ashr_i32 s73, s72, 31
	s_lshl_b64 s[12:13], s[72:73], 19
	s_add_u32 s74, s87, s12
	s_addc_u32 s75, s88, s13
	s_and_b64 s[12:13], s[4:5], exec
	s_cselect_b32 s7, s75, s11
	s_cselect_b32 s14, s74, s10
	s_ashr_i32 s71, s70, 31
	s_lshl_b64 s[12:13], s[70:71], 19
	s_add_u32 s76, s89, s12
	s_addc_u32 s77, s90, s13
	s_and_b64 s[12:13], s[4:5], exec
	s_cselect_b32 s15, s77, s9
	s_cselect_b32 s16, s76, s8
	s_add_u32 s17, s8, 0x100
	s_addc_u32 s18, s9, 0
	s_add_u32 s8, s10, 0x40080
	s_addc_u32 s9, s11, 0
	s_mov_b32 s19, -2
	ds_read_b128 v[130:133], v171
	ds_read_b128 v[134:137], v171 offset:1024
	ds_read_b128 v[156:159], v171 offset:2048
	ds_read_b128 v[160:163], v171 offset:3072
	ds_read_b128 v[164:167], v172
	ds_read_b128 v[178:181], v172 offset:1024
	ds_read_b128 v[182:185], v172 offset:2048
	ds_read_b128 v[186:189], v172 offset:3072
	s_add_u32 s10, s8, 0xfffc0080
	s_addc_u32 s11, s9, -1
	s_cmp_eq_u32 s19, 12
	s_cselect_b32 s13, s7, s11
	s_cselect_b32 s12, s14, s10
	s_cselect_b32 s11, s15, s18
	s_cselect_b32 s10, s16, s17
	v_lshl_add_u64 v[222:223], s[8:9], 0, v[150:151]
	s_add_i32 m0, s95, 0xc000
	ds_read_b128 v[190:193], v173
	ds_read_b128 v[194:197], v173 offset:1024
	ds_read_b128 v[198:201], v173 offset:2048
	ds_read_b128 v[202:205], v173 offset:3072
	ds_read_b128 v[206:209], v173 offset:4096
	ds_read_b128 v[210:213], v173 offset:5120
	ds_read_b128 v[214:217], v173 offset:6144
	ds_read_b128 v[218:221], v173 offset:7168
	global_load_lds_dwordx4 v[222:223], off
	v_lshl_add_u64 v[222:223], s[8:9], 0, v[148:149]
	s_add_i32 m0, s95, 0xe000
	s_nop 0
	global_load_lds_dwordx4 v[222:223], off
	s_waitcnt vmcnt(8)
	s_waitcnt lgkmcnt(0)
	s_barrier
	s_setprio 1
	s_waitcnt lgkmcnt(0)
	v_mfma_f32_16x16x32_bf16 v[126:129], v[130:133], v[190:193], 0
	v_mfma_f32_16x16x32_bf16 v[122:125], v[156:159], v[190:193], 0
	v_mfma_f32_16x16x32_bf16 v[110:113], v[130:133], v[198:201], 0
	v_mfma_f32_16x16x32_bf16 v[106:109], v[156:159], v[198:201], 0
	v_mfma_f32_16x16x32_bf16 v[94:97], v[130:133], v[206:209], 0
	v_mfma_f32_16x16x32_bf16 v[90:93], v[156:159], v[206:209], 0
	v_mfma_f32_16x16x32_bf16 v[78:81], v[130:133], v[214:217], 0
	v_mfma_f32_16x16x32_bf16 v[74:77], v[156:159], v[214:217], 0
	v_mfma_f32_16x16x32_bf16 v[126:129], v[134:137], v[194:197], v[126:129]
	v_mfma_f32_16x16x32_bf16 v[122:125], v[160:163], v[194:197], v[122:125]
	v_mfma_f32_16x16x32_bf16 v[110:113], v[134:137], v[202:205], v[110:113]
	v_mfma_f32_16x16x32_bf16 v[106:109], v[160:163], v[202:205], v[106:109]
	v_mfma_f32_16x16x32_bf16 v[94:97], v[134:137], v[210:213], v[94:97]
	v_mfma_f32_16x16x32_bf16 v[90:93], v[160:163], v[210:213], v[90:93]
	v_mfma_f32_16x16x32_bf16 v[78:81], v[134:137], v[218:221], v[78:81]
	v_mfma_f32_16x16x32_bf16 v[74:77], v[160:163], v[218:221], v[74:77]
	s_setprio 0
	s_setprio 1
	v_mfma_f32_16x16x32_bf16 v[118:121], v[164:167], v[190:193], 0
	v_mfma_f32_16x16x32_bf16 v[114:117], v[182:185], v[190:193], 0
	v_mfma_f32_16x16x32_bf16 v[102:105], v[164:167], v[198:201], 0
	v_mfma_f32_16x16x32_bf16 v[98:101], v[182:185], v[198:201], 0
	v_mfma_f32_16x16x32_bf16 v[86:89], v[164:167], v[206:209], 0
	v_mfma_f32_16x16x32_bf16 v[82:85], v[182:185], v[206:209], 0
	v_mfma_f32_16x16x32_bf16 v[70:73], v[164:167], v[214:217], 0
	v_mfma_f32_16x16x32_bf16 v[66:69], v[182:185], v[214:217], 0
	v_mfma_f32_16x16x32_bf16 v[118:121], v[178:181], v[194:197], v[118:121]
	v_mfma_f32_16x16x32_bf16 v[114:117], v[186:189], v[194:197], v[114:117]
	v_mfma_f32_16x16x32_bf16 v[102:105], v[178:181], v[202:205], v[102:105]
	v_mfma_f32_16x16x32_bf16 v[98:101], v[186:189], v[202:205], v[98:101]
	v_mfma_f32_16x16x32_bf16 v[86:89], v[178:181], v[210:213], v[86:89]
	v_mfma_f32_16x16x32_bf16 v[82:85], v[186:189], v[210:213], v[82:85]
	v_mfma_f32_16x16x32_bf16 v[70:73], v[178:181], v[218:221], v[70:73]
	v_mfma_f32_16x16x32_bf16 v[66:69], v[186:189], v[218:221], v[66:69]
	s_setprio 0
	s_barrier
	s_mov_b32 m0, s91
	v_lshl_add_u64 v[222:223], s[10:11], 0, v[138:139]
	s_add_u32 s20, s10, 0x40000
	ds_read_b128 v[190:193], v173 offset:16384
	ds_read_b128 v[194:197], v173 offset:17408
	ds_read_b128 v[198:201], v173 offset:18432
	ds_read_b128 v[202:205], v173 offset:19456
	ds_read_b128 v[206:209], v173 offset:20480
	ds_read_b128 v[210:213], v173 offset:21504
	ds_read_b128 v[214:217], v173 offset:22528
	ds_read_b128 v[218:221], v173 offset:23552
	global_load_lds_dwordx4 v[222:223], off
	v_lshl_add_u64 v[224:225], s[10:11], 0, v[140:141]
	s_mov_b32 m0, s92
	s_addc_u32 s21, s11, 0
	global_load_lds_dwordx4 v[224:225], off
	v_lshl_add_u64 v[226:227], s[20:21], 0, v[138:139]
	s_mov_b32 m0, s93
	v_lshl_add_u64 v[228:229], s[12:13], 0, v[140:141]
	global_load_lds_dwordx4 v[226:227], off
	v_lshl_add_u64 v[226:227], s[20:21], 0, v[140:141]
	s_mov_b32 m0, s94
	s_nop 0
	global_load_lds_dwordx4 v[226:227], off
	v_lshl_add_u64 v[226:227], s[12:13], 0, v[138:139]
	s_waitcnt vmcnt(6)
	s_waitcnt lgkmcnt(0)
	s_barrier
; #define PG8_STAGE(bufoff, gbase, voff) do { _Pragma("unroll") for (int _i = 0; _i < 2; ++_i) \
;         __builtin_amdgcn_global_load_lds((const unsigned*)((const char*)(gbase) + (voff)[_i]), (PG8_LAS unsigned*)(lds + (bufoff) + ldsw + _i * 8192), 16, 0, 0); } while (0)
; #define PG8_LDA(dst, b, h) do { _Pragma("unroll") for (int m = 0; m < 4; ++m) _Pragma("unroll") for (int k = 0; k < 2; ++k) dst[m][k] = *(const PG8_LAS bf16x8*)(lds + PG8_SA(b, h) + aoff + m * 2048 + k * 1024); } while (0)
; #define PG8_LDB(dst, b, h) do { _Pragma("unroll") for (int n = 0; n < 2; ++n) _Pragma("unroll") for (int k = 0; k < 2; ++k) dst[n][k] = *(const PG8_LAS bf16x8*)(lds + PG8_SB(b, h) + boff + n * 2048 + k * 1024); } while (0)
; #define PG8_MMA(ai, bj, At, Bt) do { __builtin_amdgcn_s_setprio(1); _Pragma("unroll") for (int m = 0; m < 4; ++m) _Pragma("unroll") for (int n = 0; n < 2; ++n) _Pragma("unroll") for (int k = 0; k < 2; ++k) \
;         acc[ai][bj][m][n] = __builtin_amdgcn_mfma_f32_16x16x32_bf16(Bt[n][k], At[m][k], acc[ai][bj][m][n], 0, 0, 0); __builtin_amdgcn_s_setprio(0); } while (0)
; #define PG8_WAIT_V(n) asm volatile("s_waitcnt vmcnt(" #n ")" ::: "memory")
; #define PG8_WAIT_L(n) asm volatile("s_waitcnt lgkmcnt(" #n ")" ::: "memory")
; #define PG8_BAR __builtin_amdgcn_s_barrier()
; #define PG8_SCHED __builtin_amdgcn_sched_barrier(0)
; template <class Epi, class Sched, bool ALIGN_EPI = false, bool SP2 = false>
; __device__ __forceinline__ void gemm_phase(PG8_LAS unsigned char* lds, const Gemm g, const Sched& S, const Epi& E) {
;     ...
;             PG8_WAIT_V(8); PG8_WAIT_L(0); PG8_BAR; PG8_MMA(1, 0, At, B0); PG8_MMA(1, 1, At, B1); PG8_BAR; PG8_SCHED;
;             PG8_LDB(B0, 1, 0); PG8_LDB(B1, 1, 1); PG8_SCHED; PG8_LDA(At, 1, 0); PG8_STAGE(PG8_SA(0, 1), a2 + hstep, voffA);
;             PG8_WAIT_V(8); PG8_WAIT_L(0); PG8_BAR; PG8_MMA(0, 0, At, B0); PG8_MMA(0, 1, At, B1); PG8_BAR; PG8_SCHED;
	s_setprio 1
	s_waitcnt lgkmcnt(0)
	v_mfma_f32_16x16x32_bf16 v[62:65], v[130:133], v[190:193], 0
	v_mfma_f32_16x16x32_bf16 v[58:61], v[156:159], v[190:193], 0
	v_mfma_f32_16x16x32_bf16 v[46:49], v[130:133], v[198:201], 0
	v_mfma_f32_16x16x32_bf16 v[42:45], v[156:159], v[198:201], 0
	v_mfma_f32_16x16x32_bf16 v[30:33], v[130:133], v[206:209], 0
	v_mfma_f32_16x16x32_bf16 v[26:29], v[156:159], v[206:209], 0
	v_mfma_f32_16x16x32_bf16 v[14:17], v[130:133], v[214:217], 0
	v_mfma_f32_16x16x32_bf16 v[10:13], v[156:159], v[214:217], 0
	v_mfma_f32_16x16x32_bf16 v[62:65], v[134:137], v[194:197], v[62:65]
	v_mfma_f32_16x16x32_bf16 v[58:61], v[160:163], v[194:197], v[58:61]
	v_mfma_f32_16x16x32_bf16 v[46:49], v[134:137], v[202:205], v[46:49]
	v_mfma_f32_16x16x32_bf16 v[42:45], v[160:163], v[202:205], v[42:45]
	v_mfma_f32_16x16x32_bf16 v[30:33], v[134:137], v[210:213], v[30:33]
	v_mfma_f32_16x16x32_bf16 v[26:29], v[160:163], v[210:213], v[26:29]
	v_mfma_f32_16x16x32_bf16 v[14:17], v[134:137], v[218:221], v[14:17]
	v_mfma_f32_16x16x32_bf16 v[10:13], v[160:163], v[218:221], v[10:13]
	s_setprio 0
	s_setprio 1
	v_mfma_f32_16x16x32_bf16 v[54:57], v[164:167], v[190:193], 0
	v_mfma_f32_16x16x32_bf16 v[50:53], v[182:185], v[190:193], 0
	v_mfma_f32_16x16x32_bf16 v[38:41], v[164:167], v[198:201], 0
	v_mfma_f32_16x16x32_bf16 v[34:37], v[182:185], v[198:201], 0
	v_mfma_f32_16x16x32_bf16 v[22:25], v[164:167], v[206:209], 0
	v_mfma_f32_16x16x32_bf16 v[18:21], v[182:185], v[206:209], 0
	v_mfma_f32_16x16x32_bf16 v[6:9], v[164:167], v[214:217], 0
	v_mfma_f32_16x16x32_bf16 v[2:5], v[182:185], v[214:217], 0
	v_mfma_f32_16x16x32_bf16 v[54:57], v[178:181], v[194:197], v[54:57]
	v_mfma_f32_16x16x32_bf16 v[50:53], v[186:189], v[194:197], v[50:53]
	v_mfma_f32_16x16x32_bf16 v[38:41], v[178:181], v[202:205], v[38:41]
	v_mfma_f32_16x16x32_bf16 v[34:37], v[186:189], v[202:205], v[34:37]
	v_mfma_f32_16x16x32_bf16 v[22:25], v[178:181], v[210:213], v[22:25]
	v_mfma_f32_16x16x32_bf16 v[18:21], v[186:189], v[210:213], v[18:21]
	v_mfma_f32_16x16x32_bf16 v[6:9], v[178:181], v[218:221], v[6:9]
	v_mfma_f32_16x16x32_bf16 v[2:5], v[186:189], v[218:221], v[2:5]
	s_setprio 0
	s_barrier
	ds_read_b128 v[130:133], v174
	ds_read_b128 v[134:137], v174 offset:1024
	ds_read_b128 v[156:159], v174 offset:2048
	ds_read_b128 v[160:163], v174 offset:3072
	ds_read_b128 v[164:167], v175
	ds_read_b128 v[178:181], v175 offset:1024
	ds_read_b128 v[182:185], v175 offset:2048
	ds_read_b128 v[186:189], v175 offset:3072
	s_add_u32 s12, s12, 0x40000
	s_addc_u32 s13, s13, 0
	s_mov_b32 m0, s95
	s_nop 0
	global_load_lds_dwordx4 v[226:227], off
	s_mov_b32 m0, s96
	s_nop 0
	global_load_lds_dwordx4 v[228:229], off
	s_mov_b32 m0, s97
	v_lshl_add_u64 v[230:231], s[12:13], 0, v[138:139]
	ds_read_b128 v[190:193], v173 offset:32768
	ds_read_b128 v[194:197], v173 offset:33792
	ds_read_b128 v[198:201], v173 offset:34816
	ds_read_b128 v[202:205], v173 offset:35840
	ds_read_b128 v[206:209], v173 offset:36864
	ds_read_b128 v[210:213], v173 offset:37888
	ds_read_b128 v[214:217], v173 offset:38912
	ds_read_b128 v[218:221], v173 offset:39936
	global_load_lds_dwordx4 v[230:231], off
	v_lshl_add_u64 v[230:231], s[12:13], 0, v[140:141]
	s_mov_b32 m0, s30
	s_nop 0
	global_load_lds_dwordx4 v[230:231], off
	s_waitcnt vmcnt(8)
	s_waitcnt lgkmcnt(0)
	s_barrier
	s_setprio 1
	s_waitcnt lgkmcnt(0)
	v_mfma_f32_16x16x32_bf16 v[126:129], v[130:133], v[190:193], v[126:129]
	v_mfma_f32_16x16x32_bf16 v[122:125], v[156:159], v[190:193], v[122:125]
	v_mfma_f32_16x16x32_bf16 v[110:113], v[130:133], v[198:201], v[110:113]
	v_mfma_f32_16x16x32_bf16 v[106:109], v[156:159], v[198:201], v[106:109]
	v_mfma_f32_16x16x32_bf16 v[94:97], v[130:133], v[206:209], v[94:97]
	v_mfma_f32_16x16x32_bf16 v[90:93], v[156:159], v[206:209], v[90:93]
	v_mfma_f32_16x16x32_bf16 v[78:81], v[130:133], v[214:217], v[78:81]
	v_mfma_f32_16x16x32_bf16 v[74:77], v[156:159], v[214:217], v[74:77]
	v_mfma_f32_16x16x32_bf16 v[126:129], v[134:137], v[194:197], v[126:129]
	v_mfma_f32_16x16x32_bf16 v[122:125], v[160:163], v[194:197], v[122:125]
	v_mfma_f32_16x16x32_bf16 v[110:113], v[134:137], v[202:205], v[110:113]
	v_mfma_f32_16x16x32_bf16 v[106:109], v[160:163], v[202:205], v[106:109]
	v_mfma_f32_16x16x32_bf16 v[94:97], v[134:137], v[210:213], v[94:97]
	v_mfma_f32_16x16x32_bf16 v[90:93], v[160:163], v[210:213], v[90:93]
	v_mfma_f32_16x16x32_bf16 v[78:81], v[134:137], v[218:221], v[78:81]
	v_mfma_f32_16x16x32_bf16 v[74:77], v[160:163], v[218:221], v[74:77]
	s_setprio 0
	s_setprio 1
	v_mfma_f32_16x16x32_bf16 v[118:121], v[164:167], v[190:193], v[118:121]
	v_mfma_f32_16x16x32_bf16 v[114:117], v[182:185], v[190:193], v[114:117]
	v_mfma_f32_16x16x32_bf16 v[102:105], v[164:167], v[198:201], v[102:105]
	v_mfma_f32_16x16x32_bf16 v[98:101], v[182:185], v[198:201], v[98:101]
	v_mfma_f32_16x16x32_bf16 v[86:89], v[164:167], v[206:209], v[86:89]
	v_mfma_f32_16x16x32_bf16 v[82:85], v[182:185], v[206:209], v[82:85]
	v_mfma_f32_16x16x32_bf16 v[70:73], v[164:167], v[214:217], v[70:73]
	v_mfma_f32_16x16x32_bf16 v[66:69], v[182:185], v[214:217], v[66:69]
	v_mfma_f32_16x16x32_bf16 v[118:121], v[178:181], v[194:197], v[118:121]
	v_mfma_f32_16x16x32_bf16 v[114:117], v[186:189], v[194:197], v[114:117]
	v_mfma_f32_16x16x32_bf16 v[102:105], v[178:181], v[202:205], v[102:105]
	v_mfma_f32_16x16x32_bf16 v[98:101], v[186:189], v[202:205], v[98:101]
	v_mfma_f32_16x16x32_bf16 v[86:89], v[178:181], v[210:213], v[86:89]
	v_mfma_f32_16x16x32_bf16 v[82:85], v[186:189], v[210:213], v[82:85]
	v_mfma_f32_16x16x32_bf16 v[70:73], v[178:181], v[218:221], v[70:73]
	v_mfma_f32_16x16x32_bf16 v[66:69], v[186:189], v[218:221], v[66:69]
	s_setprio 0
	s_barrier
; #define PG8_STAGE(bufoff, gbase, voff) do { _Pragma("unroll") for (int _i = 0; _i < 2; ++_i) \
;         __builtin_amdgcn_global_load_lds((const unsigned*)((const char*)(gbase) + (voff)[_i]), (PG8_LAS unsigned*)(lds + (bufoff) + ldsw + _i * 8192), 16, 0, 0); } while (0)
; #define PG8_LDA(dst, b, h) do { _Pragma("unroll") for (int m = 0; m < 4; ++m) _Pragma("unroll") for (int k = 0; k < 2; ++k) dst[m][k] = *(const PG8_LAS bf16x8*)(lds + PG8_SA(b, h) + aoff + m * 2048 + k * 1024); } while (0)
; #define PG8_LDB(dst, b, h) do { _Pragma("unroll") for (int n = 0; n < 2; ++n) _Pragma("unroll") for (int k = 0; k < 2; ++k) dst[n][k] = *(const PG8_LAS bf16x8*)(lds + PG8_SB(b, h) + boff + n * 2048 + k * 1024); } while (0)
; #define PG8_MMA(ai, bj, At, Bt) do { __builtin_amdgcn_s_setprio(1); _Pragma("unroll") for (int m = 0; m < 4; ++m) _Pragma("unroll") for (int n = 0; n < 2; ++n) _Pragma("unroll") for (int k = 0; k < 2; ++k) \
;         acc[ai][bj][m][n] = __builtin_amdgcn_mfma_f32_16x16x32_bf16(Bt[n][k], At[m][k], acc[ai][bj][m][n], 0, 0, 0); __builtin_amdgcn_s_setprio(0); } while (0)
; #define PG8_WAIT_V(n) asm volatile("s_waitcnt vmcnt(" #n ")" ::: "memory")
; #define PG8_BAR __builtin_amdgcn_s_barrier()
; template <class Epi, class Sched, bool ALIGN_EPI = false, bool SP2 = false>
; __device__ __forceinline__ void gemm_phase(PG8_LAS unsigned char* lds, const Gemm g, const Sched& S, const Epi& E) {
;     ...
;         for (int t = 0; t < nt; t += 2) {
;             const bool last = (t == nt - 2);
;             const char* a1 = cA + (size_t)(t + 1) * kstep;
;             const char* a2 = last ? nA : cA + (size_t)(t + 2) * kstep; const char* b2 = last ? nB : cB + (size_t)(t + 2) * kstep;
;             const char* a3 = a2 + kstep; const char* b3 = b2 + kstep;
;             if (last && has_next) S.a_ready(nxt);
;             if constexpr (SP2) {
;             PG8_LDB(B0, 0, 0); PG8_LDB(B1, 0, 1); PG8_SCHED; PG8_LDA(At, 0, 0); PG8_STAGE(PG8_SA(1, 1), a1 + hstep, voffA);
;             PG8_WAIT_V(8); PG8_WAIT_L(0); PG8_BAR; PG8_MMA(0, 0, At, B0); PG8_MMA(0, 1, At, B1); PG8_BAR; PG8_SCHED;
;     ...
;             PG8_LDA(At, 1, 1); PG8_STAGE(PG8_SB(1, 0), b3, voffB); PG8_STAGE(PG8_SB(1, 1), b3 + hstep, voffB); PG8_STAGE(PG8_SA(1, 0), a3, voffA);
;             PG8_WAIT_V(8); PG8_WAIT_L(0); PG8_BAR; PG8_MMA(1, 0, At, B0); PG8_MMA(1, 1, At, B1); PG8_BAR; PG8_SCHED;
	s_mov_b32 m0, s63
	v_lshl_add_u64 v[222:223], v[222:223], 0, s[56:57]
	s_add_u32 s10, s10, 0x40080
	ds_read_b128 v[190:193], v173 offset:49152
	ds_read_b128 v[194:197], v173 offset:50176
	ds_read_b128 v[198:201], v173 offset:51200
	ds_read_b128 v[202:205], v173 offset:52224
	ds_read_b128 v[206:209], v173 offset:53248
	ds_read_b128 v[210:213], v173 offset:54272
	ds_read_b128 v[214:217], v173 offset:55296
	ds_read_b128 v[218:221], v173 offset:56320
	global_load_lds_dwordx4 v[222:223], off
	v_lshl_add_u64 v[222:223], v[224:225], 0, s[56:57]
	s_mov_b32 m0, s64
	s_addc_u32 s11, s11, 0
	global_load_lds_dwordx4 v[222:223], off
	v_lshl_add_u64 v[222:223], s[10:11], 0, v[138:139]
	s_mov_b32 m0, s67
	s_nop 0
	global_load_lds_dwordx4 v[222:223], off
	v_lshl_add_u64 v[222:223], s[10:11], 0, v[140:141]
	s_mov_b32 m0, s26
	s_nop 0
	global_load_lds_dwordx4 v[222:223], off
	v_lshl_add_u64 v[222:223], v[226:227], 0, s[56:57]
	s_mov_b32 m0, s65
	s_nop 0
	global_load_lds_dwordx4 v[222:223], off
	v_lshl_add_u64 v[222:223], v[228:229], 0, s[56:57]
	s_mov_b32 m0, s66
	s_nop 0
	global_load_lds_dwordx4 v[222:223], off
	s_waitcnt vmcnt(8)
	s_waitcnt lgkmcnt(0)
	s_barrier
	s_setprio 1
	s_waitcnt lgkmcnt(0)
	v_mfma_f32_16x16x32_bf16 v[62:65], v[130:133], v[190:193], v[62:65]
	v_mfma_f32_16x16x32_bf16 v[58:61], v[156:159], v[190:193], v[58:61]
	v_mfma_f32_16x16x32_bf16 v[46:49], v[130:133], v[198:201], v[46:49]
	v_mfma_f32_16x16x32_bf16 v[42:45], v[156:159], v[198:201], v[42:45]
	v_mfma_f32_16x16x32_bf16 v[30:33], v[130:133], v[206:209], v[30:33]
	v_mfma_f32_16x16x32_bf16 v[26:29], v[156:159], v[206:209], v[26:29]
	v_mfma_f32_16x16x32_bf16 v[14:17], v[130:133], v[214:217], v[14:17]
	v_mfma_f32_16x16x32_bf16 v[10:13], v[156:159], v[214:217], v[10:13]
	v_mfma_f32_16x16x32_bf16 v[62:65], v[134:137], v[194:197], v[62:65]
	v_mfma_f32_16x16x32_bf16 v[58:61], v[160:163], v[194:197], v[58:61]
	v_mfma_f32_16x16x32_bf16 v[46:49], v[134:137], v[202:205], v[46:49]
	v_mfma_f32_16x16x32_bf16 v[42:45], v[160:163], v[202:205], v[42:45]
	v_mfma_f32_16x16x32_bf16 v[30:33], v[134:137], v[210:213], v[30:33]
	v_mfma_f32_16x16x32_bf16 v[26:29], v[160:163], v[210:213], v[26:29]
	v_mfma_f32_16x16x32_bf16 v[14:17], v[134:137], v[218:221], v[14:17]
	v_mfma_f32_16x16x32_bf16 v[10:13], v[160:163], v[218:221], v[10:13]
	s_setprio 0
	s_setprio 1
	v_mfma_f32_16x16x32_bf16 v[54:57], v[164:167], v[190:193], v[54:57]
	v_mfma_f32_16x16x32_bf16 v[50:53], v[182:185], v[190:193], v[50:53]
	v_mfma_f32_16x16x32_bf16 v[38:41], v[164:167], v[198:201], v[38:41]
	v_mfma_f32_16x16x32_bf16 v[34:37], v[182:185], v[198:201], v[34:37]
	v_mfma_f32_16x16x32_bf16 v[22:25], v[164:167], v[206:209], v[22:25]
	v_mfma_f32_16x16x32_bf16 v[18:21], v[182:185], v[206:209], v[18:21]
	v_mfma_f32_16x16x32_bf16 v[6:9], v[164:167], v[214:217], v[6:9]
	v_mfma_f32_16x16x32_bf16 v[2:5], v[182:185], v[214:217], v[2:5]
	v_mfma_f32_16x16x32_bf16 v[54:57], v[178:181], v[194:197], v[54:57]
	v_mfma_f32_16x16x32_bf16 v[50:53], v[186:189], v[194:197], v[50:53]
	v_mfma_f32_16x16x32_bf16 v[38:41], v[178:181], v[202:205], v[38:41]
	v_mfma_f32_16x16x32_bf16 v[34:37], v[186:189], v[202:205], v[34:37]
	v_mfma_f32_16x16x32_bf16 v[22:25], v[178:181], v[210:213], v[22:25]
	v_mfma_f32_16x16x32_bf16 v[18:21], v[186:189], v[210:213], v[18:21]
	v_mfma_f32_16x16x32_bf16 v[6:9], v[178:181], v[218:221], v[6:9]
	v_mfma_f32_16x16x32_bf16 v[2:5], v[186:189], v[218:221], v[2:5]
	s_setprio 0
	s_barrier
	s_add_i32 s19, s19, 2
	s_add_u32 s17, s17, 0x100
	s_addc_u32 s18, s18, 0
	s_add_u32 s8, s8, 0x100
	s_addc_u32 s9, s9, 0
	s_cmp_gt_u32 s19, 13
.LBB0_1583:
	ds_read_b128 v[130:133], v171
	ds_read_b128 v[134:137], v171 offset:1024
	ds_read_b128 v[156:159], v171 offset:2048
	ds_read_b128 v[160:163], v171 offset:3072
	ds_read_b128 v[164:167], v172
	ds_read_b128 v[178:181], v172 offset:1024
	ds_read_b128 v[182:185], v172 offset:2048
	ds_read_b128 v[186:189], v172 offset:3072
	s_add_u32 s10, s8, 0xfffc0080
	s_addc_u32 s11, s9, -1
	s_cmp_eq_u32 s19, 12
	s_cselect_b32 s13, s7, s11
	s_cselect_b32 s12, s14, s10
	s_cselect_b32 s11, s15, s18
	s_cselect_b32 s10, s16, s17
	v_lshl_add_u64 v[222:223], s[8:9], 0, v[150:151]
	s_add_i32 m0, s95, 0xc000
	ds_read_b128 v[190:193], v173
	ds_read_b128 v[194:197], v173 offset:1024
	ds_read_b128 v[198:201], v173 offset:2048
	ds_read_b128 v[202:205], v173 offset:3072
	ds_read_b128 v[206:209], v173 offset:4096
	ds_read_b128 v[210:213], v173 offset:5120
	ds_read_b128 v[214:217], v173 offset:6144
	ds_read_b128 v[218:221], v173 offset:7168
	global_load_lds_dwordx4 v[222:223], off
	v_lshl_add_u64 v[222:223], s[8:9], 0, v[148:149]
	s_add_i32 m0, s95, 0xe000
	s_nop 0
	global_load_lds_dwordx4 v[222:223], off
	s_waitcnt vmcnt(8)
	s_waitcnt lgkmcnt(0)
	s_barrier
; #define PG8_STAGE(bufoff, gbase, voff) do { _Pragma("unroll") for (int _i = 0; _i < 2; ++_i) \
;         __builtin_amdgcn_global_load_lds((const unsigned*)((const char*)(gbase) + (voff)[_i]), (PG8_LAS unsigned*)(lds + (bufoff) + ldsw + _i * 8192), 16, 0, 0); } while (0)
; #define PG8_LDA(dst, b, h) do { _Pragma("unroll") for (int m = 0; m < 4; ++m) _Pragma("unroll") for (int k = 0; k < 2; ++k) dst[m][k] = *(const PG8_LAS bf16x8*)(lds + PG8_SA(b, h) + aoff + m * 2048 + k * 1024); } while (0)
; #define PG8_MMA(ai, bj, At, Bt) do { __builtin_amdgcn_s_setprio(1); _Pragma("unroll") for (int m = 0; m < 4; ++m) _Pragma("unroll") for (int n = 0; n < 2; ++n) _Pragma("unroll") for (int k = 0; k < 2; ++k) \
;         acc[ai][bj][m][n] = __builtin_amdgcn_mfma_f32_16x16x32_bf16(Bt[n][k], At[m][k], acc[ai][bj][m][n], 0, 0, 0); __builtin_amdgcn_s_setprio(0); } while (0)
; #define PG8_WAIT_V(n) asm volatile("s_waitcnt vmcnt(" #n ")" ::: "memory")
; #define PG8_WAIT_L(n) asm volatile("s_waitcnt lgkmcnt(" #n ")" ::: "memory")
; #define PG8_BAR __builtin_amdgcn_s_barrier()
; #define PG8_SCHED __builtin_amdgcn_sched_barrier(0)
; template <class Epi, class Sched, bool ALIGN_EPI = false, bool SP2 = false>
; __device__ __forceinline__ void gemm_phase(PG8_LAS unsigned char* lds, const Gemm g, const Sched& S, const Epi& E) {
;     ...
;             PG8_WAIT_V(8); PG8_WAIT_L(0); PG8_BAR; PG8_MMA(0, 0, At, B0); PG8_MMA(0, 1, At, B1); PG8_BAR; PG8_SCHED;
;             PG8_LDA(At, 0, 1); PG8_STAGE(PG8_SB(0, 0), b2, voffB); PG8_STAGE(PG8_SB(0, 1), b2 + hstep, voffB); PG8_STAGE(PG8_SA(0, 0), a2, voffA);
;             PG8_WAIT_V(8); PG8_WAIT_L(0); PG8_BAR; PG8_MMA(1, 0, At, B0); PG8_MMA(1, 1, At, B1); PG8_BAR; PG8_SCHED;
	s_setprio 1
	s_waitcnt lgkmcnt(0)
	v_mfma_f32_16x16x32_bf16 v[126:129], v[130:133], v[190:193], v[126:129]
	v_mfma_f32_16x16x32_bf16 v[122:125], v[156:159], v[190:193], v[122:125]
	v_mfma_f32_16x16x32_bf16 v[110:113], v[130:133], v[198:201], v[110:113]
	v_mfma_f32_16x16x32_bf16 v[106:109], v[156:159], v[198:201], v[106:109]
	v_mfma_f32_16x16x32_bf16 v[94:97], v[130:133], v[206:209], v[94:97]
	v_mfma_f32_16x16x32_bf16 v[90:93], v[156:159], v[206:209], v[90:93]
	v_mfma_f32_16x16x32_bf16 v[78:81], v[130:133], v[214:217], v[78:81]
	v_mfma_f32_16x16x32_bf16 v[74:77], v[156:159], v[214:217], v[74:77]
	v_mfma_f32_16x16x32_bf16 v[126:129], v[134:137], v[194:197], v[126:129]
	v_mfma_f32_16x16x32_bf16 v[122:125], v[160:163], v[194:197], v[122:125]
	v_mfma_f32_16x16x32_bf16 v[110:113], v[134:137], v[202:205], v[110:113]
	v_mfma_f32_16x16x32_bf16 v[106:109], v[160:163], v[202:205], v[106:109]
	v_mfma_f32_16x16x32_bf16 v[94:97], v[134:137], v[210:213], v[94:97]
	v_mfma_f32_16x16x32_bf16 v[90:93], v[160:163], v[210:213], v[90:93]
	v_mfma_f32_16x16x32_bf16 v[78:81], v[134:137], v[218:221], v[78:81]
	v_mfma_f32_16x16x32_bf16 v[74:77], v[160:163], v[218:221], v[74:77]
	s_setprio 0
	s_setprio 1
	v_mfma_f32_16x16x32_bf16 v[118:121], v[164:167], v[190:193], v[118:121]
	v_mfma_f32_16x16x32_bf16 v[114:117], v[182:185], v[190:193], v[114:117]
	v_mfma_f32_16x16x32_bf16 v[102:105], v[164:167], v[198:201], v[102:105]
	v_mfma_f32_16x16x32_bf16 v[98:101], v[182:185], v[198:201], v[98:101]
	v_mfma_f32_16x16x32_bf16 v[86:89], v[164:167], v[206:209], v[86:89]
	v_mfma_f32_16x16x32_bf16 v[82:85], v[182:185], v[206:209], v[82:85]
	v_mfma_f32_16x16x32_bf16 v[70:73], v[164:167], v[214:217], v[70:73]
	v_mfma_f32_16x16x32_bf16 v[66:69], v[182:185], v[214:217], v[66:69]
	v_mfma_f32_16x16x32_bf16 v[118:121], v[178:181], v[194:197], v[118:121]
	v_mfma_f32_16x16x32_bf16 v[114:117], v[186:189], v[194:197], v[114:117]
	v_mfma_f32_16x16x32_bf16 v[102:105], v[178:181], v[202:205], v[102:105]
	v_mfma_f32_16x16x32_bf16 v[98:101], v[186:189], v[202:205], v[98:101]
	v_mfma_f32_16x16x32_bf16 v[86:89], v[178:181], v[210:213], v[86:89]
	v_mfma_f32_16x16x32_bf16 v[82:85], v[186:189], v[210:213], v[82:85]
	v_mfma_f32_16x16x32_bf16 v[70:73], v[178:181], v[218:221], v[70:73]
	v_mfma_f32_16x16x32_bf16 v[66:69], v[186:189], v[218:221], v[66:69]
	s_setprio 0
	s_barrier
	s_mov_b32 m0, s91
	v_lshl_add_u64 v[222:223], s[10:11], 0, v[138:139]
	s_add_u32 s20, s10, 0x40000
	ds_read_b128 v[190:193], v173 offset:16384
	ds_read_b128 v[194:197], v173 offset:17408
	ds_read_b128 v[198:201], v173 offset:18432
	ds_read_b128 v[202:205], v173 offset:19456
	ds_read_b128 v[206:209], v173 offset:20480
	ds_read_b128 v[210:213], v173 offset:21504
	ds_read_b128 v[214:217], v173 offset:22528
	ds_read_b128 v[218:221], v173 offset:23552
	global_load_lds_dwordx4 v[222:223], off
	v_lshl_add_u64 v[224:225], s[10:11], 0, v[140:141]
	s_mov_b32 m0, s92
	s_addc_u32 s21, s11, 0
	global_load_lds_dwordx4 v[224:225], off
	v_lshl_add_u64 v[226:227], s[20:21], 0, v[138:139]
	s_mov_b32 m0, s93
	v_lshl_add_u64 v[228:229], s[12:13], 0, v[140:141]
	global_load_lds_dwordx4 v[226:227], off
	v_lshl_add_u64 v[226:227], s[20:21], 0, v[140:141]
	s_mov_b32 m0, s94
	s_nop 0
	global_load_lds_dwordx4 v[226:227], off
	v_lshl_add_u64 v[226:227], s[12:13], 0, v[138:139]
	s_waitcnt vmcnt(6)
	s_waitcnt lgkmcnt(0)
	s_barrier
	s_setprio 1
	s_waitcnt lgkmcnt(0)
	v_mfma_f32_16x16x32_bf16 v[62:65], v[130:133], v[190:193], v[62:65]
	v_mfma_f32_16x16x32_bf16 v[58:61], v[156:159], v[190:193], v[58:61]
	v_mfma_f32_16x16x32_bf16 v[46:49], v[130:133], v[198:201], v[46:49]
	v_mfma_f32_16x16x32_bf16 v[42:45], v[156:159], v[198:201], v[42:45]
	v_mfma_f32_16x16x32_bf16 v[30:33], v[130:133], v[206:209], v[30:33]
	v_mfma_f32_16x16x32_bf16 v[26:29], v[156:159], v[206:209], v[26:29]
	v_mfma_f32_16x16x32_bf16 v[14:17], v[130:133], v[214:217], v[14:17]
	v_mfma_f32_16x16x32_bf16 v[10:13], v[156:159], v[214:217], v[10:13]
	v_mfma_f32_16x16x32_bf16 v[62:65], v[134:137], v[194:197], v[62:65]
	v_mfma_f32_16x16x32_bf16 v[58:61], v[160:163], v[194:197], v[58:61]
	v_mfma_f32_16x16x32_bf16 v[46:49], v[134:137], v[202:205], v[46:49]
	v_mfma_f32_16x16x32_bf16 v[42:45], v[160:163], v[202:205], v[42:45]
	v_mfma_f32_16x16x32_bf16 v[30:33], v[134:137], v[210:213], v[30:33]
	v_mfma_f32_16x16x32_bf16 v[26:29], v[160:163], v[210:213], v[26:29]
	v_mfma_f32_16x16x32_bf16 v[14:17], v[134:137], v[218:221], v[14:17]
	v_mfma_f32_16x16x32_bf16 v[10:13], v[160:163], v[218:221], v[10:13]
	s_setprio 0
	s_setprio 1
	v_mfma_f32_16x16x32_bf16 v[54:57], v[164:167], v[190:193], v[54:57]
	v_mfma_f32_16x16x32_bf16 v[50:53], v[182:185], v[190:193], v[50:53]
	v_mfma_f32_16x16x32_bf16 v[38:41], v[164:167], v[198:201], v[38:41]
	v_mfma_f32_16x16x32_bf16 v[34:37], v[182:185], v[198:201], v[34:37]
	v_mfma_f32_16x16x32_bf16 v[22:25], v[164:167], v[206:209], v[22:25]
	v_mfma_f32_16x16x32_bf16 v[18:21], v[182:185], v[206:209], v[18:21]
	v_mfma_f32_16x16x32_bf16 v[6:9], v[164:167], v[214:217], v[6:9]
	v_mfma_f32_16x16x32_bf16 v[2:5], v[182:185], v[214:217], v[2:5]
	v_mfma_f32_16x16x32_bf16 v[54:57], v[178:181], v[194:197], v[54:57]
	v_mfma_f32_16x16x32_bf16 v[50:53], v[186:189], v[194:197], v[50:53]
	v_mfma_f32_16x16x32_bf16 v[38:41], v[178:181], v[202:205], v[38:41]
	v_mfma_f32_16x16x32_bf16 v[34:37], v[186:189], v[202:205], v[34:37]
	v_mfma_f32_16x16x32_bf16 v[22:25], v[178:181], v[210:213], v[22:25]
	v_mfma_f32_16x16x32_bf16 v[18:21], v[186:189], v[210:213], v[18:21]
	v_mfma_f32_16x16x32_bf16 v[6:9], v[178:181], v[218:221], v[6:9]
	v_mfma_f32_16x16x32_bf16 v[2:5], v[186:189], v[218:221], v[2:5]
	s_setprio 0
	s_barrier
; #define PG8_STAGE(bufoff, gbase, voff) do { _Pragma("unroll") for (int _i = 0; _i < 2; ++_i) \
;         __builtin_amdgcn_global_load_lds((const unsigned*)((const char*)(gbase) + (voff)[_i]), (PG8_LAS unsigned*)(lds + (bufoff) + ldsw + _i * 8192), 16, 0, 0); } while (0)
; #define PG8_LDA(dst, b, h) do { _Pragma("unroll") for (int m = 0; m < 4; ++m) _Pragma("unroll") for (int k = 0; k < 2; ++k) dst[m][k] = *(const PG8_LAS bf16x8*)(lds + PG8_SA(b, h) + aoff + m * 2048 + k * 1024); } while (0)
; #define PG8_LDB(dst, b, h) do { _Pragma("unroll") for (int n = 0; n < 2; ++n) _Pragma("unroll") for (int k = 0; k < 2; ++k) dst[n][k] = *(const PG8_LAS bf16x8*)(lds + PG8_SB(b, h) + boff + n * 2048 + k * 1024); } while (0)
; #define PG8_MMA(ai, bj, At, Bt) do { __builtin_amdgcn_s_setprio(1); _Pragma("unroll") for (int m = 0; m < 4; ++m) _Pragma("unroll") for (int n = 0; n < 2; ++n) _Pragma("unroll") for (int k = 0; k < 2; ++k) \
;         acc[ai][bj][m][n] = __builtin_amdgcn_mfma_f32_16x16x32_bf16(Bt[n][k], At[m][k], acc[ai][bj][m][n], 0, 0, 0); __builtin_amdgcn_s_setprio(0); } while (0)
; #define PG8_WAIT_V(n) asm volatile("s_waitcnt vmcnt(" #n ")" ::: "memory")
; #define PG8_WAIT_L(n) asm volatile("s_waitcnt lgkmcnt(" #n ")" ::: "memory")
; #define PG8_BAR __builtin_amdgcn_s_barrier()
; #define PG8_SCHED __builtin_amdgcn_sched_barrier(0)
; template <class Epi, class Sched, bool ALIGN_EPI = false, bool SP2 = false>
; __device__ __forceinline__ void gemm_phase(PG8_LAS unsigned char* lds, const Gemm g, const Sched& S, const Epi& E) {
;     ...
;             PG8_LDB(B0, 1, 0); PG8_LDB(B1, 1, 1); PG8_SCHED; PG8_LDA(At, 1, 0); PG8_STAGE(PG8_SA(0, 1), a2 + hstep, voffA);
;             PG8_WAIT_V(8); PG8_WAIT_L(0); PG8_BAR; PG8_MMA(0, 0, At, B0); PG8_MMA(0, 1, At, B1); PG8_BAR; PG8_SCHED;
	ds_read_b128 v[130:133], v174
	ds_read_b128 v[134:137], v174 offset:1024
	ds_read_b128 v[156:159], v174 offset:2048
	ds_read_b128 v[160:163], v174 offset:3072
	ds_read_b128 v[164:167], v175
	ds_read_b128 v[178:181], v175 offset:1024
	ds_read_b128 v[182:185], v175 offset:2048
	ds_read_b128 v[186:189], v175 offset:3072
	s_add_u32 s12, s12, 0x40000
	s_addc_u32 s13, s13, 0
	s_mov_b32 m0, s95
	s_nop 0
	global_load_lds_dwordx4 v[226:227], off
	s_mov_b32 m0, s96
	s_nop 0
	global_load_lds_dwordx4 v[228:229], off
	s_mov_b32 m0, s97
	v_lshl_add_u64 v[230:231], s[12:13], 0, v[138:139]
	ds_read_b128 v[190:193], v173 offset:32768
	ds_read_b128 v[194:197], v173 offset:33792
	ds_read_b128 v[198:201], v173 offset:34816
	ds_read_b128 v[202:205], v173 offset:35840
	ds_read_b128 v[206:209], v173 offset:36864
	ds_read_b128 v[210:213], v173 offset:37888
	ds_read_b128 v[214:217], v173 offset:38912
	ds_read_b128 v[218:221], v173 offset:39936
	global_load_lds_dwordx4 v[230:231], off
	v_lshl_add_u64 v[230:231], s[12:13], 0, v[140:141]
	s_mov_b32 m0, s30
	s_nop 0
	global_load_lds_dwordx4 v[230:231], off
	s_waitcnt vmcnt(8)
	s_waitcnt lgkmcnt(0)
	s_barrier
	s_setprio 1
	s_waitcnt lgkmcnt(0)
	v_mfma_f32_16x16x32_bf16 v[126:129], v[130:133], v[190:193], v[126:129]
	v_mfma_f32_16x16x32_bf16 v[122:125], v[156:159], v[190:193], v[122:125]
	v_mfma_f32_16x16x32_bf16 v[110:113], v[130:133], v[198:201], v[110:113]
	v_mfma_f32_16x16x32_bf16 v[106:109], v[156:159], v[198:201], v[106:109]
	v_mfma_f32_16x16x32_bf16 v[94:97], v[130:133], v[206:209], v[94:97]
	v_mfma_f32_16x16x32_bf16 v[90:93], v[156:159], v[206:209], v[90:93]
	v_mfma_f32_16x16x32_bf16 v[78:81], v[130:133], v[214:217], v[78:81]
	v_mfma_f32_16x16x32_bf16 v[74:77], v[156:159], v[214:217], v[74:77]
	v_mfma_f32_16x16x32_bf16 v[126:129], v[134:137], v[194:197], v[126:129]
	v_mfma_f32_16x16x32_bf16 v[122:125], v[160:163], v[194:197], v[122:125]
	v_mfma_f32_16x16x32_bf16 v[110:113], v[134:137], v[202:205], v[110:113]
	v_mfma_f32_16x16x32_bf16 v[106:109], v[160:163], v[202:205], v[106:109]
	v_mfma_f32_16x16x32_bf16 v[94:97], v[134:137], v[210:213], v[94:97]
	v_mfma_f32_16x16x32_bf16 v[90:93], v[160:163], v[210:213], v[90:93]
	v_mfma_f32_16x16x32_bf16 v[78:81], v[134:137], v[218:221], v[78:81]
	v_mfma_f32_16x16x32_bf16 v[74:77], v[160:163], v[218:221], v[74:77]
	s_setprio 0
	s_setprio 1
	v_mfma_f32_16x16x32_bf16 v[118:121], v[164:167], v[190:193], v[118:121]
	v_mfma_f32_16x16x32_bf16 v[114:117], v[182:185], v[190:193], v[114:117]
	v_mfma_f32_16x16x32_bf16 v[102:105], v[164:167], v[198:201], v[102:105]
	v_mfma_f32_16x16x32_bf16 v[98:101], v[182:185], v[198:201], v[98:101]
	v_mfma_f32_16x16x32_bf16 v[86:89], v[164:167], v[206:209], v[86:89]
	v_mfma_f32_16x16x32_bf16 v[82:85], v[182:185], v[206:209], v[82:85]
	v_mfma_f32_16x16x32_bf16 v[70:73], v[164:167], v[214:217], v[70:73]
	v_mfma_f32_16x16x32_bf16 v[66:69], v[182:185], v[214:217], v[66:69]
	v_mfma_f32_16x16x32_bf16 v[118:121], v[178:181], v[194:197], v[118:121]
	v_mfma_f32_16x16x32_bf16 v[114:117], v[186:189], v[194:197], v[114:117]
	v_mfma_f32_16x16x32_bf16 v[102:105], v[178:181], v[202:205], v[102:105]
	v_mfma_f32_16x16x32_bf16 v[98:101], v[186:189], v[202:205], v[98:101]
	v_mfma_f32_16x16x32_bf16 v[86:89], v[178:181], v[210:213], v[86:89]
	v_mfma_f32_16x16x32_bf16 v[82:85], v[186:189], v[210:213], v[82:85]
	v_mfma_f32_16x16x32_bf16 v[70:73], v[178:181], v[218:221], v[70:73]
	v_mfma_f32_16x16x32_bf16 v[66:69], v[186:189], v[218:221], v[66:69]
	s_setprio 0
	s_barrier
; #define PG8_STAGE(bufoff, gbase, voff) do { _Pragma("unroll") for (int _i = 0; _i < 2; ++_i) \
;         __builtin_amdgcn_global_load_lds((const unsigned*)((const char*)(gbase) + (voff)[_i]), (PG8_LAS unsigned*)(lds + (bufoff) + ldsw + _i * 8192), 16, 0, 0); } while (0)
; #define PG8_LDA(dst, b, h) do { _Pragma("unroll") for (int m = 0; m < 4; ++m) _Pragma("unroll") for (int k = 0; k < 2; ++k) dst[m][k] = *(const PG8_LAS bf16x8*)(lds + PG8_SA(b, h) + aoff + m * 2048 + k * 1024); } while (0)
; #define PG8_MMA(ai, bj, At, Bt) do { __builtin_amdgcn_s_setprio(1); _Pragma("unroll") for (int m = 0; m < 4; ++m) _Pragma("unroll") for (int n = 0; n < 2; ++n) _Pragma("unroll") for (int k = 0; k < 2; ++k) \
;         acc[ai][bj][m][n] = __builtin_amdgcn_mfma_f32_16x16x32_bf16(Bt[n][k], At[m][k], acc[ai][bj][m][n], 0, 0, 0); __builtin_amdgcn_s_setprio(0); } while (0)
; #define PG8_WAIT_V(n) asm volatile("s_waitcnt vmcnt(" #n ")" ::: "memory")
; #define PG8_WAIT_L(n) asm volatile("s_waitcnt lgkmcnt(" #n ")" ::: "memory")
; #define PG8_BAR __builtin_amdgcn_s_barrier()
; #define PG8_SCHED __builtin_amdgcn_sched_barrier(0)
; template <class Epi, class Sched, bool ALIGN_EPI = false, bool SP2 = false>
; __device__ __forceinline__ void gemm_phase(PG8_LAS unsigned char* lds, const Gemm g, const Sched& S, const Epi& E) {
;     ...
;             PG8_LDA(At, 1, 1); PG8_STAGE(PG8_SB(1, 0), b3, voffB); PG8_STAGE(PG8_SB(1, 1), b3 + hstep, voffB); PG8_STAGE(PG8_SA(1, 0), a3, voffA);
;             PG8_WAIT_V(8); PG8_WAIT_L(0); PG8_BAR; PG8_MMA(1, 0, At, B0); PG8_MMA(1, 1, At, B1); PG8_BAR; PG8_SCHED;
	s_mov_b32 m0, s63
	v_lshl_add_u64 v[222:223], v[222:223], 0, s[56:57]
	s_add_u32 s10, s10, 0x40080
	ds_read_b128 v[190:193], v173 offset:49152
	ds_read_b128 v[194:197], v173 offset:50176
	ds_read_b128 v[198:201], v173 offset:51200
	ds_read_b128 v[202:205], v173 offset:52224
	ds_read_b128 v[206:209], v173 offset:53248
	ds_read_b128 v[210:213], v173 offset:54272
	ds_read_b128 v[214:217], v173 offset:55296
	ds_read_b128 v[218:221], v173 offset:56320
	global_load_lds_dwordx4 v[222:223], off
	v_lshl_add_u64 v[222:223], v[224:225], 0, s[56:57]
	s_mov_b32 m0, s64
	s_addc_u32 s11, s11, 0
	global_load_lds_dwordx4 v[222:223], off
	v_lshl_add_u64 v[222:223], s[10:11], 0, v[138:139]
	s_mov_b32 m0, s67
	s_nop 0
	global_load_lds_dwordx4 v[222:223], off
	v_lshl_add_u64 v[222:223], s[10:11], 0, v[140:141]
	s_mov_b32 m0, s26
	s_nop 0
	global_load_lds_dwordx4 v[222:223], off
	v_lshl_add_u64 v[222:223], v[226:227], 0, s[56:57]
	s_mov_b32 m0, s65
	s_nop 0
	global_load_lds_dwordx4 v[222:223], off
	v_lshl_add_u64 v[222:223], v[228:229], 0, s[56:57]
	s_mov_b32 m0, s66
	s_nop 0
	global_load_lds_dwordx4 v[222:223], off
	s_waitcnt vmcnt(8)
	s_waitcnt lgkmcnt(0)
	s_barrier
	s_setprio 1
	s_waitcnt lgkmcnt(0)
	v_mfma_f32_16x16x32_bf16 v[62:65], v[130:133], v[190:193], v[62:65]
	v_mfma_f32_16x16x32_bf16 v[58:61], v[156:159], v[190:193], v[58:61]
	v_mfma_f32_16x16x32_bf16 v[46:49], v[130:133], v[198:201], v[46:49]
	v_mfma_f32_16x16x32_bf16 v[42:45], v[156:159], v[198:201], v[42:45]
	v_mfma_f32_16x16x32_bf16 v[30:33], v[130:133], v[206:209], v[30:33]
	v_mfma_f32_16x16x32_bf16 v[26:29], v[156:159], v[206:209], v[26:29]
	v_mfma_f32_16x16x32_bf16 v[14:17], v[130:133], v[214:217], v[14:17]
	v_mfma_f32_16x16x32_bf16 v[10:13], v[156:159], v[214:217], v[10:13]
	v_mfma_f32_16x16x32_bf16 v[62:65], v[134:137], v[194:197], v[62:65]
	v_mfma_f32_16x16x32_bf16 v[58:61], v[160:163], v[194:197], v[58:61]
	v_mfma_f32_16x16x32_bf16 v[46:49], v[134:137], v[202:205], v[46:49]
	v_mfma_f32_16x16x32_bf16 v[42:45], v[160:163], v[202:205], v[42:45]
	v_mfma_f32_16x16x32_bf16 v[30:33], v[134:137], v[210:213], v[30:33]
	v_mfma_f32_16x16x32_bf16 v[26:29], v[160:163], v[210:213], v[26:29]
	v_mfma_f32_16x16x32_bf16 v[14:17], v[134:137], v[218:221], v[14:17]
	v_mfma_f32_16x16x32_bf16 v[10:13], v[160:163], v[218:221], v[10:13]
	s_setprio 0
	s_setprio 1
	v_mfma_f32_16x16x32_bf16 v[54:57], v[164:167], v[190:193], v[54:57]
	v_mfma_f32_16x16x32_bf16 v[50:53], v[182:185], v[190:193], v[50:53]
	v_mfma_f32_16x16x32_bf16 v[38:41], v[164:167], v[198:201], v[38:41]
	v_mfma_f32_16x16x32_bf16 v[34:37], v[182:185], v[198:201], v[34:37]
	v_mfma_f32_16x16x32_bf16 v[22:25], v[164:167], v[206:209], v[22:25]
	v_mfma_f32_16x16x32_bf16 v[18:21], v[182:185], v[206:209], v[18:21]
	v_mfma_f32_16x16x32_bf16 v[6:9], v[164:167], v[214:217], v[6:9]
	v_mfma_f32_16x16x32_bf16 v[2:5], v[182:185], v[214:217], v[2:5]
	v_mfma_f32_16x16x32_bf16 v[54:57], v[178:181], v[194:197], v[54:57]
	v_mfma_f32_16x16x32_bf16 v[50:53], v[186:189], v[194:197], v[50:53]
	v_mfma_f32_16x16x32_bf16 v[38:41], v[178:181], v[202:205], v[38:41]
	v_mfma_f32_16x16x32_bf16 v[34:37], v[186:189], v[202:205], v[34:37]
	v_mfma_f32_16x16x32_bf16 v[22:25], v[178:181], v[210:213], v[22:25]
	v_mfma_f32_16x16x32_bf16 v[18:21], v[186:189], v[210:213], v[18:21]
	v_mfma_f32_16x16x32_bf16 v[6:9], v[178:181], v[218:221], v[6:9]
	v_mfma_f32_16x16x32_bf16 v[2:5], v[186:189], v[218:221], v[2:5]
	s_setprio 0
	s_barrier
	s_add_i32 s19, s19, 2
	s_add_u32 s17, s17, 0x100
	s_addc_u32 s18, s18, 0
	s_add_u32 s8, s8, 0x100
	s_addc_u32 s9, s9, 0
	s_cmp_gt_u32 s19, 13
	s_cbranch_scc0 .LBB0_1583
	s_and_b64 vcc, exec, s[60:61]
	s_cbranch_vccz .LBB0_1586
	s_barrier

; #define PG8_STAGE(bufoff, gbase, voff) do { _Pragma("unroll") for (int _i = 0; _i < 2; ++_i) \
;         __builtin_amdgcn_global_load_lds((const unsigned*)((const char*)(gbase) + (voff)[_i]), (PG8_LAS unsigned*)(lds + (bufoff) + ldsw + _i * 8192), 16, 0, 0); } while (0)
; #define PG8_LDA(dst, b, h) do { _Pragma("unroll") for (int m = 0; m < 4; ++m) _Pragma("unroll") for (int k = 0; k < 2; ++k) dst[m][k] = *(const PG8_LAS bf16x8*)(lds + PG8_SA(b, h) + aoff + m * 2048 + k * 1024); } while (0)
; #define PG8_LDB(dst, b, h) do { _Pragma("unroll") for (int n = 0; n < 2; ++n) _Pragma("unroll") for (int k = 0; k < 2; ++k) dst[n][k] = *(const PG8_LAS bf16x8*)(lds + PG8_SB(b, h) + boff + n * 2048 + k * 1024); } while (0)
; #define PG8_WAIT_V(n) asm volatile("s_waitcnt vmcnt(" #n ")" ::: "memory")
; #define PG8_WAIT_L(n) asm volatile("s_waitcnt lgkmcnt(" #n ")" ::: "memory")
; #define PG8_BAR __builtin_amdgcn_s_barrier()
; template <class Epi, class Sched, bool ALIGN_EPI = false, bool SP2 = false>
; __device__ __forceinline__ void gemm_phase(PG8_LAS unsigned char* lds, const Gemm g, const Sched& S, const Epi& E) {
;     ...
;     for (;;) {
;         const bool has_next = S.next(ui + 1, nxt);
;         const char* nA = has_next ? (const char*)g.A + (size_t)nxt.pm * tstep + (size_t)nxt.ks * K * 2 : cA; const char* nB = has_next ? (const char*)g.Bt + (size_t)nxt.pn * tstep + (size_t)nxt.ks * K * 2 : cB;
;         for (int t = 0; t < nt; t += 2) {
;             const bool last = (t == nt - 2);
;             const char* a1 = cA + (size_t)(t + 1) * kstep;
;             const char* a2 = last ? nA : cA + (size_t)(t + 2) * kstep; const char* b2 = last ? nB : cB + (size_t)(t + 2) * kstep;
;             const char* a3 = a2 + kstep; const char* b3 = b2 + kstep;
;             if (last && has_next) S.a_ready(nxt);
;             if constexpr (SP2) {
;             PG8_LDB(B0, 0, 0); PG8_LDB(B1, 0, 1); PG8_SCHED; PG8_LDA(At, 0, 0); PG8_STAGE(PG8_SA(1, 1), a1 + hstep, voffA);
;             PG8_WAIT_V(8); PG8_WAIT_L(0); PG8_BAR; PG8_MMA(0, 0, At, B0); PG8_MMA(0, 1, At, B1); PG8_BAR; PG8_SCHED;
;             PG8_LDA(At, 0, 1); PG8_STAGE(PG8_SB(0, 0), b2, voffB); PG8_STAGE(PG8_SB(0, 1), b2 + hstep, voffB); PG8_STAGE(PG8_SA(0, 0), a2, voffA);
;             PG8_WAIT_V(8); PG8_WAIT_L(0); PG8_BAR; PG8_MMA(1, 0, At, B0); PG8_MMA(1, 1, At, B1); PG8_BAR; PG8_SCHED;
.LBB0_2133:
	s_ashr_i32 s21, s20, 31
	s_lshl_b64 s[24:25], s[20:21], 19
	s_add_u32 s24, s31, s24
	s_addc_u32 s25, s33, s25
	s_and_b64 s[36:37], s[2:3], exec
	s_cselect_b32 s21, s25, s41
	s_cselect_b32 s64, s24, s40
	s_ashr_i32 s23, s22, 31
	s_lshl_b64 s[36:37], s[22:23], 19
	s_add_u32 s36, s29, s36
	s_addc_u32 s37, s30, s37
	s_and_b64 s[42:43], s[2:3], exec
	s_cselect_b32 s23, s37, s39
	s_cselect_b32 s65, s36, s38
	s_add_u32 s66, s38, 0x100
	s_addc_u32 s67, s39, 0
	s_add_u32 s38, s40, 0x40080
	s_addc_u32 s39, s41, 0
	s_mov_b32 s68, -2
	ds_read_b128 v[154:157], v148
	ds_read_b128 v[158:161], v148 offset:1024
	ds_read_b128 v[162:165], v148 offset:2048
	ds_read_b128 v[166:169], v148 offset:3072
	ds_read_b128 v[170:173], v149
	ds_read_b128 v[174:177], v149 offset:1024
	ds_read_b128 v[178:181], v149 offset:2048
	ds_read_b128 v[182:185], v149 offset:3072
	s_add_u32 s40, s38, 0xfffc0080
	s_addc_u32 s41, s39, -1
	s_cmp_eq_u32 s68, 12
	s_cselect_b32 s43, s21, s41
	s_cselect_b32 s42, s64, s40
	s_cselect_b32 s41, s23, s67
	s_cselect_b32 s40, s65, s66
	v_lshl_add_u64 v[218:219], s[38:39], 0, v[140:141]
	s_add_i32 m0, s47, 0xc000
	ds_read_b128 v[186:189], v150
	ds_read_b128 v[190:193], v150 offset:1024
	ds_read_b128 v[194:197], v150 offset:2048
	ds_read_b128 v[198:201], v150 offset:3072
	ds_read_b128 v[202:205], v150 offset:4096
	ds_read_b128 v[206:209], v150 offset:5120
	ds_read_b128 v[210:213], v150 offset:6144
	ds_read_b128 v[214:217], v150 offset:7168
	global_load_lds_dwordx4 v[218:219], off
	v_lshl_add_u64 v[218:219], s[38:39], 0, v[138:139]
	s_add_i32 m0, s47, 0xe000
	s_nop 0
	global_load_lds_dwordx4 v[218:219], off
	s_waitcnt vmcnt(8)
	s_waitcnt lgkmcnt(0)
	s_barrier
	s_setprio 1
	s_waitcnt lgkmcnt(0)
	v_mfma_f32_16x16x32_bf16 v[126:129], v[154:157], v[186:189], 0
	v_mfma_f32_16x16x32_bf16 v[122:125], v[162:165], v[186:189], 0
	v_mfma_f32_16x16x32_bf16 v[118:121], v[154:157], v[194:197], 0
	v_mfma_f32_16x16x32_bf16 v[114:117], v[162:165], v[194:197], 0
	v_mfma_f32_16x16x32_bf16 v[102:105], v[154:157], v[202:205], 0
	v_mfma_f32_16x16x32_bf16 v[98:101], v[162:165], v[202:205], 0
	v_mfma_f32_16x16x32_bf16 v[86:89], v[154:157], v[210:213], 0
	v_mfma_f32_16x16x32_bf16 v[82:85], v[162:165], v[210:213], 0
	v_mfma_f32_16x16x32_bf16 v[126:129], v[158:161], v[190:193], v[126:129]
	v_mfma_f32_16x16x32_bf16 v[122:125], v[166:169], v[190:193], v[122:125]
	v_mfma_f32_16x16x32_bf16 v[118:121], v[158:161], v[198:201], v[118:121]
	v_mfma_f32_16x16x32_bf16 v[114:117], v[166:169], v[198:201], v[114:117]
	v_mfma_f32_16x16x32_bf16 v[102:105], v[158:161], v[206:209], v[102:105]
	v_mfma_f32_16x16x32_bf16 v[98:101], v[166:169], v[206:209], v[98:101]
	v_mfma_f32_16x16x32_bf16 v[86:89], v[158:161], v[214:217], v[86:89]
	v_mfma_f32_16x16x32_bf16 v[82:85], v[166:169], v[214:217], v[82:85]
	s_setprio 0
	s_setprio 1
	v_mfma_f32_16x16x32_bf16 v[110:113], v[170:173], v[186:189], 0
	v_mfma_f32_16x16x32_bf16 v[106:109], v[178:181], v[186:189], 0
	v_mfma_f32_16x16x32_bf16 v[94:97], v[170:173], v[194:197], 0
	v_mfma_f32_16x16x32_bf16 v[90:93], v[178:181], v[194:197], 0
	v_mfma_f32_16x16x32_bf16 v[78:81], v[170:173], v[202:205], 0
	v_mfma_f32_16x16x32_bf16 v[74:77], v[178:181], v[202:205], 0
	v_mfma_f32_16x16x32_bf16 v[70:73], v[170:173], v[210:213], 0
	v_mfma_f32_16x16x32_bf16 v[66:69], v[178:181], v[210:213], 0
	v_mfma_f32_16x16x32_bf16 v[110:113], v[174:177], v[190:193], v[110:113]
	v_mfma_f32_16x16x32_bf16 v[106:109], v[182:185], v[190:193], v[106:109]
	v_mfma_f32_16x16x32_bf16 v[94:97], v[174:177], v[198:201], v[94:97]
	v_mfma_f32_16x16x32_bf16 v[90:93], v[182:185], v[198:201], v[90:93]
	v_mfma_f32_16x16x32_bf16 v[78:81], v[174:177], v[206:209], v[78:81]
	v_mfma_f32_16x16x32_bf16 v[74:77], v[182:185], v[206:209], v[74:77]
	v_mfma_f32_16x16x32_bf16 v[70:73], v[174:177], v[214:217], v[70:73]
	v_mfma_f32_16x16x32_bf16 v[66:69], v[182:185], v[214:217], v[66:69]
	s_setprio 0
	s_barrier
	s_mov_b32 m0, s19
	v_lshl_add_u64 v[218:219], s[40:41], 0, v[132:133]
	s_add_u32 s70, s40, 0x40000
	ds_read_b128 v[186:189], v150 offset:16384
	ds_read_b128 v[190:193], v150 offset:17408
	ds_read_b128 v[194:197], v150 offset:18432
	ds_read_b128 v[198:201], v150 offset:19456
	ds_read_b128 v[202:205], v150 offset:20480
	ds_read_b128 v[206:209], v150 offset:21504
	ds_read_b128 v[210:213], v150 offset:22528
	ds_read_b128 v[214:217], v150 offset:23552
	global_load_lds_dwordx4 v[218:219], off
	v_lshl_add_u64 v[220:221], s[40:41], 0, v[136:137]
	s_mov_b32 m0, s44
	s_addc_u32 s71, s41, 0
	global_load_lds_dwordx4 v[220:221], off
	v_lshl_add_u64 v[222:223], s[70:71], 0, v[132:133]
	s_mov_b32 m0, s45
	v_lshl_add_u64 v[224:225], s[42:43], 0, v[134:135]
	global_load_lds_dwordx4 v[222:223], off
	v_lshl_add_u64 v[222:223], s[70:71], 0, v[136:137]
	s_mov_b32 m0, s46
	s_nop 0
	global_load_lds_dwordx4 v[222:223], off
	v_lshl_add_u64 v[222:223], s[42:43], 0, v[130:131]
	s_waitcnt vmcnt(6)
	s_waitcnt lgkmcnt(0)
	s_barrier
; #define PG8_STAGE(bufoff, gbase, voff) do { _Pragma("unroll") for (int _i = 0; _i < 2; ++_i) \
;         __builtin_amdgcn_global_load_lds((const unsigned*)((const char*)(gbase) + (voff)[_i]), (PG8_LAS unsigned*)(lds + (bufoff) + ldsw + _i * 8192), 16, 0, 0); } while (0)
; #define PG8_LDA(dst, b, h) do { _Pragma("unroll") for (int m = 0; m < 4; ++m) _Pragma("unroll") for (int k = 0; k < 2; ++k) dst[m][k] = *(const PG8_LAS bf16x8*)(lds + PG8_SA(b, h) + aoff + m * 2048 + k * 1024); } while (0)
; #define PG8_LDB(dst, b, h) do { _Pragma("unroll") for (int n = 0; n < 2; ++n) _Pragma("unroll") for (int k = 0; k < 2; ++k) dst[n][k] = *(const PG8_LAS bf16x8*)(lds + PG8_SB(b, h) + boff + n * 2048 + k * 1024); } while (0)
; #define PG8_MMA(ai, bj, At, Bt) do { __builtin_amdgcn_s_setprio(1); _Pragma("unroll") for (int m = 0; m < 4; ++m) _Pragma("unroll") for (int n = 0; n < 2; ++n) _Pragma("unroll") for (int k = 0; k < 2; ++k) \
;         acc[ai][bj][m][n] = __builtin_amdgcn_mfma_f32_16x16x32_bf16(Bt[n][k], At[m][k], acc[ai][bj][m][n], 0, 0, 0); __builtin_amdgcn_s_setprio(0); } while (0)
; #define PG8_WAIT_V(n) asm volatile("s_waitcnt vmcnt(" #n ")" ::: "memory")
; #define PG8_WAIT_L(n) asm volatile("s_waitcnt lgkmcnt(" #n ")" ::: "memory")
; #define PG8_BAR __builtin_amdgcn_s_barrier()
; #define PG8_SCHED __builtin_amdgcn_sched_barrier(0)
; template <class Epi, class Sched, bool ALIGN_EPI = false, bool SP2 = false>
; __device__ __forceinline__ void gemm_phase(PG8_LAS unsigned char* lds, const Gemm g, const Sched& S, const Epi& E) {
;     ...
;             PG8_WAIT_V(8); PG8_WAIT_L(0); PG8_BAR; PG8_MMA(1, 0, At, B0); PG8_MMA(1, 1, At, B1); PG8_BAR; PG8_SCHED;
;             PG8_LDB(B0, 1, 0); PG8_LDB(B1, 1, 1); PG8_SCHED; PG8_LDA(At, 1, 0); PG8_STAGE(PG8_SA(0, 1), a2 + hstep, voffA);
;             PG8_WAIT_V(8); PG8_WAIT_L(0); PG8_BAR; PG8_MMA(0, 0, At, B0); PG8_MMA(0, 1, At, B1); PG8_BAR; PG8_SCHED;
	s_setprio 1
	s_waitcnt lgkmcnt(0)
	v_mfma_f32_16x16x32_bf16 v[62:65], v[154:157], v[186:189], 0
	v_mfma_f32_16x16x32_bf16 v[58:61], v[162:165], v[186:189], 0
	v_mfma_f32_16x16x32_bf16 v[54:57], v[154:157], v[194:197], 0
	v_mfma_f32_16x16x32_bf16 v[50:53], v[162:165], v[194:197], 0
	v_mfma_f32_16x16x32_bf16 v[38:41], v[154:157], v[202:205], 0
	v_mfma_f32_16x16x32_bf16 v[34:37], v[162:165], v[202:205], 0
	v_mfma_f32_16x16x32_bf16 v[22:25], v[154:157], v[210:213], 0
	v_mfma_f32_16x16x32_bf16 v[18:21], v[162:165], v[210:213], 0
	v_mfma_f32_16x16x32_bf16 v[62:65], v[158:161], v[190:193], v[62:65]
	v_mfma_f32_16x16x32_bf16 v[58:61], v[166:169], v[190:193], v[58:61]
	v_mfma_f32_16x16x32_bf16 v[54:57], v[158:161], v[198:201], v[54:57]
	v_mfma_f32_16x16x32_bf16 v[50:53], v[166:169], v[198:201], v[50:53]
	v_mfma_f32_16x16x32_bf16 v[38:41], v[158:161], v[206:209], v[38:41]
	v_mfma_f32_16x16x32_bf16 v[34:37], v[166:169], v[206:209], v[34:37]
	v_mfma_f32_16x16x32_bf16 v[22:25], v[158:161], v[214:217], v[22:25]
	v_mfma_f32_16x16x32_bf16 v[18:21], v[166:169], v[214:217], v[18:21]
	s_setprio 0
	s_setprio 1
	v_mfma_f32_16x16x32_bf16 v[46:49], v[170:173], v[186:189], 0
	v_mfma_f32_16x16x32_bf16 v[42:45], v[178:181], v[186:189], 0
	v_mfma_f32_16x16x32_bf16 v[30:33], v[170:173], v[194:197], 0
	v_mfma_f32_16x16x32_bf16 v[26:29], v[178:181], v[194:197], 0
	v_mfma_f32_16x16x32_bf16 v[14:17], v[170:173], v[202:205], 0
	v_mfma_f32_16x16x32_bf16 v[10:13], v[178:181], v[202:205], 0
	v_mfma_f32_16x16x32_bf16 v[6:9], v[170:173], v[210:213], 0
	v_mfma_f32_16x16x32_bf16 v[2:5], v[178:181], v[210:213], 0
	v_mfma_f32_16x16x32_bf16 v[46:49], v[174:177], v[190:193], v[46:49]
	v_mfma_f32_16x16x32_bf16 v[42:45], v[182:185], v[190:193], v[42:45]
	v_mfma_f32_16x16x32_bf16 v[30:33], v[174:177], v[198:201], v[30:33]
	v_mfma_f32_16x16x32_bf16 v[26:29], v[182:185], v[198:201], v[26:29]
	v_mfma_f32_16x16x32_bf16 v[14:17], v[174:177], v[206:209], v[14:17]
	v_mfma_f32_16x16x32_bf16 v[10:13], v[182:185], v[206:209], v[10:13]
	v_mfma_f32_16x16x32_bf16 v[6:9], v[174:177], v[214:217], v[6:9]
	v_mfma_f32_16x16x32_bf16 v[2:5], v[182:185], v[214:217], v[2:5]
	s_setprio 0
	s_barrier
	ds_read_b128 v[154:157], v151
	ds_read_b128 v[158:161], v151 offset:1024
	ds_read_b128 v[162:165], v151 offset:2048
	ds_read_b128 v[166:169], v151 offset:3072
	ds_read_b128 v[170:173], v152
	ds_read_b128 v[174:177], v152 offset:1024
	ds_read_b128 v[178:181], v152 offset:2048
	ds_read_b128 v[182:185], v152 offset:3072
	s_add_u32 s42, s42, 0x40000
	s_addc_u32 s43, s43, 0
	s_mov_b32 m0, s47
	s_nop 0
	global_load_lds_dwordx4 v[222:223], off
	s_mov_b32 m0, s48
	s_nop 0
	global_load_lds_dwordx4 v[224:225], off
	s_mov_b32 m0, s49
	v_lshl_add_u64 v[226:227], s[42:43], 0, v[130:131]
	ds_read_b128 v[186:189], v150 offset:32768
	ds_read_b128 v[190:193], v150 offset:33792
	ds_read_b128 v[194:197], v150 offset:34816
	ds_read_b128 v[198:201], v150 offset:35840
	ds_read_b128 v[202:205], v150 offset:36864
	ds_read_b128 v[206:209], v150 offset:37888
	ds_read_b128 v[210:213], v150 offset:38912
	ds_read_b128 v[214:217], v150 offset:39936
	global_load_lds_dwordx4 v[226:227], off
	v_lshl_add_u64 v[226:227], s[42:43], 0, v[134:135]
	s_mov_b32 m0, s50
	s_nop 0
	global_load_lds_dwordx4 v[226:227], off
	s_waitcnt vmcnt(8)
	s_waitcnt lgkmcnt(0)
	s_barrier
	s_setprio 1
	s_waitcnt lgkmcnt(0)
	v_mfma_f32_16x16x32_bf16 v[126:129], v[154:157], v[186:189], v[126:129]
	v_mfma_f32_16x16x32_bf16 v[122:125], v[162:165], v[186:189], v[122:125]
	v_mfma_f32_16x16x32_bf16 v[118:121], v[154:157], v[194:197], v[118:121]
	v_mfma_f32_16x16x32_bf16 v[114:117], v[162:165], v[194:197], v[114:117]
	v_mfma_f32_16x16x32_bf16 v[102:105], v[154:157], v[202:205], v[102:105]
	v_mfma_f32_16x16x32_bf16 v[98:101], v[162:165], v[202:205], v[98:101]
	v_mfma_f32_16x16x32_bf16 v[86:89], v[154:157], v[210:213], v[86:89]
	v_mfma_f32_16x16x32_bf16 v[82:85], v[162:165], v[210:213], v[82:85]
	v_mfma_f32_16x16x32_bf16 v[126:129], v[158:161], v[190:193], v[126:129]
	v_mfma_f32_16x16x32_bf16 v[122:125], v[166:169], v[190:193], v[122:125]
	v_mfma_f32_16x16x32_bf16 v[118:121], v[158:161], v[198:201], v[118:121]
	v_mfma_f32_16x16x32_bf16 v[114:117], v[166:169], v[198:201], v[114:117]
	v_mfma_f32_16x16x32_bf16 v[102:105], v[158:161], v[206:209], v[102:105]
	v_mfma_f32_16x16x32_bf16 v[98:101], v[166:169], v[206:209], v[98:101]
	v_mfma_f32_16x16x32_bf16 v[86:89], v[158:161], v[214:217], v[86:89]
	v_mfma_f32_16x16x32_bf16 v[82:85], v[166:169], v[214:217], v[82:85]
	s_setprio 0
	s_setprio 1
	v_mfma_f32_16x16x32_bf16 v[110:113], v[170:173], v[186:189], v[110:113]
	v_mfma_f32_16x16x32_bf16 v[106:109], v[178:181], v[186:189], v[106:109]
	v_mfma_f32_16x16x32_bf16 v[94:97], v[170:173], v[194:197], v[94:97]
	v_mfma_f32_16x16x32_bf16 v[90:93], v[178:181], v[194:197], v[90:93]
	v_mfma_f32_16x16x32_bf16 v[78:81], v[170:173], v[202:205], v[78:81]
	v_mfma_f32_16x16x32_bf16 v[74:77], v[178:181], v[202:205], v[74:77]
	v_mfma_f32_16x16x32_bf16 v[70:73], v[170:173], v[210:213], v[70:73]
	v_mfma_f32_16x16x32_bf16 v[66:69], v[178:181], v[210:213], v[66:69]
	v_mfma_f32_16x16x32_bf16 v[110:113], v[174:177], v[190:193], v[110:113]
	v_mfma_f32_16x16x32_bf16 v[106:109], v[182:185], v[190:193], v[106:109]
	v_mfma_f32_16x16x32_bf16 v[94:97], v[174:177], v[198:201], v[94:97]
	v_mfma_f32_16x16x32_bf16 v[90:93], v[182:185], v[198:201], v[90:93]
	v_mfma_f32_16x16x32_bf16 v[78:81], v[174:177], v[206:209], v[78:81]
	v_mfma_f32_16x16x32_bf16 v[74:77], v[182:185], v[206:209], v[74:77]
	v_mfma_f32_16x16x32_bf16 v[70:73], v[174:177], v[214:217], v[70:73]
	v_mfma_f32_16x16x32_bf16 v[66:69], v[182:185], v[214:217], v[66:69]
	s_setprio 0
	s_barrier
; #define PG8_STAGE(bufoff, gbase, voff) do { _Pragma("unroll") for (int _i = 0; _i < 2; ++_i) \
;         __builtin_amdgcn_global_load_lds((const unsigned*)((const char*)(gbase) + (voff)[_i]), (PG8_LAS unsigned*)(lds + (bufoff) + ldsw + _i * 8192), 16, 0, 0); } while (0)
; #define PG8_LDA(dst, b, h) do { _Pragma("unroll") for (int m = 0; m < 4; ++m) _Pragma("unroll") for (int k = 0; k < 2; ++k) dst[m][k] = *(const PG8_LAS bf16x8*)(lds + PG8_SA(b, h) + aoff + m * 2048 + k * 1024); } while (0)
; #define PG8_LDB(dst, b, h) do { _Pragma("unroll") for (int n = 0; n < 2; ++n) _Pragma("unroll") for (int k = 0; k < 2; ++k) dst[n][k] = *(const PG8_LAS bf16x8*)(lds + PG8_SB(b, h) + boff + n * 2048 + k * 1024); } while (0)
; #define PG8_MMA(ai, bj, At, Bt) do { __builtin_amdgcn_s_setprio(1); _Pragma("unroll") for (int m = 0; m < 4; ++m) _Pragma("unroll") for (int n = 0; n < 2; ++n) _Pragma("unroll") for (int k = 0; k < 2; ++k) \
;         acc[ai][bj][m][n] = __builtin_amdgcn_mfma_f32_16x16x32_bf16(Bt[n][k], At[m][k], acc[ai][bj][m][n], 0, 0, 0); __builtin_amdgcn_s_setprio(0); } while (0)
; #define PG8_WAIT_V(n) asm volatile("s_waitcnt vmcnt(" #n ")" ::: "memory")
; #define PG8_BAR __builtin_amdgcn_s_barrier()
; template <class Epi, class Sched, bool ALIGN_EPI = false, bool SP2 = false>
; __device__ __forceinline__ void gemm_phase(PG8_LAS unsigned char* lds, const Gemm g, const Sched& S, const Epi& E) {
;     ...
;         for (int t = 0; t < nt; t += 2) {
;             const bool last = (t == nt - 2);
;             const char* a1 = cA + (size_t)(t + 1) * kstep;
;             const char* a2 = last ? nA : cA + (size_t)(t + 2) * kstep; const char* b2 = last ? nB : cB + (size_t)(t + 2) * kstep;
;             const char* a3 = a2 + kstep; const char* b3 = b2 + kstep;
;             if (last && has_next) S.a_ready(nxt);
;             if constexpr (SP2) {
;             PG8_LDB(B0, 0, 0); PG8_LDB(B1, 0, 1); PG8_SCHED; PG8_LDA(At, 0, 0); PG8_STAGE(PG8_SA(1, 1), a1 + hstep, voffA);
;             PG8_WAIT_V(8); PG8_WAIT_L(0); PG8_BAR; PG8_MMA(0, 0, At, B0); PG8_MMA(0, 1, At, B1); PG8_BAR; PG8_SCHED;
;     ...
;             PG8_LDA(At, 1, 1); PG8_STAGE(PG8_SB(1, 0), b3, voffB); PG8_STAGE(PG8_SB(1, 1), b3 + hstep, voffB); PG8_STAGE(PG8_SA(1, 0), a3, voffA);
;             PG8_WAIT_V(8); PG8_WAIT_L(0); PG8_BAR; PG8_MMA(1, 0, At, B0); PG8_MMA(1, 1, At, B1); PG8_BAR; PG8_SCHED;
	s_mov_b32 m0, s52
	v_lshl_add_u64 v[218:219], v[218:219], 0, s[8:9]
	s_add_u32 s40, s40, 0x40080
	ds_read_b128 v[186:189], v150 offset:49152
	ds_read_b128 v[190:193], v150 offset:50176
	ds_read_b128 v[194:197], v150 offset:51200
	ds_read_b128 v[198:201], v150 offset:52224
	ds_read_b128 v[202:205], v150 offset:53248
	ds_read_b128 v[206:209], v150 offset:54272
	ds_read_b128 v[210:213], v150 offset:55296
	ds_read_b128 v[214:217], v150 offset:56320
	global_load_lds_dwordx4 v[218:219], off
	v_lshl_add_u64 v[218:219], v[220:221], 0, s[8:9]
	s_mov_b32 m0, s53
	s_addc_u32 s41, s41, 0
	global_load_lds_dwordx4 v[218:219], off
	v_lshl_add_u64 v[218:219], s[40:41], 0, v[132:133]
	s_mov_b32 m0, s56
	s_nop 0
	global_load_lds_dwordx4 v[218:219], off
	v_lshl_add_u64 v[218:219], s[40:41], 0, v[136:137]
	s_mov_b32 m0, s57
	s_nop 0
	global_load_lds_dwordx4 v[218:219], off
	v_lshl_add_u64 v[218:219], v[222:223], 0, s[8:9]
	s_mov_b32 m0, s54
	s_nop 0
	global_load_lds_dwordx4 v[218:219], off
	v_lshl_add_u64 v[218:219], v[224:225], 0, s[8:9]
	s_mov_b32 m0, s55
	s_nop 0
	global_load_lds_dwordx4 v[218:219], off
	s_waitcnt vmcnt(8)
	s_waitcnt lgkmcnt(0)
	s_barrier
	s_setprio 1
	s_waitcnt lgkmcnt(0)
	v_mfma_f32_16x16x32_bf16 v[62:65], v[154:157], v[186:189], v[62:65]
	v_mfma_f32_16x16x32_bf16 v[58:61], v[162:165], v[186:189], v[58:61]
	v_mfma_f32_16x16x32_bf16 v[54:57], v[154:157], v[194:197], v[54:57]
	v_mfma_f32_16x16x32_bf16 v[50:53], v[162:165], v[194:197], v[50:53]
	v_mfma_f32_16x16x32_bf16 v[38:41], v[154:157], v[202:205], v[38:41]
	v_mfma_f32_16x16x32_bf16 v[34:37], v[162:165], v[202:205], v[34:37]
	v_mfma_f32_16x16x32_bf16 v[22:25], v[154:157], v[210:213], v[22:25]
	v_mfma_f32_16x16x32_bf16 v[18:21], v[162:165], v[210:213], v[18:21]
	v_mfma_f32_16x16x32_bf16 v[62:65], v[158:161], v[190:193], v[62:65]
	v_mfma_f32_16x16x32_bf16 v[58:61], v[166:169], v[190:193], v[58:61]
	v_mfma_f32_16x16x32_bf16 v[54:57], v[158:161], v[198:201], v[54:57]
	v_mfma_f32_16x16x32_bf16 v[50:53], v[166:169], v[198:201], v[50:53]
	v_mfma_f32_16x16x32_bf16 v[38:41], v[158:161], v[206:209], v[38:41]
	v_mfma_f32_16x16x32_bf16 v[34:37], v[166:169], v[206:209], v[34:37]
	v_mfma_f32_16x16x32_bf16 v[22:25], v[158:161], v[214:217], v[22:25]
	v_mfma_f32_16x16x32_bf16 v[18:21], v[166:169], v[214:217], v[18:21]
	s_setprio 0
	s_setprio 1
	v_mfma_f32_16x16x32_bf16 v[46:49], v[170:173], v[186:189], v[46:49]
	v_mfma_f32_16x16x32_bf16 v[42:45], v[178:181], v[186:189], v[42:45]
	v_mfma_f32_16x16x32_bf16 v[30:33], v[170:173], v[194:197], v[30:33]
	v_mfma_f32_16x16x32_bf16 v[26:29], v[178:181], v[194:197], v[26:29]
	v_mfma_f32_16x16x32_bf16 v[14:17], v[170:173], v[202:205], v[14:17]
	v_mfma_f32_16x16x32_bf16 v[10:13], v[178:181], v[202:205], v[10:13]
	v_mfma_f32_16x16x32_bf16 v[6:9], v[170:173], v[210:213], v[6:9]
	v_mfma_f32_16x16x32_bf16 v[2:5], v[178:181], v[210:213], v[2:5]
	v_mfma_f32_16x16x32_bf16 v[46:49], v[174:177], v[190:193], v[46:49]
	v_mfma_f32_16x16x32_bf16 v[42:45], v[182:185], v[190:193], v[42:45]
	v_mfma_f32_16x16x32_bf16 v[30:33], v[174:177], v[198:201], v[30:33]
	v_mfma_f32_16x16x32_bf16 v[26:29], v[182:185], v[198:201], v[26:29]
	v_mfma_f32_16x16x32_bf16 v[14:17], v[174:177], v[206:209], v[14:17]
	v_mfma_f32_16x16x32_bf16 v[10:13], v[182:185], v[206:209], v[10:13]
	v_mfma_f32_16x16x32_bf16 v[6:9], v[174:177], v[214:217], v[6:9]
	v_mfma_f32_16x16x32_bf16 v[2:5], v[182:185], v[214:217], v[2:5]
	s_setprio 0
	s_barrier
	s_add_i32 s68, s68, 2
	s_add_u32 s66, s66, 0x100
	s_addc_u32 s67, s67, 0
	s_add_u32 s38, s38, 0x100
	s_addc_u32 s39, s39, 0
	s_cmp_gt_u32 s68, 13
.LBB0_2134:
	ds_read_b128 v[154:157], v148
	ds_read_b128 v[158:161], v148 offset:1024
	ds_read_b128 v[162:165], v148 offset:2048
	ds_read_b128 v[166:169], v148 offset:3072
	ds_read_b128 v[170:173], v149
	ds_read_b128 v[174:177], v149 offset:1024
	ds_read_b128 v[178:181], v149 offset:2048
	ds_read_b128 v[182:185], v149 offset:3072
	s_add_u32 s40, s38, 0xfffc0080
	s_addc_u32 s41, s39, -1
	s_cmp_eq_u32 s68, 12
	s_cselect_b32 s43, s21, s41
	s_cselect_b32 s42, s64, s40
	s_cselect_b32 s41, s23, s67
	s_cselect_b32 s40, s65, s66
	v_lshl_add_u64 v[218:219], s[38:39], 0, v[140:141]
	s_add_i32 m0, s47, 0xc000
	ds_read_b128 v[186:189], v150
	ds_read_b128 v[190:193], v150 offset:1024
	ds_read_b128 v[194:197], v150 offset:2048
	ds_read_b128 v[198:201], v150 offset:3072
	ds_read_b128 v[202:205], v150 offset:4096
	ds_read_b128 v[206:209], v150 offset:5120
	ds_read_b128 v[210:213], v150 offset:6144
	ds_read_b128 v[214:217], v150 offset:7168
	global_load_lds_dwordx4 v[218:219], off
	v_lshl_add_u64 v[218:219], s[38:39], 0, v[138:139]
	s_add_i32 m0, s47, 0xe000
	s_nop 0
	global_load_lds_dwordx4 v[218:219], off
	s_waitcnt vmcnt(8)
	s_waitcnt lgkmcnt(0)
	s_barrier
; #define PG8_STAGE(bufoff, gbase, voff) do { _Pragma("unroll") for (int _i = 0; _i < 2; ++_i) \
;         __builtin_amdgcn_global_load_lds((const unsigned*)((const char*)(gbase) + (voff)[_i]), (PG8_LAS unsigned*)(lds + (bufoff) + ldsw + _i * 8192), 16, 0, 0); } while (0)
; #define PG8_LDA(dst, b, h) do { _Pragma("unroll") for (int m = 0; m < 4; ++m) _Pragma("unroll") for (int k = 0; k < 2; ++k) dst[m][k] = *(const PG8_LAS bf16x8*)(lds + PG8_SA(b, h) + aoff + m * 2048 + k * 1024); } while (0)
; #define PG8_MMA(ai, bj, At, Bt) do { __builtin_amdgcn_s_setprio(1); _Pragma("unroll") for (int m = 0; m < 4; ++m) _Pragma("unroll") for (int n = 0; n < 2; ++n) _Pragma("unroll") for (int k = 0; k < 2; ++k) \
;         acc[ai][bj][m][n] = __builtin_amdgcn_mfma_f32_16x16x32_bf16(Bt[n][k], At[m][k], acc[ai][bj][m][n], 0, 0, 0); __builtin_amdgcn_s_setprio(0); } while (0)
; #define PG8_WAIT_V(n) asm volatile("s_waitcnt vmcnt(" #n ")" ::: "memory")
; #define PG8_WAIT_L(n) asm volatile("s_waitcnt lgkmcnt(" #n ")" ::: "memory")
; #define PG8_BAR __builtin_amdgcn_s_barrier()
; #define PG8_SCHED __builtin_amdgcn_sched_barrier(0)
; template <class Epi, class Sched, bool ALIGN_EPI = false, bool SP2 = false>
; __device__ __forceinline__ void gemm_phase(PG8_LAS unsigned char* lds, const Gemm g, const Sched& S, const Epi& E) {
;     ...
;             PG8_WAIT_V(8); PG8_WAIT_L(0); PG8_BAR; PG8_MMA(0, 0, At, B0); PG8_MMA(0, 1, At, B1); PG8_BAR; PG8_SCHED;
;             PG8_LDA(At, 0, 1); PG8_STAGE(PG8_SB(0, 0), b2, voffB); PG8_STAGE(PG8_SB(0, 1), b2 + hstep, voffB); PG8_STAGE(PG8_SA(0, 0), a2, voffA);
;             PG8_WAIT_V(8); PG8_WAIT_L(0); PG8_BAR; PG8_MMA(1, 0, At, B0); PG8_MMA(1, 1, At, B1); PG8_BAR; PG8_SCHED;
	s_setprio 1
	s_waitcnt lgkmcnt(0)
	v_mfma_f32_16x16x32_bf16 v[126:129], v[154:157], v[186:189], v[126:129]
	v_mfma_f32_16x16x32_bf16 v[122:125], v[162:165], v[186:189], v[122:125]
	v_mfma_f32_16x16x32_bf16 v[118:121], v[154:157], v[194:197], v[118:121]
	v_mfma_f32_16x16x32_bf16 v[114:117], v[162:165], v[194:197], v[114:117]
	v_mfma_f32_16x16x32_bf16 v[102:105], v[154:157], v[202:205], v[102:105]
	v_mfma_f32_16x16x32_bf16 v[98:101], v[162:165], v[202:205], v[98:101]
	v_mfma_f32_16x16x32_bf16 v[86:89], v[154:157], v[210:213], v[86:89]
	v_mfma_f32_16x16x32_bf16 v[82:85], v[162:165], v[210:213], v[82:85]
	v_mfma_f32_16x16x32_bf16 v[126:129], v[158:161], v[190:193], v[126:129]
	v_mfma_f32_16x16x32_bf16 v[122:125], v[166:169], v[190:193], v[122:125]
	v_mfma_f32_16x16x32_bf16 v[118:121], v[158:161], v[198:201], v[118:121]
	v_mfma_f32_16x16x32_bf16 v[114:117], v[166:169], v[198:201], v[114:117]
	v_mfma_f32_16x16x32_bf16 v[102:105], v[158:161], v[206:209], v[102:105]
	v_mfma_f32_16x16x32_bf16 v[98:101], v[166:169], v[206:209], v[98:101]
	v_mfma_f32_16x16x32_bf16 v[86:89], v[158:161], v[214:217], v[86:89]
	v_mfma_f32_16x16x32_bf16 v[82:85], v[166:169], v[214:217], v[82:85]
	s_setprio 0
	s_setprio 1
	v_mfma_f32_16x16x32_bf16 v[110:113], v[170:173], v[186:189], v[110:113]
	v_mfma_f32_16x16x32_bf16 v[106:109], v[178:181], v[186:189], v[106:109]
	v_mfma_f32_16x16x32_bf16 v[94:97], v[170:173], v[194:197], v[94:97]
	v_mfma_f32_16x16x32_bf16 v[90:93], v[178:181], v[194:197], v[90:93]
	v_mfma_f32_16x16x32_bf16 v[78:81], v[170:173], v[202:205], v[78:81]
	v_mfma_f32_16x16x32_bf16 v[74:77], v[178:181], v[202:205], v[74:77]
	v_mfma_f32_16x16x32_bf16 v[70:73], v[170:173], v[210:213], v[70:73]
	v_mfma_f32_16x16x32_bf16 v[66:69], v[178:181], v[210:213], v[66:69]
	v_mfma_f32_16x16x32_bf16 v[110:113], v[174:177], v[190:193], v[110:113]
	v_mfma_f32_16x16x32_bf16 v[106:109], v[182:185], v[190:193], v[106:109]
	v_mfma_f32_16x16x32_bf16 v[94:97], v[174:177], v[198:201], v[94:97]
	v_mfma_f32_16x16x32_bf16 v[90:93], v[182:185], v[198:201], v[90:93]
	v_mfma_f32_16x16x32_bf16 v[78:81], v[174:177], v[206:209], v[78:81]
	v_mfma_f32_16x16x32_bf16 v[74:77], v[182:185], v[206:209], v[74:77]
	v_mfma_f32_16x16x32_bf16 v[70:73], v[174:177], v[214:217], v[70:73]
	v_mfma_f32_16x16x32_bf16 v[66:69], v[182:185], v[214:217], v[66:69]
	s_setprio 0
	s_barrier
	s_mov_b32 m0, s19
	v_lshl_add_u64 v[218:219], s[40:41], 0, v[132:133]
	s_add_u32 s70, s40, 0x40000
	ds_read_b128 v[186:189], v150 offset:16384
	ds_read_b128 v[190:193], v150 offset:17408
	ds_read_b128 v[194:197], v150 offset:18432
	ds_read_b128 v[198:201], v150 offset:19456
	ds_read_b128 v[202:205], v150 offset:20480
	ds_read_b128 v[206:209], v150 offset:21504
	ds_read_b128 v[210:213], v150 offset:22528
	ds_read_b128 v[214:217], v150 offset:23552
	global_load_lds_dwordx4 v[218:219], off
	v_lshl_add_u64 v[220:221], s[40:41], 0, v[136:137]
	s_mov_b32 m0, s44
	s_addc_u32 s71, s41, 0
	global_load_lds_dwordx4 v[220:221], off
	v_lshl_add_u64 v[222:223], s[70:71], 0, v[132:133]
	s_mov_b32 m0, s45
	v_lshl_add_u64 v[224:225], s[42:43], 0, v[134:135]
	global_load_lds_dwordx4 v[222:223], off
	v_lshl_add_u64 v[222:223], s[70:71], 0, v[136:137]
	s_mov_b32 m0, s46
	s_nop 0
	global_load_lds_dwordx4 v[222:223], off
	v_lshl_add_u64 v[222:223], s[42:43], 0, v[130:131]
	s_waitcnt vmcnt(6)
	s_waitcnt lgkmcnt(0)
	s_barrier
	s_setprio 1
	s_waitcnt lgkmcnt(0)
	v_mfma_f32_16x16x32_bf16 v[62:65], v[154:157], v[186:189], v[62:65]
	v_mfma_f32_16x16x32_bf16 v[58:61], v[162:165], v[186:189], v[58:61]
	v_mfma_f32_16x16x32_bf16 v[54:57], v[154:157], v[194:197], v[54:57]
	v_mfma_f32_16x16x32_bf16 v[50:53], v[162:165], v[194:197], v[50:53]
	v_mfma_f32_16x16x32_bf16 v[38:41], v[154:157], v[202:205], v[38:41]
	v_mfma_f32_16x16x32_bf16 v[34:37], v[162:165], v[202:205], v[34:37]
	v_mfma_f32_16x16x32_bf16 v[22:25], v[154:157], v[210:213], v[22:25]
	v_mfma_f32_16x16x32_bf16 v[18:21], v[162:165], v[210:213], v[18:21]
	v_mfma_f32_16x16x32_bf16 v[62:65], v[158:161], v[190:193], v[62:65]
	v_mfma_f32_16x16x32_bf16 v[58:61], v[166:169], v[190:193], v[58:61]
	v_mfma_f32_16x16x32_bf16 v[54:57], v[158:161], v[198:201], v[54:57]
	v_mfma_f32_16x16x32_bf16 v[50:53], v[166:169], v[198:201], v[50:53]
	v_mfma_f32_16x16x32_bf16 v[38:41], v[158:161], v[206:209], v[38:41]
	v_mfma_f32_16x16x32_bf16 v[34:37], v[166:169], v[206:209], v[34:37]
	v_mfma_f32_16x16x32_bf16 v[22:25], v[158:161], v[214:217], v[22:25]
	v_mfma_f32_16x16x32_bf16 v[18:21], v[166:169], v[214:217], v[18:21]
	s_setprio 0
	s_setprio 1
	v_mfma_f32_16x16x32_bf16 v[46:49], v[170:173], v[186:189], v[46:49]
	v_mfma_f32_16x16x32_bf16 v[42:45], v[178:181], v[186:189], v[42:45]
	v_mfma_f32_16x16x32_bf16 v[30:33], v[170:173], v[194:197], v[30:33]
	v_mfma_f32_16x16x32_bf16 v[26:29], v[178:181], v[194:197], v[26:29]
	v_mfma_f32_16x16x32_bf16 v[14:17], v[170:173], v[202:205], v[14:17]
	v_mfma_f32_16x16x32_bf16 v[10:13], v[178:181], v[202:205], v[10:13]
	v_mfma_f32_16x16x32_bf16 v[6:9], v[170:173], v[210:213], v[6:9]
	v_mfma_f32_16x16x32_bf16 v[2:5], v[178:181], v[210:213], v[2:5]
	v_mfma_f32_16x16x32_bf16 v[46:49], v[174:177], v[190:193], v[46:49]
	v_mfma_f32_16x16x32_bf16 v[42:45], v[182:185], v[190:193], v[42:45]
	v_mfma_f32_16x16x32_bf16 v[30:33], v[174:177], v[198:201], v[30:33]
	v_mfma_f32_16x16x32_bf16 v[26:29], v[182:185], v[198:201], v[26:29]
	v_mfma_f32_16x16x32_bf16 v[14:17], v[174:177], v[206:209], v[14:17]
	v_mfma_f32_16x16x32_bf16 v[10:13], v[182:185], v[206:209], v[10:13]
	v_mfma_f32_16x16x32_bf16 v[6:9], v[174:177], v[214:217], v[6:9]
	v_mfma_f32_16x16x32_bf16 v[2:5], v[182:185], v[214:217], v[2:5]
	s_setprio 0
	s_barrier
; #define PG8_STAGE(bufoff, gbase, voff) do { _Pragma("unroll") for (int _i = 0; _i < 2; ++_i) \
;         __builtin_amdgcn_global_load_lds((const unsigned*)((const char*)(gbase) + (voff)[_i]), (PG8_LAS unsigned*)(lds + (bufoff) + ldsw + _i * 8192), 16, 0, 0); } while (0)
; #define PG8_LDA(dst, b, h) do { _Pragma("unroll") for (int m = 0; m < 4; ++m) _Pragma("unroll") for (int k = 0; k < 2; ++k) dst[m][k] = *(const PG8_LAS bf16x8*)(lds + PG8_SA(b, h) + aoff + m * 2048 + k * 1024); } while (0)
; #define PG8_LDB(dst, b, h) do { _Pragma("unroll") for (int n = 0; n < 2; ++n) _Pragma("unroll") for (int k = 0; k < 2; ++k) dst[n][k] = *(const PG8_LAS bf16x8*)(lds + PG8_SB(b, h) + boff + n * 2048 + k * 1024); } while (0)
; #define PG8_MMA(ai, bj, At, Bt) do { __builtin_amdgcn_s_setprio(1); _Pragma("unroll") for (int m = 0; m < 4; ++m) _Pragma("unroll") for (int n = 0; n < 2; ++n) _Pragma("unroll") for (int k = 0; k < 2; ++k) \
;         acc[ai][bj][m][n] = __builtin_amdgcn_mfma_f32_16x16x32_bf16(Bt[n][k], At[m][k], acc[ai][bj][m][n], 0, 0, 0); __builtin_amdgcn_s_setprio(0); } while (0)
; #define PG8_WAIT_V(n) asm volatile("s_waitcnt vmcnt(" #n ")" ::: "memory")
; #define PG8_WAIT_L(n) asm volatile("s_waitcnt lgkmcnt(" #n ")" ::: "memory")
; #define PG8_BAR __builtin_amdgcn_s_barrier()
; #define PG8_SCHED __builtin_amdgcn_sched_barrier(0)
; template <class Epi, class Sched, bool ALIGN_EPI = false, bool SP2 = false>
; __device__ __forceinline__ void gemm_phase(PG8_LAS unsigned char* lds, const Gemm g, const Sched& S, const Epi& E) {
;     ...
;             PG8_LDB(B0, 1, 0); PG8_LDB(B1, 1, 1); PG8_SCHED; PG8_LDA(At, 1, 0); PG8_STAGE(PG8_SA(0, 1), a2 + hstep, voffA);
;             PG8_WAIT_V(8); PG8_WAIT_L(0); PG8_BAR; PG8_MMA(0, 0, At, B0); PG8_MMA(0, 1, At, B1); PG8_BAR; PG8_SCHED;
	ds_read_b128 v[154:157], v151
	ds_read_b128 v[158:161], v151 offset:1024
	ds_read_b128 v[162:165], v151 offset:2048
	ds_read_b128 v[166:169], v151 offset:3072
	ds_read_b128 v[170:173], v152
	ds_read_b128 v[174:177], v152 offset:1024
	ds_read_b128 v[178:181], v152 offset:2048
	ds_read_b128 v[182:185], v152 offset:3072
	s_add_u32 s42, s42, 0x40000
	s_addc_u32 s43, s43, 0
	s_mov_b32 m0, s47
	s_nop 0
	global_load_lds_dwordx4 v[222:223], off
	s_mov_b32 m0, s48
	s_nop 0
	global_load_lds_dwordx4 v[224:225], off
	s_mov_b32 m0, s49
	v_lshl_add_u64 v[226:227], s[42:43], 0, v[130:131]
	ds_read_b128 v[186:189], v150 offset:32768
	ds_read_b128 v[190:193], v150 offset:33792
	ds_read_b128 v[194:197], v150 offset:34816
	ds_read_b128 v[198:201], v150 offset:35840
	ds_read_b128 v[202:205], v150 offset:36864
	ds_read_b128 v[206:209], v150 offset:37888
	ds_read_b128 v[210:213], v150 offset:38912
	ds_read_b128 v[214:217], v150 offset:39936
	global_load_lds_dwordx4 v[226:227], off
	v_lshl_add_u64 v[226:227], s[42:43], 0, v[134:135]
	s_mov_b32 m0, s50
	s_nop 0
	global_load_lds_dwordx4 v[226:227], off
	s_waitcnt vmcnt(8)
	s_waitcnt lgkmcnt(0)
	s_barrier
	s_setprio 1
	s_waitcnt lgkmcnt(0)
	v_mfma_f32_16x16x32_bf16 v[126:129], v[154:157], v[186:189], v[126:129]
	v_mfma_f32_16x16x32_bf16 v[122:125], v[162:165], v[186:189], v[122:125]
	v_mfma_f32_16x16x32_bf16 v[118:121], v[154:157], v[194:197], v[118:121]
	v_mfma_f32_16x16x32_bf16 v[114:117], v[162:165], v[194:197], v[114:117]
	v_mfma_f32_16x16x32_bf16 v[102:105], v[154:157], v[202:205], v[102:105]
	v_mfma_f32_16x16x32_bf16 v[98:101], v[162:165], v[202:205], v[98:101]
	v_mfma_f32_16x16x32_bf16 v[86:89], v[154:157], v[210:213], v[86:89]
	v_mfma_f32_16x16x32_bf16 v[82:85], v[162:165], v[210:213], v[82:85]
	v_mfma_f32_16x16x32_bf16 v[126:129], v[158:161], v[190:193], v[126:129]
	v_mfma_f32_16x16x32_bf16 v[122:125], v[166:169], v[190:193], v[122:125]
	v_mfma_f32_16x16x32_bf16 v[118:121], v[158:161], v[198:201], v[118:121]
	v_mfma_f32_16x16x32_bf16 v[114:117], v[166:169], v[198:201], v[114:117]
	v_mfma_f32_16x16x32_bf16 v[102:105], v[158:161], v[206:209], v[102:105]
	v_mfma_f32_16x16x32_bf16 v[98:101], v[166:169], v[206:209], v[98:101]
	v_mfma_f32_16x16x32_bf16 v[86:89], v[158:161], v[214:217], v[86:89]
	v_mfma_f32_16x16x32_bf16 v[82:85], v[166:169], v[214:217], v[82:85]
	s_setprio 0
	s_setprio 1
	v_mfma_f32_16x16x32_bf16 v[110:113], v[170:173], v[186:189], v[110:113]
	v_mfma_f32_16x16x32_bf16 v[106:109], v[178:181], v[186:189], v[106:109]
	v_mfma_f32_16x16x32_bf16 v[94:97], v[170:173], v[194:197], v[94:97]
	v_mfma_f32_16x16x32_bf16 v[90:93], v[178:181], v[194:197], v[90:93]
	v_mfma_f32_16x16x32_bf16 v[78:81], v[170:173], v[202:205], v[78:81]
	v_mfma_f32_16x16x32_bf16 v[74:77], v[178:181], v[202:205], v[74:77]
	v_mfma_f32_16x16x32_bf16 v[70:73], v[170:173], v[210:213], v[70:73]
	v_mfma_f32_16x16x32_bf16 v[66:69], v[178:181], v[210:213], v[66:69]
	v_mfma_f32_16x16x32_bf16 v[110:113], v[174:177], v[190:193], v[110:113]
	v_mfma_f32_16x16x32_bf16 v[106:109], v[182:185], v[190:193], v[106:109]
	v_mfma_f32_16x16x32_bf16 v[94:97], v[174:177], v[198:201], v[94:97]
	v_mfma_f32_16x16x32_bf16 v[90:93], v[182:185], v[198:201], v[90:93]
	v_mfma_f32_16x16x32_bf16 v[78:81], v[174:177], v[206:209], v[78:81]
	v_mfma_f32_16x16x32_bf16 v[74:77], v[182:185], v[206:209], v[74:77]
	v_mfma_f32_16x16x32_bf16 v[70:73], v[174:177], v[214:217], v[70:73]
	v_mfma_f32_16x16x32_bf16 v[66:69], v[182:185], v[214:217], v[66:69]
	s_setprio 0
	s_barrier
; #define PG8_STAGE(bufoff, gbase, voff) do { _Pragma("unroll") for (int _i = 0; _i < 2; ++_i) \
;         __builtin_amdgcn_global_load_lds((const unsigned*)((const char*)(gbase) + (voff)[_i]), (PG8_LAS unsigned*)(lds + (bufoff) + ldsw + _i * 8192), 16, 0, 0); } while (0)
; #define PG8_LDA(dst, b, h) do { _Pragma("unroll") for (int m = 0; m < 4; ++m) _Pragma("unroll") for (int k = 0; k < 2; ++k) dst[m][k] = *(const PG8_LAS bf16x8*)(lds + PG8_SA(b, h) + aoff + m * 2048 + k * 1024); } while (0)
; #define PG8_MMA(ai, bj, At, Bt) do { __builtin_amdgcn_s_setprio(1); _Pragma("unroll") for (int m = 0; m < 4; ++m) _Pragma("unroll") for (int n = 0; n < 2; ++n) _Pragma("unroll") for (int k = 0; k < 2; ++k) \
;         acc[ai][bj][m][n] = __builtin_amdgcn_mfma_f32_16x16x32_bf16(Bt[n][k], At[m][k], acc[ai][bj][m][n], 0, 0, 0); __builtin_amdgcn_s_setprio(0); } while (0)
; #define PG8_WAIT_V(n) asm volatile("s_waitcnt vmcnt(" #n ")" ::: "memory")
; #define PG8_WAIT_L(n) asm volatile("s_waitcnt lgkmcnt(" #n ")" ::: "memory")
; #define PG8_BAR __builtin_amdgcn_s_barrier()
; #define PG8_SCHED __builtin_amdgcn_sched_barrier(0)
; template <class Epi, class Sched, bool ALIGN_EPI = false, bool SP2 = false>
; __device__ __forceinline__ void gemm_phase(PG8_LAS unsigned char* lds, const Gemm g, const Sched& S, const Epi& E) {
;     ...
;             PG8_LDA(At, 1, 1); PG8_STAGE(PG8_SB(1, 0), b3, voffB); PG8_STAGE(PG8_SB(1, 1), b3 + hstep, voffB); PG8_STAGE(PG8_SA(1, 0), a3, voffA);
;             PG8_WAIT_V(8); PG8_WAIT_L(0); PG8_BAR; PG8_MMA(1, 0, At, B0); PG8_MMA(1, 1, At, B1); PG8_BAR; PG8_SCHED;
	s_mov_b32 m0, s52
	v_lshl_add_u64 v[218:219], v[218:219], 0, s[8:9]
	s_add_u32 s40, s40, 0x40080
	ds_read_b128 v[186:189], v150 offset:49152
	ds_read_b128 v[190:193], v150 offset:50176
	ds_read_b128 v[194:197], v150 offset:51200
	ds_read_b128 v[198:201], v150 offset:52224
	ds_read_b128 v[202:205], v150 offset:53248
	ds_read_b128 v[206:209], v150 offset:54272
	ds_read_b128 v[210:213], v150 offset:55296
	ds_read_b128 v[214:217], v150 offset:56320
	global_load_lds_dwordx4 v[218:219], off
	v_lshl_add_u64 v[218:219], v[220:221], 0, s[8:9]
	s_mov_b32 m0, s53
	s_addc_u32 s41, s41, 0
	global_load_lds_dwordx4 v[218:219], off
	v_lshl_add_u64 v[218:219], s[40:41], 0, v[132:133]
	s_mov_b32 m0, s56
	s_nop 0
	global_load_lds_dwordx4 v[218:219], off
	v_lshl_add_u64 v[218:219], s[40:41], 0, v[136:137]
	s_mov_b32 m0, s57
	s_nop 0
	global_load_lds_dwordx4 v[218:219], off
	v_lshl_add_u64 v[218:219], v[222:223], 0, s[8:9]
	s_mov_b32 m0, s54
	s_nop 0
	global_load_lds_dwordx4 v[218:219], off
	v_lshl_add_u64 v[218:219], v[224:225], 0, s[8:9]
	s_mov_b32 m0, s55
	s_nop 0
	global_load_lds_dwordx4 v[218:219], off
	s_waitcnt vmcnt(8)
	s_waitcnt lgkmcnt(0)
	s_barrier
	s_setprio 1
	s_waitcnt lgkmcnt(0)
	v_mfma_f32_16x16x32_bf16 v[62:65], v[154:157], v[186:189], v[62:65]
	v_mfma_f32_16x16x32_bf16 v[58:61], v[162:165], v[186:189], v[58:61]
	v_mfma_f32_16x16x32_bf16 v[54:57], v[154:157], v[194:197], v[54:57]
	v_mfma_f32_16x16x32_bf16 v[50:53], v[162:165], v[194:197], v[50:53]
	v_mfma_f32_16x16x32_bf16 v[38:41], v[154:157], v[202:205], v[38:41]
	v_mfma_f32_16x16x32_bf16 v[34:37], v[162:165], v[202:205], v[34:37]
	v_mfma_f32_16x16x32_bf16 v[22:25], v[154:157], v[210:213], v[22:25]
	v_mfma_f32_16x16x32_bf16 v[18:21], v[162:165], v[210:213], v[18:21]
	v_mfma_f32_16x16x32_bf16 v[62:65], v[158:161], v[190:193], v[62:65]
	v_mfma_f32_16x16x32_bf16 v[58:61], v[166:169], v[190:193], v[58:61]
	v_mfma_f32_16x16x32_bf16 v[54:57], v[158:161], v[198:201], v[54:57]
	v_mfma_f32_16x16x32_bf16 v[50:53], v[166:169], v[198:201], v[50:53]
	v_mfma_f32_16x16x32_bf16 v[38:41], v[158:161], v[206:209], v[38:41]
	v_mfma_f32_16x16x32_bf16 v[34:37], v[166:169], v[206:209], v[34:37]
	v_mfma_f32_16x16x32_bf16 v[22:25], v[158:161], v[214:217], v[22:25]
	v_mfma_f32_16x16x32_bf16 v[18:21], v[166:169], v[214:217], v[18:21]
	s_setprio 0
	s_setprio 1
	v_mfma_f32_16x16x32_bf16 v[46:49], v[170:173], v[186:189], v[46:49]
	v_mfma_f32_16x16x32_bf16 v[42:45], v[178:181], v[186:189], v[42:45]
	v_mfma_f32_16x16x32_bf16 v[30:33], v[170:173], v[194:197], v[30:33]
	v_mfma_f32_16x16x32_bf16 v[26:29], v[178:181], v[194:197], v[26:29]
	v_mfma_f32_16x16x32_bf16 v[14:17], v[170:173], v[202:205], v[14:17]
	v_mfma_f32_16x16x32_bf16 v[10:13], v[178:181], v[202:205], v[10:13]
	v_mfma_f32_16x16x32_bf16 v[6:9], v[170:173], v[210:213], v[6:9]
	v_mfma_f32_16x16x32_bf16 v[2:5], v[178:181], v[210:213], v[2:5]
	v_mfma_f32_16x16x32_bf16 v[46:49], v[174:177], v[190:193], v[46:49]
	v_mfma_f32_16x16x32_bf16 v[42:45], v[182:185], v[190:193], v[42:45]
	v_mfma_f32_16x16x32_bf16 v[30:33], v[174:177], v[198:201], v[30:33]
	v_mfma_f32_16x16x32_bf16 v[26:29], v[182:185], v[198:201], v[26:29]
	v_mfma_f32_16x16x32_bf16 v[14:17], v[174:177], v[206:209], v[14:17]
	v_mfma_f32_16x16x32_bf16 v[10:13], v[182:185], v[206:209], v[10:13]
	v_mfma_f32_16x16x32_bf16 v[6:9], v[174:177], v[214:217], v[6:9]
	v_mfma_f32_16x16x32_bf16 v[2:5], v[182:185], v[214:217], v[2:5]
	s_setprio 0
	s_barrier
	s_add_i32 s68, s68, 2
	s_add_u32 s66, s66, 0x100
	s_addc_u32 s67, s67, 0
	s_add_u32 s38, s38, 0x100
	s_addc_u32 s39, s39, 0
	s_cmp_gt_u32 s68, 13
	s_cbranch_scc0 .LBB0_2134
	s_and_b64 vcc, exec, s[10:11]
	s_cbranch_vccz .LBB0_2137
	s_barrier

; #define PG8_STAGE(bufoff, gbase, voff) do { _Pragma("unroll") for (int _i = 0; _i < 2; ++_i) \
;         __builtin_amdgcn_global_load_lds((const unsigned*)((const char*)(gbase) + (voff)[_i]), (PG8_LAS unsigned*)(lds + (bufoff) + ldsw + _i * 8192), 16, 0, 0); } while (0)
; #define PG8_LDA(dst, b, h) do { _Pragma("unroll") for (int m = 0; m < 4; ++m) _Pragma("unroll") for (int k = 0; k < 2; ++k) dst[m][k] = *(const PG8_LAS bf16x8*)(lds + PG8_SA(b, h) + aoff + m * 2048 + k * 1024); } while (0)
; #define PG8_LDB(dst, b, h) do { _Pragma("unroll") for (int n = 0; n < 2; ++n) _Pragma("unroll") for (int k = 0; k < 2; ++k) dst[n][k] = *(const PG8_LAS bf16x8*)(lds + PG8_SB(b, h) + boff + n * 2048 + k * 1024); } while (0)
; #define PG8_WAIT_V(n) asm volatile("s_waitcnt vmcnt(" #n ")" ::: "memory")
; #define PG8_WAIT_L(n) asm volatile("s_waitcnt lgkmcnt(" #n ")" ::: "memory")
; #define PG8_BAR __builtin_amdgcn_s_barrier()
; template <class Epi, class Sched, bool ALIGN_EPI = false, bool SP2 = false>
; __device__ __forceinline__ void gemm_phase(PG8_LAS unsigned char* lds, const Gemm g, const Sched& S, const Epi& E) {
;     ...
;     for (;;) {
;         const bool has_next = S.next(ui + 1, nxt);
;         const char* nA = has_next ? (const char*)g.A + (size_t)nxt.pm * tstep + (size_t)nxt.ks * K * 2 : cA; const char* nB = has_next ? (const char*)g.Bt + (size_t)nxt.pn * tstep + (size_t)nxt.ks * K * 2 : cB;
;         for (int t = 0; t < nt; t += 2) {
;             const bool last = (t == nt - 2);
;             const char* a1 = cA + (size_t)(t + 1) * kstep;
;             const char* a2 = last ? nA : cA + (size_t)(t + 2) * kstep; const char* b2 = last ? nB : cB + (size_t)(t + 2) * kstep;
;             const char* a3 = a2 + kstep; const char* b3 = b2 + kstep;
;             if (last && has_next) S.a_ready(nxt);
;             if constexpr (SP2) {
;             PG8_LDB(B0, 0, 0); PG8_LDB(B1, 0, 1); PG8_SCHED; PG8_LDA(At, 0, 0); PG8_STAGE(PG8_SA(1, 1), a1 + hstep, voffA);
;             PG8_WAIT_V(8); PG8_WAIT_L(0); PG8_BAR; PG8_MMA(0, 0, At, B0); PG8_MMA(0, 1, At, B1); PG8_BAR; PG8_SCHED;
;             PG8_LDA(At, 0, 1); PG8_STAGE(PG8_SB(0, 0), b2, voffB); PG8_STAGE(PG8_SB(0, 1), b2 + hstep, voffB); PG8_STAGE(PG8_SA(0, 0), a2, voffA);
;             PG8_WAIT_V(8); PG8_WAIT_L(0); PG8_BAR; PG8_MMA(1, 0, At, B0); PG8_MMA(1, 1, At, B1); PG8_BAR; PG8_SCHED;
.LBB0_2284:
	s_ashr_i32 s13, s12, 31
	s_lshl_b64 s[14:15], s[12:13], 19
	s_add_u32 s14, s28, s14
	s_addc_u32 s15, s29, s15
	s_and_b64 s[16:17], s[2:3], exec
	s_cselect_b32 s13, s15, s23
	s_cselect_b32 s50, s14, s22
	s_ashr_i32 s11, s10, 31
	s_lshl_b64 s[16:17], s[10:11], 19
	s_add_u32 s16, s30, s16
	s_addc_u32 s17, s31, s17
	s_and_b64 s[24:25], s[2:3], exec
	s_cselect_b32 s11, s17, s21
	s_cselect_b32 s51, s16, s20
	s_add_u32 s54, s20, 0x100
	s_addc_u32 s55, s21, 0
	s_add_u32 s20, s22, 0x40080
	s_addc_u32 s21, s23, 0
	s_mov_b32 s58, -2
	ds_read_b128 v[146:149], v152
	ds_read_b128 v[158:161], v152 offset:1024
	ds_read_b128 v[162:165], v152 offset:2048
	ds_read_b128 v[166:169], v152 offset:3072
	ds_read_b128 v[170:173], v153
	ds_read_b128 v[174:177], v153 offset:1024
	ds_read_b128 v[178:181], v153 offset:2048
	ds_read_b128 v[182:185], v153 offset:3072
	s_add_u32 s22, s20, 0xfffc0080
	s_addc_u32 s23, s21, -1
	s_cmp_eq_u32 s58, 12
	s_cselect_b32 s25, s13, s23
	s_cselect_b32 s24, s50, s22
	s_cselect_b32 s23, s11, s55
	s_cselect_b32 s22, s51, s54
	v_lshl_add_u64 v[218:219], s[20:21], 0, v[140:141]
	s_add_i32 m0, s41, 0xc000
	ds_read_b128 v[186:189], v154
	ds_read_b128 v[190:193], v154 offset:1024
	ds_read_b128 v[194:197], v154 offset:2048
	ds_read_b128 v[198:201], v154 offset:3072
	ds_read_b128 v[202:205], v154 offset:4096
	ds_read_b128 v[206:209], v154 offset:5120
	ds_read_b128 v[210:213], v154 offset:6144
	ds_read_b128 v[214:217], v154 offset:7168
	global_load_lds_dwordx4 v[218:219], off
	v_lshl_add_u64 v[218:219], s[20:21], 0, v[138:139]
	s_add_i32 m0, s41, 0xe000
	s_nop 0
	global_load_lds_dwordx4 v[218:219], off
	s_waitcnt vmcnt(8)
	s_waitcnt lgkmcnt(0)
	s_barrier
	s_setprio 1
	s_waitcnt lgkmcnt(0)
	v_mfma_f32_16x16x32_bf16 v[126:129], v[146:149], v[186:189], 0
	v_mfma_f32_16x16x32_bf16 v[118:121], v[162:165], v[186:189], 0
	v_mfma_f32_16x16x32_bf16 v[110:113], v[146:149], v[194:197], 0
	v_mfma_f32_16x16x32_bf16 v[102:105], v[162:165], v[194:197], 0
	v_mfma_f32_16x16x32_bf16 v[94:97], v[146:149], v[202:205], 0
	v_mfma_f32_16x16x32_bf16 v[86:89], v[162:165], v[202:205], 0
	v_mfma_f32_16x16x32_bf16 v[78:81], v[146:149], v[210:213], 0
	v_mfma_f32_16x16x32_bf16 v[70:73], v[162:165], v[210:213], 0
	v_mfma_f32_16x16x32_bf16 v[126:129], v[158:161], v[190:193], v[126:129]
	v_mfma_f32_16x16x32_bf16 v[118:121], v[166:169], v[190:193], v[118:121]
	v_mfma_f32_16x16x32_bf16 v[110:113], v[158:161], v[198:201], v[110:113]
	v_mfma_f32_16x16x32_bf16 v[102:105], v[166:169], v[198:201], v[102:105]
	v_mfma_f32_16x16x32_bf16 v[94:97], v[158:161], v[206:209], v[94:97]
	v_mfma_f32_16x16x32_bf16 v[86:89], v[166:169], v[206:209], v[86:89]
	v_mfma_f32_16x16x32_bf16 v[78:81], v[158:161], v[214:217], v[78:81]
	v_mfma_f32_16x16x32_bf16 v[70:73], v[166:169], v[214:217], v[70:73]
	s_setprio 0
	s_setprio 1
	v_mfma_f32_16x16x32_bf16 v[122:125], v[170:173], v[186:189], 0
	v_mfma_f32_16x16x32_bf16 v[114:117], v[178:181], v[186:189], 0
	v_mfma_f32_16x16x32_bf16 v[106:109], v[170:173], v[194:197], 0
	v_mfma_f32_16x16x32_bf16 v[98:101], v[178:181], v[194:197], 0
	v_mfma_f32_16x16x32_bf16 v[90:93], v[170:173], v[202:205], 0
	v_mfma_f32_16x16x32_bf16 v[82:85], v[178:181], v[202:205], 0
	v_mfma_f32_16x16x32_bf16 v[74:77], v[170:173], v[210:213], 0
	v_mfma_f32_16x16x32_bf16 v[66:69], v[178:181], v[210:213], 0
	v_mfma_f32_16x16x32_bf16 v[122:125], v[174:177], v[190:193], v[122:125]
	v_mfma_f32_16x16x32_bf16 v[114:117], v[182:185], v[190:193], v[114:117]
	v_mfma_f32_16x16x32_bf16 v[106:109], v[174:177], v[198:201], v[106:109]
	v_mfma_f32_16x16x32_bf16 v[98:101], v[182:185], v[198:201], v[98:101]
	v_mfma_f32_16x16x32_bf16 v[90:93], v[174:177], v[206:209], v[90:93]
	v_mfma_f32_16x16x32_bf16 v[82:85], v[182:185], v[206:209], v[82:85]
	v_mfma_f32_16x16x32_bf16 v[74:77], v[174:177], v[214:217], v[74:77]
	v_mfma_f32_16x16x32_bf16 v[66:69], v[182:185], v[214:217], v[66:69]
	s_setprio 0
	s_barrier
	s_mov_b32 m0, s19
	v_lshl_add_u64 v[218:219], s[22:23], 0, v[134:135]
	s_add_u32 s60, s22, 0x40000
	ds_read_b128 v[186:189], v154 offset:16384
	ds_read_b128 v[190:193], v154 offset:17408
	ds_read_b128 v[194:197], v154 offset:18432
	ds_read_b128 v[198:201], v154 offset:19456
	ds_read_b128 v[202:205], v154 offset:20480
	ds_read_b128 v[206:209], v154 offset:21504
	ds_read_b128 v[210:213], v154 offset:22528
	ds_read_b128 v[214:217], v154 offset:23552
	global_load_lds_dwordx4 v[218:219], off
	v_lshl_add_u64 v[220:221], s[22:23], 0, v[130:131]
	s_mov_b32 m0, s38
	s_addc_u32 s61, s23, 0
	global_load_lds_dwordx4 v[220:221], off
	v_lshl_add_u64 v[222:223], s[60:61], 0, v[134:135]
	s_mov_b32 m0, s39
	v_lshl_add_u64 v[224:225], s[24:25], 0, v[132:133]
	global_load_lds_dwordx4 v[222:223], off
	v_lshl_add_u64 v[222:223], s[60:61], 0, v[130:131]
	s_mov_b32 m0, s40
	s_nop 0
	global_load_lds_dwordx4 v[222:223], off
	v_lshl_add_u64 v[222:223], s[24:25], 0, v[136:137]
	s_waitcnt vmcnt(6)
	s_waitcnt lgkmcnt(0)
	s_barrier
; #define PG8_STAGE(bufoff, gbase, voff) do { _Pragma("unroll") for (int _i = 0; _i < 2; ++_i) \
;         __builtin_amdgcn_global_load_lds((const unsigned*)((const char*)(gbase) + (voff)[_i]), (PG8_LAS unsigned*)(lds + (bufoff) + ldsw + _i * 8192), 16, 0, 0); } while (0)
; #define PG8_LDA(dst, b, h) do { _Pragma("unroll") for (int m = 0; m < 4; ++m) _Pragma("unroll") for (int k = 0; k < 2; ++k) dst[m][k] = *(const PG8_LAS bf16x8*)(lds + PG8_SA(b, h) + aoff + m * 2048 + k * 1024); } while (0)
; #define PG8_LDB(dst, b, h) do { _Pragma("unroll") for (int n = 0; n < 2; ++n) _Pragma("unroll") for (int k = 0; k < 2; ++k) dst[n][k] = *(const PG8_LAS bf16x8*)(lds + PG8_SB(b, h) + boff + n * 2048 + k * 1024); } while (0)
; #define PG8_MMA(ai, bj, At, Bt) do { __builtin_amdgcn_s_setprio(1); _Pragma("unroll") for (int m = 0; m < 4; ++m) _Pragma("unroll") for (int n = 0; n < 2; ++n) _Pragma("unroll") for (int k = 0; k < 2; ++k) \
;         acc[ai][bj][m][n] = __builtin_amdgcn_mfma_f32_16x16x32_bf16(Bt[n][k], At[m][k], acc[ai][bj][m][n], 0, 0, 0); __builtin_amdgcn_s_setprio(0); } while (0)
; #define PG8_WAIT_V(n) asm volatile("s_waitcnt vmcnt(" #n ")" ::: "memory")
; #define PG8_WAIT_L(n) asm volatile("s_waitcnt lgkmcnt(" #n ")" ::: "memory")
; #define PG8_BAR __builtin_amdgcn_s_barrier()
; #define PG8_SCHED __builtin_amdgcn_sched_barrier(0)
; template <class Epi, class Sched, bool ALIGN_EPI = false, bool SP2 = false>
; __device__ __forceinline__ void gemm_phase(PG8_LAS unsigned char* lds, const Gemm g, const Sched& S, const Epi& E) {
;     ...
;             PG8_WAIT_V(8); PG8_WAIT_L(0); PG8_BAR; PG8_MMA(1, 0, At, B0); PG8_MMA(1, 1, At, B1); PG8_BAR; PG8_SCHED;
;             PG8_LDB(B0, 1, 0); PG8_LDB(B1, 1, 1); PG8_SCHED; PG8_LDA(At, 1, 0); PG8_STAGE(PG8_SA(0, 1), a2 + hstep, voffA);
;             PG8_WAIT_V(8); PG8_WAIT_L(0); PG8_BAR; PG8_MMA(0, 0, At, B0); PG8_MMA(0, 1, At, B1); PG8_BAR; PG8_SCHED;
	s_setprio 1
	s_waitcnt lgkmcnt(0)
	v_mfma_f32_16x16x32_bf16 v[62:65], v[146:149], v[186:189], 0
	v_mfma_f32_16x16x32_bf16 v[54:57], v[162:165], v[186:189], 0
	v_mfma_f32_16x16x32_bf16 v[46:49], v[146:149], v[194:197], 0
	v_mfma_f32_16x16x32_bf16 v[38:41], v[162:165], v[194:197], 0
	v_mfma_f32_16x16x32_bf16 v[30:33], v[146:149], v[202:205], 0
	v_mfma_f32_16x16x32_bf16 v[22:25], v[162:165], v[202:205], 0
	v_mfma_f32_16x16x32_bf16 v[14:17], v[146:149], v[210:213], 0
	v_mfma_f32_16x16x32_bf16 v[6:9], v[162:165], v[210:213], 0
	v_mfma_f32_16x16x32_bf16 v[62:65], v[158:161], v[190:193], v[62:65]
	v_mfma_f32_16x16x32_bf16 v[54:57], v[166:169], v[190:193], v[54:57]
	v_mfma_f32_16x16x32_bf16 v[46:49], v[158:161], v[198:201], v[46:49]
	v_mfma_f32_16x16x32_bf16 v[38:41], v[166:169], v[198:201], v[38:41]
	v_mfma_f32_16x16x32_bf16 v[30:33], v[158:161], v[206:209], v[30:33]
	v_mfma_f32_16x16x32_bf16 v[22:25], v[166:169], v[206:209], v[22:25]
	v_mfma_f32_16x16x32_bf16 v[14:17], v[158:161], v[214:217], v[14:17]
	v_mfma_f32_16x16x32_bf16 v[6:9], v[166:169], v[214:217], v[6:9]
	s_setprio 0
	s_setprio 1
	v_mfma_f32_16x16x32_bf16 v[58:61], v[170:173], v[186:189], 0
	v_mfma_f32_16x16x32_bf16 v[50:53], v[178:181], v[186:189], 0
	v_mfma_f32_16x16x32_bf16 v[42:45], v[170:173], v[194:197], 0
	v_mfma_f32_16x16x32_bf16 v[34:37], v[178:181], v[194:197], 0
	v_mfma_f32_16x16x32_bf16 v[26:29], v[170:173], v[202:205], 0
	v_mfma_f32_16x16x32_bf16 v[18:21], v[178:181], v[202:205], 0
	v_mfma_f32_16x16x32_bf16 v[10:13], v[170:173], v[210:213], 0
	v_mfma_f32_16x16x32_bf16 v[2:5], v[178:181], v[210:213], 0
	v_mfma_f32_16x16x32_bf16 v[58:61], v[174:177], v[190:193], v[58:61]
	v_mfma_f32_16x16x32_bf16 v[50:53], v[182:185], v[190:193], v[50:53]
	v_mfma_f32_16x16x32_bf16 v[42:45], v[174:177], v[198:201], v[42:45]
	v_mfma_f32_16x16x32_bf16 v[34:37], v[182:185], v[198:201], v[34:37]
	v_mfma_f32_16x16x32_bf16 v[26:29], v[174:177], v[206:209], v[26:29]
	v_mfma_f32_16x16x32_bf16 v[18:21], v[182:185], v[206:209], v[18:21]
	v_mfma_f32_16x16x32_bf16 v[10:13], v[174:177], v[214:217], v[10:13]
	v_mfma_f32_16x16x32_bf16 v[2:5], v[182:185], v[214:217], v[2:5]
	s_setprio 0
	s_barrier
	ds_read_b128 v[146:149], v155
	ds_read_b128 v[158:161], v155 offset:1024
	ds_read_b128 v[162:165], v155 offset:2048
	ds_read_b128 v[166:169], v155 offset:3072
	ds_read_b128 v[170:173], v156
	ds_read_b128 v[174:177], v156 offset:1024
	ds_read_b128 v[178:181], v156 offset:2048
	ds_read_b128 v[182:185], v156 offset:3072
	s_add_u32 s24, s24, 0x40000
	s_addc_u32 s25, s25, 0
	s_mov_b32 m0, s41
	s_nop 0
	global_load_lds_dwordx4 v[222:223], off
	s_mov_b32 m0, s42
	s_nop 0
	global_load_lds_dwordx4 v[224:225], off
	s_mov_b32 m0, s43
	v_lshl_add_u64 v[226:227], s[24:25], 0, v[136:137]
	ds_read_b128 v[186:189], v154 offset:32768
	ds_read_b128 v[190:193], v154 offset:33792
	ds_read_b128 v[194:197], v154 offset:34816
	ds_read_b128 v[198:201], v154 offset:35840
	ds_read_b128 v[202:205], v154 offset:36864
	ds_read_b128 v[206:209], v154 offset:37888
	ds_read_b128 v[210:213], v154 offset:38912
	ds_read_b128 v[214:217], v154 offset:39936
	global_load_lds_dwordx4 v[226:227], off
	v_lshl_add_u64 v[226:227], s[24:25], 0, v[132:133]
	s_mov_b32 m0, s44
	s_nop 0
	global_load_lds_dwordx4 v[226:227], off
	s_waitcnt vmcnt(8)
	s_waitcnt lgkmcnt(0)
	s_barrier
	s_setprio 1
	s_waitcnt lgkmcnt(0)
	v_mfma_f32_16x16x32_bf16 v[126:129], v[146:149], v[186:189], v[126:129]
	v_mfma_f32_16x16x32_bf16 v[118:121], v[162:165], v[186:189], v[118:121]
	v_mfma_f32_16x16x32_bf16 v[110:113], v[146:149], v[194:197], v[110:113]
	v_mfma_f32_16x16x32_bf16 v[102:105], v[162:165], v[194:197], v[102:105]
	v_mfma_f32_16x16x32_bf16 v[94:97], v[146:149], v[202:205], v[94:97]
	v_mfma_f32_16x16x32_bf16 v[86:89], v[162:165], v[202:205], v[86:89]
	v_mfma_f32_16x16x32_bf16 v[78:81], v[146:149], v[210:213], v[78:81]
	v_mfma_f32_16x16x32_bf16 v[70:73], v[162:165], v[210:213], v[70:73]
	v_mfma_f32_16x16x32_bf16 v[126:129], v[158:161], v[190:193], v[126:129]
	v_mfma_f32_16x16x32_bf16 v[118:121], v[166:169], v[190:193], v[118:121]
	v_mfma_f32_16x16x32_bf16 v[110:113], v[158:161], v[198:201], v[110:113]
	v_mfma_f32_16x16x32_bf16 v[102:105], v[166:169], v[198:201], v[102:105]
	v_mfma_f32_16x16x32_bf16 v[94:97], v[158:161], v[206:209], v[94:97]
	v_mfma_f32_16x16x32_bf16 v[86:89], v[166:169], v[206:209], v[86:89]
	v_mfma_f32_16x16x32_bf16 v[78:81], v[158:161], v[214:217], v[78:81]
	v_mfma_f32_16x16x32_bf16 v[70:73], v[166:169], v[214:217], v[70:73]
	s_setprio 0
	s_setprio 1
	v_mfma_f32_16x16x32_bf16 v[122:125], v[170:173], v[186:189], v[122:125]
	v_mfma_f32_16x16x32_bf16 v[114:117], v[178:181], v[186:189], v[114:117]
	v_mfma_f32_16x16x32_bf16 v[106:109], v[170:173], v[194:197], v[106:109]
	v_mfma_f32_16x16x32_bf16 v[98:101], v[178:181], v[194:197], v[98:101]
	v_mfma_f32_16x16x32_bf16 v[90:93], v[170:173], v[202:205], v[90:93]
	v_mfma_f32_16x16x32_bf16 v[82:85], v[178:181], v[202:205], v[82:85]
	v_mfma_f32_16x16x32_bf16 v[74:77], v[170:173], v[210:213], v[74:77]
	v_mfma_f32_16x16x32_bf16 v[66:69], v[178:181], v[210:213], v[66:69]
	v_mfma_f32_16x16x32_bf16 v[122:125], v[174:177], v[190:193], v[122:125]
	v_mfma_f32_16x16x32_bf16 v[114:117], v[182:185], v[190:193], v[114:117]
	v_mfma_f32_16x16x32_bf16 v[106:109], v[174:177], v[198:201], v[106:109]
	v_mfma_f32_16x16x32_bf16 v[98:101], v[182:185], v[198:201], v[98:101]
	v_mfma_f32_16x16x32_bf16 v[90:93], v[174:177], v[206:209], v[90:93]
	v_mfma_f32_16x16x32_bf16 v[82:85], v[182:185], v[206:209], v[82:85]
	v_mfma_f32_16x16x32_bf16 v[74:77], v[174:177], v[214:217], v[74:77]
	v_mfma_f32_16x16x32_bf16 v[66:69], v[182:185], v[214:217], v[66:69]
	s_setprio 0
	s_barrier
; #define PG8_STAGE(bufoff, gbase, voff) do { _Pragma("unroll") for (int _i = 0; _i < 2; ++_i) \
;         __builtin_amdgcn_global_load_lds((const unsigned*)((const char*)(gbase) + (voff)[_i]), (PG8_LAS unsigned*)(lds + (bufoff) + ldsw + _i * 8192), 16, 0, 0); } while (0)
; #define PG8_LDA(dst, b, h) do { _Pragma("unroll") for (int m = 0; m < 4; ++m) _Pragma("unroll") for (int k = 0; k < 2; ++k) dst[m][k] = *(const PG8_LAS bf16x8*)(lds + PG8_SA(b, h) + aoff + m * 2048 + k * 1024); } while (0)
; #define PG8_LDB(dst, b, h) do { _Pragma("unroll") for (int n = 0; n < 2; ++n) _Pragma("unroll") for (int k = 0; k < 2; ++k) dst[n][k] = *(const PG8_LAS bf16x8*)(lds + PG8_SB(b, h) + boff + n * 2048 + k * 1024); } while (0)
; #define PG8_MMA(ai, bj, At, Bt) do { __builtin_amdgcn_s_setprio(1); _Pragma("unroll") for (int m = 0; m < 4; ++m) _Pragma("unroll") for (int n = 0; n < 2; ++n) _Pragma("unroll") for (int k = 0; k < 2; ++k) \
;         acc[ai][bj][m][n] = __builtin_amdgcn_mfma_f32_16x16x32_bf16(Bt[n][k], At[m][k], acc[ai][bj][m][n], 0, 0, 0); __builtin_amdgcn_s_setprio(0); } while (0)
; #define PG8_WAIT_V(n) asm volatile("s_waitcnt vmcnt(" #n ")" ::: "memory")
; #define PG8_BAR __builtin_amdgcn_s_barrier()
; template <class Epi, class Sched, bool ALIGN_EPI = false, bool SP2 = false>
; __device__ __forceinline__ void gemm_phase(PG8_LAS unsigned char* lds, const Gemm g, const Sched& S, const Epi& E) {
;     ...
;         for (int t = 0; t < nt; t += 2) {
;             const bool last = (t == nt - 2);
;             const char* a1 = cA + (size_t)(t + 1) * kstep;
;             const char* a2 = last ? nA : cA + (size_t)(t + 2) * kstep; const char* b2 = last ? nB : cB + (size_t)(t + 2) * kstep;
;             const char* a3 = a2 + kstep; const char* b3 = b2 + kstep;
;             if (last && has_next) S.a_ready(nxt);
;             if constexpr (SP2) {
;             PG8_LDB(B0, 0, 0); PG8_LDB(B1, 0, 1); PG8_SCHED; PG8_LDA(At, 0, 0); PG8_STAGE(PG8_SA(1, 1), a1 + hstep, voffA);
;             PG8_WAIT_V(8); PG8_WAIT_L(0); PG8_BAR; PG8_MMA(0, 0, At, B0); PG8_MMA(0, 1, At, B1); PG8_BAR; PG8_SCHED;
;     ...
;             PG8_LDA(At, 1, 1); PG8_STAGE(PG8_SB(1, 0), b3, voffB); PG8_STAGE(PG8_SB(1, 1), b3 + hstep, voffB); PG8_STAGE(PG8_SA(1, 0), a3, voffA);
;             PG8_WAIT_V(8); PG8_WAIT_L(0); PG8_BAR; PG8_MMA(1, 0, At, B0); PG8_MMA(1, 1, At, B1); PG8_BAR; PG8_SCHED;
	s_mov_b32 m0, s45
	v_lshl_add_u64 v[218:219], v[218:219], 0, s[6:7]
	s_add_u32 s22, s22, 0x40080
	ds_read_b128 v[186:189], v154 offset:49152
	ds_read_b128 v[190:193], v154 offset:50176
	ds_read_b128 v[194:197], v154 offset:51200
	ds_read_b128 v[198:201], v154 offset:52224
	ds_read_b128 v[202:205], v154 offset:53248
	ds_read_b128 v[206:209], v154 offset:54272
	ds_read_b128 v[210:213], v154 offset:55296
	ds_read_b128 v[214:217], v154 offset:56320
	global_load_lds_dwordx4 v[218:219], off
	v_lshl_add_u64 v[218:219], v[220:221], 0, s[6:7]
	s_mov_b32 m0, s46
	s_addc_u32 s23, s23, 0
	global_load_lds_dwordx4 v[218:219], off
	v_lshl_add_u64 v[218:219], s[22:23], 0, v[134:135]
	s_mov_b32 m0, s49
	s_nop 0
	global_load_lds_dwordx4 v[218:219], off
	v_lshl_add_u64 v[218:219], s[22:23], 0, v[130:131]
	s_mov_b32 m0, s52
	s_nop 0
	global_load_lds_dwordx4 v[218:219], off
	v_lshl_add_u64 v[218:219], v[222:223], 0, s[6:7]
	s_mov_b32 m0, s47
	s_nop 0
	global_load_lds_dwordx4 v[218:219], off
	v_lshl_add_u64 v[218:219], v[224:225], 0, s[6:7]
	s_mov_b32 m0, s48
	s_nop 0
	global_load_lds_dwordx4 v[218:219], off
	s_waitcnt vmcnt(8)
	s_waitcnt lgkmcnt(0)
	s_barrier
	s_setprio 1
	s_waitcnt lgkmcnt(0)
	v_mfma_f32_16x16x32_bf16 v[62:65], v[146:149], v[186:189], v[62:65]
	v_mfma_f32_16x16x32_bf16 v[54:57], v[162:165], v[186:189], v[54:57]
	v_mfma_f32_16x16x32_bf16 v[46:49], v[146:149], v[194:197], v[46:49]
	v_mfma_f32_16x16x32_bf16 v[38:41], v[162:165], v[194:197], v[38:41]
	v_mfma_f32_16x16x32_bf16 v[30:33], v[146:149], v[202:205], v[30:33]
	v_mfma_f32_16x16x32_bf16 v[22:25], v[162:165], v[202:205], v[22:25]
	v_mfma_f32_16x16x32_bf16 v[14:17], v[146:149], v[210:213], v[14:17]
	v_mfma_f32_16x16x32_bf16 v[6:9], v[162:165], v[210:213], v[6:9]
	v_mfma_f32_16x16x32_bf16 v[62:65], v[158:161], v[190:193], v[62:65]
	v_mfma_f32_16x16x32_bf16 v[54:57], v[166:169], v[190:193], v[54:57]
	v_mfma_f32_16x16x32_bf16 v[46:49], v[158:161], v[198:201], v[46:49]
	v_mfma_f32_16x16x32_bf16 v[38:41], v[166:169], v[198:201], v[38:41]
	v_mfma_f32_16x16x32_bf16 v[30:33], v[158:161], v[206:209], v[30:33]
	v_mfma_f32_16x16x32_bf16 v[22:25], v[166:169], v[206:209], v[22:25]
	v_mfma_f32_16x16x32_bf16 v[14:17], v[158:161], v[214:217], v[14:17]
	v_mfma_f32_16x16x32_bf16 v[6:9], v[166:169], v[214:217], v[6:9]
	s_setprio 0
	s_setprio 1
	v_mfma_f32_16x16x32_bf16 v[58:61], v[170:173], v[186:189], v[58:61]
	v_mfma_f32_16x16x32_bf16 v[50:53], v[178:181], v[186:189], v[50:53]
	v_mfma_f32_16x16x32_bf16 v[42:45], v[170:173], v[194:197], v[42:45]
	v_mfma_f32_16x16x32_bf16 v[34:37], v[178:181], v[194:197], v[34:37]
	v_mfma_f32_16x16x32_bf16 v[26:29], v[170:173], v[202:205], v[26:29]
	v_mfma_f32_16x16x32_bf16 v[18:21], v[178:181], v[202:205], v[18:21]
	v_mfma_f32_16x16x32_bf16 v[10:13], v[170:173], v[210:213], v[10:13]
	v_mfma_f32_16x16x32_bf16 v[2:5], v[178:181], v[210:213], v[2:5]
	v_mfma_f32_16x16x32_bf16 v[58:61], v[174:177], v[190:193], v[58:61]
	v_mfma_f32_16x16x32_bf16 v[50:53], v[182:185], v[190:193], v[50:53]
	v_mfma_f32_16x16x32_bf16 v[42:45], v[174:177], v[198:201], v[42:45]
	v_mfma_f32_16x16x32_bf16 v[34:37], v[182:185], v[198:201], v[34:37]
	v_mfma_f32_16x16x32_bf16 v[26:29], v[174:177], v[206:209], v[26:29]
	v_mfma_f32_16x16x32_bf16 v[18:21], v[182:185], v[206:209], v[18:21]
	v_mfma_f32_16x16x32_bf16 v[10:13], v[174:177], v[214:217], v[10:13]
	v_mfma_f32_16x16x32_bf16 v[2:5], v[182:185], v[214:217], v[2:5]
	s_setprio 0
	s_barrier
	s_add_i32 s58, s58, 2
	s_add_u32 s54, s54, 0x100
	s_addc_u32 s55, s55, 0
	s_add_u32 s20, s20, 0x100
	s_addc_u32 s21, s21, 0
	s_cmp_gt_u32 s58, 13
.LBB0_2285:
	ds_read_b128 v[146:149], v152
	ds_read_b128 v[158:161], v152 offset:1024
	ds_read_b128 v[162:165], v152 offset:2048
	ds_read_b128 v[166:169], v152 offset:3072
	ds_read_b128 v[170:173], v153
	ds_read_b128 v[174:177], v153 offset:1024
	ds_read_b128 v[178:181], v153 offset:2048
	ds_read_b128 v[182:185], v153 offset:3072
	s_add_u32 s22, s20, 0xfffc0080
	s_addc_u32 s23, s21, -1
	s_cmp_eq_u32 s58, 12
	s_cselect_b32 s25, s13, s23
	s_cselect_b32 s24, s50, s22
	s_cselect_b32 s23, s11, s55
	s_cselect_b32 s22, s51, s54
	v_lshl_add_u64 v[218:219], s[20:21], 0, v[140:141]
	s_add_i32 m0, s41, 0xc000
	ds_read_b128 v[186:189], v154
	ds_read_b128 v[190:193], v154 offset:1024
	ds_read_b128 v[194:197], v154 offset:2048
	ds_read_b128 v[198:201], v154 offset:3072
	ds_read_b128 v[202:205], v154 offset:4096
	ds_read_b128 v[206:209], v154 offset:5120
	ds_read_b128 v[210:213], v154 offset:6144
	ds_read_b128 v[214:217], v154 offset:7168
	global_load_lds_dwordx4 v[218:219], off
	v_lshl_add_u64 v[218:219], s[20:21], 0, v[138:139]
	s_add_i32 m0, s41, 0xe000
	s_nop 0
	global_load_lds_dwordx4 v[218:219], off
	s_waitcnt vmcnt(8)
	s_waitcnt lgkmcnt(0)
	s_barrier
; #define PG8_STAGE(bufoff, gbase, voff) do { _Pragma("unroll") for (int _i = 0; _i < 2; ++_i) \
;         __builtin_amdgcn_global_load_lds((const unsigned*)((const char*)(gbase) + (voff)[_i]), (PG8_LAS unsigned*)(lds + (bufoff) + ldsw + _i * 8192), 16, 0, 0); } while (0)
; #define PG8_LDA(dst, b, h) do { _Pragma("unroll") for (int m = 0; m < 4; ++m) _Pragma("unroll") for (int k = 0; k < 2; ++k) dst[m][k] = *(const PG8_LAS bf16x8*)(lds + PG8_SA(b, h) + aoff + m * 2048 + k * 1024); } while (0)
; #define PG8_MMA(ai, bj, At, Bt) do { __builtin_amdgcn_s_setprio(1); _Pragma("unroll") for (int m = 0; m < 4; ++m) _Pragma("unroll") for (int n = 0; n < 2; ++n) _Pragma("unroll") for (int k = 0; k < 2; ++k) \
;         acc[ai][bj][m][n] = __builtin_amdgcn_mfma_f32_16x16x32_bf16(Bt[n][k], At[m][k], acc[ai][bj][m][n], 0, 0, 0); __builtin_amdgcn_s_setprio(0); } while (0)
; #define PG8_WAIT_V(n) asm volatile("s_waitcnt vmcnt(" #n ")" ::: "memory")
; #define PG8_WAIT_L(n) asm volatile("s_waitcnt lgkmcnt(" #n ")" ::: "memory")
; #define PG8_BAR __builtin_amdgcn_s_barrier()
; #define PG8_SCHED __builtin_amdgcn_sched_barrier(0)
; template <class Epi, class Sched, bool ALIGN_EPI = false, bool SP2 = false>
; __device__ __forceinline__ void gemm_phase(PG8_LAS unsigned char* lds, const Gemm g, const Sched& S, const Epi& E) {
;     ...
;             PG8_WAIT_V(8); PG8_WAIT_L(0); PG8_BAR; PG8_MMA(0, 0, At, B0); PG8_MMA(0, 1, At, B1); PG8_BAR; PG8_SCHED;
;             PG8_LDA(At, 0, 1); PG8_STAGE(PG8_SB(0, 0), b2, voffB); PG8_STAGE(PG8_SB(0, 1), b2 + hstep, voffB); PG8_STAGE(PG8_SA(0, 0), a2, voffA);
;             PG8_WAIT_V(8); PG8_WAIT_L(0); PG8_BAR; PG8_MMA(1, 0, At, B0); PG8_MMA(1, 1, At, B1); PG8_BAR; PG8_SCHED;
	s_setprio 1
	s_waitcnt lgkmcnt(0)
	v_mfma_f32_16x16x32_bf16 v[126:129], v[146:149], v[186:189], v[126:129]
	v_mfma_f32_16x16x32_bf16 v[118:121], v[162:165], v[186:189], v[118:121]
	v_mfma_f32_16x16x32_bf16 v[110:113], v[146:149], v[194:197], v[110:113]
	v_mfma_f32_16x16x32_bf16 v[102:105], v[162:165], v[194:197], v[102:105]
	v_mfma_f32_16x16x32_bf16 v[94:97], v[146:149], v[202:205], v[94:97]
	v_mfma_f32_16x16x32_bf16 v[86:89], v[162:165], v[202:205], v[86:89]
	v_mfma_f32_16x16x32_bf16 v[78:81], v[146:149], v[210:213], v[78:81]
	v_mfma_f32_16x16x32_bf16 v[70:73], v[162:165], v[210:213], v[70:73]
	v_mfma_f32_16x16x32_bf16 v[126:129], v[158:161], v[190:193], v[126:129]
	v_mfma_f32_16x16x32_bf16 v[118:121], v[166:169], v[190:193], v[118:121]
	v_mfma_f32_16x16x32_bf16 v[110:113], v[158:161], v[198:201], v[110:113]
	v_mfma_f32_16x16x32_bf16 v[102:105], v[166:169], v[198:201], v[102:105]
	v_mfma_f32_16x16x32_bf16 v[94:97], v[158:161], v[206:209], v[94:97]
	v_mfma_f32_16x16x32_bf16 v[86:89], v[166:169], v[206:209], v[86:89]
	v_mfma_f32_16x16x32_bf16 v[78:81], v[158:161], v[214:217], v[78:81]
	v_mfma_f32_16x16x32_bf16 v[70:73], v[166:169], v[214:217], v[70:73]
	s_setprio 0
	s_setprio 1
	v_mfma_f32_16x16x32_bf16 v[122:125], v[170:173], v[186:189], v[122:125]
	v_mfma_f32_16x16x32_bf16 v[114:117], v[178:181], v[186:189], v[114:117]
	v_mfma_f32_16x16x32_bf16 v[106:109], v[170:173], v[194:197], v[106:109]
	v_mfma_f32_16x16x32_bf16 v[98:101], v[178:181], v[194:197], v[98:101]
	v_mfma_f32_16x16x32_bf16 v[90:93], v[170:173], v[202:205], v[90:93]
	v_mfma_f32_16x16x32_bf16 v[82:85], v[178:181], v[202:205], v[82:85]
	v_mfma_f32_16x16x32_bf16 v[74:77], v[170:173], v[210:213], v[74:77]
	v_mfma_f32_16x16x32_bf16 v[66:69], v[178:181], v[210:213], v[66:69]
	v_mfma_f32_16x16x32_bf16 v[122:125], v[174:177], v[190:193], v[122:125]
	v_mfma_f32_16x16x32_bf16 v[114:117], v[182:185], v[190:193], v[114:117]
	v_mfma_f32_16x16x32_bf16 v[106:109], v[174:177], v[198:201], v[106:109]
	v_mfma_f32_16x16x32_bf16 v[98:101], v[182:185], v[198:201], v[98:101]
	v_mfma_f32_16x16x32_bf16 v[90:93], v[174:177], v[206:209], v[90:93]
	v_mfma_f32_16x16x32_bf16 v[82:85], v[182:185], v[206:209], v[82:85]
	v_mfma_f32_16x16x32_bf16 v[74:77], v[174:177], v[214:217], v[74:77]
	v_mfma_f32_16x16x32_bf16 v[66:69], v[182:185], v[214:217], v[66:69]
	s_setprio 0
	s_barrier
	s_mov_b32 m0, s19
	v_lshl_add_u64 v[218:219], s[22:23], 0, v[134:135]
	s_add_u32 s60, s22, 0x40000
	ds_read_b128 v[186:189], v154 offset:16384
	ds_read_b128 v[190:193], v154 offset:17408
	ds_read_b128 v[194:197], v154 offset:18432
	ds_read_b128 v[198:201], v154 offset:19456
	ds_read_b128 v[202:205], v154 offset:20480
	ds_read_b128 v[206:209], v154 offset:21504
	ds_read_b128 v[210:213], v154 offset:22528
	ds_read_b128 v[214:217], v154 offset:23552
	global_load_lds_dwordx4 v[218:219], off
	v_lshl_add_u64 v[220:221], s[22:23], 0, v[130:131]
	s_mov_b32 m0, s38
	s_addc_u32 s61, s23, 0
	global_load_lds_dwordx4 v[220:221], off
	v_lshl_add_u64 v[222:223], s[60:61], 0, v[134:135]
	s_mov_b32 m0, s39
	v_lshl_add_u64 v[224:225], s[24:25], 0, v[132:133]
	global_load_lds_dwordx4 v[222:223], off
	v_lshl_add_u64 v[222:223], s[60:61], 0, v[130:131]
	s_mov_b32 m0, s40
	s_nop 0
	global_load_lds_dwordx4 v[222:223], off
	v_lshl_add_u64 v[222:223], s[24:25], 0, v[136:137]
	s_waitcnt vmcnt(6)
	s_waitcnt lgkmcnt(0)
	s_barrier
	s_setprio 1
	s_waitcnt lgkmcnt(0)
	v_mfma_f32_16x16x32_bf16 v[62:65], v[146:149], v[186:189], v[62:65]
	v_mfma_f32_16x16x32_bf16 v[54:57], v[162:165], v[186:189], v[54:57]
	v_mfma_f32_16x16x32_bf16 v[46:49], v[146:149], v[194:197], v[46:49]
	v_mfma_f32_16x16x32_bf16 v[38:41], v[162:165], v[194:197], v[38:41]
	v_mfma_f32_16x16x32_bf16 v[30:33], v[146:149], v[202:205], v[30:33]
	v_mfma_f32_16x16x32_bf16 v[22:25], v[162:165], v[202:205], v[22:25]
	v_mfma_f32_16x16x32_bf16 v[14:17], v[146:149], v[210:213], v[14:17]
	v_mfma_f32_16x16x32_bf16 v[6:9], v[162:165], v[210:213], v[6:9]
	v_mfma_f32_16x16x32_bf16 v[62:65], v[158:161], v[190:193], v[62:65]
	v_mfma_f32_16x16x32_bf16 v[54:57], v[166:169], v[190:193], v[54:57]
	v_mfma_f32_16x16x32_bf16 v[46:49], v[158:161], v[198:201], v[46:49]
	v_mfma_f32_16x16x32_bf16 v[38:41], v[166:169], v[198:201], v[38:41]
	v_mfma_f32_16x16x32_bf16 v[30:33], v[158:161], v[206:209], v[30:33]
	v_mfma_f32_16x16x32_bf16 v[22:25], v[166:169], v[206:209], v[22:25]
	v_mfma_f32_16x16x32_bf16 v[14:17], v[158:161], v[214:217], v[14:17]
	v_mfma_f32_16x16x32_bf16 v[6:9], v[166:169], v[214:217], v[6:9]
	s_setprio 0
	s_setprio 1
	v_mfma_f32_16x16x32_bf16 v[58:61], v[170:173], v[186:189], v[58:61]
	v_mfma_f32_16x16x32_bf16 v[50:53], v[178:181], v[186:189], v[50:53]
	v_mfma_f32_16x16x32_bf16 v[42:45], v[170:173], v[194:197], v[42:45]
	v_mfma_f32_16x16x32_bf16 v[34:37], v[178:181], v[194:197], v[34:37]
	v_mfma_f32_16x16x32_bf16 v[26:29], v[170:173], v[202:205], v[26:29]
	v_mfma_f32_16x16x32_bf16 v[18:21], v[178:181], v[202:205], v[18:21]
	v_mfma_f32_16x16x32_bf16 v[10:13], v[170:173], v[210:213], v[10:13]
	v_mfma_f32_16x16x32_bf16 v[2:5], v[178:181], v[210:213], v[2:5]
	v_mfma_f32_16x16x32_bf16 v[58:61], v[174:177], v[190:193], v[58:61]
	v_mfma_f32_16x16x32_bf16 v[50:53], v[182:185], v[190:193], v[50:53]
	v_mfma_f32_16x16x32_bf16 v[42:45], v[174:177], v[198:201], v[42:45]
	v_mfma_f32_16x16x32_bf16 v[34:37], v[182:185], v[198:201], v[34:37]
	v_mfma_f32_16x16x32_bf16 v[26:29], v[174:177], v[206:209], v[26:29]
	v_mfma_f32_16x16x32_bf16 v[18:21], v[182:185], v[206:209], v[18:21]
	v_mfma_f32_16x16x32_bf16 v[10:13], v[174:177], v[214:217], v[10:13]
	v_mfma_f32_16x16x32_bf16 v[2:5], v[182:185], v[214:217], v[2:5]
	s_setprio 0
	s_barrier
; #define PG8_STAGE(bufoff, gbase, voff) do { _Pragma("unroll") for (int _i = 0; _i < 2; ++_i) \
;         __builtin_amdgcn_global_load_lds((const unsigned*)((const char*)(gbase) + (voff)[_i]), (PG8_LAS unsigned*)(lds + (bufoff) + ldsw + _i * 8192), 16, 0, 0); } while (0)
; #define PG8_LDA(dst, b, h) do { _Pragma("unroll") for (int m = 0; m < 4; ++m) _Pragma("unroll") for (int k = 0; k < 2; ++k) dst[m][k] = *(const PG8_LAS bf16x8*)(lds + PG8_SA(b, h) + aoff + m * 2048 + k * 1024); } while (0)
; #define PG8_LDB(dst, b, h) do { _Pragma("unroll") for (int n = 0; n < 2; ++n) _Pragma("unroll") for (int k = 0; k < 2; ++k) dst[n][k] = *(const PG8_LAS bf16x8*)(lds + PG8_SB(b, h) + boff + n * 2048 + k * 1024); } while (0)
; #define PG8_MMA(ai, bj, At, Bt) do { __builtin_amdgcn_s_setprio(1); _Pragma("unroll") for (int m = 0; m < 4; ++m) _Pragma("unroll") for (int n = 0; n < 2; ++n) _Pragma("unroll") for (int k = 0; k < 2; ++k) \
;         acc[ai][bj][m][n] = __builtin_amdgcn_mfma_f32_16x16x32_bf16(Bt[n][k], At[m][k], acc[ai][bj][m][n], 0, 0, 0); __builtin_amdgcn_s_setprio(0); } while (0)
; #define PG8_WAIT_V(n) asm volatile("s_waitcnt vmcnt(" #n ")" ::: "memory")
; #define PG8_WAIT_L(n) asm volatile("s_waitcnt lgkmcnt(" #n ")" ::: "memory")
; #define PG8_BAR __builtin_amdgcn_s_barrier()
; #define PG8_SCHED __builtin_amdgcn_sched_barrier(0)
; template <class Epi, class Sched, bool ALIGN_EPI = false, bool SP2 = false>
; __device__ __forceinline__ void gemm_phase(PG8_LAS unsigned char* lds, const Gemm g, const Sched& S, const Epi& E) {
;     ...
;             PG8_LDB(B0, 1, 0); PG8_LDB(B1, 1, 1); PG8_SCHED; PG8_LDA(At, 1, 0); PG8_STAGE(PG8_SA(0, 1), a2 + hstep, voffA);
;             PG8_WAIT_V(8); PG8_WAIT_L(0); PG8_BAR; PG8_MMA(0, 0, At, B0); PG8_MMA(0, 1, At, B1); PG8_BAR; PG8_SCHED;
	ds_read_b128 v[146:149], v155
	ds_read_b128 v[158:161], v155 offset:1024
	ds_read_b128 v[162:165], v155 offset:2048
	ds_read_b128 v[166:169], v155 offset:3072
	ds_read_b128 v[170:173], v156
	ds_read_b128 v[174:177], v156 offset:1024
	ds_read_b128 v[178:181], v156 offset:2048
	ds_read_b128 v[182:185], v156 offset:3072
	s_add_u32 s24, s24, 0x40000
	s_addc_u32 s25, s25, 0
	s_mov_b32 m0, s41
	s_nop 0
	global_load_lds_dwordx4 v[222:223], off
	s_mov_b32 m0, s42
	s_nop 0
	global_load_lds_dwordx4 v[224:225], off
	s_mov_b32 m0, s43
	v_lshl_add_u64 v[226:227], s[24:25], 0, v[136:137]
	ds_read_b128 v[186:189], v154 offset:32768
	ds_read_b128 v[190:193], v154 offset:33792
	ds_read_b128 v[194:197], v154 offset:34816
	ds_read_b128 v[198:201], v154 offset:35840
	ds_read_b128 v[202:205], v154 offset:36864
	ds_read_b128 v[206:209], v154 offset:37888
	ds_read_b128 v[210:213], v154 offset:38912
	ds_read_b128 v[214:217], v154 offset:39936
	global_load_lds_dwordx4 v[226:227], off
	v_lshl_add_u64 v[226:227], s[24:25], 0, v[132:133]
	s_mov_b32 m0, s44
	s_nop 0
	global_load_lds_dwordx4 v[226:227], off
	s_waitcnt vmcnt(8)
	s_waitcnt lgkmcnt(0)
	s_barrier
	s_setprio 1
	s_waitcnt lgkmcnt(0)
	v_mfma_f32_16x16x32_bf16 v[126:129], v[146:149], v[186:189], v[126:129]
	v_mfma_f32_16x16x32_bf16 v[118:121], v[162:165], v[186:189], v[118:121]
	v_mfma_f32_16x16x32_bf16 v[110:113], v[146:149], v[194:197], v[110:113]
	v_mfma_f32_16x16x32_bf16 v[102:105], v[162:165], v[194:197], v[102:105]
	v_mfma_f32_16x16x32_bf16 v[94:97], v[146:149], v[202:205], v[94:97]
	v_mfma_f32_16x16x32_bf16 v[86:89], v[162:165], v[202:205], v[86:89]
	v_mfma_f32_16x16x32_bf16 v[78:81], v[146:149], v[210:213], v[78:81]
	v_mfma_f32_16x16x32_bf16 v[70:73], v[162:165], v[210:213], v[70:73]
	v_mfma_f32_16x16x32_bf16 v[126:129], v[158:161], v[190:193], v[126:129]
	v_mfma_f32_16x16x32_bf16 v[118:121], v[166:169], v[190:193], v[118:121]
	v_mfma_f32_16x16x32_bf16 v[110:113], v[158:161], v[198:201], v[110:113]
	v_mfma_f32_16x16x32_bf16 v[102:105], v[166:169], v[198:201], v[102:105]
	v_mfma_f32_16x16x32_bf16 v[94:97], v[158:161], v[206:209], v[94:97]
	v_mfma_f32_16x16x32_bf16 v[86:89], v[166:169], v[206:209], v[86:89]
	v_mfma_f32_16x16x32_bf16 v[78:81], v[158:161], v[214:217], v[78:81]
	v_mfma_f32_16x16x32_bf16 v[70:73], v[166:169], v[214:217], v[70:73]
	s_setprio 0
	s_setprio 1
	v_mfma_f32_16x16x32_bf16 v[122:125], v[170:173], v[186:189], v[122:125]
	v_mfma_f32_16x16x32_bf16 v[114:117], v[178:181], v[186:189], v[114:117]
	v_mfma_f32_16x16x32_bf16 v[106:109], v[170:173], v[194:197], v[106:109]
	v_mfma_f32_16x16x32_bf16 v[98:101], v[178:181], v[194:197], v[98:101]
	v_mfma_f32_16x16x32_bf16 v[90:93], v[170:173], v[202:205], v[90:93]
	v_mfma_f32_16x16x32_bf16 v[82:85], v[178:181], v[202:205], v[82:85]
	v_mfma_f32_16x16x32_bf16 v[74:77], v[170:173], v[210:213], v[74:77]
	v_mfma_f32_16x16x32_bf16 v[66:69], v[178:181], v[210:213], v[66:69]
	v_mfma_f32_16x16x32_bf16 v[122:125], v[174:177], v[190:193], v[122:125]
	v_mfma_f32_16x16x32_bf16 v[114:117], v[182:185], v[190:193], v[114:117]
	v_mfma_f32_16x16x32_bf16 v[106:109], v[174:177], v[198:201], v[106:109]
	v_mfma_f32_16x16x32_bf16 v[98:101], v[182:185], v[198:201], v[98:101]
	v_mfma_f32_16x16x32_bf16 v[90:93], v[174:177], v[206:209], v[90:93]
	v_mfma_f32_16x16x32_bf16 v[82:85], v[182:185], v[206:209], v[82:85]
	v_mfma_f32_16x16x32_bf16 v[74:77], v[174:177], v[214:217], v[74:77]
	v_mfma_f32_16x16x32_bf16 v[66:69], v[182:185], v[214:217], v[66:69]
	s_setprio 0
	s_barrier
; #define PG8_STAGE(bufoff, gbase, voff) do { _Pragma("unroll") for (int _i = 0; _i < 2; ++_i) \
;         __builtin_amdgcn_global_load_lds((const unsigned*)((const char*)(gbase) + (voff)[_i]), (PG8_LAS unsigned*)(lds + (bufoff) + ldsw + _i * 8192), 16, 0, 0); } while (0)
; #define PG8_LDA(dst, b, h) do { _Pragma("unroll") for (int m = 0; m < 4; ++m) _Pragma("unroll") for (int k = 0; k < 2; ++k) dst[m][k] = *(const PG8_LAS bf16x8*)(lds + PG8_SA(b, h) + aoff + m * 2048 + k * 1024); } while (0)
; #define PG8_MMA(ai, bj, At, Bt) do { __builtin_amdgcn_s_setprio(1); _Pragma("unroll") for (int m = 0; m < 4; ++m) _Pragma("unroll") for (int n = 0; n < 2; ++n) _Pragma("unroll") for (int k = 0; k < 2; ++k) \
;         acc[ai][bj][m][n] = __builtin_amdgcn_mfma_f32_16x16x32_bf16(Bt[n][k], At[m][k], acc[ai][bj][m][n], 0, 0, 0); __builtin_amdgcn_s_setprio(0); } while (0)
; #define PG8_WAIT_V(n) asm volatile("s_waitcnt vmcnt(" #n ")" ::: "memory")
; #define PG8_WAIT_L(n) asm volatile("s_waitcnt lgkmcnt(" #n ")" ::: "memory")
; #define PG8_BAR __builtin_amdgcn_s_barrier()
; #define PG8_SCHED __builtin_amdgcn_sched_barrier(0)
; template <class Epi, class Sched, bool ALIGN_EPI = false, bool SP2 = false>
; __device__ __forceinline__ void gemm_phase(PG8_LAS unsigned char* lds, const Gemm g, const Sched& S, const Epi& E) {
;     ...
;         for (int t = 0; t < nt; t += 2) {
;     ...
;             PG8_LDA(At, 1, 1); PG8_STAGE(PG8_SB(1, 0), b3, voffB); PG8_STAGE(PG8_SB(1, 1), b3 + hstep, voffB); PG8_STAGE(PG8_SA(1, 0), a3, voffA);
;             PG8_WAIT_V(8); PG8_WAIT_L(0); PG8_BAR; PG8_MMA(1, 0, At, B0); PG8_MMA(1, 1, At, B1); PG8_BAR; PG8_SCHED;
	s_mov_b32 m0, s45
	v_lshl_add_u64 v[218:219], v[218:219], 0, s[6:7]
	s_add_u32 s22, s22, 0x40080
	ds_read_b128 v[186:189], v154 offset:49152
	ds_read_b128 v[190:193], v154 offset:50176
	ds_read_b128 v[194:197], v154 offset:51200
	ds_read_b128 v[198:201], v154 offset:52224
	ds_read_b128 v[202:205], v154 offset:53248
	ds_read_b128 v[206:209], v154 offset:54272
	ds_read_b128 v[210:213], v154 offset:55296
	ds_read_b128 v[214:217], v154 offset:56320
	global_load_lds_dwordx4 v[218:219], off
	v_lshl_add_u64 v[218:219], v[220:221], 0, s[6:7]
	s_mov_b32 m0, s46
	s_addc_u32 s23, s23, 0
	global_load_lds_dwordx4 v[218:219], off
	v_lshl_add_u64 v[218:219], s[22:23], 0, v[134:135]
	s_mov_b32 m0, s49
	s_nop 0
	global_load_lds_dwordx4 v[218:219], off
	v_lshl_add_u64 v[218:219], s[22:23], 0, v[130:131]
	s_mov_b32 m0, s52
	s_nop 0
	global_load_lds_dwordx4 v[218:219], off
	v_lshl_add_u64 v[218:219], v[222:223], 0, s[6:7]
	s_mov_b32 m0, s47
	s_nop 0
	global_load_lds_dwordx4 v[218:219], off
	v_lshl_add_u64 v[218:219], v[224:225], 0, s[6:7]
	s_mov_b32 m0, s48
	s_nop 0
	global_load_lds_dwordx4 v[218:219], off
	s_waitcnt vmcnt(8)
	s_waitcnt lgkmcnt(0)
	s_barrier
	s_setprio 1
	s_waitcnt lgkmcnt(0)
	v_mfma_f32_16x16x32_bf16 v[62:65], v[146:149], v[186:189], v[62:65]
	v_mfma_f32_16x16x32_bf16 v[54:57], v[162:165], v[186:189], v[54:57]
	v_mfma_f32_16x16x32_bf16 v[46:49], v[146:149], v[194:197], v[46:49]
	v_mfma_f32_16x16x32_bf16 v[38:41], v[162:165], v[194:197], v[38:41]
	v_mfma_f32_16x16x32_bf16 v[30:33], v[146:149], v[202:205], v[30:33]
	v_mfma_f32_16x16x32_bf16 v[22:25], v[162:165], v[202:205], v[22:25]
	v_mfma_f32_16x16x32_bf16 v[14:17], v[146:149], v[210:213], v[14:17]
	v_mfma_f32_16x16x32_bf16 v[6:9], v[162:165], v[210:213], v[6:9]
	v_mfma_f32_16x16x32_bf16 v[62:65], v[158:161], v[190:193], v[62:65]
	v_mfma_f32_16x16x32_bf16 v[54:57], v[166:169], v[190:193], v[54:57]
	v_mfma_f32_16x16x32_bf16 v[46:49], v[158:161], v[198:201], v[46:49]
	v_mfma_f32_16x16x32_bf16 v[38:41], v[166:169], v[198:201], v[38:41]
	v_mfma_f32_16x16x32_bf16 v[30:33], v[158:161], v[206:209], v[30:33]
	v_mfma_f32_16x16x32_bf16 v[22:25], v[166:169], v[206:209], v[22:25]
	v_mfma_f32_16x16x32_bf16 v[14:17], v[158:161], v[214:217], v[14:17]
	v_mfma_f32_16x16x32_bf16 v[6:9], v[166:169], v[214:217], v[6:9]
	s_setprio 0
	s_setprio 1
	v_mfma_f32_16x16x32_bf16 v[58:61], v[170:173], v[186:189], v[58:61]
	v_mfma_f32_16x16x32_bf16 v[50:53], v[178:181], v[186:189], v[50:53]
	v_mfma_f32_16x16x32_bf16 v[42:45], v[170:173], v[194:197], v[42:45]
	v_mfma_f32_16x16x32_bf16 v[34:37], v[178:181], v[194:197], v[34:37]
	v_mfma_f32_16x16x32_bf16 v[26:29], v[170:173], v[202:205], v[26:29]
	v_mfma_f32_16x16x32_bf16 v[18:21], v[178:181], v[202:205], v[18:21]
	v_mfma_f32_16x16x32_bf16 v[10:13], v[170:173], v[210:213], v[10:13]
	v_mfma_f32_16x16x32_bf16 v[2:5], v[178:181], v[210:213], v[2:5]
	v_mfma_f32_16x16x32_bf16 v[58:61], v[174:177], v[190:193], v[58:61]
	v_mfma_f32_16x16x32_bf16 v[50:53], v[182:185], v[190:193], v[50:53]
	v_mfma_f32_16x16x32_bf16 v[42:45], v[174:177], v[198:201], v[42:45]
	v_mfma_f32_16x16x32_bf16 v[34:37], v[182:185], v[198:201], v[34:37]
	v_mfma_f32_16x16x32_bf16 v[26:29], v[174:177], v[206:209], v[26:29]
	v_mfma_f32_16x16x32_bf16 v[18:21], v[182:185], v[206:209], v[18:21]
	v_mfma_f32_16x16x32_bf16 v[10:13], v[174:177], v[214:217], v[10:13]
	v_mfma_f32_16x16x32_bf16 v[2:5], v[182:185], v[214:217], v[2:5]
	s_setprio 0
	s_barrier
	s_add_i32 s58, s58, 2
	s_add_u32 s54, s54, 0x100
	s_addc_u32 s55, s55, 0
	s_add_u32 s20, s20, 0x100
	s_addc_u32 s21, s21, 0
	s_cmp_gt_u32 s58, 13
	s_cbranch_scc0 .LBB0_2285
	s_and_b64 vcc, exec, s[8:9]
	s_cbranch_vccz .LBB0_2288
	s_barrier

; #define PG8_STAGE(bufoff, gbase, voff) do { _Pragma("unroll") for (int _i = 0; _i < 2; ++_i) \
;         __builtin_amdgcn_global_load_lds((const unsigned*)((const char*)(gbase) + (voff)[_i]), (PG8_LAS unsigned*)(lds + (bufoff) + ldsw + _i * 8192), 16, 0, 0); } while (0)
; #define PG8_LDA(dst, b, h) do { _Pragma("unroll") for (int m = 0; m < 4; ++m) _Pragma("unroll") for (int k = 0; k < 2; ++k) dst[m][k] = *(const PG8_LAS bf16x8*)(lds + PG8_SA(b, h) + aoff + m * 2048 + k * 1024); } while (0)
; #define PG8_LDB(dst, b, h) do { _Pragma("unroll") for (int n = 0; n < 2; ++n) _Pragma("unroll") for (int k = 0; k < 2; ++k) dst[n][k] = *(const PG8_LAS bf16x8*)(lds + PG8_SB(b, h) + boff + n * 2048 + k * 1024); } while (0)
; #define PG8_MMA(ai, bj, At, Bt) do { __builtin_amdgcn_s_setprio(1); _Pragma("unroll") for (int m = 0; m < 4; ++m) _Pragma("unroll") for (int n = 0; n < 2; ++n) _Pragma("unroll") for (int k = 0; k < 2; ++k) \
;         acc[ai][bj][m][n] = __builtin_amdgcn_mfma_f32_16x16x32_bf16(Bt[n][k], At[m][k], acc[ai][bj][m][n], 0, 0, 0); __builtin_amdgcn_s_setprio(0); } while (0)
; #define PG8_WAIT_V(n) asm volatile("s_waitcnt vmcnt(" #n ")" ::: "memory")
; #define PG8_BAR __builtin_amdgcn_s_barrier()
; template <class Epi, class Sched, bool ALIGN_EPI = false, bool SP2 = false>
; __device__ __forceinline__ void gemm_phase(PG8_LAS unsigned char* lds, const Gemm g, const Sched& S, const Epi& E) {
;     ...
;         for (int t = 0; t < nt; t += 2) {
;             const bool last = (t == nt - 2);
;             const char* a1 = cA + (size_t)(t + 1) * kstep;
;             const char* a2 = last ? nA : cA + (size_t)(t + 2) * kstep; const char* b2 = last ? nB : cB + (size_t)(t + 2) * kstep;
;             const char* a3 = a2 + kstep; const char* b3 = b2 + kstep;
;             if (last && has_next) S.a_ready(nxt);
;             if constexpr (SP2) {
;             PG8_LDB(B0, 0, 0); PG8_LDB(B1, 0, 1); PG8_SCHED; PG8_LDA(At, 0, 0); PG8_STAGE(PG8_SA(1, 1), a1 + hstep, voffA);
;             PG8_WAIT_V(8); PG8_WAIT_L(0); PG8_BAR; PG8_MMA(0, 0, At, B0); PG8_MMA(0, 1, At, B1); PG8_BAR; PG8_SCHED;
;             PG8_LDA(At, 0, 1); PG8_STAGE(PG8_SB(0, 0), b2, voffB); PG8_STAGE(PG8_SB(0, 1), b2 + hstep, voffB); PG8_STAGE(PG8_SA(0, 0), a2, voffA);
;             PG8_WAIT_V(8); PG8_WAIT_L(0); PG8_BAR; PG8_MMA(1, 0, At, B0); PG8_MMA(1, 1, At, B1); PG8_BAR; PG8_SCHED;
.LBB0_2366:
	s_add_u32 s64, s24, 0x100
	s_addc_u32 s65, s25, 0
	s_mov_b32 s66, -2
	ds_read_b128 v[154:157], v148
	ds_read_b128 v[158:161], v148 offset:1024
	ds_read_b128 v[162:165], v148 offset:2048
	ds_read_b128 v[166:169], v148 offset:3072
	ds_read_b128 v[170:173], v149
	ds_read_b128 v[174:177], v149 offset:1024
	ds_read_b128 v[178:181], v149 offset:2048
	ds_read_b128 v[182:185], v149 offset:3072
	s_add_u32 s24, s22, 0x100
	s_addc_u32 s25, s23, 0
	s_cmp_eq_u32 s66, 40
	s_cselect_b32 s39, s5, s25
	s_cselect_b32 s38, s4, s24
	s_cselect_b32 s37, s21, s65
	s_cselect_b32 s36, s20, s64
	v_lshl_add_u64 v[218:219], s[22:23], 0, v[140:141]
	s_add_i32 m0, s44, 0xc000
	ds_read_b128 v[186:189], v150
	ds_read_b128 v[190:193], v150 offset:1024
	ds_read_b128 v[194:197], v150 offset:2048
	ds_read_b128 v[198:201], v150 offset:3072
	ds_read_b128 v[202:205], v150 offset:4096
	ds_read_b128 v[206:209], v150 offset:5120
	ds_read_b128 v[210:213], v150 offset:6144
	ds_read_b128 v[214:217], v150 offset:7168
	global_load_lds_dwordx4 v[218:219], off
	v_lshl_add_u64 v[218:219], s[22:23], 0, v[138:139]
	s_add_i32 m0, s44, 0xe000
	s_nop 0
	global_load_lds_dwordx4 v[218:219], off
	s_waitcnt vmcnt(8)
	s_waitcnt lgkmcnt(0)
	s_barrier
	s_setprio 1
	s_waitcnt lgkmcnt(0)
	v_mfma_f32_16x16x32_bf16 v[126:129], v[154:157], v[186:189], 0
	v_mfma_f32_16x16x32_bf16 v[122:125], v[162:165], v[186:189], 0
	v_mfma_f32_16x16x32_bf16 v[118:121], v[154:157], v[194:197], 0
	v_mfma_f32_16x16x32_bf16 v[114:117], v[162:165], v[194:197], 0
	v_mfma_f32_16x16x32_bf16 v[102:105], v[154:157], v[202:205], 0
	v_mfma_f32_16x16x32_bf16 v[98:101], v[162:165], v[202:205], 0
	v_mfma_f32_16x16x32_bf16 v[86:89], v[154:157], v[210:213], 0
	v_mfma_f32_16x16x32_bf16 v[82:85], v[162:165], v[210:213], 0
	v_mfma_f32_16x16x32_bf16 v[126:129], v[158:161], v[190:193], v[126:129]
	v_mfma_f32_16x16x32_bf16 v[122:125], v[166:169], v[190:193], v[122:125]
	v_mfma_f32_16x16x32_bf16 v[118:121], v[158:161], v[198:201], v[118:121]
	v_mfma_f32_16x16x32_bf16 v[114:117], v[166:169], v[198:201], v[114:117]
	v_mfma_f32_16x16x32_bf16 v[102:105], v[158:161], v[206:209], v[102:105]
	v_mfma_f32_16x16x32_bf16 v[98:101], v[166:169], v[206:209], v[98:101]
	v_mfma_f32_16x16x32_bf16 v[86:89], v[158:161], v[214:217], v[86:89]
	v_mfma_f32_16x16x32_bf16 v[82:85], v[166:169], v[214:217], v[82:85]
	s_setprio 0
	s_setprio 1
	v_mfma_f32_16x16x32_bf16 v[110:113], v[170:173], v[186:189], 0
	v_mfma_f32_16x16x32_bf16 v[106:109], v[178:181], v[186:189], 0
	v_mfma_f32_16x16x32_bf16 v[94:97], v[170:173], v[194:197], 0
	v_mfma_f32_16x16x32_bf16 v[90:93], v[178:181], v[194:197], 0
	v_mfma_f32_16x16x32_bf16 v[78:81], v[170:173], v[202:205], 0
	v_mfma_f32_16x16x32_bf16 v[74:77], v[178:181], v[202:205], 0
	v_mfma_f32_16x16x32_bf16 v[70:73], v[170:173], v[210:213], 0
	v_mfma_f32_16x16x32_bf16 v[66:69], v[178:181], v[210:213], 0
	v_mfma_f32_16x16x32_bf16 v[110:113], v[174:177], v[190:193], v[110:113]
	v_mfma_f32_16x16x32_bf16 v[106:109], v[182:185], v[190:193], v[106:109]
	v_mfma_f32_16x16x32_bf16 v[94:97], v[174:177], v[198:201], v[94:97]
	v_mfma_f32_16x16x32_bf16 v[90:93], v[182:185], v[198:201], v[90:93]
	v_mfma_f32_16x16x32_bf16 v[78:81], v[174:177], v[206:209], v[78:81]
	v_mfma_f32_16x16x32_bf16 v[74:77], v[182:185], v[206:209], v[74:77]
	v_mfma_f32_16x16x32_bf16 v[70:73], v[174:177], v[214:217], v[70:73]
	v_mfma_f32_16x16x32_bf16 v[66:69], v[182:185], v[214:217], v[66:69]
	s_setprio 0
	s_barrier
	s_mov_b32 m0, s40
	v_lshl_add_u64 v[218:219], s[36:37], 0, v[132:133]
	s_add_u32 s22, s36, 0xb0000
	ds_read_b128 v[186:189], v150 offset:16384
	ds_read_b128 v[190:193], v150 offset:17408
	ds_read_b128 v[194:197], v150 offset:18432
	ds_read_b128 v[198:201], v150 offset:19456
	ds_read_b128 v[202:205], v150 offset:20480
	ds_read_b128 v[206:209], v150 offset:21504
	ds_read_b128 v[210:213], v150 offset:22528
	ds_read_b128 v[214:217], v150 offset:23552
	global_load_lds_dwordx4 v[218:219], off
	v_lshl_add_u64 v[220:221], s[36:37], 0, v[136:137]
	s_mov_b32 m0, s41
	s_addc_u32 s23, s37, 0
	global_load_lds_dwordx4 v[220:221], off
	v_lshl_add_u64 v[222:223], s[22:23], 0, v[132:133]
	s_mov_b32 m0, s42
	v_lshl_add_u64 v[224:225], s[38:39], 0, v[134:135]
	global_load_lds_dwordx4 v[222:223], off
	v_lshl_add_u64 v[222:223], s[22:23], 0, v[136:137]
	s_mov_b32 m0, s43
	s_nop 0
	global_load_lds_dwordx4 v[222:223], off
	v_lshl_add_u64 v[222:223], s[38:39], 0, v[130:131]
	s_waitcnt vmcnt(6)
	s_waitcnt lgkmcnt(0)
	s_barrier
	s_setprio 1
	s_waitcnt lgkmcnt(0)
	v_mfma_f32_16x16x32_bf16 v[62:65], v[154:157], v[186:189], 0
	v_mfma_f32_16x16x32_bf16 v[58:61], v[162:165], v[186:189], 0
	v_mfma_f32_16x16x32_bf16 v[54:57], v[154:157], v[194:197], 0
	v_mfma_f32_16x16x32_bf16 v[50:53], v[162:165], v[194:197], 0
	v_mfma_f32_16x16x32_bf16 v[38:41], v[154:157], v[202:205], 0
	v_mfma_f32_16x16x32_bf16 v[34:37], v[162:165], v[202:205], 0
	v_mfma_f32_16x16x32_bf16 v[22:25], v[154:157], v[210:213], 0
	v_mfma_f32_16x16x32_bf16 v[18:21], v[162:165], v[210:213], 0
	v_mfma_f32_16x16x32_bf16 v[62:65], v[158:161], v[190:193], v[62:65]
	v_mfma_f32_16x16x32_bf16 v[58:61], v[166:169], v[190:193], v[58:61]
	v_mfma_f32_16x16x32_bf16 v[54:57], v[158:161], v[198:201], v[54:57]
	v_mfma_f32_16x16x32_bf16 v[50:53], v[166:169], v[198:201], v[50:53]
	v_mfma_f32_16x16x32_bf16 v[38:41], v[158:161], v[206:209], v[38:41]
	v_mfma_f32_16x16x32_bf16 v[34:37], v[166:169], v[206:209], v[34:37]
	v_mfma_f32_16x16x32_bf16 v[22:25], v[158:161], v[214:217], v[22:25]
	v_mfma_f32_16x16x32_bf16 v[18:21], v[166:169], v[214:217], v[18:21]
	s_setprio 0
	s_setprio 1
	v_mfma_f32_16x16x32_bf16 v[46:49], v[170:173], v[186:189], 0
	v_mfma_f32_16x16x32_bf16 v[42:45], v[178:181], v[186:189], 0
	v_mfma_f32_16x16x32_bf16 v[30:33], v[170:173], v[194:197], 0
	v_mfma_f32_16x16x32_bf16 v[26:29], v[178:181], v[194:197], 0
	v_mfma_f32_16x16x32_bf16 v[14:17], v[170:173], v[202:205], 0
	v_mfma_f32_16x16x32_bf16 v[10:13], v[178:181], v[202:205], 0
	v_mfma_f32_16x16x32_bf16 v[6:9], v[170:173], v[210:213], 0
	v_mfma_f32_16x16x32_bf16 v[2:5], v[178:181], v[210:213], 0
	v_mfma_f32_16x16x32_bf16 v[46:49], v[174:177], v[190:193], v[46:49]
	v_mfma_f32_16x16x32_bf16 v[42:45], v[182:185], v[190:193], v[42:45]
	v_mfma_f32_16x16x32_bf16 v[30:33], v[174:177], v[198:201], v[30:33]
	v_mfma_f32_16x16x32_bf16 v[26:29], v[182:185], v[198:201], v[26:29]
	v_mfma_f32_16x16x32_bf16 v[14:17], v[174:177], v[206:209], v[14:17]
	v_mfma_f32_16x16x32_bf16 v[10:13], v[182:185], v[206:209], v[10:13]
	v_mfma_f32_16x16x32_bf16 v[6:9], v[174:177], v[214:217], v[6:9]
	v_mfma_f32_16x16x32_bf16 v[2:5], v[182:185], v[214:217], v[2:5]
	s_setprio 0
	s_barrier
; #define PG8_STAGE(bufoff, gbase, voff) do { _Pragma("unroll") for (int _i = 0; _i < 2; ++_i) \
;         __builtin_amdgcn_global_load_lds((const unsigned*)((const char*)(gbase) + (voff)[_i]), (PG8_LAS unsigned*)(lds + (bufoff) + ldsw + _i * 8192), 16, 0, 0); } while (0)
; #define PG8_LDA(dst, b, h) do { _Pragma("unroll") for (int m = 0; m < 4; ++m) _Pragma("unroll") for (int k = 0; k < 2; ++k) dst[m][k] = *(const PG8_LAS bf16x8*)(lds + PG8_SA(b, h) + aoff + m * 2048 + k * 1024); } while (0)
; #define PG8_LDB(dst, b, h) do { _Pragma("unroll") for (int n = 0; n < 2; ++n) _Pragma("unroll") for (int k = 0; k < 2; ++k) dst[n][k] = *(const PG8_LAS bf16x8*)(lds + PG8_SB(b, h) + boff + n * 2048 + k * 1024); } while (0)
; #define PG8_MMA(ai, bj, At, Bt) do { __builtin_amdgcn_s_setprio(1); _Pragma("unroll") for (int m = 0; m < 4; ++m) _Pragma("unroll") for (int n = 0; n < 2; ++n) _Pragma("unroll") for (int k = 0; k < 2; ++k) \
;         acc[ai][bj][m][n] = __builtin_amdgcn_mfma_f32_16x16x32_bf16(Bt[n][k], At[m][k], acc[ai][bj][m][n], 0, 0, 0); __builtin_amdgcn_s_setprio(0); } while (0)
; #define PG8_WAIT_V(n) asm volatile("s_waitcnt vmcnt(" #n ")" ::: "memory")
; #define PG8_WAIT_L(n) asm volatile("s_waitcnt lgkmcnt(" #n ")" ::: "memory")
; #define PG8_BAR __builtin_amdgcn_s_barrier()
; #define PG8_SCHED __builtin_amdgcn_sched_barrier(0)
; template <class Epi, class Sched, bool ALIGN_EPI = false, bool SP2 = false>
; __device__ __forceinline__ void gemm_phase(PG8_LAS unsigned char* lds, const Gemm g, const Sched& S, const Epi& E) {
;     ...
;             PG8_WAIT_V(8); PG8_WAIT_L(0); PG8_BAR; PG8_MMA(1, 0, At, B0); PG8_MMA(1, 1, At, B1); PG8_BAR; PG8_SCHED;
;             PG8_LDB(B0, 1, 0); PG8_LDB(B1, 1, 1); PG8_SCHED; PG8_LDA(At, 1, 0); PG8_STAGE(PG8_SA(0, 1), a2 + hstep, voffA);
;             PG8_WAIT_V(8); PG8_WAIT_L(0); PG8_BAR; PG8_MMA(0, 0, At, B0); PG8_MMA(0, 1, At, B1); PG8_BAR; PG8_SCHED;
;             PG8_LDA(At, 1, 1); PG8_STAGE(PG8_SB(1, 0), b3, voffB); PG8_STAGE(PG8_SB(1, 1), b3 + hstep, voffB); PG8_STAGE(PG8_SA(1, 0), a3, voffA);
	ds_read_b128 v[154:157], v151
	ds_read_b128 v[158:161], v151 offset:1024
	ds_read_b128 v[162:165], v151 offset:2048
	ds_read_b128 v[166:169], v151 offset:3072
	ds_read_b128 v[170:173], v152
	ds_read_b128 v[174:177], v152 offset:1024
	ds_read_b128 v[178:181], v152 offset:2048
	ds_read_b128 v[182:185], v152 offset:3072
	s_add_u32 s22, s38, 0xb0000
	s_addc_u32 s23, s39, 0
	s_mov_b32 m0, s44
	s_nop 0
	global_load_lds_dwordx4 v[222:223], off
	s_mov_b32 m0, s45
	s_nop 0
	global_load_lds_dwordx4 v[224:225], off
	s_mov_b32 m0, s46
	v_lshl_add_u64 v[226:227], s[22:23], 0, v[130:131]
	ds_read_b128 v[186:189], v150 offset:32768
	ds_read_b128 v[190:193], v150 offset:33792
	ds_read_b128 v[194:197], v150 offset:34816
	ds_read_b128 v[198:201], v150 offset:35840
	ds_read_b128 v[202:205], v150 offset:36864
	ds_read_b128 v[206:209], v150 offset:37888
	ds_read_b128 v[210:213], v150 offset:38912
	ds_read_b128 v[214:217], v150 offset:39936
	global_load_lds_dwordx4 v[226:227], off
	v_lshl_add_u64 v[226:227], s[22:23], 0, v[134:135]
	s_mov_b32 m0, s47
	s_nop 0
	global_load_lds_dwordx4 v[226:227], off
	s_waitcnt vmcnt(8)
	s_waitcnt lgkmcnt(0)
	s_barrier
	s_setprio 1
	s_waitcnt lgkmcnt(0)
	v_mfma_f32_16x16x32_bf16 v[126:129], v[154:157], v[186:189], v[126:129]
	v_mfma_f32_16x16x32_bf16 v[122:125], v[162:165], v[186:189], v[122:125]
	v_mfma_f32_16x16x32_bf16 v[118:121], v[154:157], v[194:197], v[118:121]
	v_mfma_f32_16x16x32_bf16 v[114:117], v[162:165], v[194:197], v[114:117]
	v_mfma_f32_16x16x32_bf16 v[102:105], v[154:157], v[202:205], v[102:105]
	v_mfma_f32_16x16x32_bf16 v[98:101], v[162:165], v[202:205], v[98:101]
	v_mfma_f32_16x16x32_bf16 v[86:89], v[154:157], v[210:213], v[86:89]
	v_mfma_f32_16x16x32_bf16 v[82:85], v[162:165], v[210:213], v[82:85]
	v_mfma_f32_16x16x32_bf16 v[126:129], v[158:161], v[190:193], v[126:129]
	v_mfma_f32_16x16x32_bf16 v[122:125], v[166:169], v[190:193], v[122:125]
	v_mfma_f32_16x16x32_bf16 v[118:121], v[158:161], v[198:201], v[118:121]
	v_mfma_f32_16x16x32_bf16 v[114:117], v[166:169], v[198:201], v[114:117]
	v_mfma_f32_16x16x32_bf16 v[102:105], v[158:161], v[206:209], v[102:105]
	v_mfma_f32_16x16x32_bf16 v[98:101], v[166:169], v[206:209], v[98:101]
	v_mfma_f32_16x16x32_bf16 v[86:89], v[158:161], v[214:217], v[86:89]
	v_mfma_f32_16x16x32_bf16 v[82:85], v[166:169], v[214:217], v[82:85]
	s_setprio 0
	s_setprio 1
	v_mfma_f32_16x16x32_bf16 v[110:113], v[170:173], v[186:189], v[110:113]
	v_mfma_f32_16x16x32_bf16 v[106:109], v[178:181], v[186:189], v[106:109]
	v_mfma_f32_16x16x32_bf16 v[94:97], v[170:173], v[194:197], v[94:97]
	v_mfma_f32_16x16x32_bf16 v[90:93], v[178:181], v[194:197], v[90:93]
	v_mfma_f32_16x16x32_bf16 v[78:81], v[170:173], v[202:205], v[78:81]
	v_mfma_f32_16x16x32_bf16 v[74:77], v[178:181], v[202:205], v[74:77]
	v_mfma_f32_16x16x32_bf16 v[70:73], v[170:173], v[210:213], v[70:73]
	v_mfma_f32_16x16x32_bf16 v[66:69], v[178:181], v[210:213], v[66:69]
	v_mfma_f32_16x16x32_bf16 v[110:113], v[174:177], v[190:193], v[110:113]
	v_mfma_f32_16x16x32_bf16 v[106:109], v[182:185], v[190:193], v[106:109]
	v_mfma_f32_16x16x32_bf16 v[94:97], v[174:177], v[198:201], v[94:97]
	v_mfma_f32_16x16x32_bf16 v[90:93], v[182:185], v[198:201], v[90:93]
	v_mfma_f32_16x16x32_bf16 v[78:81], v[174:177], v[206:209], v[78:81]
	v_mfma_f32_16x16x32_bf16 v[74:77], v[182:185], v[206:209], v[74:77]
	v_mfma_f32_16x16x32_bf16 v[70:73], v[174:177], v[214:217], v[70:73]
	v_mfma_f32_16x16x32_bf16 v[66:69], v[182:185], v[214:217], v[66:69]
	s_setprio 0
	s_barrier
	s_mov_b32 m0, s49
	v_lshl_add_u64 v[218:219], v[218:219], 0, s[8:9]
	s_add_u32 s22, s36, 0xb0080
	ds_read_b128 v[186:189], v150 offset:49152
	ds_read_b128 v[190:193], v150 offset:50176
	ds_read_b128 v[194:197], v150 offset:51200
	ds_read_b128 v[198:201], v150 offset:52224
	ds_read_b128 v[202:205], v150 offset:53248
	ds_read_b128 v[206:209], v150 offset:54272
	ds_read_b128 v[210:213], v150 offset:55296
	ds_read_b128 v[214:217], v150 offset:56320
	global_load_lds_dwordx4 v[218:219], off
	v_lshl_add_u64 v[218:219], v[220:221], 0, s[8:9]
	s_mov_b32 m0, s50
	s_addc_u32 s23, s37, 0
	global_load_lds_dwordx4 v[218:219], off
	v_lshl_add_u64 v[218:219], s[22:23], 0, v[132:133]
	s_mov_b32 m0, s53
	s_nop 0
	global_load_lds_dwordx4 v[218:219], off
	v_lshl_add_u64 v[218:219], s[22:23], 0, v[136:137]
	s_mov_b32 m0, s54
	s_nop 0
	global_load_lds_dwordx4 v[218:219], off
	v_lshl_add_u64 v[218:219], v[222:223], 0, s[8:9]
	s_mov_b32 m0, s51
	s_nop 0
	global_load_lds_dwordx4 v[218:219], off
	v_lshl_add_u64 v[218:219], v[224:225], 0, s[8:9]
	s_mov_b32 m0, s52
	s_nop 0
	global_load_lds_dwordx4 v[218:219], off
	s_waitcnt vmcnt(8)
	s_waitcnt lgkmcnt(0)
	s_barrier
; #define PG8_STAGE(bufoff, gbase, voff) do { _Pragma("unroll") for (int _i = 0; _i < 2; ++_i) \
;         __builtin_amdgcn_global_load_lds((const unsigned*)((const char*)(gbase) + (voff)[_i]), (PG8_LAS unsigned*)(lds + (bufoff) + ldsw + _i * 8192), 16, 0, 0); } while (0)
; #define PG8_LDA(dst, b, h) do { _Pragma("unroll") for (int m = 0; m < 4; ++m) _Pragma("unroll") for (int k = 0; k < 2; ++k) dst[m][k] = *(const PG8_LAS bf16x8*)(lds + PG8_SA(b, h) + aoff + m * 2048 + k * 1024); } while (0)
; #define PG8_LDB(dst, b, h) do { _Pragma("unroll") for (int n = 0; n < 2; ++n) _Pragma("unroll") for (int k = 0; k < 2; ++k) dst[n][k] = *(const PG8_LAS bf16x8*)(lds + PG8_SB(b, h) + boff + n * 2048 + k * 1024); } while (0)
; #define PG8_MMA(ai, bj, At, Bt) do { __builtin_amdgcn_s_setprio(1); _Pragma("unroll") for (int m = 0; m < 4; ++m) _Pragma("unroll") for (int n = 0; n < 2; ++n) _Pragma("unroll") for (int k = 0; k < 2; ++k) \
;         acc[ai][bj][m][n] = __builtin_amdgcn_mfma_f32_16x16x32_bf16(Bt[n][k], At[m][k], acc[ai][bj][m][n], 0, 0, 0); __builtin_amdgcn_s_setprio(0); } while (0)
; #define PG8_WAIT_V(n) asm volatile("s_waitcnt vmcnt(" #n ")" ::: "memory")
; #define PG8_WAIT_L(n) asm volatile("s_waitcnt lgkmcnt(" #n ")" ::: "memory")
; #define PG8_BAR __builtin_amdgcn_s_barrier()
; #define PG8_SCHED __builtin_amdgcn_sched_barrier(0)
; template <class Epi, class Sched, bool ALIGN_EPI = false, bool SP2 = false>
; __device__ __forceinline__ void gemm_phase(PG8_LAS unsigned char* lds, const Gemm g, const Sched& S, const Epi& E) {
;     ...
;             PG8_LDB(B0, 0, 0); PG8_LDB(B1, 0, 1); PG8_SCHED; PG8_LDA(At, 0, 0); PG8_STAGE(PG8_SA(1, 1), a1 + hstep, voffA);
;             PG8_WAIT_V(8); PG8_WAIT_L(0); PG8_BAR; PG8_MMA(0, 0, At, B0); PG8_MMA(0, 1, At, B1); PG8_BAR; PG8_SCHED;
;             PG8_LDA(At, 0, 1); PG8_STAGE(PG8_SB(0, 0), b2, voffB); PG8_STAGE(PG8_SB(0, 1), b2 + hstep, voffB); PG8_STAGE(PG8_SA(0, 0), a2, voffA);
;             PG8_WAIT_V(8); PG8_WAIT_L(0); PG8_BAR; PG8_MMA(1, 0, At, B0); PG8_MMA(1, 1, At, B1); PG8_BAR; PG8_SCHED;
;             PG8_LDB(B0, 1, 0); PG8_LDB(B1, 1, 1); PG8_SCHED; PG8_LDA(At, 1, 0); PG8_STAGE(PG8_SA(0, 1), a2 + hstep, voffA);
;             PG8_WAIT_V(8); PG8_WAIT_L(0); PG8_BAR; PG8_MMA(0, 0, At, B0); PG8_MMA(0, 1, At, B1); PG8_BAR; PG8_SCHED;
	s_setprio 1
	s_waitcnt lgkmcnt(0)
	v_mfma_f32_16x16x32_bf16 v[62:65], v[154:157], v[186:189], v[62:65]
	v_mfma_f32_16x16x32_bf16 v[58:61], v[162:165], v[186:189], v[58:61]
	v_mfma_f32_16x16x32_bf16 v[54:57], v[154:157], v[194:197], v[54:57]
	v_mfma_f32_16x16x32_bf16 v[50:53], v[162:165], v[194:197], v[50:53]
	v_mfma_f32_16x16x32_bf16 v[38:41], v[154:157], v[202:205], v[38:41]
	v_mfma_f32_16x16x32_bf16 v[34:37], v[162:165], v[202:205], v[34:37]
	v_mfma_f32_16x16x32_bf16 v[22:25], v[154:157], v[210:213], v[22:25]
	v_mfma_f32_16x16x32_bf16 v[18:21], v[162:165], v[210:213], v[18:21]
	v_mfma_f32_16x16x32_bf16 v[62:65], v[158:161], v[190:193], v[62:65]
	v_mfma_f32_16x16x32_bf16 v[58:61], v[166:169], v[190:193], v[58:61]
	v_mfma_f32_16x16x32_bf16 v[54:57], v[158:161], v[198:201], v[54:57]
	v_mfma_f32_16x16x32_bf16 v[50:53], v[166:169], v[198:201], v[50:53]
	v_mfma_f32_16x16x32_bf16 v[38:41], v[158:161], v[206:209], v[38:41]
	v_mfma_f32_16x16x32_bf16 v[34:37], v[166:169], v[206:209], v[34:37]
	v_mfma_f32_16x16x32_bf16 v[22:25], v[158:161], v[214:217], v[22:25]
	v_mfma_f32_16x16x32_bf16 v[18:21], v[166:169], v[214:217], v[18:21]
	s_setprio 0
	s_setprio 1
	v_mfma_f32_16x16x32_bf16 v[46:49], v[170:173], v[186:189], v[46:49]
	v_mfma_f32_16x16x32_bf16 v[42:45], v[178:181], v[186:189], v[42:45]
	v_mfma_f32_16x16x32_bf16 v[30:33], v[170:173], v[194:197], v[30:33]
	v_mfma_f32_16x16x32_bf16 v[26:29], v[178:181], v[194:197], v[26:29]
	v_mfma_f32_16x16x32_bf16 v[14:17], v[170:173], v[202:205], v[14:17]
	v_mfma_f32_16x16x32_bf16 v[10:13], v[178:181], v[202:205], v[10:13]
	v_mfma_f32_16x16x32_bf16 v[6:9], v[170:173], v[210:213], v[6:9]
	v_mfma_f32_16x16x32_bf16 v[2:5], v[178:181], v[210:213], v[2:5]
	v_mfma_f32_16x16x32_bf16 v[46:49], v[174:177], v[190:193], v[46:49]
	v_mfma_f32_16x16x32_bf16 v[42:45], v[182:185], v[190:193], v[42:45]
	v_mfma_f32_16x16x32_bf16 v[30:33], v[174:177], v[198:201], v[30:33]
	v_mfma_f32_16x16x32_bf16 v[26:29], v[182:185], v[198:201], v[26:29]
	v_mfma_f32_16x16x32_bf16 v[14:17], v[174:177], v[206:209], v[14:17]
	v_mfma_f32_16x16x32_bf16 v[10:13], v[182:185], v[206:209], v[10:13]
	v_mfma_f32_16x16x32_bf16 v[6:9], v[174:177], v[214:217], v[6:9]
	v_mfma_f32_16x16x32_bf16 v[2:5], v[182:185], v[214:217], v[2:5]
	s_setprio 0
	s_barrier
	s_add_i32 s66, s66, 2
	s_add_u32 s64, s64, 0x100
	s_addc_u32 s65, s65, 0
	s_cmp_gt_u32 s66, 41
	s_mov_b64 s[22:23], s[24:25]
.LBB0_2367:
	ds_read_b128 v[154:157], v148
	ds_read_b128 v[158:161], v148 offset:1024
	ds_read_b128 v[162:165], v148 offset:2048
	ds_read_b128 v[166:169], v148 offset:3072
	ds_read_b128 v[170:173], v149
	ds_read_b128 v[174:177], v149 offset:1024
	ds_read_b128 v[178:181], v149 offset:2048
	ds_read_b128 v[182:185], v149 offset:3072
	s_add_u32 s24, s22, 0x100
	s_addc_u32 s25, s23, 0
	s_cmp_eq_u32 s66, 40
	s_cselect_b32 s39, s5, s25
	s_cselect_b32 s38, s4, s24
	s_cselect_b32 s37, s21, s65
	s_cselect_b32 s36, s20, s64
	v_lshl_add_u64 v[218:219], s[22:23], 0, v[140:141]
	s_add_i32 m0, s44, 0xc000
	ds_read_b128 v[186:189], v150
	ds_read_b128 v[190:193], v150 offset:1024
	ds_read_b128 v[194:197], v150 offset:2048
	ds_read_b128 v[198:201], v150 offset:3072
	ds_read_b128 v[202:205], v150 offset:4096
	ds_read_b128 v[206:209], v150 offset:5120
	ds_read_b128 v[210:213], v150 offset:6144
	ds_read_b128 v[214:217], v150 offset:7168
	global_load_lds_dwordx4 v[218:219], off
	v_lshl_add_u64 v[218:219], s[22:23], 0, v[138:139]
	s_add_i32 m0, s44, 0xe000
	s_nop 0
	global_load_lds_dwordx4 v[218:219], off
	s_waitcnt vmcnt(8)
	s_waitcnt lgkmcnt(0)
	s_barrier
	s_setprio 1
	s_waitcnt lgkmcnt(0)
	v_mfma_f32_16x16x32_bf16 v[126:129], v[154:157], v[186:189], v[126:129]
	v_mfma_f32_16x16x32_bf16 v[122:125], v[162:165], v[186:189], v[122:125]
	v_mfma_f32_16x16x32_bf16 v[118:121], v[154:157], v[194:197], v[118:121]
	v_mfma_f32_16x16x32_bf16 v[114:117], v[162:165], v[194:197], v[114:117]
	v_mfma_f32_16x16x32_bf16 v[102:105], v[154:157], v[202:205], v[102:105]
	v_mfma_f32_16x16x32_bf16 v[98:101], v[162:165], v[202:205], v[98:101]
	v_mfma_f32_16x16x32_bf16 v[86:89], v[154:157], v[210:213], v[86:89]
	v_mfma_f32_16x16x32_bf16 v[82:85], v[162:165], v[210:213], v[82:85]
	v_mfma_f32_16x16x32_bf16 v[126:129], v[158:161], v[190:193], v[126:129]
	v_mfma_f32_16x16x32_bf16 v[122:125], v[166:169], v[190:193], v[122:125]
	v_mfma_f32_16x16x32_bf16 v[118:121], v[158:161], v[198:201], v[118:121]
	v_mfma_f32_16x16x32_bf16 v[114:117], v[166:169], v[198:201], v[114:117]
	v_mfma_f32_16x16x32_bf16 v[102:105], v[158:161], v[206:209], v[102:105]
	v_mfma_f32_16x16x32_bf16 v[98:101], v[166:169], v[206:209], v[98:101]
	v_mfma_f32_16x16x32_bf16 v[86:89], v[158:161], v[214:217], v[86:89]
	v_mfma_f32_16x16x32_bf16 v[82:85], v[166:169], v[214:217], v[82:85]
	s_setprio 0
	s_setprio 1
	v_mfma_f32_16x16x32_bf16 v[110:113], v[170:173], v[186:189], v[110:113]
	v_mfma_f32_16x16x32_bf16 v[106:109], v[178:181], v[186:189], v[106:109]
	v_mfma_f32_16x16x32_bf16 v[94:97], v[170:173], v[194:197], v[94:97]
	v_mfma_f32_16x16x32_bf16 v[90:93], v[178:181], v[194:197], v[90:93]
	v_mfma_f32_16x16x32_bf16 v[78:81], v[170:173], v[202:205], v[78:81]
	v_mfma_f32_16x16x32_bf16 v[74:77], v[178:181], v[202:205], v[74:77]
	v_mfma_f32_16x16x32_bf16 v[70:73], v[170:173], v[210:213], v[70:73]
	v_mfma_f32_16x16x32_bf16 v[66:69], v[178:181], v[210:213], v[66:69]
	v_mfma_f32_16x16x32_bf16 v[110:113], v[174:177], v[190:193], v[110:113]
	v_mfma_f32_16x16x32_bf16 v[106:109], v[182:185], v[190:193], v[106:109]
	v_mfma_f32_16x16x32_bf16 v[94:97], v[174:177], v[198:201], v[94:97]
	v_mfma_f32_16x16x32_bf16 v[90:93], v[182:185], v[198:201], v[90:93]
	v_mfma_f32_16x16x32_bf16 v[78:81], v[174:177], v[206:209], v[78:81]
	v_mfma_f32_16x16x32_bf16 v[74:77], v[182:185], v[206:209], v[74:77]
	v_mfma_f32_16x16x32_bf16 v[70:73], v[174:177], v[214:217], v[70:73]
	v_mfma_f32_16x16x32_bf16 v[66:69], v[182:185], v[214:217], v[66:69]
	s_setprio 0
	s_barrier
; #define PG8_STAGE(bufoff, gbase, voff) do { _Pragma("unroll") for (int _i = 0; _i < 2; ++_i) \
;         __builtin_amdgcn_global_load_lds((const unsigned*)((const char*)(gbase) + (voff)[_i]), (PG8_LAS unsigned*)(lds + (bufoff) + ldsw + _i * 8192), 16, 0, 0); } while (0)
; #define PG8_LDA(dst, b, h) do { _Pragma("unroll") for (int m = 0; m < 4; ++m) _Pragma("unroll") for (int k = 0; k < 2; ++k) dst[m][k] = *(const PG8_LAS bf16x8*)(lds + PG8_SA(b, h) + aoff + m * 2048 + k * 1024); } while (0)
; #define PG8_LDB(dst, b, h) do { _Pragma("unroll") for (int n = 0; n < 2; ++n) _Pragma("unroll") for (int k = 0; k < 2; ++k) dst[n][k] = *(const PG8_LAS bf16x8*)(lds + PG8_SB(b, h) + boff + n * 2048 + k * 1024); } while (0)
; #define PG8_MMA(ai, bj, At, Bt) do { __builtin_amdgcn_s_setprio(1); _Pragma("unroll") for (int m = 0; m < 4; ++m) _Pragma("unroll") for (int n = 0; n < 2; ++n) _Pragma("unroll") for (int k = 0; k < 2; ++k) \
;         acc[ai][bj][m][n] = __builtin_amdgcn_mfma_f32_16x16x32_bf16(Bt[n][k], At[m][k], acc[ai][bj][m][n], 0, 0, 0); __builtin_amdgcn_s_setprio(0); } while (0)
; #define PG8_WAIT_V(n) asm volatile("s_waitcnt vmcnt(" #n ")" ::: "memory")
; #define PG8_WAIT_L(n) asm volatile("s_waitcnt lgkmcnt(" #n ")" ::: "memory")
; #define PG8_BAR __builtin_amdgcn_s_barrier()
; #define PG8_SCHED __builtin_amdgcn_sched_barrier(0)
; template <class Epi, class Sched, bool ALIGN_EPI = false, bool SP2 = false>
; __device__ __forceinline__ void gemm_phase(PG8_LAS unsigned char* lds, const Gemm g, const Sched& S, const Epi& E) {
;     ...
;             PG8_LDA(At, 0, 1); PG8_STAGE(PG8_SB(0, 0), b2, voffB); PG8_STAGE(PG8_SB(0, 1), b2 + hstep, voffB); PG8_STAGE(PG8_SA(0, 0), a2, voffA);
;             PG8_WAIT_V(8); PG8_WAIT_L(0); PG8_BAR; PG8_MMA(1, 0, At, B0); PG8_MMA(1, 1, At, B1); PG8_BAR; PG8_SCHED;
;             PG8_LDB(B0, 1, 0); PG8_LDB(B1, 1, 1); PG8_SCHED; PG8_LDA(At, 1, 0); PG8_STAGE(PG8_SA(0, 1), a2 + hstep, voffA);
	s_mov_b32 m0, s40
	v_lshl_add_u64 v[218:219], s[36:37], 0, v[132:133]
	s_add_u32 s22, s36, 0xb0000
	ds_read_b128 v[186:189], v150 offset:16384
	ds_read_b128 v[190:193], v150 offset:17408
	ds_read_b128 v[194:197], v150 offset:18432
	ds_read_b128 v[198:201], v150 offset:19456
	ds_read_b128 v[202:205], v150 offset:20480
	ds_read_b128 v[206:209], v150 offset:21504
	ds_read_b128 v[210:213], v150 offset:22528
	ds_read_b128 v[214:217], v150 offset:23552
	global_load_lds_dwordx4 v[218:219], off
	v_lshl_add_u64 v[220:221], s[36:37], 0, v[136:137]
	s_mov_b32 m0, s41
	s_addc_u32 s23, s37, 0
	global_load_lds_dwordx4 v[220:221], off
	v_lshl_add_u64 v[222:223], s[22:23], 0, v[132:133]
	s_mov_b32 m0, s42
	v_lshl_add_u64 v[224:225], s[38:39], 0, v[134:135]
	global_load_lds_dwordx4 v[222:223], off
	v_lshl_add_u64 v[222:223], s[22:23], 0, v[136:137]
	s_mov_b32 m0, s43
	s_nop 0
	global_load_lds_dwordx4 v[222:223], off
	v_lshl_add_u64 v[222:223], s[38:39], 0, v[130:131]
	s_waitcnt vmcnt(6)
	s_waitcnt lgkmcnt(0)
	s_barrier
	s_setprio 1
	s_waitcnt lgkmcnt(0)
	v_mfma_f32_16x16x32_bf16 v[62:65], v[154:157], v[186:189], v[62:65]
	v_mfma_f32_16x16x32_bf16 v[58:61], v[162:165], v[186:189], v[58:61]
	v_mfma_f32_16x16x32_bf16 v[54:57], v[154:157], v[194:197], v[54:57]
	v_mfma_f32_16x16x32_bf16 v[50:53], v[162:165], v[194:197], v[50:53]
	v_mfma_f32_16x16x32_bf16 v[38:41], v[154:157], v[202:205], v[38:41]
	v_mfma_f32_16x16x32_bf16 v[34:37], v[162:165], v[202:205], v[34:37]
	v_mfma_f32_16x16x32_bf16 v[22:25], v[154:157], v[210:213], v[22:25]
	v_mfma_f32_16x16x32_bf16 v[18:21], v[162:165], v[210:213], v[18:21]
	v_mfma_f32_16x16x32_bf16 v[62:65], v[158:161], v[190:193], v[62:65]
	v_mfma_f32_16x16x32_bf16 v[58:61], v[166:169], v[190:193], v[58:61]
	v_mfma_f32_16x16x32_bf16 v[54:57], v[158:161], v[198:201], v[54:57]
	v_mfma_f32_16x16x32_bf16 v[50:53], v[166:169], v[198:201], v[50:53]
	v_mfma_f32_16x16x32_bf16 v[38:41], v[158:161], v[206:209], v[38:41]
	v_mfma_f32_16x16x32_bf16 v[34:37], v[166:169], v[206:209], v[34:37]
	v_mfma_f32_16x16x32_bf16 v[22:25], v[158:161], v[214:217], v[22:25]
	v_mfma_f32_16x16x32_bf16 v[18:21], v[166:169], v[214:217], v[18:21]
	s_setprio 0
	s_setprio 1
	v_mfma_f32_16x16x32_bf16 v[46:49], v[170:173], v[186:189], v[46:49]
	v_mfma_f32_16x16x32_bf16 v[42:45], v[178:181], v[186:189], v[42:45]
	v_mfma_f32_16x16x32_bf16 v[30:33], v[170:173], v[194:197], v[30:33]
	v_mfma_f32_16x16x32_bf16 v[26:29], v[178:181], v[194:197], v[26:29]
	v_mfma_f32_16x16x32_bf16 v[14:17], v[170:173], v[202:205], v[14:17]
	v_mfma_f32_16x16x32_bf16 v[10:13], v[178:181], v[202:205], v[10:13]
	v_mfma_f32_16x16x32_bf16 v[6:9], v[170:173], v[210:213], v[6:9]
	v_mfma_f32_16x16x32_bf16 v[2:5], v[178:181], v[210:213], v[2:5]
	v_mfma_f32_16x16x32_bf16 v[46:49], v[174:177], v[190:193], v[46:49]
	v_mfma_f32_16x16x32_bf16 v[42:45], v[182:185], v[190:193], v[42:45]
	v_mfma_f32_16x16x32_bf16 v[30:33], v[174:177], v[198:201], v[30:33]
	v_mfma_f32_16x16x32_bf16 v[26:29], v[182:185], v[198:201], v[26:29]
	v_mfma_f32_16x16x32_bf16 v[14:17], v[174:177], v[206:209], v[14:17]
	v_mfma_f32_16x16x32_bf16 v[10:13], v[182:185], v[206:209], v[10:13]
	v_mfma_f32_16x16x32_bf16 v[6:9], v[174:177], v[214:217], v[6:9]
	v_mfma_f32_16x16x32_bf16 v[2:5], v[182:185], v[214:217], v[2:5]
	s_setprio 0
	s_barrier
	ds_read_b128 v[154:157], v151
	ds_read_b128 v[158:161], v151 offset:1024
	ds_read_b128 v[162:165], v151 offset:2048
	ds_read_b128 v[166:169], v151 offset:3072
	ds_read_b128 v[170:173], v152
	ds_read_b128 v[174:177], v152 offset:1024
	ds_read_b128 v[178:181], v152 offset:2048
	ds_read_b128 v[182:185], v152 offset:3072
	s_add_u32 s22, s38, 0xb0000
	s_addc_u32 s23, s39, 0
	s_mov_b32 m0, s44
	s_nop 0
	global_load_lds_dwordx4 v[222:223], off
	s_mov_b32 m0, s45
	s_nop 0
	global_load_lds_dwordx4 v[224:225], off
	s_mov_b32 m0, s46
	v_lshl_add_u64 v[226:227], s[22:23], 0, v[130:131]
	ds_read_b128 v[186:189], v150 offset:32768
	ds_read_b128 v[190:193], v150 offset:33792
	ds_read_b128 v[194:197], v150 offset:34816
	ds_read_b128 v[198:201], v150 offset:35840
	ds_read_b128 v[202:205], v150 offset:36864
	ds_read_b128 v[206:209], v150 offset:37888
	ds_read_b128 v[210:213], v150 offset:38912
	ds_read_b128 v[214:217], v150 offset:39936
	global_load_lds_dwordx4 v[226:227], off
	v_lshl_add_u64 v[226:227], s[22:23], 0, v[134:135]
	s_mov_b32 m0, s47
	s_nop 0
	global_load_lds_dwordx4 v[226:227], off
	s_waitcnt vmcnt(8)
	s_waitcnt lgkmcnt(0)
	s_barrier
; #define PG8_STAGE(bufoff, gbase, voff) do { _Pragma("unroll") for (int _i = 0; _i < 2; ++_i) \
;         __builtin_amdgcn_global_load_lds((const unsigned*)((const char*)(gbase) + (voff)[_i]), (PG8_LAS unsigned*)(lds + (bufoff) + ldsw + _i * 8192), 16, 0, 0); } while (0)
; #define PG8_LDA(dst, b, h) do { _Pragma("unroll") for (int m = 0; m < 4; ++m) _Pragma("unroll") for (int k = 0; k < 2; ++k) dst[m][k] = *(const PG8_LAS bf16x8*)(lds + PG8_SA(b, h) + aoff + m * 2048 + k * 1024); } while (0)
; #define PG8_LDB(dst, b, h) do { _Pragma("unroll") for (int n = 0; n < 2; ++n) _Pragma("unroll") for (int k = 0; k < 2; ++k) dst[n][k] = *(const PG8_LAS bf16x8*)(lds + PG8_SB(b, h) + boff + n * 2048 + k * 1024); } while (0)
; #define PG8_MMA(ai, bj, At, Bt) do { __builtin_amdgcn_s_setprio(1); _Pragma("unroll") for (int m = 0; m < 4; ++m) _Pragma("unroll") for (int n = 0; n < 2; ++n) _Pragma("unroll") for (int k = 0; k < 2; ++k) \
;         acc[ai][bj][m][n] = __builtin_amdgcn_mfma_f32_16x16x32_bf16(Bt[n][k], At[m][k], acc[ai][bj][m][n], 0, 0, 0); __builtin_amdgcn_s_setprio(0); } while (0)
; #define PG8_WAIT_V(n) asm volatile("s_waitcnt vmcnt(" #n ")" ::: "memory")
; #define PG8_WAIT_L(n) asm volatile("s_waitcnt lgkmcnt(" #n ")" ::: "memory")
; #define PG8_BAR __builtin_amdgcn_s_barrier()
; #define PG8_SCHED __builtin_amdgcn_sched_barrier(0)
; template <class Epi, class Sched, bool ALIGN_EPI = false, bool SP2 = false>
; __device__ __forceinline__ void gemm_phase(PG8_LAS unsigned char* lds, const Gemm g, const Sched& S, const Epi& E) {
;     ...
;             PG8_LDB(B0, 1, 0); PG8_LDB(B1, 1, 1); PG8_SCHED; PG8_LDA(At, 1, 0); PG8_STAGE(PG8_SA(0, 1), a2 + hstep, voffA);
;             PG8_WAIT_V(8); PG8_WAIT_L(0); PG8_BAR; PG8_MMA(0, 0, At, B0); PG8_MMA(0, 1, At, B1); PG8_BAR; PG8_SCHED;
;             PG8_LDA(At, 1, 1); PG8_STAGE(PG8_SB(1, 0), b3, voffB); PG8_STAGE(PG8_SB(1, 1), b3 + hstep, voffB); PG8_STAGE(PG8_SA(1, 0), a3, voffA);
;             PG8_WAIT_V(8); PG8_WAIT_L(0); PG8_BAR; PG8_MMA(1, 0, At, B0); PG8_MMA(1, 1, At, B1); PG8_BAR; PG8_SCHED;
	s_setprio 1
	s_waitcnt lgkmcnt(0)
	v_mfma_f32_16x16x32_bf16 v[126:129], v[154:157], v[186:189], v[126:129]
	v_mfma_f32_16x16x32_bf16 v[122:125], v[162:165], v[186:189], v[122:125]
	v_mfma_f32_16x16x32_bf16 v[118:121], v[154:157], v[194:197], v[118:121]
	v_mfma_f32_16x16x32_bf16 v[114:117], v[162:165], v[194:197], v[114:117]
	v_mfma_f32_16x16x32_bf16 v[102:105], v[154:157], v[202:205], v[102:105]
	v_mfma_f32_16x16x32_bf16 v[98:101], v[162:165], v[202:205], v[98:101]
	v_mfma_f32_16x16x32_bf16 v[86:89], v[154:157], v[210:213], v[86:89]
	v_mfma_f32_16x16x32_bf16 v[82:85], v[162:165], v[210:213], v[82:85]
	v_mfma_f32_16x16x32_bf16 v[126:129], v[158:161], v[190:193], v[126:129]
	v_mfma_f32_16x16x32_bf16 v[122:125], v[166:169], v[190:193], v[122:125]
	v_mfma_f32_16x16x32_bf16 v[118:121], v[158:161], v[198:201], v[118:121]
	v_mfma_f32_16x16x32_bf16 v[114:117], v[166:169], v[198:201], v[114:117]
	v_mfma_f32_16x16x32_bf16 v[102:105], v[158:161], v[206:209], v[102:105]
	v_mfma_f32_16x16x32_bf16 v[98:101], v[166:169], v[206:209], v[98:101]
	v_mfma_f32_16x16x32_bf16 v[86:89], v[158:161], v[214:217], v[86:89]
	v_mfma_f32_16x16x32_bf16 v[82:85], v[166:169], v[214:217], v[82:85]
	s_setprio 0
	s_setprio 1
	v_mfma_f32_16x16x32_bf16 v[110:113], v[170:173], v[186:189], v[110:113]
	v_mfma_f32_16x16x32_bf16 v[106:109], v[178:181], v[186:189], v[106:109]
	v_mfma_f32_16x16x32_bf16 v[94:97], v[170:173], v[194:197], v[94:97]
	v_mfma_f32_16x16x32_bf16 v[90:93], v[178:181], v[194:197], v[90:93]
	v_mfma_f32_16x16x32_bf16 v[78:81], v[170:173], v[202:205], v[78:81]
	v_mfma_f32_16x16x32_bf16 v[74:77], v[178:181], v[202:205], v[74:77]
	v_mfma_f32_16x16x32_bf16 v[70:73], v[170:173], v[210:213], v[70:73]
	v_mfma_f32_16x16x32_bf16 v[66:69], v[178:181], v[210:213], v[66:69]
	v_mfma_f32_16x16x32_bf16 v[110:113], v[174:177], v[190:193], v[110:113]
	v_mfma_f32_16x16x32_bf16 v[106:109], v[182:185], v[190:193], v[106:109]
	v_mfma_f32_16x16x32_bf16 v[94:97], v[174:177], v[198:201], v[94:97]
	v_mfma_f32_16x16x32_bf16 v[90:93], v[182:185], v[198:201], v[90:93]
	v_mfma_f32_16x16x32_bf16 v[78:81], v[174:177], v[206:209], v[78:81]
	v_mfma_f32_16x16x32_bf16 v[74:77], v[182:185], v[206:209], v[74:77]
	v_mfma_f32_16x16x32_bf16 v[70:73], v[174:177], v[214:217], v[70:73]
	v_mfma_f32_16x16x32_bf16 v[66:69], v[182:185], v[214:217], v[66:69]
	s_setprio 0
	s_barrier
	s_mov_b32 m0, s49
	v_lshl_add_u64 v[218:219], v[218:219], 0, s[8:9]
	s_add_u32 s22, s36, 0xb0080
	ds_read_b128 v[186:189], v150 offset:49152
	ds_read_b128 v[190:193], v150 offset:50176
	ds_read_b128 v[194:197], v150 offset:51200
	ds_read_b128 v[198:201], v150 offset:52224
	ds_read_b128 v[202:205], v150 offset:53248
	ds_read_b128 v[206:209], v150 offset:54272
	ds_read_b128 v[210:213], v150 offset:55296
	ds_read_b128 v[214:217], v150 offset:56320
	global_load_lds_dwordx4 v[218:219], off
	v_lshl_add_u64 v[218:219], v[220:221], 0, s[8:9]
	s_mov_b32 m0, s50
	s_addc_u32 s23, s37, 0
	global_load_lds_dwordx4 v[218:219], off
	v_lshl_add_u64 v[218:219], s[22:23], 0, v[132:133]
	s_mov_b32 m0, s53
	s_nop 0
	global_load_lds_dwordx4 v[218:219], off
	v_lshl_add_u64 v[218:219], s[22:23], 0, v[136:137]
	s_mov_b32 m0, s54
	s_nop 0
	global_load_lds_dwordx4 v[218:219], off
	v_lshl_add_u64 v[218:219], v[222:223], 0, s[8:9]
	s_mov_b32 m0, s51
	s_nop 0
	global_load_lds_dwordx4 v[218:219], off
	v_lshl_add_u64 v[218:219], v[224:225], 0, s[8:9]
	s_mov_b32 m0, s52
	s_nop 0
	global_load_lds_dwordx4 v[218:219], off
	s_waitcnt vmcnt(8)
	s_waitcnt lgkmcnt(0)
	s_barrier
	s_setprio 1
	s_waitcnt lgkmcnt(0)
	v_mfma_f32_16x16x32_bf16 v[62:65], v[154:157], v[186:189], v[62:65]
	v_mfma_f32_16x16x32_bf16 v[58:61], v[162:165], v[186:189], v[58:61]
	v_mfma_f32_16x16x32_bf16 v[54:57], v[154:157], v[194:197], v[54:57]
	v_mfma_f32_16x16x32_bf16 v[50:53], v[162:165], v[194:197], v[50:53]
	v_mfma_f32_16x16x32_bf16 v[38:41], v[154:157], v[202:205], v[38:41]
	v_mfma_f32_16x16x32_bf16 v[34:37], v[162:165], v[202:205], v[34:37]
	v_mfma_f32_16x16x32_bf16 v[22:25], v[154:157], v[210:213], v[22:25]
	v_mfma_f32_16x16x32_bf16 v[18:21], v[162:165], v[210:213], v[18:21]
	v_mfma_f32_16x16x32_bf16 v[62:65], v[158:161], v[190:193], v[62:65]
	v_mfma_f32_16x16x32_bf16 v[58:61], v[166:169], v[190:193], v[58:61]
	v_mfma_f32_16x16x32_bf16 v[54:57], v[158:161], v[198:201], v[54:57]
	v_mfma_f32_16x16x32_bf16 v[50:53], v[166:169], v[198:201], v[50:53]
	v_mfma_f32_16x16x32_bf16 v[38:41], v[158:161], v[206:209], v[38:41]
	v_mfma_f32_16x16x32_bf16 v[34:37], v[166:169], v[206:209], v[34:37]
	v_mfma_f32_16x16x32_bf16 v[22:25], v[158:161], v[214:217], v[22:25]
	v_mfma_f32_16x16x32_bf16 v[18:21], v[166:169], v[214:217], v[18:21]
	s_setprio 0
	s_setprio 1
	v_mfma_f32_16x16x32_bf16 v[46:49], v[170:173], v[186:189], v[46:49]
	v_mfma_f32_16x16x32_bf16 v[42:45], v[178:181], v[186:189], v[42:45]
	v_mfma_f32_16x16x32_bf16 v[30:33], v[170:173], v[194:197], v[30:33]
	v_mfma_f32_16x16x32_bf16 v[26:29], v[178:181], v[194:197], v[26:29]
	v_mfma_f32_16x16x32_bf16 v[14:17], v[170:173], v[202:205], v[14:17]
	v_mfma_f32_16x16x32_bf16 v[10:13], v[178:181], v[202:205], v[10:13]
	v_mfma_f32_16x16x32_bf16 v[6:9], v[170:173], v[210:213], v[6:9]
	v_mfma_f32_16x16x32_bf16 v[2:5], v[178:181], v[210:213], v[2:5]
	v_mfma_f32_16x16x32_bf16 v[46:49], v[174:177], v[190:193], v[46:49]
	v_mfma_f32_16x16x32_bf16 v[42:45], v[182:185], v[190:193], v[42:45]
	v_mfma_f32_16x16x32_bf16 v[30:33], v[174:177], v[198:201], v[30:33]
	v_mfma_f32_16x16x32_bf16 v[26:29], v[182:185], v[198:201], v[26:29]
	v_mfma_f32_16x16x32_bf16 v[14:17], v[174:177], v[206:209], v[14:17]
	v_mfma_f32_16x16x32_bf16 v[10:13], v[182:185], v[206:209], v[10:13]
	v_mfma_f32_16x16x32_bf16 v[6:9], v[174:177], v[214:217], v[6:9]
	v_mfma_f32_16x16x32_bf16 v[2:5], v[182:185], v[214:217], v[2:5]
	s_setprio 0
	s_barrier
	s_add_i32 s66, s66, 2
	s_add_u32 s64, s64, 0x100
	s_addc_u32 s65, s65, 0
	s_cmp_gt_u32 s66, 41
	s_mov_b64 s[22:23], s[24:25]
	s_cbranch_scc0 .LBB0_2367
	s_and_b64 vcc, exec, s[10:11]
	s_cbranch_vccz .LBB0_2370
	s_barrier
